# first K-iteration of each unit peeled with C=0 first-touch MFMAs (no accumulator clearing moves), steady-state loop without first-barrier skip test
# speedup vs baseline: 1.0154x; 1.0154x over previous
; #define G_STAGE(bufoff, gbase, o0, h64) do { \
;         __builtin_amdgcn_global_load_lds((const unsigned*)((const char*)(gbase) + (o0)), (LAS unsigned*)(lds + (bufoff) + ldsw), 16, 0, 0); \
;         __builtin_amdgcn_global_load_lds((const unsigned*)((const char*)(gbase) + (h64) + (o0)), (LAS unsigned*)(lds + (bufoff) + ldsw + 8192), 16, 0, 0); } while (0)
; #define G_LDA(dst, b, h) do { _Pragma("unroll") for (int m = 0; m < 4; ++m) _Pragma("unroll") for (int k = 0; k < 2; ++k) dst[m][k] = *(const LAS bf16x8*)(lds + G_SA(b, h) + aoff + m * 2048 + k * 1024); } while (0)
; #define G_LDB(dst, b, h) do { _Pragma("unroll") for (int n = 0; n < 2; ++n) _Pragma("unroll") for (int k = 0; k < 2; ++k) dst[n][k] = *(const LAS bf16x8*)(lds + G_SB(b, h) + boff + n * 2048 + k * 1024); } while (0)
; #define G_WAIT_L(n) asm volatile("s_waitcnt lgkmcnt(" #n ")" ::: "memory")
; #define G_BAR __builtin_amdgcn_s_barrier()
; #define G_SCHED __builtin_amdgcn_sched_barrier(0)
;     ...
;         for (int t = 0; t < nt; t += 2) {
;             const bool last = (t == nt - 2);
;             const char* a1 = cA + (size_t)(t + 1) * ckA;
;             const char* a2 = last ? nA : cA + (size_t)(t + 2) * ckA; const char* b2 = last ? nB : cB + (size_t)(t + 2) * kB;
;             const char* a3 = a2 + ckA; const char* b3 = b2 + kB;
;             G_LDB(B0, 0, 0); G_SCHED; G_LDA(At, 0, 0); G_STAGE(G_SA(1, 1), a1 + chA, cA0, qA);
;             G_WAIT_L(8); G_BAR; G_WAIT_L(0); G_MMA(0, 0, At, B0); G_BAR; G_SCHED;
;             G_LDB(B1, 0, 1); G_STAGE(G_SB(0, 0), b2, cB0, qB);
;             G_BAR; G_WAIT_L(0); G_MMA(0, 1, At, B1); G_BAR;
;             G_LDA(At, 0, 1); G_STAGE(G_SA(0, 0), a2, cA0, qA);
;             G_BAR; G_WAIT_L(0); G_MMA(1, 0, At, B0); G_BAR; G_SCHED;
;     ...
;         for (int a = 0; a < 2; ++a)
; #pragma unroll
;             for (int b = 0; b < 2; ++b)
; #pragma unroll
;                 for (int m = 0; m < 4; ++m)
; #pragma unroll
;                     for (int n = 0; n < 2; ++n) acc[a][b][m][n] = (f32x4){0.f, 0.f, 0.f, 0.f};
.LBB0_211:
	s_add_u32 s2, s2, 0x40080
	s_addc_u32 s3, s3, 0
	s_add_u32 s7, s22, 0x100
	s_addc_u32 s22, s23, 0
	s_mov_b32 s23, -2
	s_mov_b64 s[52:53], 0x40000
	s_mov_b64 s[54:55], 0x60000
	s_mov_b64 s[58:59], 0x20080
	s_mov_b64 s[62:63], 0x40080
	s_mov_b64 s[64:65], 0x60080
	s_cmp_eq_u32 s101, 2
	s_cselect_b32 s101, 0, s101
	v_add_u32_e32 v255, 0x10000, v167
	s_add_u32 s4, s2, 0xfffc0080
	s_addc_u32 s5, s3, -1
	s_add_i32 s41, 0, 0x10000
	ds_read_b128 v[136:139], v255 offset:0
	ds_read_b128 v[144:147], v255 offset:1024
	ds_read_b128 v[148:151], v255 offset:2048
	ds_read_b128 v[152:155], v255 offset:3072
	s_cmp_eq_u32 s23, 12
	s_cselect_b32 s43, s19, s5
	s_cselect_b32 s42, s18, s4
	s_cselect_b32 s51, s21, s22
	s_cselect_b32 s50, s20, s7
	s_add_i32 m0, s27, 0xc000
	ds_read_b128 v[156:159], v172
	ds_read_b128 v[160:163], v172 offset:1024
	ds_read_b128 v[174:177], v172 offset:2048
	ds_read_b128 v[178:181], v172 offset:3072
	ds_read_b128 v[182:185], v172 offset:4096
	ds_read_b128 v[196:199], v172 offset:5120
	ds_read_b128 v[200:203], v172 offset:6144
	ds_read_b128 v[204:207], v172 offset:7168
	global_load_lds_dwordx4 v142, s[2:3]
	s_add_i32 m0, s27, 0xe000
	s_nop 0
	s_add_u32 vcc_lo, s2, s0
	s_addc_u32 vcc_hi, s3, s1
	global_load_lds_dwordx4 v142, vcc
	s_waitcnt lgkmcnt(8)
	s_cmp_eq_u32 s101, 1
	s_cbranch_scc1 .Ldb_WIN_skp
	s_barrier
.Ldb_WIN_skp:
	s_mov_b32 s101, 0
	s_waitcnt lgkmcnt(0)
	v_mfma_f32_16x16x32_bf16 v[132:135], v[136:139], v[156:159], 0
	v_mfma_f32_16x16x32_bf16 v[128:131], v[148:151], v[156:159], 0
	v_mfma_f32_16x16x32_bf16 v[116:119], v[136:139], v[174:177], 0
	v_mfma_f32_16x16x32_bf16 v[112:115], v[148:151], v[174:177], 0
	v_mfma_f32_16x16x32_bf16 v[100:103], v[136:139], v[182:185], 0
	v_mfma_f32_16x16x32_bf16 v[96:99], v[148:151], v[182:185], 0
	v_mfma_f32_16x16x32_bf16 v[84:87], v[136:139], v[200:203], 0
	v_mfma_f32_16x16x32_bf16 v[80:83], v[148:151], v[200:203], 0
	v_mfma_f32_16x16x32_bf16 v[132:135], v[144:147], v[160:163], v[132:135]
	v_mfma_f32_16x16x32_bf16 v[128:131], v[152:155], v[160:163], v[128:131]
	v_mfma_f32_16x16x32_bf16 v[116:119], v[144:147], v[178:181], v[116:119]
	v_mfma_f32_16x16x32_bf16 v[112:115], v[152:155], v[178:181], v[112:115]
	v_mfma_f32_16x16x32_bf16 v[100:103], v[144:147], v[196:199], v[100:103]
	v_mfma_f32_16x16x32_bf16 v[96:99], v[152:155], v[196:199], v[96:99]
	v_mfma_f32_16x16x32_bf16 v[84:87], v[144:147], v[204:207], v[84:87]
	v_mfma_f32_16x16x32_bf16 v[80:83], v[152:155], v[204:207], v[80:83]
	s_barrier
	s_add_i32 s4, 0, 0x14000
	s_add_i32 s5, s41, s26
	s_mov_b32 m0, s5
	ds_read_b128 v[208:211], v255 offset:16384
	ds_read_b128 v[212:215], v255 offset:17408
	ds_read_b128 v[216:219], v255 offset:18432
	ds_read_b128 v[220:223], v255 offset:19456
	global_load_lds_dwordx4 v140, s[50:51]
	s_add_i32 m0, s5, 0x2000
	s_nop 0
	s_add_u32 vcc_lo, s50, s0
	s_addc_u32 vcc_hi, s51, s1
	global_load_lds_dwordx4 v140, vcc
	s_barrier
	s_waitcnt lgkmcnt(0)
	v_mfma_f32_16x16x32_bf16 v[124:127], v[208:211], v[156:159], 0
	v_mfma_f32_16x16x32_bf16 v[120:123], v[216:219], v[156:159], 0
	v_mfma_f32_16x16x32_bf16 v[108:111], v[208:211], v[174:177], 0
	v_mfma_f32_16x16x32_bf16 v[104:107], v[216:219], v[174:177], 0
	v_mfma_f32_16x16x32_bf16 v[92:95], v[208:211], v[182:185], 0
	v_mfma_f32_16x16x32_bf16 v[88:91], v[216:219], v[182:185], 0
	v_mfma_f32_16x16x32_bf16 v[76:79], v[208:211], v[200:203], 0
	v_mfma_f32_16x16x32_bf16 v[72:75], v[216:219], v[200:203], 0
	v_mfma_f32_16x16x32_bf16 v[124:127], v[212:215], v[160:163], v[124:127]
	v_mfma_f32_16x16x32_bf16 v[120:123], v[220:223], v[160:163], v[120:123]
	v_mfma_f32_16x16x32_bf16 v[108:111], v[212:215], v[178:181], v[108:111]
	v_mfma_f32_16x16x32_bf16 v[104:107], v[220:223], v[178:181], v[104:107]
	v_mfma_f32_16x16x32_bf16 v[92:95], v[212:215], v[196:199], v[92:95]
	v_mfma_f32_16x16x32_bf16 v[88:91], v[220:223], v[196:199], v[88:91]
	v_mfma_f32_16x16x32_bf16 v[76:79], v[212:215], v[204:207], v[76:79]
	v_mfma_f32_16x16x32_bf16 v[72:75], v[220:223], v[204:207], v[72:75]
	s_barrier
	s_mov_b32 m0, s27
	ds_read_b128 v[156:159], v172 offset:16384
	ds_read_b128 v[160:163], v172 offset:17408
	ds_read_b128 v[174:177], v172 offset:18432
	ds_read_b128 v[178:181], v172 offset:19456
	ds_read_b128 v[182:185], v172 offset:20480
	ds_read_b128 v[196:199], v172 offset:21504
	ds_read_b128 v[200:203], v172 offset:22528
	ds_read_b128 v[204:207], v172 offset:23552
	global_load_lds_dwordx4 v2, s[42:43]
	s_mov_b32 m0, s28
	s_nop 0
	s_add_u32 vcc_lo, s42, s0
	s_addc_u32 vcc_hi, s43, s1
	global_load_lds_dwordx4 v2, vcc
	s_barrier
	s_waitcnt lgkmcnt(0)
	v_mfma_f32_16x16x32_bf16 v[68:71], v[136:139], v[156:159], 0
	v_mfma_f32_16x16x32_bf16 v[64:67], v[148:151], v[156:159], 0
	v_mfma_f32_16x16x32_bf16 v[52:55], v[136:139], v[174:177], 0
	v_mfma_f32_16x16x32_bf16 v[48:51], v[148:151], v[174:177], 0
	v_mfma_f32_16x16x32_bf16 v[36:39], v[136:139], v[182:185], 0
	v_mfma_f32_16x16x32_bf16 v[32:35], v[148:151], v[182:185], 0
	v_mfma_f32_16x16x32_bf16 v[20:23], v[136:139], v[200:203], 0
	v_mfma_f32_16x16x32_bf16 v[16:19], v[148:151], v[200:203], 0
	v_mfma_f32_16x16x32_bf16 v[68:71], v[144:147], v[160:163], v[68:71]
	v_mfma_f32_16x16x32_bf16 v[64:67], v[152:155], v[160:163], v[64:67]
	v_mfma_f32_16x16x32_bf16 v[52:55], v[144:147], v[178:181], v[52:55]
	v_mfma_f32_16x16x32_bf16 v[48:51], v[152:155], v[178:181], v[48:51]
	v_mfma_f32_16x16x32_bf16 v[36:39], v[144:147], v[196:199], v[36:39]
	v_mfma_f32_16x16x32_bf16 v[32:35], v[152:155], v[196:199], v[32:35]
	v_mfma_f32_16x16x32_bf16 v[20:23], v[144:147], v[204:207], v[20:23]
	v_mfma_f32_16x16x32_bf16 v[16:19], v[152:155], v[204:207], v[16:19]
	s_barrier
; #define G_STAGE(bufoff, gbase, o0, h64) do { \
;         __builtin_amdgcn_global_load_lds((const unsigned*)((const char*)(gbase) + (o0)), (LAS unsigned*)(lds + (bufoff) + ldsw), 16, 0, 0); \
;         __builtin_amdgcn_global_load_lds((const unsigned*)((const char*)(gbase) + (h64) + (o0)), (LAS unsigned*)(lds + (bufoff) + ldsw + 8192), 16, 0, 0); } while (0)
; #define G_LDA(dst, b, h) do { _Pragma("unroll") for (int m = 0; m < 4; ++m) _Pragma("unroll") for (int k = 0; k < 2; ++k) dst[m][k] = *(const LAS bf16x8*)(lds + G_SA(b, h) + aoff + m * 2048 + k * 1024); } while (0)
; #define G_LDB(dst, b, h) do { _Pragma("unroll") for (int n = 0; n < 2; ++n) _Pragma("unroll") for (int k = 0; k < 2; ++k) dst[n][k] = *(const LAS bf16x8*)(lds + G_SB(b, h) + boff + n * 2048 + k * 1024); } while (0)
; #define G_WAIT_V(n) asm volatile("s_waitcnt vmcnt(" #n ")" ::: "memory")
; #define G_WAIT_L(n) asm volatile("s_waitcnt lgkmcnt(" #n ")" ::: "memory")
; #define G_BAR __builtin_amdgcn_s_barrier()
; #define G_SCHED __builtin_amdgcn_sched_barrier(0)
;     ...
;             G_BAR; G_WAIT_L(0); G_MMA(1, 0, At, B0); G_BAR; G_SCHED;
;             G_STAGE(G_SB(0, 1), b2 + chB, cB0, qB);
;             G_WAIT_V(6); G_BAR; G_MMA(1, 1, At, B1); G_BAR;
;             G_LDB(B0, 1, 0); G_SCHED; G_LDA(At, 1, 0); G_STAGE(G_SA(0, 1), a2 + chA, cA0, qA);
;             G_WAIT_L(8); G_BAR; G_WAIT_L(0); G_MMA(0, 0, At, B0); G_BAR; G_SCHED;
;             G_LDB(B1, 1, 1); G_STAGE(G_SB(1, 0), b3, cB0, qB);
;             G_BAR; G_WAIT_L(0); G_MMA(0, 1, At, B1); G_BAR;
;             G_LDA(At, 1, 1); G_STAGE(G_SA(1, 0), a3, cA0, qA);
;             G_BAR; G_WAIT_L(0); G_MMA(1, 0, At, B0); G_BAR; G_SCHED;
	s_add_i32 s4, s4, s26
	s_mov_b32 m0, s4
	s_nop 0
	s_add_u32 vcc_lo, s50, s52
	s_addc_u32 vcc_hi, s51, s53
	global_load_lds_dwordx4 v140, vcc
	s_add_i32 m0, s4, 0x2000
	s_nop 0
	s_add_u32 vcc_lo, s50, s54
	s_addc_u32 vcc_hi, s51, s55
	global_load_lds_dwordx4 v140, vcc
	s_waitcnt vmcnt(6)
	s_barrier
	v_mfma_f32_16x16x32_bf16 v[60:63], v[208:211], v[156:159], 0
	v_mfma_f32_16x16x32_bf16 v[56:59], v[216:219], v[156:159], 0
	v_mfma_f32_16x16x32_bf16 v[44:47], v[208:211], v[174:177], 0
	v_mfma_f32_16x16x32_bf16 v[40:43], v[216:219], v[174:177], 0
	v_mfma_f32_16x16x32_bf16 v[28:31], v[208:211], v[182:185], 0
	v_mfma_f32_16x16x32_bf16 v[24:27], v[216:219], v[182:185], 0
	v_mfma_f32_16x16x32_bf16 v[12:15], v[208:211], v[200:203], 0
	v_mfma_f32_16x16x32_bf16 v[8:11], v[216:219], v[200:203], 0
	v_mfma_f32_16x16x32_bf16 v[60:63], v[212:215], v[160:163], v[60:63]
	v_mfma_f32_16x16x32_bf16 v[56:59], v[220:223], v[160:163], v[56:59]
	v_mfma_f32_16x16x32_bf16 v[44:47], v[212:215], v[178:181], v[44:47]
	v_mfma_f32_16x16x32_bf16 v[40:43], v[220:223], v[178:181], v[40:43]
	v_mfma_f32_16x16x32_bf16 v[28:31], v[212:215], v[196:199], v[28:31]
	v_mfma_f32_16x16x32_bf16 v[24:27], v[220:223], v[196:199], v[24:27]
	v_mfma_f32_16x16x32_bf16 v[12:15], v[212:215], v[204:207], v[12:15]
	v_mfma_f32_16x16x32_bf16 v[8:11], v[220:223], v[204:207], v[8:11]
	s_barrier
	s_add_i32 s4, 0, 0x18000
	ds_read_b128 v[136:139], v255 offset:32768
	ds_read_b128 v[144:147], v255 offset:33792
	ds_read_b128 v[148:151], v255 offset:34816
	ds_read_b128 v[152:155], v255 offset:35840
	s_mov_b32 m0, s29
	ds_read_b128 v[156:159], v172 offset:32768
	ds_read_b128 v[160:163], v172 offset:33792
	ds_read_b128 v[174:177], v172 offset:34816
	ds_read_b128 v[178:181], v172 offset:35840
	ds_read_b128 v[182:185], v172 offset:36864
	ds_read_b128 v[196:199], v172 offset:37888
	ds_read_b128 v[200:203], v172 offset:38912
	ds_read_b128 v[204:207], v172 offset:39936
	s_add_u32 vcc_lo, s42, s52
	s_addc_u32 vcc_hi, s43, s53
	global_load_lds_dwordx4 v2, vcc
	s_mov_b32 m0, s30
	s_nop 0
	s_add_u32 vcc_lo, s42, s54
	s_addc_u32 vcc_hi, s43, s55
	global_load_lds_dwordx4 v2, vcc
	s_waitcnt lgkmcnt(8)
	s_barrier
	s_waitcnt lgkmcnt(0)
	v_mfma_f32_16x16x32_bf16 v[132:135], v[136:139], v[156:159], v[132:135]
	v_mfma_f32_16x16x32_bf16 v[128:131], v[148:151], v[156:159], v[128:131]
	v_mfma_f32_16x16x32_bf16 v[116:119], v[136:139], v[174:177], v[116:119]
	v_mfma_f32_16x16x32_bf16 v[112:115], v[148:151], v[174:177], v[112:115]
	v_mfma_f32_16x16x32_bf16 v[100:103], v[136:139], v[182:185], v[100:103]
	v_mfma_f32_16x16x32_bf16 v[96:99], v[148:151], v[182:185], v[96:99]
	v_mfma_f32_16x16x32_bf16 v[84:87], v[136:139], v[200:203], v[84:87]
	v_mfma_f32_16x16x32_bf16 v[80:83], v[148:151], v[200:203], v[80:83]
	v_mfma_f32_16x16x32_bf16 v[132:135], v[144:147], v[160:163], v[132:135]
	v_mfma_f32_16x16x32_bf16 v[128:131], v[152:155], v[160:163], v[128:131]
	v_mfma_f32_16x16x32_bf16 v[116:119], v[144:147], v[178:181], v[116:119]
	v_mfma_f32_16x16x32_bf16 v[112:115], v[152:155], v[178:181], v[112:115]
	v_mfma_f32_16x16x32_bf16 v[100:103], v[144:147], v[196:199], v[100:103]
	v_mfma_f32_16x16x32_bf16 v[96:99], v[152:155], v[196:199], v[96:99]
	v_mfma_f32_16x16x32_bf16 v[84:87], v[144:147], v[204:207], v[84:87]
	v_mfma_f32_16x16x32_bf16 v[80:83], v[152:155], v[204:207], v[80:83]
	s_barrier
	s_add_i32 s5, 0, 0x1c000
	s_add_i32 s4, s4, s26
	s_mov_b32 m0, s4
	ds_read_b128 v[208:211], v255 offset:49152
	ds_read_b128 v[212:215], v255 offset:50176
	ds_read_b128 v[216:219], v255 offset:51200
	ds_read_b128 v[220:223], v255 offset:52224
	s_add_u32 vcc_lo, s50, s46
	s_addc_u32 vcc_hi, s51, s47
	global_load_lds_dwordx4 v140, vcc
	s_add_i32 m0, s4, 0x2000
	s_nop 0
	s_add_u32 vcc_lo, s50, s58
	s_addc_u32 vcc_hi, s51, s59
	global_load_lds_dwordx4 v140, vcc
	s_barrier
	s_waitcnt lgkmcnt(0)
	v_mfma_f32_16x16x32_bf16 v[124:127], v[208:211], v[156:159], v[124:127]
	v_mfma_f32_16x16x32_bf16 v[120:123], v[216:219], v[156:159], v[120:123]
	v_mfma_f32_16x16x32_bf16 v[108:111], v[208:211], v[174:177], v[108:111]
	v_mfma_f32_16x16x32_bf16 v[104:107], v[216:219], v[174:177], v[104:107]
	v_mfma_f32_16x16x32_bf16 v[92:95], v[208:211], v[182:185], v[92:95]
	v_mfma_f32_16x16x32_bf16 v[88:91], v[216:219], v[182:185], v[88:91]
	v_mfma_f32_16x16x32_bf16 v[76:79], v[208:211], v[200:203], v[76:79]
	v_mfma_f32_16x16x32_bf16 v[72:75], v[216:219], v[200:203], v[72:75]
	v_mfma_f32_16x16x32_bf16 v[124:127], v[212:215], v[160:163], v[124:127]
	v_mfma_f32_16x16x32_bf16 v[120:123], v[220:223], v[160:163], v[120:123]
	v_mfma_f32_16x16x32_bf16 v[108:111], v[212:215], v[178:181], v[108:111]
	v_mfma_f32_16x16x32_bf16 v[104:107], v[220:223], v[178:181], v[104:107]
	v_mfma_f32_16x16x32_bf16 v[92:95], v[212:215], v[196:199], v[92:95]
	v_mfma_f32_16x16x32_bf16 v[88:91], v[220:223], v[196:199], v[88:91]
	v_mfma_f32_16x16x32_bf16 v[76:79], v[212:215], v[204:207], v[76:79]
	v_mfma_f32_16x16x32_bf16 v[72:75], v[220:223], v[204:207], v[72:75]
	s_barrier
	s_mov_b32 m0, s31
	ds_read_b128 v[156:159], v172 offset:49152
	ds_read_b128 v[160:163], v172 offset:50176
	ds_read_b128 v[174:177], v172 offset:51200
	ds_read_b128 v[178:181], v172 offset:52224
	ds_read_b128 v[182:185], v172 offset:53248
	ds_read_b128 v[196:199], v172 offset:54272
	ds_read_b128 v[200:203], v172 offset:55296
	ds_read_b128 v[204:207], v172 offset:56320
	s_add_u32 vcc_lo, s42, s46
	s_addc_u32 vcc_hi, s43, s47
	global_load_lds_dwordx4 v2, vcc
	s_mov_b32 m0, s34
	s_nop 0
	s_add_u32 vcc_lo, s42, s58
	s_addc_u32 vcc_hi, s43, s59
	global_load_lds_dwordx4 v2, vcc
	s_barrier
; #define G_STAGE(bufoff, gbase, o0, h64) do { \
;         __builtin_amdgcn_global_load_lds((const unsigned*)((const char*)(gbase) + (o0)), (LAS unsigned*)(lds + (bufoff) + ldsw), 16, 0, 0); \
;         __builtin_amdgcn_global_load_lds((const unsigned*)((const char*)(gbase) + (h64) + (o0)), (LAS unsigned*)(lds + (bufoff) + ldsw + 8192), 16, 0, 0); } while (0)
; #define G_LDA(dst, b, h) do { _Pragma("unroll") for (int m = 0; m < 4; ++m) _Pragma("unroll") for (int k = 0; k < 2; ++k) dst[m][k] = *(const LAS bf16x8*)(lds + G_SA(b, h) + aoff + m * 2048 + k * 1024); } while (0)
; #define G_LDB(dst, b, h) do { _Pragma("unroll") for (int n = 0; n < 2; ++n) _Pragma("unroll") for (int k = 0; k < 2; ++k) dst[n][k] = *(const LAS bf16x8*)(lds + G_SB(b, h) + boff + n * 2048 + k * 1024); } while (0)
; #define G_WAIT_V(n) asm volatile("s_waitcnt vmcnt(" #n ")" ::: "memory")
; #define G_WAIT_L(n) asm volatile("s_waitcnt lgkmcnt(" #n ")" ::: "memory")
; #define G_BAR __builtin_amdgcn_s_barrier()
; #define G_SCHED __builtin_amdgcn_sched_barrier(0)
;     ...
;         for (int t = 0; t < nt; t += 2) {
;             const bool last = (t == nt - 2);
;             const char* a1 = cA + (size_t)(t + 1) * ckA;
;             const char* a2 = last ? nA : cA + (size_t)(t + 2) * ckA; const char* b2 = last ? nB : cB + (size_t)(t + 2) * kB;
;             const char* a3 = a2 + ckA; const char* b3 = b2 + kB;
;             G_LDB(B0, 0, 0); G_SCHED; G_LDA(At, 0, 0); G_STAGE(G_SA(1, 1), a1 + chA, cA0, qA);
;             G_WAIT_L(8); G_BAR; G_WAIT_L(0); G_MMA(0, 0, At, B0); G_BAR; G_SCHED;
;     ...
;             G_BAR; G_WAIT_L(0); G_MMA(1, 0, At, B0); G_BAR; G_SCHED;
;             G_STAGE(G_SB(1, 1), b3 + chB, cB0, qB);
;             G_WAIT_V(6); G_BAR; G_MMA(1, 1, At, B1); G_BAR;
;         }
	s_waitcnt lgkmcnt(0)
	v_mfma_f32_16x16x32_bf16 v[68:71], v[136:139], v[156:159], v[68:71]
	v_mfma_f32_16x16x32_bf16 v[64:67], v[148:151], v[156:159], v[64:67]
	v_mfma_f32_16x16x32_bf16 v[52:55], v[136:139], v[174:177], v[52:55]
	v_mfma_f32_16x16x32_bf16 v[48:51], v[148:151], v[174:177], v[48:51]
	v_mfma_f32_16x16x32_bf16 v[36:39], v[136:139], v[182:185], v[36:39]
	v_mfma_f32_16x16x32_bf16 v[32:35], v[148:151], v[182:185], v[32:35]
	v_mfma_f32_16x16x32_bf16 v[20:23], v[136:139], v[200:203], v[20:23]
	v_mfma_f32_16x16x32_bf16 v[16:19], v[148:151], v[200:203], v[16:19]
	v_mfma_f32_16x16x32_bf16 v[68:71], v[144:147], v[160:163], v[68:71]
	v_mfma_f32_16x16x32_bf16 v[64:67], v[152:155], v[160:163], v[64:67]
	v_mfma_f32_16x16x32_bf16 v[52:55], v[144:147], v[178:181], v[52:55]
	v_mfma_f32_16x16x32_bf16 v[48:51], v[152:155], v[178:181], v[48:51]
	v_mfma_f32_16x16x32_bf16 v[36:39], v[144:147], v[196:199], v[36:39]
	v_mfma_f32_16x16x32_bf16 v[32:35], v[152:155], v[196:199], v[32:35]
	v_mfma_f32_16x16x32_bf16 v[20:23], v[144:147], v[204:207], v[20:23]
	v_mfma_f32_16x16x32_bf16 v[16:19], v[152:155], v[204:207], v[16:19]
	s_barrier
	s_add_i32 s4, s5, s26
	s_mov_b32 m0, s4
	s_nop 0
	s_add_u32 vcc_lo, s50, s62
	s_addc_u32 vcc_hi, s51, s63
	global_load_lds_dwordx4 v140, vcc
	s_add_i32 m0, s4, 0x2000
	s_nop 0
	s_add_u32 vcc_lo, s50, s64
	s_addc_u32 vcc_hi, s51, s65
	global_load_lds_dwordx4 v140, vcc
	s_add_i32 s23, s23, 2
	s_add_u32 s2, s2, 0x100
	s_addc_u32 s3, s3, 0
	s_add_u32 s7, s7, 0x100
	s_addc_u32 s22, s22, 0
	s_cmp_gt_u32 s23, 13
	s_waitcnt vmcnt(6)
	s_barrier
	v_mfma_f32_16x16x32_bf16 v[60:63], v[208:211], v[156:159], v[60:63]
	v_mfma_f32_16x16x32_bf16 v[56:59], v[216:219], v[156:159], v[56:59]
	v_mfma_f32_16x16x32_bf16 v[44:47], v[208:211], v[174:177], v[44:47]
	v_mfma_f32_16x16x32_bf16 v[40:43], v[216:219], v[174:177], v[40:43]
	v_mfma_f32_16x16x32_bf16 v[28:31], v[208:211], v[182:185], v[28:31]
	v_mfma_f32_16x16x32_bf16 v[24:27], v[216:219], v[182:185], v[24:27]
	v_mfma_f32_16x16x32_bf16 v[12:15], v[208:211], v[200:203], v[12:15]
	v_mfma_f32_16x16x32_bf16 v[8:11], v[216:219], v[200:203], v[8:11]
	v_mfma_f32_16x16x32_bf16 v[60:63], v[212:215], v[160:163], v[60:63]
	v_mfma_f32_16x16x32_bf16 v[56:59], v[220:223], v[160:163], v[56:59]
	v_mfma_f32_16x16x32_bf16 v[44:47], v[212:215], v[178:181], v[44:47]
	v_mfma_f32_16x16x32_bf16 v[40:43], v[220:223], v[178:181], v[40:43]
	v_mfma_f32_16x16x32_bf16 v[28:31], v[212:215], v[196:199], v[28:31]
	v_mfma_f32_16x16x32_bf16 v[24:27], v[220:223], v[196:199], v[24:27]
	v_mfma_f32_16x16x32_bf16 v[12:15], v[212:215], v[204:207], v[12:15]
	v_mfma_f32_16x16x32_bf16 v[8:11], v[220:223], v[204:207], v[8:11]
	s_cbranch_scc0 .Ldb_WIN_cont
	s_branch .Ldb_WIN_xl
.LBB0_212:
	s_add_u32 s4, s2, 0xfffc0080
	s_addc_u32 s5, s3, -1
	s_add_i32 s41, 0, 0x10000
	ds_read_b128 v[136:139], v255 offset:0
	ds_read_b128 v[144:147], v255 offset:1024
	ds_read_b128 v[148:151], v255 offset:2048
	ds_read_b128 v[152:155], v255 offset:3072
	s_cmp_eq_u32 s23, 12
	s_cselect_b32 s43, s19, s5
	s_cselect_b32 s42, s18, s4
	s_cselect_b32 s51, s21, s22
	s_cselect_b32 s50, s20, s7
	s_add_i32 m0, s27, 0xc000
	ds_read_b128 v[156:159], v172
	ds_read_b128 v[160:163], v172 offset:1024
	ds_read_b128 v[174:177], v172 offset:2048
	ds_read_b128 v[178:181], v172 offset:3072
	ds_read_b128 v[182:185], v172 offset:4096
	ds_read_b128 v[196:199], v172 offset:5120
	ds_read_b128 v[200:203], v172 offset:6144
	ds_read_b128 v[204:207], v172 offset:7168
	global_load_lds_dwordx4 v142, s[2:3]
	s_add_i32 m0, s27, 0xe000
	s_nop 0
	s_add_u32 vcc_lo, s2, s0
	s_addc_u32 vcc_hi, s3, s1
	global_load_lds_dwordx4 v142, vcc
	s_waitcnt lgkmcnt(8)
	s_barrier
	s_waitcnt lgkmcnt(0)
	v_mfma_f32_16x16x32_bf16 v[132:135], v[136:139], v[156:159], v[132:135]
	v_mfma_f32_16x16x32_bf16 v[128:131], v[148:151], v[156:159], v[128:131]
	v_mfma_f32_16x16x32_bf16 v[116:119], v[136:139], v[174:177], v[116:119]
	v_mfma_f32_16x16x32_bf16 v[112:115], v[148:151], v[174:177], v[112:115]
	v_mfma_f32_16x16x32_bf16 v[100:103], v[136:139], v[182:185], v[100:103]
	v_mfma_f32_16x16x32_bf16 v[96:99], v[148:151], v[182:185], v[96:99]
	v_mfma_f32_16x16x32_bf16 v[84:87], v[136:139], v[200:203], v[84:87]
	v_mfma_f32_16x16x32_bf16 v[80:83], v[148:151], v[200:203], v[80:83]
	v_mfma_f32_16x16x32_bf16 v[132:135], v[144:147], v[160:163], v[132:135]
	v_mfma_f32_16x16x32_bf16 v[128:131], v[152:155], v[160:163], v[128:131]
	v_mfma_f32_16x16x32_bf16 v[116:119], v[144:147], v[178:181], v[116:119]
	v_mfma_f32_16x16x32_bf16 v[112:115], v[152:155], v[178:181], v[112:115]
	v_mfma_f32_16x16x32_bf16 v[100:103], v[144:147], v[196:199], v[100:103]
	v_mfma_f32_16x16x32_bf16 v[96:99], v[152:155], v[196:199], v[96:99]
	v_mfma_f32_16x16x32_bf16 v[84:87], v[144:147], v[204:207], v[84:87]
	v_mfma_f32_16x16x32_bf16 v[80:83], v[152:155], v[204:207], v[80:83]
	s_barrier
	s_add_i32 s4, 0, 0x14000
	s_add_i32 s5, s41, s26
	s_mov_b32 m0, s5
	ds_read_b128 v[208:211], v255 offset:16384
	ds_read_b128 v[212:215], v255 offset:17408
	ds_read_b128 v[216:219], v255 offset:18432
	ds_read_b128 v[220:223], v255 offset:19456
	global_load_lds_dwordx4 v140, s[50:51]
	s_add_i32 m0, s5, 0x2000
	s_nop 0
	s_add_u32 vcc_lo, s50, s0
	s_addc_u32 vcc_hi, s51, s1
	global_load_lds_dwordx4 v140, vcc
	s_barrier
; #define G_STAGE(bufoff, gbase, o0, h64) do { \
;         __builtin_amdgcn_global_load_lds((const unsigned*)((const char*)(gbase) + (o0)), (LAS unsigned*)(lds + (bufoff) + ldsw), 16, 0, 0); \
;         __builtin_amdgcn_global_load_lds((const unsigned*)((const char*)(gbase) + (h64) + (o0)), (LAS unsigned*)(lds + (bufoff) + ldsw + 8192), 16, 0, 0); } while (0)
; #define G_LDA(dst, b, h) do { _Pragma("unroll") for (int m = 0; m < 4; ++m) _Pragma("unroll") for (int k = 0; k < 2; ++k) dst[m][k] = *(const LAS bf16x8*)(lds + G_SA(b, h) + aoff + m * 2048 + k * 1024); } while (0)
; #define G_LDB(dst, b, h) do { _Pragma("unroll") for (int n = 0; n < 2; ++n) _Pragma("unroll") for (int k = 0; k < 2; ++k) dst[n][k] = *(const LAS bf16x8*)(lds + G_SB(b, h) + boff + n * 2048 + k * 1024); } while (0)
; #define G_WAIT_V(n) asm volatile("s_waitcnt vmcnt(" #n ")" ::: "memory")
; #define G_WAIT_L(n) asm volatile("s_waitcnt lgkmcnt(" #n ")" ::: "memory")
; #define G_BAR __builtin_amdgcn_s_barrier()
; #define G_SCHED __builtin_amdgcn_sched_barrier(0)
;     ...
;             G_WAIT_L(8); G_BAR; G_WAIT_L(0); G_MMA(0, 0, At, B0); G_BAR; G_SCHED;
;             G_LDB(B1, 0, 1); G_STAGE(G_SB(0, 0), b2, cB0, qB);
;             G_BAR; G_WAIT_L(0); G_MMA(0, 1, At, B1); G_BAR;
;             G_LDA(At, 0, 1); G_STAGE(G_SA(0, 0), a2, cA0, qA);
;             G_BAR; G_WAIT_L(0); G_MMA(1, 0, At, B0); G_BAR; G_SCHED;
;             G_STAGE(G_SB(0, 1), b2 + chB, cB0, qB);
;             G_WAIT_V(6); G_BAR; G_MMA(1, 1, At, B1); G_BAR;
;             G_LDB(B0, 1, 0); G_SCHED; G_LDA(At, 1, 0); G_STAGE(G_SA(0, 1), a2 + chA, cA0, qA);
;             G_WAIT_L(8); G_BAR; G_WAIT_L(0); G_MMA(0, 0, At, B0); G_BAR; G_SCHED;
	s_waitcnt lgkmcnt(0)
	v_mfma_f32_16x16x32_bf16 v[124:127], v[208:211], v[156:159], v[124:127]
	v_mfma_f32_16x16x32_bf16 v[120:123], v[216:219], v[156:159], v[120:123]
	v_mfma_f32_16x16x32_bf16 v[108:111], v[208:211], v[174:177], v[108:111]
	v_mfma_f32_16x16x32_bf16 v[104:107], v[216:219], v[174:177], v[104:107]
	v_mfma_f32_16x16x32_bf16 v[92:95], v[208:211], v[182:185], v[92:95]
	v_mfma_f32_16x16x32_bf16 v[88:91], v[216:219], v[182:185], v[88:91]
	v_mfma_f32_16x16x32_bf16 v[76:79], v[208:211], v[200:203], v[76:79]
	v_mfma_f32_16x16x32_bf16 v[72:75], v[216:219], v[200:203], v[72:75]
	v_mfma_f32_16x16x32_bf16 v[124:127], v[212:215], v[160:163], v[124:127]
	v_mfma_f32_16x16x32_bf16 v[120:123], v[220:223], v[160:163], v[120:123]
	v_mfma_f32_16x16x32_bf16 v[108:111], v[212:215], v[178:181], v[108:111]
	v_mfma_f32_16x16x32_bf16 v[104:107], v[220:223], v[178:181], v[104:107]
	v_mfma_f32_16x16x32_bf16 v[92:95], v[212:215], v[196:199], v[92:95]
	v_mfma_f32_16x16x32_bf16 v[88:91], v[220:223], v[196:199], v[88:91]
	v_mfma_f32_16x16x32_bf16 v[76:79], v[212:215], v[204:207], v[76:79]
	v_mfma_f32_16x16x32_bf16 v[72:75], v[220:223], v[204:207], v[72:75]
	s_barrier
	s_mov_b32 m0, s27
	ds_read_b128 v[156:159], v172 offset:16384
	ds_read_b128 v[160:163], v172 offset:17408
	ds_read_b128 v[174:177], v172 offset:18432
	ds_read_b128 v[178:181], v172 offset:19456
	ds_read_b128 v[182:185], v172 offset:20480
	ds_read_b128 v[196:199], v172 offset:21504
	ds_read_b128 v[200:203], v172 offset:22528
	ds_read_b128 v[204:207], v172 offset:23552
	global_load_lds_dwordx4 v2, s[42:43]
	s_mov_b32 m0, s28
	s_nop 0
	s_add_u32 vcc_lo, s42, s0
	s_addc_u32 vcc_hi, s43, s1
	global_load_lds_dwordx4 v2, vcc
	s_barrier
	s_waitcnt lgkmcnt(0)
	v_mfma_f32_16x16x32_bf16 v[68:71], v[136:139], v[156:159], v[68:71]
	v_mfma_f32_16x16x32_bf16 v[64:67], v[148:151], v[156:159], v[64:67]
	v_mfma_f32_16x16x32_bf16 v[52:55], v[136:139], v[174:177], v[52:55]
	v_mfma_f32_16x16x32_bf16 v[48:51], v[148:151], v[174:177], v[48:51]
	v_mfma_f32_16x16x32_bf16 v[36:39], v[136:139], v[182:185], v[36:39]
	v_mfma_f32_16x16x32_bf16 v[32:35], v[148:151], v[182:185], v[32:35]
	v_mfma_f32_16x16x32_bf16 v[20:23], v[136:139], v[200:203], v[20:23]
	v_mfma_f32_16x16x32_bf16 v[16:19], v[148:151], v[200:203], v[16:19]
	v_mfma_f32_16x16x32_bf16 v[68:71], v[144:147], v[160:163], v[68:71]
	v_mfma_f32_16x16x32_bf16 v[64:67], v[152:155], v[160:163], v[64:67]
	v_mfma_f32_16x16x32_bf16 v[52:55], v[144:147], v[178:181], v[52:55]
	v_mfma_f32_16x16x32_bf16 v[48:51], v[152:155], v[178:181], v[48:51]
	v_mfma_f32_16x16x32_bf16 v[36:39], v[144:147], v[196:199], v[36:39]
	v_mfma_f32_16x16x32_bf16 v[32:35], v[152:155], v[196:199], v[32:35]
	v_mfma_f32_16x16x32_bf16 v[20:23], v[144:147], v[204:207], v[20:23]
	v_mfma_f32_16x16x32_bf16 v[16:19], v[152:155], v[204:207], v[16:19]
	s_barrier
	s_add_i32 s4, s4, s26
	s_mov_b32 m0, s4
	s_nop 0
	s_add_u32 vcc_lo, s50, s52
	s_addc_u32 vcc_hi, s51, s53
	global_load_lds_dwordx4 v140, vcc
	s_add_i32 m0, s4, 0x2000
	s_nop 0
	s_add_u32 vcc_lo, s50, s54
	s_addc_u32 vcc_hi, s51, s55
	global_load_lds_dwordx4 v140, vcc
	s_waitcnt vmcnt(6)
	s_barrier
	v_mfma_f32_16x16x32_bf16 v[60:63], v[208:211], v[156:159], v[60:63]
	v_mfma_f32_16x16x32_bf16 v[56:59], v[216:219], v[156:159], v[56:59]
	v_mfma_f32_16x16x32_bf16 v[44:47], v[208:211], v[174:177], v[44:47]
	v_mfma_f32_16x16x32_bf16 v[40:43], v[216:219], v[174:177], v[40:43]
	v_mfma_f32_16x16x32_bf16 v[28:31], v[208:211], v[182:185], v[28:31]
	v_mfma_f32_16x16x32_bf16 v[24:27], v[216:219], v[182:185], v[24:27]
	v_mfma_f32_16x16x32_bf16 v[12:15], v[208:211], v[200:203], v[12:15]
	v_mfma_f32_16x16x32_bf16 v[8:11], v[216:219], v[200:203], v[8:11]
	v_mfma_f32_16x16x32_bf16 v[60:63], v[212:215], v[160:163], v[60:63]
	v_mfma_f32_16x16x32_bf16 v[56:59], v[220:223], v[160:163], v[56:59]
	v_mfma_f32_16x16x32_bf16 v[44:47], v[212:215], v[178:181], v[44:47]
	v_mfma_f32_16x16x32_bf16 v[40:43], v[220:223], v[178:181], v[40:43]
	v_mfma_f32_16x16x32_bf16 v[28:31], v[212:215], v[196:199], v[28:31]
	v_mfma_f32_16x16x32_bf16 v[24:27], v[220:223], v[196:199], v[24:27]
	v_mfma_f32_16x16x32_bf16 v[12:15], v[212:215], v[204:207], v[12:15]
	v_mfma_f32_16x16x32_bf16 v[8:11], v[220:223], v[204:207], v[8:11]
	s_barrier
	s_add_i32 s4, 0, 0x18000
	ds_read_b128 v[136:139], v255 offset:32768
	ds_read_b128 v[144:147], v255 offset:33792
	ds_read_b128 v[148:151], v255 offset:34816
	ds_read_b128 v[152:155], v255 offset:35840
	s_mov_b32 m0, s29
	ds_read_b128 v[156:159], v172 offset:32768
	ds_read_b128 v[160:163], v172 offset:33792
	ds_read_b128 v[174:177], v172 offset:34816
	ds_read_b128 v[178:181], v172 offset:35840
	ds_read_b128 v[182:185], v172 offset:36864
	ds_read_b128 v[196:199], v172 offset:37888
	ds_read_b128 v[200:203], v172 offset:38912
	ds_read_b128 v[204:207], v172 offset:39936
	s_add_u32 vcc_lo, s42, s52
	s_addc_u32 vcc_hi, s43, s53
	global_load_lds_dwordx4 v2, vcc
	s_mov_b32 m0, s30
	s_nop 0
	s_add_u32 vcc_lo, s42, s54
	s_addc_u32 vcc_hi, s43, s55
	global_load_lds_dwordx4 v2, vcc
	s_waitcnt lgkmcnt(8)
	s_barrier
; #define G_STAGE(bufoff, gbase, o0, h64) do { \
;         __builtin_amdgcn_global_load_lds((const unsigned*)((const char*)(gbase) + (o0)), (LAS unsigned*)(lds + (bufoff) + ldsw), 16, 0, 0); \
;         __builtin_amdgcn_global_load_lds((const unsigned*)((const char*)(gbase) + (h64) + (o0)), (LAS unsigned*)(lds + (bufoff) + ldsw + 8192), 16, 0, 0); } while (0)
; #define G_LDA(dst, b, h) do { _Pragma("unroll") for (int m = 0; m < 4; ++m) _Pragma("unroll") for (int k = 0; k < 2; ++k) dst[m][k] = *(const LAS bf16x8*)(lds + G_SA(b, h) + aoff + m * 2048 + k * 1024); } while (0)
; #define G_LDB(dst, b, h) do { _Pragma("unroll") for (int n = 0; n < 2; ++n) _Pragma("unroll") for (int k = 0; k < 2; ++k) dst[n][k] = *(const LAS bf16x8*)(lds + G_SB(b, h) + boff + n * 2048 + k * 1024); } while (0)
; #define G_WAIT_V(n) asm volatile("s_waitcnt vmcnt(" #n ")" ::: "memory")
; #define G_WAIT_L(n) asm volatile("s_waitcnt lgkmcnt(" #n ")" ::: "memory")
; #define G_BAR __builtin_amdgcn_s_barrier()
; #define G_SCHED __builtin_amdgcn_sched_barrier(0)
;     ...
;             G_WAIT_L(8); G_BAR; G_WAIT_L(0); G_MMA(0, 0, At, B0); G_BAR; G_SCHED;
;             G_LDB(B1, 1, 1); G_STAGE(G_SB(1, 0), b3, cB0, qB);
;             G_BAR; G_WAIT_L(0); G_MMA(0, 1, At, B1); G_BAR;
;             G_LDA(At, 1, 1); G_STAGE(G_SA(1, 0), a3, cA0, qA);
;             G_BAR; G_WAIT_L(0); G_MMA(1, 0, At, B0); G_BAR; G_SCHED;
;             G_STAGE(G_SB(1, 1), b3 + chB, cB0, qB);
;             G_WAIT_V(6); G_BAR; G_MMA(1, 1, At, B1); G_BAR;
;         }
;         E.template run<cs.kind>(acc, cur, tid);
;         if (!has_next) break;
	s_waitcnt lgkmcnt(0)
	v_mfma_f32_16x16x32_bf16 v[132:135], v[136:139], v[156:159], v[132:135]
	v_mfma_f32_16x16x32_bf16 v[128:131], v[148:151], v[156:159], v[128:131]
	v_mfma_f32_16x16x32_bf16 v[116:119], v[136:139], v[174:177], v[116:119]
	v_mfma_f32_16x16x32_bf16 v[112:115], v[148:151], v[174:177], v[112:115]
	v_mfma_f32_16x16x32_bf16 v[100:103], v[136:139], v[182:185], v[100:103]
	v_mfma_f32_16x16x32_bf16 v[96:99], v[148:151], v[182:185], v[96:99]
	v_mfma_f32_16x16x32_bf16 v[84:87], v[136:139], v[200:203], v[84:87]
	v_mfma_f32_16x16x32_bf16 v[80:83], v[148:151], v[200:203], v[80:83]
	v_mfma_f32_16x16x32_bf16 v[132:135], v[144:147], v[160:163], v[132:135]
	v_mfma_f32_16x16x32_bf16 v[128:131], v[152:155], v[160:163], v[128:131]
	v_mfma_f32_16x16x32_bf16 v[116:119], v[144:147], v[178:181], v[116:119]
	v_mfma_f32_16x16x32_bf16 v[112:115], v[152:155], v[178:181], v[112:115]
	v_mfma_f32_16x16x32_bf16 v[100:103], v[144:147], v[196:199], v[100:103]
	v_mfma_f32_16x16x32_bf16 v[96:99], v[152:155], v[196:199], v[96:99]
	v_mfma_f32_16x16x32_bf16 v[84:87], v[144:147], v[204:207], v[84:87]
	v_mfma_f32_16x16x32_bf16 v[80:83], v[152:155], v[204:207], v[80:83]
	s_barrier
	s_add_i32 s5, 0, 0x1c000
	s_add_i32 s4, s4, s26
	s_mov_b32 m0, s4
	ds_read_b128 v[208:211], v255 offset:49152
	ds_read_b128 v[212:215], v255 offset:50176
	ds_read_b128 v[216:219], v255 offset:51200
	ds_read_b128 v[220:223], v255 offset:52224
	s_add_u32 vcc_lo, s50, s46
	s_addc_u32 vcc_hi, s51, s47
	global_load_lds_dwordx4 v140, vcc
	s_add_i32 m0, s4, 0x2000
	s_nop 0
	s_add_u32 vcc_lo, s50, s58
	s_addc_u32 vcc_hi, s51, s59
	global_load_lds_dwordx4 v140, vcc
	s_barrier
	s_waitcnt lgkmcnt(0)
	v_mfma_f32_16x16x32_bf16 v[124:127], v[208:211], v[156:159], v[124:127]
	v_mfma_f32_16x16x32_bf16 v[120:123], v[216:219], v[156:159], v[120:123]
	v_mfma_f32_16x16x32_bf16 v[108:111], v[208:211], v[174:177], v[108:111]
	v_mfma_f32_16x16x32_bf16 v[104:107], v[216:219], v[174:177], v[104:107]
	v_mfma_f32_16x16x32_bf16 v[92:95], v[208:211], v[182:185], v[92:95]
	v_mfma_f32_16x16x32_bf16 v[88:91], v[216:219], v[182:185], v[88:91]
	v_mfma_f32_16x16x32_bf16 v[76:79], v[208:211], v[200:203], v[76:79]
	v_mfma_f32_16x16x32_bf16 v[72:75], v[216:219], v[200:203], v[72:75]
	v_mfma_f32_16x16x32_bf16 v[124:127], v[212:215], v[160:163], v[124:127]
	v_mfma_f32_16x16x32_bf16 v[120:123], v[220:223], v[160:163], v[120:123]
	v_mfma_f32_16x16x32_bf16 v[108:111], v[212:215], v[178:181], v[108:111]
	v_mfma_f32_16x16x32_bf16 v[104:107], v[220:223], v[178:181], v[104:107]
	v_mfma_f32_16x16x32_bf16 v[92:95], v[212:215], v[196:199], v[92:95]
	v_mfma_f32_16x16x32_bf16 v[88:91], v[220:223], v[196:199], v[88:91]
	v_mfma_f32_16x16x32_bf16 v[76:79], v[212:215], v[204:207], v[76:79]
	v_mfma_f32_16x16x32_bf16 v[72:75], v[220:223], v[204:207], v[72:75]
	s_barrier
	s_mov_b32 m0, s31
	ds_read_b128 v[156:159], v172 offset:49152
	ds_read_b128 v[160:163], v172 offset:50176
	ds_read_b128 v[174:177], v172 offset:51200
	ds_read_b128 v[178:181], v172 offset:52224
	ds_read_b128 v[182:185], v172 offset:53248
	ds_read_b128 v[196:199], v172 offset:54272
	ds_read_b128 v[200:203], v172 offset:55296
	ds_read_b128 v[204:207], v172 offset:56320
	s_add_u32 vcc_lo, s42, s46
	s_addc_u32 vcc_hi, s43, s47
	global_load_lds_dwordx4 v2, vcc
	s_mov_b32 m0, s34
	s_nop 0
	s_add_u32 vcc_lo, s42, s58
	s_addc_u32 vcc_hi, s43, s59
	global_load_lds_dwordx4 v2, vcc
	s_barrier
	s_waitcnt lgkmcnt(0)
	v_mfma_f32_16x16x32_bf16 v[68:71], v[136:139], v[156:159], v[68:71]
	v_mfma_f32_16x16x32_bf16 v[64:67], v[148:151], v[156:159], v[64:67]
	v_mfma_f32_16x16x32_bf16 v[52:55], v[136:139], v[174:177], v[52:55]
	v_mfma_f32_16x16x32_bf16 v[48:51], v[148:151], v[174:177], v[48:51]
	v_mfma_f32_16x16x32_bf16 v[36:39], v[136:139], v[182:185], v[36:39]
	v_mfma_f32_16x16x32_bf16 v[32:35], v[148:151], v[182:185], v[32:35]
	v_mfma_f32_16x16x32_bf16 v[20:23], v[136:139], v[200:203], v[20:23]
	v_mfma_f32_16x16x32_bf16 v[16:19], v[148:151], v[200:203], v[16:19]
	v_mfma_f32_16x16x32_bf16 v[68:71], v[144:147], v[160:163], v[68:71]
	v_mfma_f32_16x16x32_bf16 v[64:67], v[152:155], v[160:163], v[64:67]
	v_mfma_f32_16x16x32_bf16 v[52:55], v[144:147], v[178:181], v[52:55]
	v_mfma_f32_16x16x32_bf16 v[48:51], v[152:155], v[178:181], v[48:51]
	v_mfma_f32_16x16x32_bf16 v[36:39], v[144:147], v[196:199], v[36:39]
	v_mfma_f32_16x16x32_bf16 v[32:35], v[152:155], v[196:199], v[32:35]
	v_mfma_f32_16x16x32_bf16 v[20:23], v[144:147], v[204:207], v[20:23]
	v_mfma_f32_16x16x32_bf16 v[16:19], v[152:155], v[204:207], v[16:19]
	s_barrier
	s_add_i32 s4, s5, s26
	s_mov_b32 m0, s4
	s_nop 0
	s_add_u32 vcc_lo, s50, s62
	s_addc_u32 vcc_hi, s51, s63
	global_load_lds_dwordx4 v140, vcc
	s_add_i32 m0, s4, 0x2000
	s_nop 0
	s_add_u32 vcc_lo, s50, s64
	s_addc_u32 vcc_hi, s51, s65
	global_load_lds_dwordx4 v140, vcc
	s_add_i32 s23, s23, 2
	s_add_u32 s2, s2, 0x100
	s_addc_u32 s3, s3, 0
	s_add_u32 s7, s7, 0x100
	s_addc_u32 s22, s22, 0
	s_cmp_gt_u32 s23, 13
	s_waitcnt vmcnt(6)
	s_barrier
	v_mfma_f32_16x16x32_bf16 v[60:63], v[208:211], v[156:159], v[60:63]
	v_mfma_f32_16x16x32_bf16 v[56:59], v[216:219], v[156:159], v[56:59]
	v_mfma_f32_16x16x32_bf16 v[44:47], v[208:211], v[174:177], v[44:47]
	v_mfma_f32_16x16x32_bf16 v[40:43], v[216:219], v[174:177], v[40:43]
	v_mfma_f32_16x16x32_bf16 v[28:31], v[208:211], v[182:185], v[28:31]
	v_mfma_f32_16x16x32_bf16 v[24:27], v[216:219], v[182:185], v[24:27]
	v_mfma_f32_16x16x32_bf16 v[12:15], v[208:211], v[200:203], v[12:15]
	v_mfma_f32_16x16x32_bf16 v[8:11], v[216:219], v[200:203], v[8:11]
	v_mfma_f32_16x16x32_bf16 v[60:63], v[212:215], v[160:163], v[60:63]
	v_mfma_f32_16x16x32_bf16 v[56:59], v[220:223], v[160:163], v[56:59]
	v_mfma_f32_16x16x32_bf16 v[44:47], v[212:215], v[178:181], v[44:47]
	v_mfma_f32_16x16x32_bf16 v[40:43], v[220:223], v[178:181], v[40:43]
	v_mfma_f32_16x16x32_bf16 v[28:31], v[212:215], v[196:199], v[28:31]
	v_mfma_f32_16x16x32_bf16 v[24:27], v[220:223], v[196:199], v[24:27]
	v_mfma_f32_16x16x32_bf16 v[12:15], v[212:215], v[204:207], v[12:15]
	v_mfma_f32_16x16x32_bf16 v[8:11], v[220:223], v[204:207], v[8:11]
	s_cbranch_scc0 .Ldb_WIN_cont
.Ldb_WIN_xl:
	v_readfirstlane_b32 s101, v186
	s_cmpk_gt_u32 s101, 0xff
	s_cbranch_scc1 .Ldb_WIN_young
	s_barrier
	s_mov_b32 s101, 1
	s_branch .Ldb_WIN_exit

; #define G_STAGE(bufoff, gbase, o0, h64) do { \
;         __builtin_amdgcn_global_load_lds((const unsigned*)((const char*)(gbase) + (o0)), (LAS unsigned*)(lds + (bufoff) + ldsw), 16, 0, 0); \
;         __builtin_amdgcn_global_load_lds((const unsigned*)((const char*)(gbase) + (h64) + (o0)), (LAS unsigned*)(lds + (bufoff) + ldsw + 8192), 16, 0, 0); } while (0)
; #define G_LDA(dst, b, h) do { _Pragma("unroll") for (int m = 0; m < 4; ++m) _Pragma("unroll") for (int k = 0; k < 2; ++k) dst[m][k] = *(const LAS bf16x8*)(lds + G_SA(b, h) + aoff + m * 2048 + k * 1024); } while (0)
; #define G_LDB(dst, b, h) do { _Pragma("unroll") for (int n = 0; n < 2; ++n) _Pragma("unroll") for (int k = 0; k < 2; ++k) dst[n][k] = *(const LAS bf16x8*)(lds + G_SB(b, h) + boff + n * 2048 + k * 1024); } while (0)
; #define G_WAIT_L(n) asm volatile("s_waitcnt lgkmcnt(" #n ")" ::: "memory")
; #define G_BAR __builtin_amdgcn_s_barrier()
; #define G_SCHED __builtin_amdgcn_sched_barrier(0)
;     ...
;         for (int t = 0; t < nt; t += 2) {
;             const bool last = (t == nt - 2);
;             const char* a1 = cA + (size_t)(t + 1) * ckA;
;             const char* a2 = last ? nA : cA + (size_t)(t + 2) * ckA; const char* b2 = last ? nB : cB + (size_t)(t + 2) * kB;
;             const char* a3 = a2 + ckA; const char* b3 = b2 + kB;
;             G_LDB(B0, 0, 0); G_SCHED; G_LDA(At, 0, 0); G_STAGE(G_SA(1, 1), a1 + chA, cA0, qA);
;             G_WAIT_L(8); G_BAR; G_WAIT_L(0); G_MMA(0, 0, At, B0); G_BAR; G_SCHED;
;             G_LDB(B1, 0, 1); G_STAGE(G_SB(0, 0), b2, cB0, qB);
;             G_BAR; G_WAIT_L(0); G_MMA(0, 1, At, B1); G_BAR;
;             G_LDA(At, 0, 1); G_STAGE(G_SA(0, 0), a2, cA0, qA);
;             G_BAR; G_WAIT_L(0); G_MMA(1, 0, At, B0); G_BAR; G_SCHED;
;     ...
;         for (int a = 0; a < 2; ++a)
; #pragma unroll
;             for (int b = 0; b < 2; ++b)
; #pragma unroll
;                 for (int m = 0; m < 4; ++m)
; #pragma unroll
;                     for (int n = 0; n < 2; ++n) acc[a][b][m][n] = (f32x4){0.f, 0.f, 0.f, 0.f};
.LBB0_449:
	s_add_u32 s6, s22, 0x20080
	s_addc_u32 s7, s23, 0
	s_add_u32 s19, s20, 0x100
	s_addc_u32 s20, s21, 0
	s_mov_b32 s21, -2
	s_mov_b64 s[50:51], 0x20080
	s_mov_b64 s[52:53], 0x10000
	s_mov_b64 s[54:55], 0x30000
	s_mov_b64 s[58:59], 0x10080
	s_mov_b64 s[62:63], 0x30080
	s_cmp_eq_u32 s101, 2
	s_cselect_b32 s101, 0, s101
	v_add_u32_e32 v255, 0x10000, v145
	s_add_u32 s4, s6, 0xfffe0080
	s_addc_u32 s5, s7, -1
	s_add_i32 s41, 0, 0x10000
	ds_read_b128 v[140:143], v255 offset:0
	ds_read_b128 v[148:151], v255 offset:1024
	ds_read_b128 v[152:155], v255 offset:2048
	ds_read_b128 v[156:159], v255 offset:3072
	s_cmp_eq_u32 s21, 4
	s_cselect_b32 s23, s11, s5
	s_cselect_b32 s22, s10, s4
	s_cselect_b32 s43, s17, s20
	s_cselect_b32 s42, s16, s19
	s_add_i32 m0, s27, 0xc000
	ds_read_b128 v[160:163], v146
	ds_read_b128 v[164:167], v146 offset:1024
	ds_read_b128 v[172:175], v146 offset:2048
	ds_read_b128 v[176:179], v146 offset:3072
	ds_read_b128 v[180:183], v146 offset:4096
	ds_read_b128 v[196:199], v146 offset:5120
	ds_read_b128 v[200:203], v146 offset:6144
	ds_read_b128 v[204:207], v146 offset:7168
	global_load_lds_dwordx4 v138, s[6:7]
	s_add_i32 m0, s27, 0xe000
	s_nop 0
	s_add_u32 vcc_lo, s6, s52
	s_addc_u32 vcc_hi, s7, s53
	global_load_lds_dwordx4 v138, vcc
	s_waitcnt lgkmcnt(8)
	s_cmp_eq_u32 s101, 1
	s_cbranch_scc1 .Ldb_SSM1_skp
	s_barrier
.Ldb_SSM1_skp:
	s_mov_b32 s101, 0
	s_waitcnt lgkmcnt(0)
	v_mfma_f32_16x16x32_bf16 v[132:135], v[140:143], v[160:163], 0
	v_mfma_f32_16x16x32_bf16 v[128:131], v[152:155], v[160:163], 0
	v_mfma_f32_16x16x32_bf16 v[116:119], v[140:143], v[172:175], 0
	v_mfma_f32_16x16x32_bf16 v[112:115], v[152:155], v[172:175], 0
	v_mfma_f32_16x16x32_bf16 v[100:103], v[140:143], v[180:183], 0
	v_mfma_f32_16x16x32_bf16 v[96:99], v[152:155], v[180:183], 0
	v_mfma_f32_16x16x32_bf16 v[84:87], v[140:143], v[200:203], 0
	v_mfma_f32_16x16x32_bf16 v[80:83], v[152:155], v[200:203], 0
	v_mfma_f32_16x16x32_bf16 v[132:135], v[148:151], v[164:167], v[132:135]
	v_mfma_f32_16x16x32_bf16 v[128:131], v[156:159], v[164:167], v[128:131]
	v_mfma_f32_16x16x32_bf16 v[116:119], v[148:151], v[176:179], v[116:119]
	v_mfma_f32_16x16x32_bf16 v[112:115], v[156:159], v[176:179], v[112:115]
	v_mfma_f32_16x16x32_bf16 v[100:103], v[148:151], v[196:199], v[100:103]
	v_mfma_f32_16x16x32_bf16 v[96:99], v[156:159], v[196:199], v[96:99]
	v_mfma_f32_16x16x32_bf16 v[84:87], v[148:151], v[204:207], v[84:87]
	v_mfma_f32_16x16x32_bf16 v[80:83], v[156:159], v[204:207], v[80:83]
	s_barrier
	s_add_i32 s4, 0, 0x14000
	s_add_i32 s5, s41, s26
	s_mov_b32 m0, s5
	ds_read_b128 v[208:211], v255 offset:16384
	ds_read_b128 v[212:215], v255 offset:17408
	ds_read_b128 v[216:219], v255 offset:18432
	ds_read_b128 v[220:223], v255 offset:19456
	global_load_lds_dwordx4 v136, s[42:43]
	s_add_i32 m0, s5, 0x2000
	s_nop 0
	s_add_u32 vcc_lo, s42, s52
	s_addc_u32 vcc_hi, s43, s53
	global_load_lds_dwordx4 v136, vcc
	s_barrier
	s_waitcnt lgkmcnt(0)
	v_mfma_f32_16x16x32_bf16 v[124:127], v[208:211], v[160:163], 0
	v_mfma_f32_16x16x32_bf16 v[120:123], v[216:219], v[160:163], 0
	v_mfma_f32_16x16x32_bf16 v[108:111], v[208:211], v[172:175], 0
	v_mfma_f32_16x16x32_bf16 v[104:107], v[216:219], v[172:175], 0
	v_mfma_f32_16x16x32_bf16 v[92:95], v[208:211], v[180:183], 0
	v_mfma_f32_16x16x32_bf16 v[88:91], v[216:219], v[180:183], 0
	v_mfma_f32_16x16x32_bf16 v[76:79], v[208:211], v[200:203], 0
	v_mfma_f32_16x16x32_bf16 v[72:75], v[216:219], v[200:203], 0
	v_mfma_f32_16x16x32_bf16 v[124:127], v[212:215], v[164:167], v[124:127]
	v_mfma_f32_16x16x32_bf16 v[120:123], v[220:223], v[164:167], v[120:123]
	v_mfma_f32_16x16x32_bf16 v[108:111], v[212:215], v[176:179], v[108:111]
	v_mfma_f32_16x16x32_bf16 v[104:107], v[220:223], v[176:179], v[104:107]
	v_mfma_f32_16x16x32_bf16 v[92:95], v[212:215], v[196:199], v[92:95]
	v_mfma_f32_16x16x32_bf16 v[88:91], v[220:223], v[196:199], v[88:91]
	v_mfma_f32_16x16x32_bf16 v[76:79], v[212:215], v[204:207], v[76:79]
	v_mfma_f32_16x16x32_bf16 v[72:75], v[220:223], v[204:207], v[72:75]
	s_barrier
	s_mov_b32 m0, s27
	ds_read_b128 v[160:163], v146 offset:16384
	ds_read_b128 v[164:167], v146 offset:17408
	ds_read_b128 v[172:175], v146 offset:18432
	ds_read_b128 v[176:179], v146 offset:19456
	ds_read_b128 v[180:183], v146 offset:20480
	ds_read_b128 v[196:199], v146 offset:21504
	ds_read_b128 v[200:203], v146 offset:22528
	ds_read_b128 v[204:207], v146 offset:23552
	global_load_lds_dwordx4 v2, s[22:23]
	s_mov_b32 m0, s28
	s_nop 0
	s_add_u32 vcc_lo, s22, s52
	s_addc_u32 vcc_hi, s23, s53
	global_load_lds_dwordx4 v2, vcc
	s_barrier
	s_waitcnt lgkmcnt(0)
	v_mfma_f32_16x16x32_bf16 v[68:71], v[140:143], v[160:163], 0
	v_mfma_f32_16x16x32_bf16 v[64:67], v[152:155], v[160:163], 0
	v_mfma_f32_16x16x32_bf16 v[52:55], v[140:143], v[172:175], 0
	v_mfma_f32_16x16x32_bf16 v[48:51], v[152:155], v[172:175], 0
	v_mfma_f32_16x16x32_bf16 v[36:39], v[140:143], v[180:183], 0
	v_mfma_f32_16x16x32_bf16 v[32:35], v[152:155], v[180:183], 0
	v_mfma_f32_16x16x32_bf16 v[20:23], v[140:143], v[200:203], 0
	v_mfma_f32_16x16x32_bf16 v[16:19], v[152:155], v[200:203], 0
	v_mfma_f32_16x16x32_bf16 v[68:71], v[148:151], v[164:167], v[68:71]
	v_mfma_f32_16x16x32_bf16 v[64:67], v[156:159], v[164:167], v[64:67]
	v_mfma_f32_16x16x32_bf16 v[52:55], v[148:151], v[176:179], v[52:55]
	v_mfma_f32_16x16x32_bf16 v[48:51], v[156:159], v[176:179], v[48:51]
	v_mfma_f32_16x16x32_bf16 v[36:39], v[148:151], v[196:199], v[36:39]
	v_mfma_f32_16x16x32_bf16 v[32:35], v[156:159], v[196:199], v[32:35]
	v_mfma_f32_16x16x32_bf16 v[20:23], v[148:151], v[204:207], v[20:23]
	v_mfma_f32_16x16x32_bf16 v[16:19], v[156:159], v[204:207], v[16:19]
	s_barrier
; #define G_STAGE(bufoff, gbase, o0, h64) do { \
;         __builtin_amdgcn_global_load_lds((const unsigned*)((const char*)(gbase) + (o0)), (LAS unsigned*)(lds + (bufoff) + ldsw), 16, 0, 0); \
;         __builtin_amdgcn_global_load_lds((const unsigned*)((const char*)(gbase) + (h64) + (o0)), (LAS unsigned*)(lds + (bufoff) + ldsw + 8192), 16, 0, 0); } while (0)
; #define G_LDA(dst, b, h) do { _Pragma("unroll") for (int m = 0; m < 4; ++m) _Pragma("unroll") for (int k = 0; k < 2; ++k) dst[m][k] = *(const LAS bf16x8*)(lds + G_SA(b, h) + aoff + m * 2048 + k * 1024); } while (0)
; #define G_LDB(dst, b, h) do { _Pragma("unroll") for (int n = 0; n < 2; ++n) _Pragma("unroll") for (int k = 0; k < 2; ++k) dst[n][k] = *(const LAS bf16x8*)(lds + G_SB(b, h) + boff + n * 2048 + k * 1024); } while (0)
; #define G_WAIT_V(n) asm volatile("s_waitcnt vmcnt(" #n ")" ::: "memory")
; #define G_WAIT_L(n) asm volatile("s_waitcnt lgkmcnt(" #n ")" ::: "memory")
; #define G_BAR __builtin_amdgcn_s_barrier()
; #define G_SCHED __builtin_amdgcn_sched_barrier(0)
;     ...
;             G_BAR; G_WAIT_L(0); G_MMA(1, 0, At, B0); G_BAR; G_SCHED;
;             G_STAGE(G_SB(0, 1), b2 + chB, cB0, qB);
;             G_WAIT_V(6); G_BAR; G_MMA(1, 1, At, B1); G_BAR;
;             G_LDB(B0, 1, 0); G_SCHED; G_LDA(At, 1, 0); G_STAGE(G_SA(0, 1), a2 + chA, cA0, qA);
;             G_WAIT_L(8); G_BAR; G_WAIT_L(0); G_MMA(0, 0, At, B0); G_BAR; G_SCHED;
;             G_LDB(B1, 1, 1); G_STAGE(G_SB(1, 0), b3, cB0, qB);
;             G_BAR; G_WAIT_L(0); G_MMA(0, 1, At, B1); G_BAR;
;             G_LDA(At, 1, 1); G_STAGE(G_SA(1, 0), a3, cA0, qA);
;             G_BAR; G_WAIT_L(0); G_MMA(1, 0, At, B0); G_BAR; G_SCHED;
	s_add_i32 s4, s4, s26
	s_mov_b32 m0, s4
	s_nop 0
	s_add_u32 vcc_lo, s42, s0
	s_addc_u32 vcc_hi, s43, s1
	global_load_lds_dwordx4 v136, vcc
	s_add_i32 m0, s4, 0x2000
	s_nop 0
	s_add_u32 vcc_lo, s42, s54
	s_addc_u32 vcc_hi, s43, s55
	global_load_lds_dwordx4 v136, vcc
	s_waitcnt vmcnt(6)
	s_barrier
	v_mfma_f32_16x16x32_bf16 v[60:63], v[208:211], v[160:163], 0
	v_mfma_f32_16x16x32_bf16 v[56:59], v[216:219], v[160:163], 0
	v_mfma_f32_16x16x32_bf16 v[44:47], v[208:211], v[172:175], 0
	v_mfma_f32_16x16x32_bf16 v[40:43], v[216:219], v[172:175], 0
	v_mfma_f32_16x16x32_bf16 v[28:31], v[208:211], v[180:183], 0
	v_mfma_f32_16x16x32_bf16 v[24:27], v[216:219], v[180:183], 0
	v_mfma_f32_16x16x32_bf16 v[12:15], v[208:211], v[200:203], 0
	v_mfma_f32_16x16x32_bf16 v[8:11], v[216:219], v[200:203], 0
	v_mfma_f32_16x16x32_bf16 v[60:63], v[212:215], v[164:167], v[60:63]
	v_mfma_f32_16x16x32_bf16 v[56:59], v[220:223], v[164:167], v[56:59]
	v_mfma_f32_16x16x32_bf16 v[44:47], v[212:215], v[176:179], v[44:47]
	v_mfma_f32_16x16x32_bf16 v[40:43], v[220:223], v[176:179], v[40:43]
	v_mfma_f32_16x16x32_bf16 v[28:31], v[212:215], v[196:199], v[28:31]
	v_mfma_f32_16x16x32_bf16 v[24:27], v[220:223], v[196:199], v[24:27]
	v_mfma_f32_16x16x32_bf16 v[12:15], v[212:215], v[204:207], v[12:15]
	v_mfma_f32_16x16x32_bf16 v[8:11], v[220:223], v[204:207], v[8:11]
	s_barrier
	s_add_i32 s4, 0, 0x18000
	ds_read_b128 v[140:143], v255 offset:32768
	ds_read_b128 v[148:151], v255 offset:33792
	ds_read_b128 v[152:155], v255 offset:34816
	ds_read_b128 v[156:159], v255 offset:35840
	s_mov_b32 m0, s29
	ds_read_b128 v[160:163], v146 offset:32768
	ds_read_b128 v[164:167], v146 offset:33792
	ds_read_b128 v[172:175], v146 offset:34816
	ds_read_b128 v[176:179], v146 offset:35840
	ds_read_b128 v[180:183], v146 offset:36864
	ds_read_b128 v[196:199], v146 offset:37888
	ds_read_b128 v[200:203], v146 offset:38912
	ds_read_b128 v[204:207], v146 offset:39936
	s_add_u32 vcc_lo, s22, s0
	s_addc_u32 vcc_hi, s23, s1
	global_load_lds_dwordx4 v2, vcc
	s_mov_b32 m0, s30
	s_nop 0
	s_add_u32 vcc_lo, s22, s54
	s_addc_u32 vcc_hi, s23, s55
	global_load_lds_dwordx4 v2, vcc
	s_waitcnt lgkmcnt(8)
	s_barrier
	s_waitcnt lgkmcnt(0)
	v_mfma_f32_16x16x32_bf16 v[132:135], v[140:143], v[160:163], v[132:135]
	v_mfma_f32_16x16x32_bf16 v[128:131], v[152:155], v[160:163], v[128:131]
	v_mfma_f32_16x16x32_bf16 v[116:119], v[140:143], v[172:175], v[116:119]
	v_mfma_f32_16x16x32_bf16 v[112:115], v[152:155], v[172:175], v[112:115]
	v_mfma_f32_16x16x32_bf16 v[100:103], v[140:143], v[180:183], v[100:103]
	v_mfma_f32_16x16x32_bf16 v[96:99], v[152:155], v[180:183], v[96:99]
	v_mfma_f32_16x16x32_bf16 v[84:87], v[140:143], v[200:203], v[84:87]
	v_mfma_f32_16x16x32_bf16 v[80:83], v[152:155], v[200:203], v[80:83]
	v_mfma_f32_16x16x32_bf16 v[132:135], v[148:151], v[164:167], v[132:135]
	v_mfma_f32_16x16x32_bf16 v[128:131], v[156:159], v[164:167], v[128:131]
	v_mfma_f32_16x16x32_bf16 v[116:119], v[148:151], v[176:179], v[116:119]
	v_mfma_f32_16x16x32_bf16 v[112:115], v[156:159], v[176:179], v[112:115]
	v_mfma_f32_16x16x32_bf16 v[100:103], v[148:151], v[196:199], v[100:103]
	v_mfma_f32_16x16x32_bf16 v[96:99], v[156:159], v[196:199], v[96:99]
	v_mfma_f32_16x16x32_bf16 v[84:87], v[148:151], v[204:207], v[84:87]
	v_mfma_f32_16x16x32_bf16 v[80:83], v[156:159], v[204:207], v[80:83]
	s_barrier
	s_add_i32 s5, 0, 0x1c000
	s_add_i32 s4, s4, s26
	s_mov_b32 m0, s4
	ds_read_b128 v[208:211], v255 offset:49152
	ds_read_b128 v[212:215], v255 offset:50176
	ds_read_b128 v[216:219], v255 offset:51200
	ds_read_b128 v[220:223], v255 offset:52224
	s_add_u32 vcc_lo, s42, s46
	s_addc_u32 vcc_hi, s43, s47
	global_load_lds_dwordx4 v136, vcc
	s_add_i32 m0, s4, 0x2000
	s_nop 0
	s_add_u32 vcc_lo, s42, s58
	s_addc_u32 vcc_hi, s43, s59
	global_load_lds_dwordx4 v136, vcc
	s_barrier
	s_waitcnt lgkmcnt(0)
	v_mfma_f32_16x16x32_bf16 v[124:127], v[208:211], v[160:163], v[124:127]
	v_mfma_f32_16x16x32_bf16 v[120:123], v[216:219], v[160:163], v[120:123]
	v_mfma_f32_16x16x32_bf16 v[108:111], v[208:211], v[172:175], v[108:111]
	v_mfma_f32_16x16x32_bf16 v[104:107], v[216:219], v[172:175], v[104:107]
	v_mfma_f32_16x16x32_bf16 v[92:95], v[208:211], v[180:183], v[92:95]
	v_mfma_f32_16x16x32_bf16 v[88:91], v[216:219], v[180:183], v[88:91]
	v_mfma_f32_16x16x32_bf16 v[76:79], v[208:211], v[200:203], v[76:79]
	v_mfma_f32_16x16x32_bf16 v[72:75], v[216:219], v[200:203], v[72:75]
	v_mfma_f32_16x16x32_bf16 v[124:127], v[212:215], v[164:167], v[124:127]
	v_mfma_f32_16x16x32_bf16 v[120:123], v[220:223], v[164:167], v[120:123]
	v_mfma_f32_16x16x32_bf16 v[108:111], v[212:215], v[176:179], v[108:111]
	v_mfma_f32_16x16x32_bf16 v[104:107], v[220:223], v[176:179], v[104:107]
	v_mfma_f32_16x16x32_bf16 v[92:95], v[212:215], v[196:199], v[92:95]
	v_mfma_f32_16x16x32_bf16 v[88:91], v[220:223], v[196:199], v[88:91]
	v_mfma_f32_16x16x32_bf16 v[76:79], v[212:215], v[204:207], v[76:79]
	v_mfma_f32_16x16x32_bf16 v[72:75], v[220:223], v[204:207], v[72:75]
	s_barrier
	s_mov_b32 m0, s31
	ds_read_b128 v[160:163], v146 offset:49152
	ds_read_b128 v[164:167], v146 offset:50176
	ds_read_b128 v[172:175], v146 offset:51200
	ds_read_b128 v[176:179], v146 offset:52224
	ds_read_b128 v[180:183], v146 offset:53248
	ds_read_b128 v[196:199], v146 offset:54272
	ds_read_b128 v[200:203], v146 offset:55296
	ds_read_b128 v[204:207], v146 offset:56320
	s_add_u32 vcc_lo, s22, s46
	s_addc_u32 vcc_hi, s23, s47
	global_load_lds_dwordx4 v2, vcc
	s_mov_b32 m0, s33
	s_nop 0
	s_add_u32 vcc_lo, s22, s58
	s_addc_u32 vcc_hi, s23, s59
	global_load_lds_dwordx4 v2, vcc
	s_barrier
; #define G_STAGE(bufoff, gbase, o0, h64) do { \
;         __builtin_amdgcn_global_load_lds((const unsigned*)((const char*)(gbase) + (o0)), (LAS unsigned*)(lds + (bufoff) + ldsw), 16, 0, 0); \
;         __builtin_amdgcn_global_load_lds((const unsigned*)((const char*)(gbase) + (h64) + (o0)), (LAS unsigned*)(lds + (bufoff) + ldsw + 8192), 16, 0, 0); } while (0)
; #define G_LDA(dst, b, h) do { _Pragma("unroll") for (int m = 0; m < 4; ++m) _Pragma("unroll") for (int k = 0; k < 2; ++k) dst[m][k] = *(const LAS bf16x8*)(lds + G_SA(b, h) + aoff + m * 2048 + k * 1024); } while (0)
; #define G_LDB(dst, b, h) do { _Pragma("unroll") for (int n = 0; n < 2; ++n) _Pragma("unroll") for (int k = 0; k < 2; ++k) dst[n][k] = *(const LAS bf16x8*)(lds + G_SB(b, h) + boff + n * 2048 + k * 1024); } while (0)
; #define G_WAIT_V(n) asm volatile("s_waitcnt vmcnt(" #n ")" ::: "memory")
; #define G_WAIT_L(n) asm volatile("s_waitcnt lgkmcnt(" #n ")" ::: "memory")
; #define G_BAR __builtin_amdgcn_s_barrier()
; #define G_SCHED __builtin_amdgcn_sched_barrier(0)
;     ...
;         for (int t = 0; t < nt; t += 2) {
;             const bool last = (t == nt - 2);
;             const char* a1 = cA + (size_t)(t + 1) * ckA;
;             const char* a2 = last ? nA : cA + (size_t)(t + 2) * ckA; const char* b2 = last ? nB : cB + (size_t)(t + 2) * kB;
;             const char* a3 = a2 + ckA; const char* b3 = b2 + kB;
;             G_LDB(B0, 0, 0); G_SCHED; G_LDA(At, 0, 0); G_STAGE(G_SA(1, 1), a1 + chA, cA0, qA);
;             G_WAIT_L(8); G_BAR; G_WAIT_L(0); G_MMA(0, 0, At, B0); G_BAR; G_SCHED;
;     ...
;             G_BAR; G_WAIT_L(0); G_MMA(1, 0, At, B0); G_BAR; G_SCHED;
;             G_STAGE(G_SB(1, 1), b3 + chB, cB0, qB);
;             G_WAIT_V(6); G_BAR; G_MMA(1, 1, At, B1); G_BAR;
;         }
	s_waitcnt lgkmcnt(0)
	v_mfma_f32_16x16x32_bf16 v[68:71], v[140:143], v[160:163], v[68:71]
	v_mfma_f32_16x16x32_bf16 v[64:67], v[152:155], v[160:163], v[64:67]
	v_mfma_f32_16x16x32_bf16 v[52:55], v[140:143], v[172:175], v[52:55]
	v_mfma_f32_16x16x32_bf16 v[48:51], v[152:155], v[172:175], v[48:51]
	v_mfma_f32_16x16x32_bf16 v[36:39], v[140:143], v[180:183], v[36:39]
	v_mfma_f32_16x16x32_bf16 v[32:35], v[152:155], v[180:183], v[32:35]
	v_mfma_f32_16x16x32_bf16 v[20:23], v[140:143], v[200:203], v[20:23]
	v_mfma_f32_16x16x32_bf16 v[16:19], v[152:155], v[200:203], v[16:19]
	v_mfma_f32_16x16x32_bf16 v[68:71], v[148:151], v[164:167], v[68:71]
	v_mfma_f32_16x16x32_bf16 v[64:67], v[156:159], v[164:167], v[64:67]
	v_mfma_f32_16x16x32_bf16 v[52:55], v[148:151], v[176:179], v[52:55]
	v_mfma_f32_16x16x32_bf16 v[48:51], v[156:159], v[176:179], v[48:51]
	v_mfma_f32_16x16x32_bf16 v[36:39], v[148:151], v[196:199], v[36:39]
	v_mfma_f32_16x16x32_bf16 v[32:35], v[156:159], v[196:199], v[32:35]
	v_mfma_f32_16x16x32_bf16 v[20:23], v[148:151], v[204:207], v[20:23]
	v_mfma_f32_16x16x32_bf16 v[16:19], v[156:159], v[204:207], v[16:19]
	s_barrier
	s_add_i32 s4, s5, s26
	s_mov_b32 m0, s4
	s_nop 0
	s_add_u32 vcc_lo, s42, s50
	s_addc_u32 vcc_hi, s43, s51
	global_load_lds_dwordx4 v136, vcc
	s_add_i32 m0, s4, 0x2000
	s_nop 0
	s_add_u32 vcc_lo, s42, s62
	s_addc_u32 vcc_hi, s43, s63
	global_load_lds_dwordx4 v136, vcc
	s_add_i32 s21, s21, 2
	s_add_u32 s6, s6, 0x100
	s_addc_u32 s7, s7, 0
	s_add_u32 s19, s19, 0x100
	s_addc_u32 s20, s20, 0
	s_cmp_gt_u32 s21, 5
	s_waitcnt vmcnt(6)
	s_barrier
	v_mfma_f32_16x16x32_bf16 v[60:63], v[208:211], v[160:163], v[60:63]
	v_mfma_f32_16x16x32_bf16 v[56:59], v[216:219], v[160:163], v[56:59]
	v_mfma_f32_16x16x32_bf16 v[44:47], v[208:211], v[172:175], v[44:47]
	v_mfma_f32_16x16x32_bf16 v[40:43], v[216:219], v[172:175], v[40:43]
	v_mfma_f32_16x16x32_bf16 v[28:31], v[208:211], v[180:183], v[28:31]
	v_mfma_f32_16x16x32_bf16 v[24:27], v[216:219], v[180:183], v[24:27]
	v_mfma_f32_16x16x32_bf16 v[12:15], v[208:211], v[200:203], v[12:15]
	v_mfma_f32_16x16x32_bf16 v[8:11], v[216:219], v[200:203], v[8:11]
	v_mfma_f32_16x16x32_bf16 v[60:63], v[212:215], v[164:167], v[60:63]
	v_mfma_f32_16x16x32_bf16 v[56:59], v[220:223], v[164:167], v[56:59]
	v_mfma_f32_16x16x32_bf16 v[44:47], v[212:215], v[176:179], v[44:47]
	v_mfma_f32_16x16x32_bf16 v[40:43], v[220:223], v[176:179], v[40:43]
	v_mfma_f32_16x16x32_bf16 v[28:31], v[212:215], v[196:199], v[28:31]
	v_mfma_f32_16x16x32_bf16 v[24:27], v[220:223], v[196:199], v[24:27]
	v_mfma_f32_16x16x32_bf16 v[12:15], v[212:215], v[204:207], v[12:15]
	v_mfma_f32_16x16x32_bf16 v[8:11], v[220:223], v[204:207], v[8:11]
	s_cbranch_scc0 .Ldb_SSM1_cont
	s_branch .Ldb_SSM1_xl
.LBB0_450:
	s_add_u32 s4, s6, 0xfffe0080
	s_addc_u32 s5, s7, -1
	s_add_i32 s41, 0, 0x10000
	ds_read_b128 v[140:143], v255 offset:0
	ds_read_b128 v[148:151], v255 offset:1024
	ds_read_b128 v[152:155], v255 offset:2048
	ds_read_b128 v[156:159], v255 offset:3072
	s_cmp_eq_u32 s21, 4
	s_cselect_b32 s23, s11, s5
	s_cselect_b32 s22, s10, s4
	s_cselect_b32 s43, s17, s20
	s_cselect_b32 s42, s16, s19
	s_add_i32 m0, s27, 0xc000
	ds_read_b128 v[160:163], v146
	ds_read_b128 v[164:167], v146 offset:1024
	ds_read_b128 v[172:175], v146 offset:2048
	ds_read_b128 v[176:179], v146 offset:3072
	ds_read_b128 v[180:183], v146 offset:4096
	ds_read_b128 v[196:199], v146 offset:5120
	ds_read_b128 v[200:203], v146 offset:6144
	ds_read_b128 v[204:207], v146 offset:7168
	global_load_lds_dwordx4 v138, s[6:7]
	s_add_i32 m0, s27, 0xe000
	s_nop 0
	s_add_u32 vcc_lo, s6, s52
	s_addc_u32 vcc_hi, s7, s53
	global_load_lds_dwordx4 v138, vcc
	s_waitcnt lgkmcnt(8)
	s_barrier
	s_waitcnt lgkmcnt(0)
	v_mfma_f32_16x16x32_bf16 v[132:135], v[140:143], v[160:163], v[132:135]
	v_mfma_f32_16x16x32_bf16 v[128:131], v[152:155], v[160:163], v[128:131]
	v_mfma_f32_16x16x32_bf16 v[116:119], v[140:143], v[172:175], v[116:119]
	v_mfma_f32_16x16x32_bf16 v[112:115], v[152:155], v[172:175], v[112:115]
	v_mfma_f32_16x16x32_bf16 v[100:103], v[140:143], v[180:183], v[100:103]
	v_mfma_f32_16x16x32_bf16 v[96:99], v[152:155], v[180:183], v[96:99]
	v_mfma_f32_16x16x32_bf16 v[84:87], v[140:143], v[200:203], v[84:87]
	v_mfma_f32_16x16x32_bf16 v[80:83], v[152:155], v[200:203], v[80:83]
	v_mfma_f32_16x16x32_bf16 v[132:135], v[148:151], v[164:167], v[132:135]
	v_mfma_f32_16x16x32_bf16 v[128:131], v[156:159], v[164:167], v[128:131]
	v_mfma_f32_16x16x32_bf16 v[116:119], v[148:151], v[176:179], v[116:119]
	v_mfma_f32_16x16x32_bf16 v[112:115], v[156:159], v[176:179], v[112:115]
	v_mfma_f32_16x16x32_bf16 v[100:103], v[148:151], v[196:199], v[100:103]
	v_mfma_f32_16x16x32_bf16 v[96:99], v[156:159], v[196:199], v[96:99]
	v_mfma_f32_16x16x32_bf16 v[84:87], v[148:151], v[204:207], v[84:87]
	v_mfma_f32_16x16x32_bf16 v[80:83], v[156:159], v[204:207], v[80:83]
	s_barrier
	s_add_i32 s4, 0, 0x14000
	s_add_i32 s5, s41, s26
	s_mov_b32 m0, s5
	ds_read_b128 v[208:211], v255 offset:16384
	ds_read_b128 v[212:215], v255 offset:17408
	ds_read_b128 v[216:219], v255 offset:18432
	ds_read_b128 v[220:223], v255 offset:19456
	global_load_lds_dwordx4 v136, s[42:43]
	s_add_i32 m0, s5, 0x2000
	s_nop 0
	s_add_u32 vcc_lo, s42, s52
	s_addc_u32 vcc_hi, s43, s53
	global_load_lds_dwordx4 v136, vcc
	s_barrier
; #define G_STAGE(bufoff, gbase, o0, h64) do { \
;         __builtin_amdgcn_global_load_lds((const unsigned*)((const char*)(gbase) + (o0)), (LAS unsigned*)(lds + (bufoff) + ldsw), 16, 0, 0); \
;         __builtin_amdgcn_global_load_lds((const unsigned*)((const char*)(gbase) + (h64) + (o0)), (LAS unsigned*)(lds + (bufoff) + ldsw + 8192), 16, 0, 0); } while (0)
; #define G_LDA(dst, b, h) do { _Pragma("unroll") for (int m = 0; m < 4; ++m) _Pragma("unroll") for (int k = 0; k < 2; ++k) dst[m][k] = *(const LAS bf16x8*)(lds + G_SA(b, h) + aoff + m * 2048 + k * 1024); } while (0)
; #define G_LDB(dst, b, h) do { _Pragma("unroll") for (int n = 0; n < 2; ++n) _Pragma("unroll") for (int k = 0; k < 2; ++k) dst[n][k] = *(const LAS bf16x8*)(lds + G_SB(b, h) + boff + n * 2048 + k * 1024); } while (0)
; #define G_WAIT_V(n) asm volatile("s_waitcnt vmcnt(" #n ")" ::: "memory")
; #define G_WAIT_L(n) asm volatile("s_waitcnt lgkmcnt(" #n ")" ::: "memory")
; #define G_BAR __builtin_amdgcn_s_barrier()
; #define G_SCHED __builtin_amdgcn_sched_barrier(0)
;     ...
;             G_WAIT_L(8); G_BAR; G_WAIT_L(0); G_MMA(0, 0, At, B0); G_BAR; G_SCHED;
;             G_LDB(B1, 0, 1); G_STAGE(G_SB(0, 0), b2, cB0, qB);
;             G_BAR; G_WAIT_L(0); G_MMA(0, 1, At, B1); G_BAR;
;             G_LDA(At, 0, 1); G_STAGE(G_SA(0, 0), a2, cA0, qA);
;             G_BAR; G_WAIT_L(0); G_MMA(1, 0, At, B0); G_BAR; G_SCHED;
;             G_STAGE(G_SB(0, 1), b2 + chB, cB0, qB);
;             G_WAIT_V(6); G_BAR; G_MMA(1, 1, At, B1); G_BAR;
;             G_LDB(B0, 1, 0); G_SCHED; G_LDA(At, 1, 0); G_STAGE(G_SA(0, 1), a2 + chA, cA0, qA);
;             G_WAIT_L(8); G_BAR; G_WAIT_L(0); G_MMA(0, 0, At, B0); G_BAR; G_SCHED;
	s_waitcnt lgkmcnt(0)
	v_mfma_f32_16x16x32_bf16 v[124:127], v[208:211], v[160:163], v[124:127]
	v_mfma_f32_16x16x32_bf16 v[120:123], v[216:219], v[160:163], v[120:123]
	v_mfma_f32_16x16x32_bf16 v[108:111], v[208:211], v[172:175], v[108:111]
	v_mfma_f32_16x16x32_bf16 v[104:107], v[216:219], v[172:175], v[104:107]
	v_mfma_f32_16x16x32_bf16 v[92:95], v[208:211], v[180:183], v[92:95]
	v_mfma_f32_16x16x32_bf16 v[88:91], v[216:219], v[180:183], v[88:91]
	v_mfma_f32_16x16x32_bf16 v[76:79], v[208:211], v[200:203], v[76:79]
	v_mfma_f32_16x16x32_bf16 v[72:75], v[216:219], v[200:203], v[72:75]
	v_mfma_f32_16x16x32_bf16 v[124:127], v[212:215], v[164:167], v[124:127]
	v_mfma_f32_16x16x32_bf16 v[120:123], v[220:223], v[164:167], v[120:123]
	v_mfma_f32_16x16x32_bf16 v[108:111], v[212:215], v[176:179], v[108:111]
	v_mfma_f32_16x16x32_bf16 v[104:107], v[220:223], v[176:179], v[104:107]
	v_mfma_f32_16x16x32_bf16 v[92:95], v[212:215], v[196:199], v[92:95]
	v_mfma_f32_16x16x32_bf16 v[88:91], v[220:223], v[196:199], v[88:91]
	v_mfma_f32_16x16x32_bf16 v[76:79], v[212:215], v[204:207], v[76:79]
	v_mfma_f32_16x16x32_bf16 v[72:75], v[220:223], v[204:207], v[72:75]
	s_barrier
	s_mov_b32 m0, s27
	ds_read_b128 v[160:163], v146 offset:16384
	ds_read_b128 v[164:167], v146 offset:17408
	ds_read_b128 v[172:175], v146 offset:18432
	ds_read_b128 v[176:179], v146 offset:19456
	ds_read_b128 v[180:183], v146 offset:20480
	ds_read_b128 v[196:199], v146 offset:21504
	ds_read_b128 v[200:203], v146 offset:22528
	ds_read_b128 v[204:207], v146 offset:23552
	global_load_lds_dwordx4 v2, s[22:23]
	s_mov_b32 m0, s28
	s_nop 0
	s_add_u32 vcc_lo, s22, s52
	s_addc_u32 vcc_hi, s23, s53
	global_load_lds_dwordx4 v2, vcc
	s_barrier
	s_waitcnt lgkmcnt(0)
	v_mfma_f32_16x16x32_bf16 v[68:71], v[140:143], v[160:163], v[68:71]
	v_mfma_f32_16x16x32_bf16 v[64:67], v[152:155], v[160:163], v[64:67]
	v_mfma_f32_16x16x32_bf16 v[52:55], v[140:143], v[172:175], v[52:55]
	v_mfma_f32_16x16x32_bf16 v[48:51], v[152:155], v[172:175], v[48:51]
	v_mfma_f32_16x16x32_bf16 v[36:39], v[140:143], v[180:183], v[36:39]
	v_mfma_f32_16x16x32_bf16 v[32:35], v[152:155], v[180:183], v[32:35]
	v_mfma_f32_16x16x32_bf16 v[20:23], v[140:143], v[200:203], v[20:23]
	v_mfma_f32_16x16x32_bf16 v[16:19], v[152:155], v[200:203], v[16:19]
	v_mfma_f32_16x16x32_bf16 v[68:71], v[148:151], v[164:167], v[68:71]
	v_mfma_f32_16x16x32_bf16 v[64:67], v[156:159], v[164:167], v[64:67]
	v_mfma_f32_16x16x32_bf16 v[52:55], v[148:151], v[176:179], v[52:55]
	v_mfma_f32_16x16x32_bf16 v[48:51], v[156:159], v[176:179], v[48:51]
	v_mfma_f32_16x16x32_bf16 v[36:39], v[148:151], v[196:199], v[36:39]
	v_mfma_f32_16x16x32_bf16 v[32:35], v[156:159], v[196:199], v[32:35]
	v_mfma_f32_16x16x32_bf16 v[20:23], v[148:151], v[204:207], v[20:23]
	v_mfma_f32_16x16x32_bf16 v[16:19], v[156:159], v[204:207], v[16:19]
	s_barrier
	s_add_i32 s4, s4, s26
	s_mov_b32 m0, s4
	s_nop 0
	s_add_u32 vcc_lo, s42, s0
	s_addc_u32 vcc_hi, s43, s1
	global_load_lds_dwordx4 v136, vcc
	s_add_i32 m0, s4, 0x2000
	s_nop 0
	s_add_u32 vcc_lo, s42, s54
	s_addc_u32 vcc_hi, s43, s55
	global_load_lds_dwordx4 v136, vcc
	s_waitcnt vmcnt(6)
	s_barrier
	v_mfma_f32_16x16x32_bf16 v[60:63], v[208:211], v[160:163], v[60:63]
	v_mfma_f32_16x16x32_bf16 v[56:59], v[216:219], v[160:163], v[56:59]
	v_mfma_f32_16x16x32_bf16 v[44:47], v[208:211], v[172:175], v[44:47]
	v_mfma_f32_16x16x32_bf16 v[40:43], v[216:219], v[172:175], v[40:43]
	v_mfma_f32_16x16x32_bf16 v[28:31], v[208:211], v[180:183], v[28:31]
	v_mfma_f32_16x16x32_bf16 v[24:27], v[216:219], v[180:183], v[24:27]
	v_mfma_f32_16x16x32_bf16 v[12:15], v[208:211], v[200:203], v[12:15]
	v_mfma_f32_16x16x32_bf16 v[8:11], v[216:219], v[200:203], v[8:11]
	v_mfma_f32_16x16x32_bf16 v[60:63], v[212:215], v[164:167], v[60:63]
	v_mfma_f32_16x16x32_bf16 v[56:59], v[220:223], v[164:167], v[56:59]
	v_mfma_f32_16x16x32_bf16 v[44:47], v[212:215], v[176:179], v[44:47]
	v_mfma_f32_16x16x32_bf16 v[40:43], v[220:223], v[176:179], v[40:43]
	v_mfma_f32_16x16x32_bf16 v[28:31], v[212:215], v[196:199], v[28:31]
	v_mfma_f32_16x16x32_bf16 v[24:27], v[220:223], v[196:199], v[24:27]
	v_mfma_f32_16x16x32_bf16 v[12:15], v[212:215], v[204:207], v[12:15]
	v_mfma_f32_16x16x32_bf16 v[8:11], v[220:223], v[204:207], v[8:11]
	s_barrier
	s_add_i32 s4, 0, 0x18000
	ds_read_b128 v[140:143], v255 offset:32768
	ds_read_b128 v[148:151], v255 offset:33792
	ds_read_b128 v[152:155], v255 offset:34816
	ds_read_b128 v[156:159], v255 offset:35840
	s_mov_b32 m0, s29
	ds_read_b128 v[160:163], v146 offset:32768
	ds_read_b128 v[164:167], v146 offset:33792
	ds_read_b128 v[172:175], v146 offset:34816
	ds_read_b128 v[176:179], v146 offset:35840
	ds_read_b128 v[180:183], v146 offset:36864
	ds_read_b128 v[196:199], v146 offset:37888
	ds_read_b128 v[200:203], v146 offset:38912
	ds_read_b128 v[204:207], v146 offset:39936
	s_add_u32 vcc_lo, s22, s0
	s_addc_u32 vcc_hi, s23, s1
	global_load_lds_dwordx4 v2, vcc
	s_mov_b32 m0, s30
	s_nop 0
	s_add_u32 vcc_lo, s22, s54
	s_addc_u32 vcc_hi, s23, s55
	global_load_lds_dwordx4 v2, vcc
	s_waitcnt lgkmcnt(8)
	s_barrier
; #define G_STAGE(bufoff, gbase, o0, h64) do { \
;         __builtin_amdgcn_global_load_lds((const unsigned*)((const char*)(gbase) + (o0)), (LAS unsigned*)(lds + (bufoff) + ldsw), 16, 0, 0); \
;         __builtin_amdgcn_global_load_lds((const unsigned*)((const char*)(gbase) + (h64) + (o0)), (LAS unsigned*)(lds + (bufoff) + ldsw + 8192), 16, 0, 0); } while (0)
; #define G_LDA(dst, b, h) do { _Pragma("unroll") for (int m = 0; m < 4; ++m) _Pragma("unroll") for (int k = 0; k < 2; ++k) dst[m][k] = *(const LAS bf16x8*)(lds + G_SA(b, h) + aoff + m * 2048 + k * 1024); } while (0)
; #define G_LDB(dst, b, h) do { _Pragma("unroll") for (int n = 0; n < 2; ++n) _Pragma("unroll") for (int k = 0; k < 2; ++k) dst[n][k] = *(const LAS bf16x8*)(lds + G_SB(b, h) + boff + n * 2048 + k * 1024); } while (0)
; #define G_WAIT_V(n) asm volatile("s_waitcnt vmcnt(" #n ")" ::: "memory")
; #define G_WAIT_L(n) asm volatile("s_waitcnt lgkmcnt(" #n ")" ::: "memory")
; #define G_BAR __builtin_amdgcn_s_barrier()
; #define G_SCHED __builtin_amdgcn_sched_barrier(0)
;     ...
;             G_WAIT_L(8); G_BAR; G_WAIT_L(0); G_MMA(0, 0, At, B0); G_BAR; G_SCHED;
;             G_LDB(B1, 1, 1); G_STAGE(G_SB(1, 0), b3, cB0, qB);
;             G_BAR; G_WAIT_L(0); G_MMA(0, 1, At, B1); G_BAR;
;             G_LDA(At, 1, 1); G_STAGE(G_SA(1, 0), a3, cA0, qA);
;             G_BAR; G_WAIT_L(0); G_MMA(1, 0, At, B0); G_BAR; G_SCHED;
;             G_STAGE(G_SB(1, 1), b3 + chB, cB0, qB);
;             G_WAIT_V(6); G_BAR; G_MMA(1, 1, At, B1); G_BAR;
;         }
	s_waitcnt lgkmcnt(0)
	v_mfma_f32_16x16x32_bf16 v[132:135], v[140:143], v[160:163], v[132:135]
	v_mfma_f32_16x16x32_bf16 v[128:131], v[152:155], v[160:163], v[128:131]
	v_mfma_f32_16x16x32_bf16 v[116:119], v[140:143], v[172:175], v[116:119]
	v_mfma_f32_16x16x32_bf16 v[112:115], v[152:155], v[172:175], v[112:115]
	v_mfma_f32_16x16x32_bf16 v[100:103], v[140:143], v[180:183], v[100:103]
	v_mfma_f32_16x16x32_bf16 v[96:99], v[152:155], v[180:183], v[96:99]
	v_mfma_f32_16x16x32_bf16 v[84:87], v[140:143], v[200:203], v[84:87]
	v_mfma_f32_16x16x32_bf16 v[80:83], v[152:155], v[200:203], v[80:83]
	v_mfma_f32_16x16x32_bf16 v[132:135], v[148:151], v[164:167], v[132:135]
	v_mfma_f32_16x16x32_bf16 v[128:131], v[156:159], v[164:167], v[128:131]
	v_mfma_f32_16x16x32_bf16 v[116:119], v[148:151], v[176:179], v[116:119]
	v_mfma_f32_16x16x32_bf16 v[112:115], v[156:159], v[176:179], v[112:115]
	v_mfma_f32_16x16x32_bf16 v[100:103], v[148:151], v[196:199], v[100:103]
	v_mfma_f32_16x16x32_bf16 v[96:99], v[156:159], v[196:199], v[96:99]
	v_mfma_f32_16x16x32_bf16 v[84:87], v[148:151], v[204:207], v[84:87]
	v_mfma_f32_16x16x32_bf16 v[80:83], v[156:159], v[204:207], v[80:83]
	s_barrier
	s_add_i32 s5, 0, 0x1c000
	s_add_i32 s4, s4, s26
	s_mov_b32 m0, s4
	ds_read_b128 v[208:211], v255 offset:49152
	ds_read_b128 v[212:215], v255 offset:50176
	ds_read_b128 v[216:219], v255 offset:51200
	ds_read_b128 v[220:223], v255 offset:52224
	s_add_u32 vcc_lo, s42, s46
	s_addc_u32 vcc_hi, s43, s47
	global_load_lds_dwordx4 v136, vcc
	s_add_i32 m0, s4, 0x2000
	s_nop 0
	s_add_u32 vcc_lo, s42, s58
	s_addc_u32 vcc_hi, s43, s59
	global_load_lds_dwordx4 v136, vcc
	s_barrier
	s_waitcnt lgkmcnt(0)
	v_mfma_f32_16x16x32_bf16 v[124:127], v[208:211], v[160:163], v[124:127]
	v_mfma_f32_16x16x32_bf16 v[120:123], v[216:219], v[160:163], v[120:123]
	v_mfma_f32_16x16x32_bf16 v[108:111], v[208:211], v[172:175], v[108:111]
	v_mfma_f32_16x16x32_bf16 v[104:107], v[216:219], v[172:175], v[104:107]
	v_mfma_f32_16x16x32_bf16 v[92:95], v[208:211], v[180:183], v[92:95]
	v_mfma_f32_16x16x32_bf16 v[88:91], v[216:219], v[180:183], v[88:91]
	v_mfma_f32_16x16x32_bf16 v[76:79], v[208:211], v[200:203], v[76:79]
	v_mfma_f32_16x16x32_bf16 v[72:75], v[216:219], v[200:203], v[72:75]
	v_mfma_f32_16x16x32_bf16 v[124:127], v[212:215], v[164:167], v[124:127]
	v_mfma_f32_16x16x32_bf16 v[120:123], v[220:223], v[164:167], v[120:123]
	v_mfma_f32_16x16x32_bf16 v[108:111], v[212:215], v[176:179], v[108:111]
	v_mfma_f32_16x16x32_bf16 v[104:107], v[220:223], v[176:179], v[104:107]
	v_mfma_f32_16x16x32_bf16 v[92:95], v[212:215], v[196:199], v[92:95]
	v_mfma_f32_16x16x32_bf16 v[88:91], v[220:223], v[196:199], v[88:91]
	v_mfma_f32_16x16x32_bf16 v[76:79], v[212:215], v[204:207], v[76:79]
	v_mfma_f32_16x16x32_bf16 v[72:75], v[220:223], v[204:207], v[72:75]
	s_barrier
	s_mov_b32 m0, s31
	ds_read_b128 v[160:163], v146 offset:49152
	ds_read_b128 v[164:167], v146 offset:50176
	ds_read_b128 v[172:175], v146 offset:51200
	ds_read_b128 v[176:179], v146 offset:52224
	ds_read_b128 v[180:183], v146 offset:53248
	ds_read_b128 v[196:199], v146 offset:54272
	ds_read_b128 v[200:203], v146 offset:55296
	ds_read_b128 v[204:207], v146 offset:56320
	s_add_u32 vcc_lo, s22, s46
	s_addc_u32 vcc_hi, s23, s47
	global_load_lds_dwordx4 v2, vcc
	s_mov_b32 m0, s33
	s_nop 0
	s_add_u32 vcc_lo, s22, s58
	s_addc_u32 vcc_hi, s23, s59
	global_load_lds_dwordx4 v2, vcc
	s_barrier
	s_waitcnt lgkmcnt(0)
	v_mfma_f32_16x16x32_bf16 v[68:71], v[140:143], v[160:163], v[68:71]
	v_mfma_f32_16x16x32_bf16 v[64:67], v[152:155], v[160:163], v[64:67]
	v_mfma_f32_16x16x32_bf16 v[52:55], v[140:143], v[172:175], v[52:55]
	v_mfma_f32_16x16x32_bf16 v[48:51], v[152:155], v[172:175], v[48:51]
	v_mfma_f32_16x16x32_bf16 v[36:39], v[140:143], v[180:183], v[36:39]
	v_mfma_f32_16x16x32_bf16 v[32:35], v[152:155], v[180:183], v[32:35]
	v_mfma_f32_16x16x32_bf16 v[20:23], v[140:143], v[200:203], v[20:23]
	v_mfma_f32_16x16x32_bf16 v[16:19], v[152:155], v[200:203], v[16:19]
	v_mfma_f32_16x16x32_bf16 v[68:71], v[148:151], v[164:167], v[68:71]
	v_mfma_f32_16x16x32_bf16 v[64:67], v[156:159], v[164:167], v[64:67]
	v_mfma_f32_16x16x32_bf16 v[52:55], v[148:151], v[176:179], v[52:55]
	v_mfma_f32_16x16x32_bf16 v[48:51], v[156:159], v[176:179], v[48:51]
	v_mfma_f32_16x16x32_bf16 v[36:39], v[148:151], v[196:199], v[36:39]
	v_mfma_f32_16x16x32_bf16 v[32:35], v[156:159], v[196:199], v[32:35]
	v_mfma_f32_16x16x32_bf16 v[20:23], v[148:151], v[204:207], v[20:23]
	v_mfma_f32_16x16x32_bf16 v[16:19], v[156:159], v[204:207], v[16:19]
	s_barrier
	s_add_i32 s4, s5, s26
	s_mov_b32 m0, s4
	s_nop 0
	s_add_u32 vcc_lo, s42, s50
	s_addc_u32 vcc_hi, s43, s51
	global_load_lds_dwordx4 v136, vcc
	s_add_i32 m0, s4, 0x2000
	s_nop 0
	s_add_u32 vcc_lo, s42, s62
	s_addc_u32 vcc_hi, s43, s63
	global_load_lds_dwordx4 v136, vcc
	s_add_i32 s21, s21, 2
	s_add_u32 s6, s6, 0x100
	s_addc_u32 s7, s7, 0
	s_add_u32 s19, s19, 0x100
	s_addc_u32 s20, s20, 0
	s_cmp_gt_u32 s21, 5
	s_waitcnt vmcnt(6)
	s_barrier
	v_mfma_f32_16x16x32_bf16 v[60:63], v[208:211], v[160:163], v[60:63]
	v_mfma_f32_16x16x32_bf16 v[56:59], v[216:219], v[160:163], v[56:59]
	v_mfma_f32_16x16x32_bf16 v[44:47], v[208:211], v[172:175], v[44:47]
	v_mfma_f32_16x16x32_bf16 v[40:43], v[216:219], v[172:175], v[40:43]
	v_mfma_f32_16x16x32_bf16 v[28:31], v[208:211], v[180:183], v[28:31]
	v_mfma_f32_16x16x32_bf16 v[24:27], v[216:219], v[180:183], v[24:27]
	v_mfma_f32_16x16x32_bf16 v[12:15], v[208:211], v[200:203], v[12:15]
	v_mfma_f32_16x16x32_bf16 v[8:11], v[216:219], v[200:203], v[8:11]
	v_mfma_f32_16x16x32_bf16 v[60:63], v[212:215], v[164:167], v[60:63]
	v_mfma_f32_16x16x32_bf16 v[56:59], v[220:223], v[164:167], v[56:59]
	v_mfma_f32_16x16x32_bf16 v[44:47], v[212:215], v[176:179], v[44:47]
	v_mfma_f32_16x16x32_bf16 v[40:43], v[220:223], v[176:179], v[40:43]
	v_mfma_f32_16x16x32_bf16 v[28:31], v[212:215], v[196:199], v[28:31]
	v_mfma_f32_16x16x32_bf16 v[24:27], v[220:223], v[196:199], v[24:27]
	v_mfma_f32_16x16x32_bf16 v[12:15], v[212:215], v[204:207], v[12:15]
	v_mfma_f32_16x16x32_bf16 v[8:11], v[220:223], v[204:207], v[8:11]
	s_cbranch_scc0 .Ldb_SSM1_cont

; #define G_STAGE(bufoff, gbase, o0, h64) do { \
;         __builtin_amdgcn_global_load_lds((const unsigned*)((const char*)(gbase) + (o0)), (LAS unsigned*)(lds + (bufoff) + ldsw), 16, 0, 0); \
;         __builtin_amdgcn_global_load_lds((const unsigned*)((const char*)(gbase) + (h64) + (o0)), (LAS unsigned*)(lds + (bufoff) + ldsw + 8192), 16, 0, 0); } while (0)
; #define G_LDA(dst, b, h) do { _Pragma("unroll") for (int m = 0; m < 4; ++m) _Pragma("unroll") for (int k = 0; k < 2; ++k) dst[m][k] = *(const LAS bf16x8*)(lds + G_SA(b, h) + aoff + m * 2048 + k * 1024); } while (0)
; #define G_LDB(dst, b, h) do { _Pragma("unroll") for (int n = 0; n < 2; ++n) _Pragma("unroll") for (int k = 0; k < 2; ++k) dst[n][k] = *(const LAS bf16x8*)(lds + G_SB(b, h) + boff + n * 2048 + k * 1024); } while (0)
; #define G_WAIT_L(n) asm volatile("s_waitcnt lgkmcnt(" #n ")" ::: "memory")
; #define G_BAR __builtin_amdgcn_s_barrier()
; #define G_SCHED __builtin_amdgcn_sched_barrier(0)
;     ...
;         for (int t = 0; t < nt; t += 2) {
;             const bool last = (t == nt - 2);
;             const char* a1 = cA + (size_t)(t + 1) * ckA;
;             const char* a2 = last ? nA : cA + (size_t)(t + 2) * ckA; const char* b2 = last ? nB : cB + (size_t)(t + 2) * kB;
;             const char* a3 = a2 + ckA; const char* b3 = b2 + kB;
;             G_LDB(B0, 0, 0); G_SCHED; G_LDA(At, 0, 0); G_STAGE(G_SA(1, 1), a1 + chA, cA0, qA);
;             G_WAIT_L(8); G_BAR; G_WAIT_L(0); G_MMA(0, 0, At, B0); G_BAR; G_SCHED;
;             G_LDB(B1, 0, 1); G_STAGE(G_SB(0, 0), b2, cB0, qB);
;             G_BAR; G_WAIT_L(0); G_MMA(0, 1, At, B1); G_BAR;
;             G_LDA(At, 0, 1); G_STAGE(G_SA(0, 0), a2, cA0, qA);
;             G_BAR; G_WAIT_L(0); G_MMA(1, 0, At, B0); G_BAR; G_SCHED;
;     ...
;         for (int a = 0; a < 2; ++a)
; #pragma unroll
;             for (int b = 0; b < 2; ++b)
; #pragma unroll
;                 for (int m = 0; m < 4; ++m)
; #pragma unroll
;                     for (int n = 0; n < 2; ++n) acc[a][b][m][n] = (f32x4){0.f, 0.f, 0.f, 0.f};
.LBB0_803:
	s_add_u32 s13, s18, 0x100
	s_addc_u32 s18, s19, 0
	s_add_u32 s2, s2, 0x800000
	s_addc_u32 s3, s3, 0
	s_mov_b32 s19, -2
	s_mov_b64 s[42:43], 0x20080
	s_mov_b64 s[50:51], 0x10000
	s_mov_b64 s[52:53], 0x30000
	s_mov_b64 s[54:55], 0x10080
	s_mov_b64 s[58:59], 0x30080
	s_mov_b64 s[62:63], 0x400000
	s_cmp_eq_u32 s101, 2
	s_cselect_b32 s101, 0, s101
	v_add_u32_e32 v255, 0x10000, v196
	s_add_i32 s40, 0, 0x10000
	ds_read_b128 v[112:115], v255 offset:0
	ds_read_b128 v[124:127], v255 offset:1024
	ds_read_b128 v[136:139], v255 offset:2048
	ds_read_b128 v[148:151], v255 offset:3072
	s_cmp_eq_u32 s19, 4
	s_cselect_b32 s5, s15, s3
	s_cselect_b32 s4, s14, s2
	s_cselect_b32 s37, s17, s18
	s_cselect_b32 s36, s16, s13
	s_mov_b32 s38, 0xffc01000
	s_mov_b32 s39, -1
	s_add_u32 vcc_lo, s2, s38
	s_addc_u32 vcc_hi, s3, s39
	s_mov_b32 s38, 0xffc01800
	s_add_i32 m0, s24, 0xc000
	s_mov_b32 s39, -1
	ds_read_b128 v[152:155], v197
	ds_read_b128 v[156:159], v197 offset:1024
	ds_read_b128 v[160:163], v197 offset:2048
	ds_read_b128 v[172:175], v197 offset:3072
	ds_read_b128 v[176:179], v197 offset:4096
	ds_read_b128 v[180:183], v197 offset:5120
	ds_read_b128 v[198:201], v197 offset:6144
	ds_read_b128 v[202:205], v197 offset:7168
	global_load_lds_dwordx4 v166, vcc
	s_add_i32 m0, s24, 0xe000
	s_nop 0
	s_add_u32 vcc_lo, s2, s38
	s_addc_u32 vcc_hi, s3, s39
	global_load_lds_dwordx4 v166, vcc
	s_waitcnt lgkmcnt(8)
	s_cmp_eq_u32 s101, 1
	s_cbranch_scc1 .Ldb_GLU_skp
	s_barrier
.Ldb_GLU_skp:
	s_mov_b32 s101, 0
	s_waitcnt lgkmcnt(0)
	v_mfma_f32_16x16x32_bf16 v[144:147], v[112:115], v[152:155], 0
	v_mfma_f32_16x16x32_bf16 v[140:143], v[136:139], v[152:155], 0
	v_mfma_f32_16x16x32_bf16 v[120:123], v[112:115], v[160:163], 0
	v_mfma_f32_16x16x32_bf16 v[116:119], v[136:139], v[160:163], 0
	v_mfma_f32_16x16x32_bf16 v[100:103], v[112:115], v[176:179], 0
	v_mfma_f32_16x16x32_bf16 v[96:99], v[136:139], v[176:179], 0
	v_mfma_f32_16x16x32_bf16 v[84:87], v[112:115], v[198:201], 0
	v_mfma_f32_16x16x32_bf16 v[80:83], v[136:139], v[198:201], 0
	v_mfma_f32_16x16x32_bf16 v[144:147], v[124:127], v[156:159], v[144:147]
	v_mfma_f32_16x16x32_bf16 v[140:143], v[148:151], v[156:159], v[140:143]
	v_mfma_f32_16x16x32_bf16 v[120:123], v[124:127], v[172:175], v[120:123]
	v_mfma_f32_16x16x32_bf16 v[116:119], v[148:151], v[172:175], v[116:119]
	v_mfma_f32_16x16x32_bf16 v[100:103], v[124:127], v[180:183], v[100:103]
	v_mfma_f32_16x16x32_bf16 v[96:99], v[148:151], v[180:183], v[96:99]
	v_mfma_f32_16x16x32_bf16 v[84:87], v[124:127], v[202:205], v[84:87]
	v_mfma_f32_16x16x32_bf16 v[80:83], v[148:151], v[202:205], v[80:83]
	s_barrier
	s_add_i32 s38, 0, 0x14000
	s_add_i32 s100, s40, s21
	s_mov_b32 m0, s100
	ds_read_b128 v[206:209], v255 offset:16384
	ds_read_b128 v[210:213], v255 offset:17408
	ds_read_b128 v[214:217], v255 offset:18432
	ds_read_b128 v[218:221], v255 offset:19456
	global_load_lds_dwordx4 v2, s[36:37]
	s_add_i32 m0, s100, 0x2000
	s_nop 0
	s_add_u32 vcc_lo, s36, s50
	s_addc_u32 vcc_hi, s37, s51
	global_load_lds_dwordx4 v2, vcc
	s_barrier
	s_waitcnt lgkmcnt(0)
	v_mfma_f32_16x16x32_bf16 v[132:135], v[206:209], v[152:155], 0
	v_mfma_f32_16x16x32_bf16 v[128:131], v[214:217], v[152:155], 0
	v_mfma_f32_16x16x32_bf16 v[108:111], v[206:209], v[160:163], 0
	v_mfma_f32_16x16x32_bf16 v[104:107], v[214:217], v[160:163], 0
	v_mfma_f32_16x16x32_bf16 v[92:95], v[206:209], v[176:179], 0
	v_mfma_f32_16x16x32_bf16 v[88:91], v[214:217], v[176:179], 0
	v_mfma_f32_16x16x32_bf16 v[76:79], v[206:209], v[198:201], 0
	v_mfma_f32_16x16x32_bf16 v[72:75], v[214:217], v[198:201], 0
	v_mfma_f32_16x16x32_bf16 v[132:135], v[210:213], v[156:159], v[132:135]
	v_mfma_f32_16x16x32_bf16 v[128:131], v[218:221], v[156:159], v[128:131]
	v_mfma_f32_16x16x32_bf16 v[108:111], v[210:213], v[172:175], v[108:111]
	v_mfma_f32_16x16x32_bf16 v[104:107], v[218:221], v[172:175], v[104:107]
	v_mfma_f32_16x16x32_bf16 v[92:95], v[210:213], v[180:183], v[92:95]
	v_mfma_f32_16x16x32_bf16 v[88:91], v[218:221], v[180:183], v[88:91]
	v_mfma_f32_16x16x32_bf16 v[76:79], v[210:213], v[202:205], v[76:79]
	v_mfma_f32_16x16x32_bf16 v[72:75], v[218:221], v[202:205], v[72:75]
	s_barrier
	s_mov_b32 m0, s24
	v_lshl_add_u64 v[222:223], s[4:5], 0, v[164:165]
	ds_read_b128 v[152:155], v197 offset:16384
	ds_read_b128 v[156:159], v197 offset:17408
	ds_read_b128 v[160:163], v197 offset:18432
	ds_read_b128 v[172:175], v197 offset:19456
	ds_read_b128 v[176:179], v197 offset:20480
	ds_read_b128 v[180:183], v197 offset:21504
	ds_read_b128 v[198:201], v197 offset:22528
	ds_read_b128 v[202:205], v197 offset:23552
	global_load_lds_dwordx4 v164, s[4:5]
	s_mov_b32 m0, s25
	s_nop 0
	s_add_u32 vcc_lo, s4, s70
	s_addc_u32 vcc_hi, s5, s71
	global_load_lds_dwordx4 v164, vcc
	s_barrier
	s_waitcnt lgkmcnt(0)
	v_mfma_f32_16x16x32_bf16 v[68:71], v[112:115], v[152:155], 0
	v_mfma_f32_16x16x32_bf16 v[64:67], v[136:139], v[152:155], 0
	v_mfma_f32_16x16x32_bf16 v[52:55], v[112:115], v[160:163], 0
	v_mfma_f32_16x16x32_bf16 v[48:51], v[136:139], v[160:163], 0
	v_mfma_f32_16x16x32_bf16 v[36:39], v[112:115], v[176:179], 0
	v_mfma_f32_16x16x32_bf16 v[32:35], v[136:139], v[176:179], 0
	v_mfma_f32_16x16x32_bf16 v[20:23], v[112:115], v[198:201], 0
	v_mfma_f32_16x16x32_bf16 v[16:19], v[136:139], v[198:201], 0
	v_mfma_f32_16x16x32_bf16 v[68:71], v[124:127], v[156:159], v[68:71]
	v_mfma_f32_16x16x32_bf16 v[64:67], v[148:151], v[156:159], v[64:67]
	v_mfma_f32_16x16x32_bf16 v[52:55], v[124:127], v[172:175], v[52:55]
	v_mfma_f32_16x16x32_bf16 v[48:51], v[148:151], v[172:175], v[48:51]
	v_mfma_f32_16x16x32_bf16 v[36:39], v[124:127], v[180:183], v[36:39]
	v_mfma_f32_16x16x32_bf16 v[32:35], v[148:151], v[180:183], v[32:35]
	v_mfma_f32_16x16x32_bf16 v[20:23], v[124:127], v[202:205], v[20:23]
	v_mfma_f32_16x16x32_bf16 v[16:19], v[148:151], v[202:205], v[16:19]
	s_barrier
; #define G_STAGE(bufoff, gbase, o0, h64) do { \
;         __builtin_amdgcn_global_load_lds((const unsigned*)((const char*)(gbase) + (o0)), (LAS unsigned*)(lds + (bufoff) + ldsw), 16, 0, 0); \
;         __builtin_amdgcn_global_load_lds((const unsigned*)((const char*)(gbase) + (h64) + (o0)), (LAS unsigned*)(lds + (bufoff) + ldsw + 8192), 16, 0, 0); } while (0)
; #define G_LDA(dst, b, h) do { _Pragma("unroll") for (int m = 0; m < 4; ++m) _Pragma("unroll") for (int k = 0; k < 2; ++k) dst[m][k] = *(const LAS bf16x8*)(lds + G_SA(b, h) + aoff + m * 2048 + k * 1024); } while (0)
; #define G_LDB(dst, b, h) do { _Pragma("unroll") for (int n = 0; n < 2; ++n) _Pragma("unroll") for (int k = 0; k < 2; ++k) dst[n][k] = *(const LAS bf16x8*)(lds + G_SB(b, h) + boff + n * 2048 + k * 1024); } while (0)
; #define G_WAIT_V(n) asm volatile("s_waitcnt vmcnt(" #n ")" ::: "memory")
; #define G_WAIT_L(n) asm volatile("s_waitcnt lgkmcnt(" #n ")" ::: "memory")
; #define G_BAR __builtin_amdgcn_s_barrier()
; #define G_SCHED __builtin_amdgcn_sched_barrier(0)
;     ...
;             G_STAGE(G_SB(0, 1), b2 + chB, cB0, qB);
;             G_WAIT_V(6); G_BAR; G_MMA(1, 1, At, B1); G_BAR;
;             G_LDB(B0, 1, 0); G_SCHED; G_LDA(At, 1, 0); G_STAGE(G_SA(0, 1), a2 + chA, cA0, qA);
;             G_WAIT_L(8); G_BAR; G_WAIT_L(0); G_MMA(0, 0, At, B0); G_BAR; G_SCHED;
;             G_LDB(B1, 1, 1); G_STAGE(G_SB(1, 0), b3, cB0, qB);
;             G_BAR; G_WAIT_L(0); G_MMA(0, 1, At, B1); G_BAR;
;             G_LDA(At, 1, 1); G_STAGE(G_SA(1, 0), a3, cA0, qA);
;             G_BAR; G_WAIT_L(0); G_MMA(1, 0, At, B0); G_BAR; G_SCHED;
	s_add_i32 s100, s38, s21
	s_mov_b32 m0, s100
	s_nop 0
	s_add_u32 vcc_lo, s36, s0
	s_addc_u32 vcc_hi, s37, s1
	global_load_lds_dwordx4 v2, vcc
	s_add_i32 m0, s100, 0x2000
	s_nop 0
	s_add_u32 vcc_lo, s36, s52
	s_addc_u32 vcc_hi, s37, s53
	global_load_lds_dwordx4 v2, vcc
	s_waitcnt vmcnt(6)
	s_barrier
	v_mfma_f32_16x16x32_bf16 v[60:63], v[206:209], v[152:155], 0
	v_mfma_f32_16x16x32_bf16 v[56:59], v[214:217], v[152:155], 0
	v_mfma_f32_16x16x32_bf16 v[44:47], v[206:209], v[160:163], 0
	v_mfma_f32_16x16x32_bf16 v[40:43], v[214:217], v[160:163], 0
	v_mfma_f32_16x16x32_bf16 v[28:31], v[206:209], v[176:179], 0
	v_mfma_f32_16x16x32_bf16 v[24:27], v[214:217], v[176:179], 0
	v_mfma_f32_16x16x32_bf16 v[12:15], v[206:209], v[198:201], 0
	v_mfma_f32_16x16x32_bf16 v[8:11], v[214:217], v[198:201], 0
	v_mfma_f32_16x16x32_bf16 v[60:63], v[210:213], v[156:159], v[60:63]
	v_mfma_f32_16x16x32_bf16 v[56:59], v[218:221], v[156:159], v[56:59]
	v_mfma_f32_16x16x32_bf16 v[44:47], v[210:213], v[172:175], v[44:47]
	v_mfma_f32_16x16x32_bf16 v[40:43], v[218:221], v[172:175], v[40:43]
	v_mfma_f32_16x16x32_bf16 v[28:31], v[210:213], v[180:183], v[28:31]
	v_mfma_f32_16x16x32_bf16 v[24:27], v[218:221], v[180:183], v[24:27]
	v_mfma_f32_16x16x32_bf16 v[12:15], v[210:213], v[202:205], v[12:15]
	v_mfma_f32_16x16x32_bf16 v[8:11], v[218:221], v[202:205], v[8:11]
	s_barrier
	s_add_i32 s100, 0, 0x18000
	ds_read_b128 v[112:115], v255 offset:32768
	ds_read_b128 v[124:127], v255 offset:33792
	ds_read_b128 v[136:139], v255 offset:34816
	ds_read_b128 v[148:151], v255 offset:35840
	s_mov_b32 m0, s26
	ds_read_b128 v[152:155], v197 offset:32768
	ds_read_b128 v[156:159], v197 offset:33792
	ds_read_b128 v[160:163], v197 offset:34816
	ds_read_b128 v[172:175], v197 offset:35840
	ds_read_b128 v[176:179], v197 offset:36864
	ds_read_b128 v[180:183], v197 offset:37888
	ds_read_b128 v[198:201], v197 offset:38912
	ds_read_b128 v[202:205], v197 offset:39936
	s_add_u32 vcc_lo, s4, s80
	s_addc_u32 vcc_hi, s5, s81
	global_load_lds_dwordx4 v164, vcc
	s_mov_b32 m0, s27
	s_nop 0
	s_add_u32 vcc_lo, s4, s82
	s_addc_u32 vcc_hi, s5, s83
	global_load_lds_dwordx4 v164, vcc
	s_waitcnt lgkmcnt(8)
	s_barrier
	s_waitcnt lgkmcnt(0)
	v_mfma_f32_16x16x32_bf16 v[144:147], v[112:115], v[152:155], v[144:147]
	v_mfma_f32_16x16x32_bf16 v[140:143], v[136:139], v[152:155], v[140:143]
	v_mfma_f32_16x16x32_bf16 v[120:123], v[112:115], v[160:163], v[120:123]
	v_mfma_f32_16x16x32_bf16 v[116:119], v[136:139], v[160:163], v[116:119]
	v_mfma_f32_16x16x32_bf16 v[100:103], v[112:115], v[176:179], v[100:103]
	v_mfma_f32_16x16x32_bf16 v[96:99], v[136:139], v[176:179], v[96:99]
	v_mfma_f32_16x16x32_bf16 v[84:87], v[112:115], v[198:201], v[84:87]
	v_mfma_f32_16x16x32_bf16 v[80:83], v[136:139], v[198:201], v[80:83]
	v_mfma_f32_16x16x32_bf16 v[144:147], v[124:127], v[156:159], v[144:147]
	v_mfma_f32_16x16x32_bf16 v[140:143], v[148:151], v[156:159], v[140:143]
	v_mfma_f32_16x16x32_bf16 v[120:123], v[124:127], v[172:175], v[120:123]
	v_mfma_f32_16x16x32_bf16 v[116:119], v[148:151], v[172:175], v[116:119]
	v_mfma_f32_16x16x32_bf16 v[100:103], v[124:127], v[180:183], v[100:103]
	v_mfma_f32_16x16x32_bf16 v[96:99], v[148:151], v[180:183], v[96:99]
	v_mfma_f32_16x16x32_bf16 v[84:87], v[124:127], v[202:205], v[84:87]
	v_mfma_f32_16x16x32_bf16 v[80:83], v[148:151], v[202:205], v[80:83]
	s_barrier
	s_add_i32 s5, 0, 0x1c000
	s_add_i32 s4, s100, s21
	s_mov_b32 m0, s4
	ds_read_b128 v[206:209], v255 offset:49152
	ds_read_b128 v[210:213], v255 offset:50176
	ds_read_b128 v[214:217], v255 offset:51200
	ds_read_b128 v[218:221], v255 offset:52224
	s_add_u32 vcc_lo, s36, s46
	s_addc_u32 vcc_hi, s37, s47
	global_load_lds_dwordx4 v2, vcc
	s_add_i32 m0, s4, 0x2000
	s_nop 0
	s_add_u32 vcc_lo, s36, s54
	s_addc_u32 vcc_hi, s37, s55
	global_load_lds_dwordx4 v2, vcc
	s_barrier
	s_waitcnt lgkmcnt(0)
	v_mfma_f32_16x16x32_bf16 v[132:135], v[206:209], v[152:155], v[132:135]
	v_mfma_f32_16x16x32_bf16 v[128:131], v[214:217], v[152:155], v[128:131]
	v_mfma_f32_16x16x32_bf16 v[108:111], v[206:209], v[160:163], v[108:111]
	v_mfma_f32_16x16x32_bf16 v[104:107], v[214:217], v[160:163], v[104:107]
	v_mfma_f32_16x16x32_bf16 v[92:95], v[206:209], v[176:179], v[92:95]
	v_mfma_f32_16x16x32_bf16 v[88:91], v[214:217], v[176:179], v[88:91]
	v_mfma_f32_16x16x32_bf16 v[76:79], v[206:209], v[198:201], v[76:79]
	v_mfma_f32_16x16x32_bf16 v[72:75], v[214:217], v[198:201], v[72:75]
	v_mfma_f32_16x16x32_bf16 v[132:135], v[210:213], v[156:159], v[132:135]
	v_mfma_f32_16x16x32_bf16 v[128:131], v[218:221], v[156:159], v[128:131]
	v_mfma_f32_16x16x32_bf16 v[108:111], v[210:213], v[172:175], v[108:111]
	v_mfma_f32_16x16x32_bf16 v[104:107], v[218:221], v[172:175], v[104:107]
	v_mfma_f32_16x16x32_bf16 v[92:95], v[210:213], v[180:183], v[92:95]
	v_mfma_f32_16x16x32_bf16 v[88:91], v[218:221], v[180:183], v[88:91]
	v_mfma_f32_16x16x32_bf16 v[76:79], v[210:213], v[202:205], v[76:79]
	v_mfma_f32_16x16x32_bf16 v[72:75], v[218:221], v[202:205], v[72:75]
	s_barrier
	s_mov_b32 m0, s29
	v_lshl_add_u64 v[224:225], v[222:223], 0, s[62:63]
	ds_read_b128 v[152:155], v197 offset:49152
	ds_read_b128 v[156:159], v197 offset:50176
	ds_read_b128 v[160:163], v197 offset:51200
	ds_read_b128 v[172:175], v197 offset:52224
	ds_read_b128 v[176:179], v197 offset:53248
	ds_read_b128 v[180:183], v197 offset:54272
	ds_read_b128 v[198:201], v197 offset:55296
	ds_read_b128 v[202:205], v197 offset:56320
	global_load_lds_dwordx4 v[224:225], off
	v_lshl_add_u64 v[222:223], v[222:223], 0, s[84:85]
	s_mov_b32 m0, s30
	s_nop 0
	global_load_lds_dwordx4 v[222:223], off
	s_barrier
; #define G_STAGE(bufoff, gbase, o0, h64) do { \
;         __builtin_amdgcn_global_load_lds((const unsigned*)((const char*)(gbase) + (o0)), (LAS unsigned*)(lds + (bufoff) + ldsw), 16, 0, 0); \
;         __builtin_amdgcn_global_load_lds((const unsigned*)((const char*)(gbase) + (h64) + (o0)), (LAS unsigned*)(lds + (bufoff) + ldsw + 8192), 16, 0, 0); } while (0)
; #define G_LDA(dst, b, h) do { _Pragma("unroll") for (int m = 0; m < 4; ++m) _Pragma("unroll") for (int k = 0; k < 2; ++k) dst[m][k] = *(const LAS bf16x8*)(lds + G_SA(b, h) + aoff + m * 2048 + k * 1024); } while (0)
; #define G_LDB(dst, b, h) do { _Pragma("unroll") for (int n = 0; n < 2; ++n) _Pragma("unroll") for (int k = 0; k < 2; ++k) dst[n][k] = *(const LAS bf16x8*)(lds + G_SB(b, h) + boff + n * 2048 + k * 1024); } while (0)
; #define G_WAIT_V(n) asm volatile("s_waitcnt vmcnt(" #n ")" ::: "memory")
; #define G_BAR __builtin_amdgcn_s_barrier()
;     ...
;         for (int t = 0; t < nt; t += 2) {
;             const bool last = (t == nt - 2);
;             const char* a1 = cA + (size_t)(t + 1) * ckA;
;             const char* a2 = last ? nA : cA + (size_t)(t + 2) * ckA; const char* b2 = last ? nB : cB + (size_t)(t + 2) * kB;
;             const char* a3 = a2 + ckA; const char* b3 = b2 + kB;
;             G_LDB(B0, 0, 0); G_SCHED; G_LDA(At, 0, 0); G_STAGE(G_SA(1, 1), a1 + chA, cA0, qA);
;             G_WAIT_L(8); G_BAR; G_WAIT_L(0); G_MMA(0, 0, At, B0); G_BAR; G_SCHED;
;             G_LDB(B1, 0, 1); G_STAGE(G_SB(0, 0), b2, cB0, qB);
;             G_BAR; G_WAIT_L(0); G_MMA(0, 1, At, B1); G_BAR;
;             G_LDA(At, 0, 1); G_STAGE(G_SA(0, 0), a2, cA0, qA);
;             G_BAR; G_WAIT_L(0); G_MMA(1, 0, At, B0); G_BAR; G_SCHED;
;             G_STAGE(G_SB(0, 1), b2 + chB, cB0, qB);
;             G_WAIT_V(6); G_BAR; G_MMA(1, 1, At, B1); G_BAR;
;             G_LDB(B0, 1, 0); G_SCHED; G_LDA(At, 1, 0); G_STAGE(G_SA(0, 1), a2 + chA, cA0, qA);
;             G_WAIT_L(8); G_BAR; G_WAIT_L(0); G_MMA(0, 0, At, B0); G_BAR; G_SCHED;
;             G_LDB(B1, 1, 1); G_STAGE(G_SB(1, 0), b3, cB0, qB);
;             G_BAR; G_WAIT_L(0); G_MMA(0, 1, At, B1); G_BAR;
;             G_LDA(At, 1, 1); G_STAGE(G_SA(1, 0), a3, cA0, qA);
;             G_BAR; G_WAIT_L(0); G_MMA(1, 0, At, B0); G_BAR; G_SCHED;
;             G_STAGE(G_SB(1, 1), b3 + chB, cB0, qB);
;             G_WAIT_V(6); G_BAR; G_MMA(1, 1, At, B1); G_BAR;
	s_waitcnt lgkmcnt(0)
	v_mfma_f32_16x16x32_bf16 v[68:71], v[112:115], v[152:155], v[68:71]
	v_mfma_f32_16x16x32_bf16 v[64:67], v[136:139], v[152:155], v[64:67]
	v_mfma_f32_16x16x32_bf16 v[52:55], v[112:115], v[160:163], v[52:55]
	v_mfma_f32_16x16x32_bf16 v[48:51], v[136:139], v[160:163], v[48:51]
	v_mfma_f32_16x16x32_bf16 v[36:39], v[112:115], v[176:179], v[36:39]
	v_mfma_f32_16x16x32_bf16 v[32:35], v[136:139], v[176:179], v[32:35]
	v_mfma_f32_16x16x32_bf16 v[20:23], v[112:115], v[198:201], v[20:23]
	v_mfma_f32_16x16x32_bf16 v[16:19], v[136:139], v[198:201], v[16:19]
	v_mfma_f32_16x16x32_bf16 v[68:71], v[124:127], v[156:159], v[68:71]
	v_mfma_f32_16x16x32_bf16 v[64:67], v[148:151], v[156:159], v[64:67]
	v_mfma_f32_16x16x32_bf16 v[52:55], v[124:127], v[172:175], v[52:55]
	v_mfma_f32_16x16x32_bf16 v[48:51], v[148:151], v[172:175], v[48:51]
	v_mfma_f32_16x16x32_bf16 v[36:39], v[124:127], v[180:183], v[36:39]
	v_mfma_f32_16x16x32_bf16 v[32:35], v[148:151], v[180:183], v[32:35]
	v_mfma_f32_16x16x32_bf16 v[20:23], v[124:127], v[202:205], v[20:23]
	v_mfma_f32_16x16x32_bf16 v[16:19], v[148:151], v[202:205], v[16:19]
	s_barrier
	s_add_i32 s4, s5, s21
	s_mov_b32 m0, s4
	s_nop 0
	s_add_u32 vcc_lo, s36, s42
	s_addc_u32 vcc_hi, s37, s43
	global_load_lds_dwordx4 v2, vcc
	s_add_i32 m0, s4, 0x2000
	s_nop 0
	s_add_u32 vcc_lo, s36, s58
	s_addc_u32 vcc_hi, s37, s59
	global_load_lds_dwordx4 v2, vcc
	s_add_i32 s19, s19, 2
	s_add_u32 s13, s13, 0x100
	s_addc_u32 s18, s18, 0
	s_add_u32 s2, s2, 0x800000
	s_addc_u32 s3, s3, 0
	s_cmp_gt_u32 s19, 5
	s_waitcnt vmcnt(6)
	s_barrier
	v_mfma_f32_16x16x32_bf16 v[60:63], v[206:209], v[152:155], v[60:63]
	v_mfma_f32_16x16x32_bf16 v[56:59], v[214:217], v[152:155], v[56:59]
	v_mfma_f32_16x16x32_bf16 v[44:47], v[206:209], v[160:163], v[44:47]
	v_mfma_f32_16x16x32_bf16 v[40:43], v[214:217], v[160:163], v[40:43]
	v_mfma_f32_16x16x32_bf16 v[28:31], v[206:209], v[176:179], v[28:31]
	v_mfma_f32_16x16x32_bf16 v[24:27], v[214:217], v[176:179], v[24:27]
	v_mfma_f32_16x16x32_bf16 v[12:15], v[206:209], v[198:201], v[12:15]
	v_mfma_f32_16x16x32_bf16 v[8:11], v[214:217], v[198:201], v[8:11]
	v_mfma_f32_16x16x32_bf16 v[60:63], v[210:213], v[156:159], v[60:63]
	v_mfma_f32_16x16x32_bf16 v[56:59], v[218:221], v[156:159], v[56:59]
	v_mfma_f32_16x16x32_bf16 v[44:47], v[210:213], v[172:175], v[44:47]
	v_mfma_f32_16x16x32_bf16 v[40:43], v[218:221], v[172:175], v[40:43]
	v_mfma_f32_16x16x32_bf16 v[28:31], v[210:213], v[180:183], v[28:31]
	v_mfma_f32_16x16x32_bf16 v[24:27], v[218:221], v[180:183], v[24:27]
	v_mfma_f32_16x16x32_bf16 v[12:15], v[210:213], v[202:205], v[12:15]
	v_mfma_f32_16x16x32_bf16 v[8:11], v[218:221], v[202:205], v[8:11]
	s_cbranch_scc0 .Ldb_GLU_cont
	s_branch .Ldb_GLU_xl
.LBB0_804:
	s_add_i32 s40, 0, 0x10000
	ds_read_b128 v[112:115], v255 offset:0
	ds_read_b128 v[124:127], v255 offset:1024
	ds_read_b128 v[136:139], v255 offset:2048
	ds_read_b128 v[148:151], v255 offset:3072
	s_cmp_eq_u32 s19, 4
	s_cselect_b32 s5, s15, s3
	s_cselect_b32 s4, s14, s2
	s_cselect_b32 s37, s17, s18
	s_cselect_b32 s36, s16, s13
	s_mov_b32 s38, 0xffc01000
	s_mov_b32 s39, -1
	s_add_u32 vcc_lo, s2, s38
	s_addc_u32 vcc_hi, s3, s39
	s_mov_b32 s38, 0xffc01800
	s_add_i32 m0, s24, 0xc000
	s_mov_b32 s39, -1
	ds_read_b128 v[152:155], v197
	ds_read_b128 v[156:159], v197 offset:1024
	ds_read_b128 v[160:163], v197 offset:2048
	ds_read_b128 v[172:175], v197 offset:3072
	ds_read_b128 v[176:179], v197 offset:4096
	ds_read_b128 v[180:183], v197 offset:5120
	ds_read_b128 v[198:201], v197 offset:6144
	ds_read_b128 v[202:205], v197 offset:7168
	global_load_lds_dwordx4 v166, vcc
	s_add_i32 m0, s24, 0xe000
	s_nop 0
	s_add_u32 vcc_lo, s2, s38
	s_addc_u32 vcc_hi, s3, s39
	global_load_lds_dwordx4 v166, vcc
	s_waitcnt lgkmcnt(8)
	s_barrier
	s_waitcnt lgkmcnt(0)
	v_mfma_f32_16x16x32_bf16 v[144:147], v[112:115], v[152:155], v[144:147]
	v_mfma_f32_16x16x32_bf16 v[140:143], v[136:139], v[152:155], v[140:143]
	v_mfma_f32_16x16x32_bf16 v[120:123], v[112:115], v[160:163], v[120:123]
	v_mfma_f32_16x16x32_bf16 v[116:119], v[136:139], v[160:163], v[116:119]
	v_mfma_f32_16x16x32_bf16 v[100:103], v[112:115], v[176:179], v[100:103]
	v_mfma_f32_16x16x32_bf16 v[96:99], v[136:139], v[176:179], v[96:99]
	v_mfma_f32_16x16x32_bf16 v[84:87], v[112:115], v[198:201], v[84:87]
	v_mfma_f32_16x16x32_bf16 v[80:83], v[136:139], v[198:201], v[80:83]
	v_mfma_f32_16x16x32_bf16 v[144:147], v[124:127], v[156:159], v[144:147]
	v_mfma_f32_16x16x32_bf16 v[140:143], v[148:151], v[156:159], v[140:143]
	v_mfma_f32_16x16x32_bf16 v[120:123], v[124:127], v[172:175], v[120:123]
	v_mfma_f32_16x16x32_bf16 v[116:119], v[148:151], v[172:175], v[116:119]
	v_mfma_f32_16x16x32_bf16 v[100:103], v[124:127], v[180:183], v[100:103]
	v_mfma_f32_16x16x32_bf16 v[96:99], v[148:151], v[180:183], v[96:99]
	v_mfma_f32_16x16x32_bf16 v[84:87], v[124:127], v[202:205], v[84:87]
	v_mfma_f32_16x16x32_bf16 v[80:83], v[148:151], v[202:205], v[80:83]
	s_barrier
	s_add_i32 s38, 0, 0x14000
	s_add_i32 s100, s40, s21
	s_mov_b32 m0, s100
	ds_read_b128 v[206:209], v255 offset:16384
	ds_read_b128 v[210:213], v255 offset:17408
	ds_read_b128 v[214:217], v255 offset:18432
	ds_read_b128 v[218:221], v255 offset:19456
	global_load_lds_dwordx4 v2, s[36:37]
	s_add_i32 m0, s100, 0x2000
	s_nop 0
	s_add_u32 vcc_lo, s36, s50
	s_addc_u32 vcc_hi, s37, s51
	global_load_lds_dwordx4 v2, vcc
	s_barrier
; #define G_STAGE(bufoff, gbase, o0, h64) do { \
;         __builtin_amdgcn_global_load_lds((const unsigned*)((const char*)(gbase) + (o0)), (LAS unsigned*)(lds + (bufoff) + ldsw), 16, 0, 0); \
;         __builtin_amdgcn_global_load_lds((const unsigned*)((const char*)(gbase) + (h64) + (o0)), (LAS unsigned*)(lds + (bufoff) + ldsw + 8192), 16, 0, 0); } while (0)
; #define G_LDA(dst, b, h) do { _Pragma("unroll") for (int m = 0; m < 4; ++m) _Pragma("unroll") for (int k = 0; k < 2; ++k) dst[m][k] = *(const LAS bf16x8*)(lds + G_SA(b, h) + aoff + m * 2048 + k * 1024); } while (0)
; #define G_LDB(dst, b, h) do { _Pragma("unroll") for (int n = 0; n < 2; ++n) _Pragma("unroll") for (int k = 0; k < 2; ++k) dst[n][k] = *(const LAS bf16x8*)(lds + G_SB(b, h) + boff + n * 2048 + k * 1024); } while (0)
; #define G_WAIT_V(n) asm volatile("s_waitcnt vmcnt(" #n ")" ::: "memory")
; #define G_WAIT_L(n) asm volatile("s_waitcnt lgkmcnt(" #n ")" ::: "memory")
; #define G_BAR __builtin_amdgcn_s_barrier()
; #define G_SCHED __builtin_amdgcn_sched_barrier(0)
;     ...
;             G_BAR; G_WAIT_L(0); G_MMA(0, 1, At, B1); G_BAR;
;             G_LDA(At, 0, 1); G_STAGE(G_SA(0, 0), a2, cA0, qA);
;             G_BAR; G_WAIT_L(0); G_MMA(1, 0, At, B0); G_BAR; G_SCHED;
;             G_STAGE(G_SB(0, 1), b2 + chB, cB0, qB);
;             G_WAIT_V(6); G_BAR; G_MMA(1, 1, At, B1); G_BAR;
;             G_LDB(B0, 1, 0); G_SCHED; G_LDA(At, 1, 0); G_STAGE(G_SA(0, 1), a2 + chA, cA0, qA);
;             G_WAIT_L(8); G_BAR; G_WAIT_L(0); G_MMA(0, 0, At, B0); G_BAR; G_SCHED;
;             G_LDB(B1, 1, 1); G_STAGE(G_SB(1, 0), b3, cB0, qB);
;             G_BAR; G_WAIT_L(0); G_MMA(0, 1, At, B1); G_BAR;
;             G_LDA(At, 1, 1); G_STAGE(G_SA(1, 0), a3, cA0, qA);
;             G_BAR; G_WAIT_L(0); G_MMA(1, 0, At, B0); G_BAR; G_SCHED;
	s_waitcnt lgkmcnt(0)
	v_mfma_f32_16x16x32_bf16 v[132:135], v[206:209], v[152:155], v[132:135]
	v_mfma_f32_16x16x32_bf16 v[128:131], v[214:217], v[152:155], v[128:131]
	v_mfma_f32_16x16x32_bf16 v[108:111], v[206:209], v[160:163], v[108:111]
	v_mfma_f32_16x16x32_bf16 v[104:107], v[214:217], v[160:163], v[104:107]
	v_mfma_f32_16x16x32_bf16 v[92:95], v[206:209], v[176:179], v[92:95]
	v_mfma_f32_16x16x32_bf16 v[88:91], v[214:217], v[176:179], v[88:91]
	v_mfma_f32_16x16x32_bf16 v[76:79], v[206:209], v[198:201], v[76:79]
	v_mfma_f32_16x16x32_bf16 v[72:75], v[214:217], v[198:201], v[72:75]
	v_mfma_f32_16x16x32_bf16 v[132:135], v[210:213], v[156:159], v[132:135]
	v_mfma_f32_16x16x32_bf16 v[128:131], v[218:221], v[156:159], v[128:131]
	v_mfma_f32_16x16x32_bf16 v[108:111], v[210:213], v[172:175], v[108:111]
	v_mfma_f32_16x16x32_bf16 v[104:107], v[218:221], v[172:175], v[104:107]
	v_mfma_f32_16x16x32_bf16 v[92:95], v[210:213], v[180:183], v[92:95]
	v_mfma_f32_16x16x32_bf16 v[88:91], v[218:221], v[180:183], v[88:91]
	v_mfma_f32_16x16x32_bf16 v[76:79], v[210:213], v[202:205], v[76:79]
	v_mfma_f32_16x16x32_bf16 v[72:75], v[218:221], v[202:205], v[72:75]
	s_barrier
	s_mov_b32 m0, s24
	v_lshl_add_u64 v[222:223], s[4:5], 0, v[164:165]
	ds_read_b128 v[152:155], v197 offset:16384
	ds_read_b128 v[156:159], v197 offset:17408
	ds_read_b128 v[160:163], v197 offset:18432
	ds_read_b128 v[172:175], v197 offset:19456
	ds_read_b128 v[176:179], v197 offset:20480
	ds_read_b128 v[180:183], v197 offset:21504
	ds_read_b128 v[198:201], v197 offset:22528
	ds_read_b128 v[202:205], v197 offset:23552
	global_load_lds_dwordx4 v164, s[4:5]
	s_mov_b32 m0, s25
	s_nop 0
	s_add_u32 vcc_lo, s4, s70
	s_addc_u32 vcc_hi, s5, s71
	global_load_lds_dwordx4 v164, vcc
	s_barrier
	s_waitcnt lgkmcnt(0)
	v_mfma_f32_16x16x32_bf16 v[68:71], v[112:115], v[152:155], v[68:71]
	v_mfma_f32_16x16x32_bf16 v[64:67], v[136:139], v[152:155], v[64:67]
	v_mfma_f32_16x16x32_bf16 v[52:55], v[112:115], v[160:163], v[52:55]
	v_mfma_f32_16x16x32_bf16 v[48:51], v[136:139], v[160:163], v[48:51]
	v_mfma_f32_16x16x32_bf16 v[36:39], v[112:115], v[176:179], v[36:39]
	v_mfma_f32_16x16x32_bf16 v[32:35], v[136:139], v[176:179], v[32:35]
	v_mfma_f32_16x16x32_bf16 v[20:23], v[112:115], v[198:201], v[20:23]
	v_mfma_f32_16x16x32_bf16 v[16:19], v[136:139], v[198:201], v[16:19]
	v_mfma_f32_16x16x32_bf16 v[68:71], v[124:127], v[156:159], v[68:71]
	v_mfma_f32_16x16x32_bf16 v[64:67], v[148:151], v[156:159], v[64:67]
	v_mfma_f32_16x16x32_bf16 v[52:55], v[124:127], v[172:175], v[52:55]
	v_mfma_f32_16x16x32_bf16 v[48:51], v[148:151], v[172:175], v[48:51]
	v_mfma_f32_16x16x32_bf16 v[36:39], v[124:127], v[180:183], v[36:39]
	v_mfma_f32_16x16x32_bf16 v[32:35], v[148:151], v[180:183], v[32:35]
	v_mfma_f32_16x16x32_bf16 v[20:23], v[124:127], v[202:205], v[20:23]
	v_mfma_f32_16x16x32_bf16 v[16:19], v[148:151], v[202:205], v[16:19]
	s_barrier
	s_add_i32 s100, s38, s21
	s_mov_b32 m0, s100
	s_nop 0
	s_add_u32 vcc_lo, s36, s0
	s_addc_u32 vcc_hi, s37, s1
	global_load_lds_dwordx4 v2, vcc
	s_add_i32 m0, s100, 0x2000
	s_nop 0
	s_add_u32 vcc_lo, s36, s52
	s_addc_u32 vcc_hi, s37, s53
	global_load_lds_dwordx4 v2, vcc
	s_waitcnt vmcnt(6)
	s_barrier
	v_mfma_f32_16x16x32_bf16 v[60:63], v[206:209], v[152:155], v[60:63]
	v_mfma_f32_16x16x32_bf16 v[56:59], v[214:217], v[152:155], v[56:59]
	v_mfma_f32_16x16x32_bf16 v[44:47], v[206:209], v[160:163], v[44:47]
	v_mfma_f32_16x16x32_bf16 v[40:43], v[214:217], v[160:163], v[40:43]
	v_mfma_f32_16x16x32_bf16 v[28:31], v[206:209], v[176:179], v[28:31]
	v_mfma_f32_16x16x32_bf16 v[24:27], v[214:217], v[176:179], v[24:27]
	v_mfma_f32_16x16x32_bf16 v[12:15], v[206:209], v[198:201], v[12:15]
	v_mfma_f32_16x16x32_bf16 v[8:11], v[214:217], v[198:201], v[8:11]
	v_mfma_f32_16x16x32_bf16 v[60:63], v[210:213], v[156:159], v[60:63]
	v_mfma_f32_16x16x32_bf16 v[56:59], v[218:221], v[156:159], v[56:59]
	v_mfma_f32_16x16x32_bf16 v[44:47], v[210:213], v[172:175], v[44:47]
	v_mfma_f32_16x16x32_bf16 v[40:43], v[218:221], v[172:175], v[40:43]
	v_mfma_f32_16x16x32_bf16 v[28:31], v[210:213], v[180:183], v[28:31]
	v_mfma_f32_16x16x32_bf16 v[24:27], v[218:221], v[180:183], v[24:27]
	v_mfma_f32_16x16x32_bf16 v[12:15], v[210:213], v[202:205], v[12:15]
	v_mfma_f32_16x16x32_bf16 v[8:11], v[218:221], v[202:205], v[8:11]
	s_barrier
	s_add_i32 s100, 0, 0x18000
	ds_read_b128 v[112:115], v255 offset:32768
	ds_read_b128 v[124:127], v255 offset:33792
	ds_read_b128 v[136:139], v255 offset:34816
	ds_read_b128 v[148:151], v255 offset:35840
	s_mov_b32 m0, s26
	ds_read_b128 v[152:155], v197 offset:32768
	ds_read_b128 v[156:159], v197 offset:33792
	ds_read_b128 v[160:163], v197 offset:34816
	ds_read_b128 v[172:175], v197 offset:35840
	ds_read_b128 v[176:179], v197 offset:36864
	ds_read_b128 v[180:183], v197 offset:37888
	ds_read_b128 v[198:201], v197 offset:38912
	ds_read_b128 v[202:205], v197 offset:39936
	s_add_u32 vcc_lo, s4, s80
	s_addc_u32 vcc_hi, s5, s81
	global_load_lds_dwordx4 v164, vcc
	s_mov_b32 m0, s27
	s_nop 0
	s_add_u32 vcc_lo, s4, s82
	s_addc_u32 vcc_hi, s5, s83
	global_load_lds_dwordx4 v164, vcc
	s_waitcnt lgkmcnt(8)
	s_barrier
; #define G_STAGE(bufoff, gbase, o0, h64) do { \
;         __builtin_amdgcn_global_load_lds((const unsigned*)((const char*)(gbase) + (o0)), (LAS unsigned*)(lds + (bufoff) + ldsw), 16, 0, 0); \
;         __builtin_amdgcn_global_load_lds((const unsigned*)((const char*)(gbase) + (h64) + (o0)), (LAS unsigned*)(lds + (bufoff) + ldsw + 8192), 16, 0, 0); } while (0)
; #define G_LDA(dst, b, h) do { _Pragma("unroll") for (int m = 0; m < 4; ++m) _Pragma("unroll") for (int k = 0; k < 2; ++k) dst[m][k] = *(const LAS bf16x8*)(lds + G_SA(b, h) + aoff + m * 2048 + k * 1024); } while (0)
; #define G_LDB(dst, b, h) do { _Pragma("unroll") for (int n = 0; n < 2; ++n) _Pragma("unroll") for (int k = 0; k < 2; ++k) dst[n][k] = *(const LAS bf16x8*)(lds + G_SB(b, h) + boff + n * 2048 + k * 1024); } while (0)
; #define G_WAIT_V(n) asm volatile("s_waitcnt vmcnt(" #n ")" ::: "memory")
; #define G_WAIT_L(n) asm volatile("s_waitcnt lgkmcnt(" #n ")" ::: "memory")
; #define G_BAR __builtin_amdgcn_s_barrier()
; #define G_SCHED __builtin_amdgcn_sched_barrier(0)
;     ...
;             G_WAIT_L(8); G_BAR; G_WAIT_L(0); G_MMA(0, 0, At, B0); G_BAR; G_SCHED;
;             G_LDB(B1, 1, 1); G_STAGE(G_SB(1, 0), b3, cB0, qB);
;             G_BAR; G_WAIT_L(0); G_MMA(0, 1, At, B1); G_BAR;
;             G_LDA(At, 1, 1); G_STAGE(G_SA(1, 0), a3, cA0, qA);
;             G_BAR; G_WAIT_L(0); G_MMA(1, 0, At, B0); G_BAR; G_SCHED;
;             G_STAGE(G_SB(1, 1), b3 + chB, cB0, qB);
;             G_WAIT_V(6); G_BAR; G_MMA(1, 1, At, B1); G_BAR;
	s_waitcnt lgkmcnt(0)
	v_mfma_f32_16x16x32_bf16 v[144:147], v[112:115], v[152:155], v[144:147]
	v_mfma_f32_16x16x32_bf16 v[140:143], v[136:139], v[152:155], v[140:143]
	v_mfma_f32_16x16x32_bf16 v[120:123], v[112:115], v[160:163], v[120:123]
	v_mfma_f32_16x16x32_bf16 v[116:119], v[136:139], v[160:163], v[116:119]
	v_mfma_f32_16x16x32_bf16 v[100:103], v[112:115], v[176:179], v[100:103]
	v_mfma_f32_16x16x32_bf16 v[96:99], v[136:139], v[176:179], v[96:99]
	v_mfma_f32_16x16x32_bf16 v[84:87], v[112:115], v[198:201], v[84:87]
	v_mfma_f32_16x16x32_bf16 v[80:83], v[136:139], v[198:201], v[80:83]
	v_mfma_f32_16x16x32_bf16 v[144:147], v[124:127], v[156:159], v[144:147]
	v_mfma_f32_16x16x32_bf16 v[140:143], v[148:151], v[156:159], v[140:143]
	v_mfma_f32_16x16x32_bf16 v[120:123], v[124:127], v[172:175], v[120:123]
	v_mfma_f32_16x16x32_bf16 v[116:119], v[148:151], v[172:175], v[116:119]
	v_mfma_f32_16x16x32_bf16 v[100:103], v[124:127], v[180:183], v[100:103]
	v_mfma_f32_16x16x32_bf16 v[96:99], v[148:151], v[180:183], v[96:99]
	v_mfma_f32_16x16x32_bf16 v[84:87], v[124:127], v[202:205], v[84:87]
	v_mfma_f32_16x16x32_bf16 v[80:83], v[148:151], v[202:205], v[80:83]
	s_barrier
	s_add_i32 s5, 0, 0x1c000
	s_add_i32 s4, s100, s21
	s_mov_b32 m0, s4
	ds_read_b128 v[206:209], v255 offset:49152
	ds_read_b128 v[210:213], v255 offset:50176
	ds_read_b128 v[214:217], v255 offset:51200
	ds_read_b128 v[218:221], v255 offset:52224
	s_add_u32 vcc_lo, s36, s46
	s_addc_u32 vcc_hi, s37, s47
	global_load_lds_dwordx4 v2, vcc
	s_add_i32 m0, s4, 0x2000
	s_nop 0
	s_add_u32 vcc_lo, s36, s54
	s_addc_u32 vcc_hi, s37, s55
	global_load_lds_dwordx4 v2, vcc
	s_barrier
	s_waitcnt lgkmcnt(0)
	v_mfma_f32_16x16x32_bf16 v[132:135], v[206:209], v[152:155], v[132:135]
	v_mfma_f32_16x16x32_bf16 v[128:131], v[214:217], v[152:155], v[128:131]
	v_mfma_f32_16x16x32_bf16 v[108:111], v[206:209], v[160:163], v[108:111]
	v_mfma_f32_16x16x32_bf16 v[104:107], v[214:217], v[160:163], v[104:107]
	v_mfma_f32_16x16x32_bf16 v[92:95], v[206:209], v[176:179], v[92:95]
	v_mfma_f32_16x16x32_bf16 v[88:91], v[214:217], v[176:179], v[88:91]
	v_mfma_f32_16x16x32_bf16 v[76:79], v[206:209], v[198:201], v[76:79]
	v_mfma_f32_16x16x32_bf16 v[72:75], v[214:217], v[198:201], v[72:75]
	v_mfma_f32_16x16x32_bf16 v[132:135], v[210:213], v[156:159], v[132:135]
	v_mfma_f32_16x16x32_bf16 v[128:131], v[218:221], v[156:159], v[128:131]
	v_mfma_f32_16x16x32_bf16 v[108:111], v[210:213], v[172:175], v[108:111]
	v_mfma_f32_16x16x32_bf16 v[104:107], v[218:221], v[172:175], v[104:107]
	v_mfma_f32_16x16x32_bf16 v[92:95], v[210:213], v[180:183], v[92:95]
	v_mfma_f32_16x16x32_bf16 v[88:91], v[218:221], v[180:183], v[88:91]
	v_mfma_f32_16x16x32_bf16 v[76:79], v[210:213], v[202:205], v[76:79]
	v_mfma_f32_16x16x32_bf16 v[72:75], v[218:221], v[202:205], v[72:75]
	s_barrier
	s_mov_b32 m0, s29
	v_lshl_add_u64 v[224:225], v[222:223], 0, s[62:63]
	ds_read_b128 v[152:155], v197 offset:49152
	ds_read_b128 v[156:159], v197 offset:50176
	ds_read_b128 v[160:163], v197 offset:51200
	ds_read_b128 v[172:175], v197 offset:52224
	ds_read_b128 v[176:179], v197 offset:53248
	ds_read_b128 v[180:183], v197 offset:54272
	ds_read_b128 v[198:201], v197 offset:55296
	ds_read_b128 v[202:205], v197 offset:56320
	global_load_lds_dwordx4 v[224:225], off
	v_lshl_add_u64 v[222:223], v[222:223], 0, s[84:85]
	s_mov_b32 m0, s30
	s_nop 0
	global_load_lds_dwordx4 v[222:223], off
	s_barrier
	s_waitcnt lgkmcnt(0)
	v_mfma_f32_16x16x32_bf16 v[68:71], v[112:115], v[152:155], v[68:71]
	v_mfma_f32_16x16x32_bf16 v[64:67], v[136:139], v[152:155], v[64:67]
	v_mfma_f32_16x16x32_bf16 v[52:55], v[112:115], v[160:163], v[52:55]
	v_mfma_f32_16x16x32_bf16 v[48:51], v[136:139], v[160:163], v[48:51]
	v_mfma_f32_16x16x32_bf16 v[36:39], v[112:115], v[176:179], v[36:39]
	v_mfma_f32_16x16x32_bf16 v[32:35], v[136:139], v[176:179], v[32:35]
	v_mfma_f32_16x16x32_bf16 v[20:23], v[112:115], v[198:201], v[20:23]
	v_mfma_f32_16x16x32_bf16 v[16:19], v[136:139], v[198:201], v[16:19]
	v_mfma_f32_16x16x32_bf16 v[68:71], v[124:127], v[156:159], v[68:71]
	v_mfma_f32_16x16x32_bf16 v[64:67], v[148:151], v[156:159], v[64:67]
	v_mfma_f32_16x16x32_bf16 v[52:55], v[124:127], v[172:175], v[52:55]
	v_mfma_f32_16x16x32_bf16 v[48:51], v[148:151], v[172:175], v[48:51]
	v_mfma_f32_16x16x32_bf16 v[36:39], v[124:127], v[180:183], v[36:39]
	v_mfma_f32_16x16x32_bf16 v[32:35], v[148:151], v[180:183], v[32:35]
	v_mfma_f32_16x16x32_bf16 v[20:23], v[124:127], v[202:205], v[20:23]
	v_mfma_f32_16x16x32_bf16 v[16:19], v[148:151], v[202:205], v[16:19]
	s_barrier
	s_add_i32 s4, s5, s21
	s_mov_b32 m0, s4
	s_nop 0
	s_add_u32 vcc_lo, s36, s42
	s_addc_u32 vcc_hi, s37, s43
	global_load_lds_dwordx4 v2, vcc
	s_add_i32 m0, s4, 0x2000
	s_nop 0
	s_add_u32 vcc_lo, s36, s58
	s_addc_u32 vcc_hi, s37, s59
	global_load_lds_dwordx4 v2, vcc
	s_add_i32 s19, s19, 2
	s_add_u32 s13, s13, 0x100
	s_addc_u32 s18, s18, 0
	s_add_u32 s2, s2, 0x800000
	s_addc_u32 s3, s3, 0
	s_cmp_gt_u32 s19, 5
	s_waitcnt vmcnt(6)
	s_barrier
	v_mfma_f32_16x16x32_bf16 v[60:63], v[206:209], v[152:155], v[60:63]
	v_mfma_f32_16x16x32_bf16 v[56:59], v[214:217], v[152:155], v[56:59]
	v_mfma_f32_16x16x32_bf16 v[44:47], v[206:209], v[160:163], v[44:47]
	v_mfma_f32_16x16x32_bf16 v[40:43], v[214:217], v[160:163], v[40:43]
	v_mfma_f32_16x16x32_bf16 v[28:31], v[206:209], v[176:179], v[28:31]
	v_mfma_f32_16x16x32_bf16 v[24:27], v[214:217], v[176:179], v[24:27]
	v_mfma_f32_16x16x32_bf16 v[12:15], v[206:209], v[198:201], v[12:15]
	v_mfma_f32_16x16x32_bf16 v[8:11], v[214:217], v[198:201], v[8:11]
	v_mfma_f32_16x16x32_bf16 v[60:63], v[210:213], v[156:159], v[60:63]
	v_mfma_f32_16x16x32_bf16 v[56:59], v[218:221], v[156:159], v[56:59]
	v_mfma_f32_16x16x32_bf16 v[44:47], v[210:213], v[172:175], v[44:47]
	v_mfma_f32_16x16x32_bf16 v[40:43], v[218:221], v[172:175], v[40:43]
	v_mfma_f32_16x16x32_bf16 v[28:31], v[210:213], v[180:183], v[28:31]
	v_mfma_f32_16x16x32_bf16 v[24:27], v[218:221], v[180:183], v[24:27]
	v_mfma_f32_16x16x32_bf16 v[12:15], v[210:213], v[202:205], v[12:15]
	v_mfma_f32_16x16x32_bf16 v[8:11], v[218:221], v[202:205], v[8:11]
	s_cbranch_scc0 .Ldb_GLU_cont

; #define G_STAGE(bufoff, gbase, o0, h64) do { \
;         __builtin_amdgcn_global_load_lds((const unsigned*)((const char*)(gbase) + (o0)), (LAS unsigned*)(lds + (bufoff) + ldsw), 16, 0, 0); \
;         __builtin_amdgcn_global_load_lds((const unsigned*)((const char*)(gbase) + (h64) + (o0)), (LAS unsigned*)(lds + (bufoff) + ldsw + 8192), 16, 0, 0); } while (0)
; #define G_LDA(dst, b, h) do { _Pragma("unroll") for (int m = 0; m < 4; ++m) _Pragma("unroll") for (int k = 0; k < 2; ++k) dst[m][k] = *(const LAS bf16x8*)(lds + G_SA(b, h) + aoff + m * 2048 + k * 1024); } while (0)
; #define G_LDB(dst, b, h) do { _Pragma("unroll") for (int n = 0; n < 2; ++n) _Pragma("unroll") for (int k = 0; k < 2; ++k) dst[n][k] = *(const LAS bf16x8*)(lds + G_SB(b, h) + boff + n * 2048 + k * 1024); } while (0)
; #define G_WAIT_V(n) asm volatile("s_waitcnt vmcnt(" #n ")" ::: "memory")
; #define G_WAIT_L(n) asm volatile("s_waitcnt lgkmcnt(" #n ")" ::: "memory")
;     ...
;         for (int t = 0; t < nt; t += 2) {
;             const bool last = (t == nt - 2);
;             const char* a1 = cA + (size_t)(t + 1) * ckA;
;             const char* a2 = last ? nA : cA + (size_t)(t + 2) * ckA; const char* b2 = last ? nB : cB + (size_t)(t + 2) * kB;
;             const char* a3 = a2 + ckA; const char* b3 = b2 + kB;
;             G_LDB(B0, 0, 0); G_SCHED; G_LDA(At, 0, 0); G_STAGE(G_SA(1, 1), a1 + chA, cA0, qA);
;             G_WAIT_L(8); G_BAR; G_WAIT_L(0); G_MMA(0, 0, At, B0); G_BAR; G_SCHED;
;             G_LDB(B1, 0, 1); G_STAGE(G_SB(0, 0), b2, cB0, qB);
;             G_BAR; G_WAIT_L(0); G_MMA(0, 1, At, B1); G_BAR;
;             G_LDA(At, 0, 1); G_STAGE(G_SA(0, 0), a2, cA0, qA);
;             G_BAR; G_WAIT_L(0); G_MMA(1, 0, At, B0); G_BAR; G_SCHED;
;             G_STAGE(G_SB(0, 1), b2 + chB, cB0, qB);
;             G_WAIT_V(6); G_BAR; G_MMA(1, 1, At, B1); G_BAR;
;             G_LDB(B0, 1, 0); G_SCHED; G_LDA(At, 1, 0); G_STAGE(G_SA(0, 1), a2 + chA, cA0, qA);
;             G_WAIT_L(8); G_BAR; G_WAIT_L(0); G_MMA(0, 0, At, B0); G_BAR; G_SCHED;
;     ...
;         if (!(cs.kind == K_MG_B && cur.aux < 2))
; #pragma unroll
;         for (int a = 0; a < 2; ++a)
; #pragma unroll
;             for (int b = 0; b < 2; ++b)
; #pragma unroll
;                 for (int m = 0; m < 4; ++m)
; #pragma unroll
;                     for (int n = 0; n < 2; ++n) acc[a][b][m][n] = (f32x4){0.f, 0.f, 0.f, 0.f};
.LBB0_871:
	s_add_u32 s2, s2, 0xb0080
	s_addc_u32 s3, s3, 0
	s_add_u32 s37, s12, 0x100
	s_addc_u32 s38, s13, 0
	s_mov_b32 s39, -2
	s_mov_b64 s[42:43], 0x20080
	s_mov_b64 s[50:51], 0x10000
	s_mov_b64 s[52:53], 0x30000
	s_mov_b64 s[54:55], 0x10080
	s_mov_b64 s[58:59], 0x30080
	s_cmp_eq_u32 s101, 2
	s_cselect_b32 s101, 0, s101
	v_add_u32_e32 v239, 0x10000, v159
	s_add_u32 s4, s2, 0xfff50080
	s_addc_u32 s5, s3, -1
	s_add_i32 s40, 0, 0x10000
	ds_read_b128 v[144:147], v239 offset:0
	ds_read_b128 v[148:151], v239 offset:1024
	ds_read_b128 v[136:139], v239 offset:2048
	ds_read_b128 v[140:143], v239 offset:3072
	s_cmp_eq_u32 s39, 4
	s_cselect_b32 s13, s9, s5
	s_cselect_b32 s12, s8, s4
	s_cselect_b32 s15, s11, s38
	s_cselect_b32 s14, s10, s37
	s_add_i32 m0, s22, 0xc000
	ds_read_b128 v[160:163], v236
	ds_read_b128 v[164:167], v236 offset:1024
	ds_read_b128 v[176:179], v236 offset:2048
	ds_read_b128 v[180:183], v236 offset:3072
	ds_read_b128 v[196:199], v236 offset:4096
	ds_read_b128 v[200:203], v236 offset:5120
	ds_read_b128 v[204:207], v236 offset:6144
	ds_read_b128 v[208:211], v236 offset:7168
	global_load_lds_dwordx4 v152, s[2:3]
	s_add_i32 m0, s22, 0xe000
	s_nop 0
	s_add_u32 vcc_lo, s2, s86
	s_addc_u32 vcc_hi, s3, s87
	global_load_lds_dwordx4 v152, vcc
	s_waitcnt lgkmcnt(8)
	s_cmp_eq_u32 s101, 1
	s_cbranch_scc1 .Ldb_MG0_skp
	s_barrier
.Ldb_MG0_skp:
	s_mov_b32 s101, 0
	s_waitcnt lgkmcnt(0)
	v_mfma_f32_16x16x128_f8f6f4 v[128:131], v[144:151], v[160:167], 0
	v_mfma_f32_16x16x128_f8f6f4 v[132:135], v[136:143], v[160:167], 0
	v_mfma_f32_16x16x128_f8f6f4 v[112:115], v[144:151], v[176:183], 0
	v_mfma_f32_16x16x128_f8f6f4 v[116:119], v[136:143], v[176:183], 0
	v_mfma_f32_16x16x128_f8f6f4 v[96:99], v[144:151], v[196:203], 0
	v_mfma_f32_16x16x128_f8f6f4 v[100:103], v[136:143], v[196:203], 0
	v_mfma_f32_16x16x128_f8f6f4 v[80:83], v[144:151], v[204:211], 0
	v_mfma_f32_16x16x128_f8f6f4 v[84:87], v[136:143], v[204:211], 0
	s_barrier
	s_add_i32 s4, 0, 0x14000
	s_add_i32 s5, s40, s17
	ds_read_b128 v[212:215], v239 offset:16384
	ds_read_b128 v[216:219], v239 offset:17408
	ds_read_b128 v[220:223], v239 offset:18432
	ds_read_b128 v[224:227], v239 offset:19456
	s_mov_b32 m0, s5
	global_load_lds_dwordx4 v0, s[14:15]
	s_add_i32 m0, s5, 0x2000
	s_nop 0
	s_add_u32 vcc_lo, s14, s50
	s_addc_u32 vcc_hi, s15, s51
	global_load_lds_dwordx4 v0, vcc
	s_barrier
	s_waitcnt lgkmcnt(0)
	v_mfma_f32_16x16x128_f8f6f4 v[124:127], v[212:219], v[160:167], 0
	v_mfma_f32_16x16x128_f8f6f4 v[120:123], v[220:227], v[160:167], 0
	v_mfma_f32_16x16x128_f8f6f4 v[108:111], v[212:219], v[176:183], 0
	v_mfma_f32_16x16x128_f8f6f4 v[104:107], v[220:227], v[176:183], 0
	v_mfma_f32_16x16x128_f8f6f4 v[92:95], v[212:219], v[196:203], 0
	v_mfma_f32_16x16x128_f8f6f4 v[88:91], v[220:227], v[196:203], 0
	v_mfma_f32_16x16x128_f8f6f4 v[76:79], v[212:219], v[204:211], 0
	v_mfma_f32_16x16x128_f8f6f4 v[72:75], v[220:227], v[204:211], 0
	s_barrier
	s_mov_b32 m0, s22
	ds_read_b128 v[160:163], v236 offset:16384
	ds_read_b128 v[164:167], v236 offset:17408
	ds_read_b128 v[176:179], v236 offset:18432
	ds_read_b128 v[180:183], v236 offset:19456
	ds_read_b128 v[196:199], v236 offset:20480
	ds_read_b128 v[200:203], v236 offset:21504
	ds_read_b128 v[204:207], v236 offset:22528
	ds_read_b128 v[208:211], v236 offset:23552
	global_load_lds_dwordx4 v2, s[12:13]
	s_mov_b32 m0, s23
	s_nop 0
	s_add_u32 vcc_lo, s12, s86
	s_addc_u32 vcc_hi, s13, s87
	global_load_lds_dwordx4 v2, vcc
	s_barrier
	s_waitcnt lgkmcnt(0)
	v_mfma_f32_16x16x128_f8f6f4 v[64:67], v[144:151], v[160:167], 0
	v_mfma_f32_16x16x128_f8f6f4 v[68:71], v[136:143], v[160:167], 0
	v_mfma_f32_16x16x128_f8f6f4 v[48:51], v[144:151], v[176:183], 0
	v_mfma_f32_16x16x128_f8f6f4 v[52:55], v[136:143], v[176:183], 0
	v_mfma_f32_16x16x128_f8f6f4 v[32:35], v[144:151], v[196:203], 0
	v_mfma_f32_16x16x128_f8f6f4 v[36:39], v[136:143], v[196:203], 0
	v_mfma_f32_16x16x128_f8f6f4 v[20:23], v[144:151], v[204:211], 0
	v_mfma_f32_16x16x128_f8f6f4 v[16:19], v[136:143], v[204:211], 0
	s_barrier
	s_add_i32 s4, s4, s17
	s_mov_b32 m0, s4
	s_nop 0
	s_add_u32 vcc_lo, s14, s0
	s_addc_u32 vcc_hi, s15, s1
	global_load_lds_dwordx4 v0, vcc
	s_add_i32 m0, s4, 0x2000
	s_nop 0
	s_add_u32 vcc_lo, s14, s52
	s_addc_u32 vcc_hi, s15, s53
	global_load_lds_dwordx4 v0, vcc
	s_waitcnt vmcnt(6)
	s_barrier
	v_mfma_f32_16x16x128_f8f6f4 v[60:63], v[212:219], v[160:167], 0
	v_mfma_f32_16x16x128_f8f6f4 v[56:59], v[220:227], v[160:167], 0
	v_mfma_f32_16x16x128_f8f6f4 v[44:47], v[212:219], v[176:183], 0
	v_mfma_f32_16x16x128_f8f6f4 v[40:43], v[220:227], v[176:183], 0
	v_mfma_f32_16x16x128_f8f6f4 v[28:31], v[212:219], v[196:203], 0
	v_mfma_f32_16x16x128_f8f6f4 v[24:27], v[220:227], v[196:203], 0
	v_mfma_f32_16x16x128_f8f6f4 v[12:15], v[212:219], v[204:211], 0
	v_mfma_f32_16x16x128_f8f6f4 v[8:11], v[220:227], v[204:211], 0
	s_barrier
	s_add_i32 s4, 0, 0x18000
	ds_read_b128 v[144:147], v239 offset:32768
	ds_read_b128 v[148:151], v239 offset:33792
	ds_read_b128 v[136:139], v239 offset:34816
	ds_read_b128 v[140:143], v239 offset:35840
	s_mov_b32 m0, s24
	ds_read_b128 v[160:163], v236 offset:32768
	ds_read_b128 v[164:167], v236 offset:33792
	ds_read_b128 v[176:179], v236 offset:34816
	ds_read_b128 v[180:183], v236 offset:35840
	ds_read_b128 v[196:199], v236 offset:36864
	ds_read_b128 v[200:203], v236 offset:37888
	ds_read_b128 v[204:207], v236 offset:38912
	ds_read_b128 v[208:211], v236 offset:39936
	s_add_u32 vcc_lo, s12, s88
	s_addc_u32 vcc_hi, s13, s89
	global_load_lds_dwordx4 v2, vcc
	s_mov_b32 m0, s25
	s_nop 0
	s_add_u32 vcc_lo, s12, s64
	s_addc_u32 vcc_hi, s13, s65
	global_load_lds_dwordx4 v2, vcc
	s_waitcnt lgkmcnt(8)
	s_barrier
; #define G_STAGE(bufoff, gbase, o0, h64) do { \
;         __builtin_amdgcn_global_load_lds((const unsigned*)((const char*)(gbase) + (o0)), (LAS unsigned*)(lds + (bufoff) + ldsw), 16, 0, 0); \
;         __builtin_amdgcn_global_load_lds((const unsigned*)((const char*)(gbase) + (h64) + (o0)), (LAS unsigned*)(lds + (bufoff) + ldsw + 8192), 16, 0, 0); } while (0)
; #define G_LDA(dst, b, h) do { _Pragma("unroll") for (int m = 0; m < 4; ++m) _Pragma("unroll") for (int k = 0; k < 2; ++k) dst[m][k] = *(const LAS bf16x8*)(lds + G_SA(b, h) + aoff + m * 2048 + k * 1024); } while (0)
; #define G_LDB(dst, b, h) do { _Pragma("unroll") for (int n = 0; n < 2; ++n) _Pragma("unroll") for (int k = 0; k < 2; ++k) dst[n][k] = *(const LAS bf16x8*)(lds + G_SB(b, h) + boff + n * 2048 + k * 1024); } while (0)
; #define G_WAIT_V(n) asm volatile("s_waitcnt vmcnt(" #n ")" ::: "memory")
; #define G_BAR __builtin_amdgcn_s_barrier()
;     ...
;         for (int t = 0; t < nt; t += 2) {
;             const bool last = (t == nt - 2);
;             const char* a1 = cA + (size_t)(t + 1) * ckA;
;             const char* a2 = last ? nA : cA + (size_t)(t + 2) * ckA; const char* b2 = last ? nB : cB + (size_t)(t + 2) * kB;
;             const char* a3 = a2 + ckA; const char* b3 = b2 + kB;
;             G_LDB(B0, 0, 0); G_SCHED; G_LDA(At, 0, 0); G_STAGE(G_SA(1, 1), a1 + chA, cA0, qA);
;             G_WAIT_L(8); G_BAR; G_WAIT_L(0); G_MMA(0, 0, At, B0); G_BAR; G_SCHED;
;             G_LDB(B1, 0, 1); G_STAGE(G_SB(0, 0), b2, cB0, qB);
;             G_BAR; G_WAIT_L(0); G_MMA(0, 1, At, B1); G_BAR;
;             G_LDA(At, 0, 1); G_STAGE(G_SA(0, 0), a2, cA0, qA);
;             G_BAR; G_WAIT_L(0); G_MMA(1, 0, At, B0); G_BAR; G_SCHED;
;             G_STAGE(G_SB(0, 1), b2 + chB, cB0, qB);
;             G_WAIT_V(6); G_BAR; G_MMA(1, 1, At, B1); G_BAR;
;             G_LDB(B0, 1, 0); G_SCHED; G_LDA(At, 1, 0); G_STAGE(G_SA(0, 1), a2 + chA, cA0, qA);
;             G_WAIT_L(8); G_BAR; G_WAIT_L(0); G_MMA(0, 0, At, B0); G_BAR; G_SCHED;
;             G_LDB(B1, 1, 1); G_STAGE(G_SB(1, 0), b3, cB0, qB);
;             G_BAR; G_WAIT_L(0); G_MMA(0, 1, At, B1); G_BAR;
;             G_LDA(At, 1, 1); G_STAGE(G_SA(1, 0), a3, cA0, qA);
;             G_BAR; G_WAIT_L(0); G_MMA(1, 0, At, B0); G_BAR; G_SCHED;
;             G_STAGE(G_SB(1, 1), b3 + chB, cB0, qB);
;             G_WAIT_V(6); G_BAR; G_MMA(1, 1, At, B1); G_BAR;
	s_waitcnt lgkmcnt(0)
	v_mfma_f32_16x16x128_f8f6f4 v[128:131], v[144:151], v[160:167], v[128:131]
	v_mfma_f32_16x16x128_f8f6f4 v[132:135], v[136:143], v[160:167], v[132:135]
	v_mfma_f32_16x16x128_f8f6f4 v[112:115], v[144:151], v[176:183], v[112:115]
	v_mfma_f32_16x16x128_f8f6f4 v[116:119], v[136:143], v[176:183], v[116:119]
	v_mfma_f32_16x16x128_f8f6f4 v[96:99], v[144:151], v[196:203], v[96:99]
	v_mfma_f32_16x16x128_f8f6f4 v[100:103], v[136:143], v[196:203], v[100:103]
	v_mfma_f32_16x16x128_f8f6f4 v[80:83], v[144:151], v[204:211], v[80:83]
	v_mfma_f32_16x16x128_f8f6f4 v[84:87], v[136:143], v[204:211], v[84:87]
	s_barrier
	s_add_i32 s5, 0, 0x1c000
	s_add_i32 s4, s4, s17
	s_mov_b32 m0, s4
	ds_read_b128 v[212:215], v239 offset:49152
	ds_read_b128 v[216:219], v239 offset:50176
	ds_read_b128 v[220:223], v239 offset:51200
	ds_read_b128 v[224:227], v239 offset:52224
	s_add_u32 vcc_lo, s14, s46
	s_addc_u32 vcc_hi, s15, s47
	global_load_lds_dwordx4 v0, vcc
	s_add_i32 m0, s4, 0x2000
	s_nop 0
	s_add_u32 vcc_lo, s14, s54
	s_addc_u32 vcc_hi, s15, s55
	global_load_lds_dwordx4 v0, vcc
	s_barrier
	s_waitcnt lgkmcnt(0)
	v_mfma_f32_16x16x128_f8f6f4 v[124:127], v[212:219], v[160:167], v[124:127]
	v_mfma_f32_16x16x128_f8f6f4 v[120:123], v[220:227], v[160:167], v[120:123]
	v_mfma_f32_16x16x128_f8f6f4 v[108:111], v[212:219], v[176:183], v[108:111]
	v_mfma_f32_16x16x128_f8f6f4 v[104:107], v[220:227], v[176:183], v[104:107]
	v_mfma_f32_16x16x128_f8f6f4 v[92:95], v[212:219], v[196:203], v[92:95]
	v_mfma_f32_16x16x128_f8f6f4 v[88:91], v[220:227], v[196:203], v[88:91]
	v_mfma_f32_16x16x128_f8f6f4 v[76:79], v[212:219], v[204:211], v[76:79]
	v_mfma_f32_16x16x128_f8f6f4 v[72:75], v[220:227], v[204:211], v[72:75]
	s_barrier
	s_mov_b32 m0, s26
	ds_read_b128 v[160:163], v236 offset:49152
	ds_read_b128 v[164:167], v236 offset:50176
	ds_read_b128 v[176:179], v236 offset:51200
	ds_read_b128 v[180:183], v236 offset:52224
	ds_read_b128 v[196:199], v236 offset:53248
	ds_read_b128 v[200:203], v236 offset:54272
	ds_read_b128 v[204:207], v236 offset:55296
	ds_read_b128 v[208:211], v236 offset:56320
	s_add_u32 vcc_lo, s12, s46
	s_addc_u32 vcc_hi, s13, s47
	global_load_lds_dwordx4 v2, vcc
	s_mov_b32 m0, s27
	s_nop 0
	s_add_u32 vcc_lo, s12, s66
	s_addc_u32 vcc_hi, s13, s67
	global_load_lds_dwordx4 v2, vcc
	s_barrier
	s_waitcnt lgkmcnt(0)
	v_mfma_f32_16x16x128_f8f6f4 v[64:67], v[144:151], v[160:167], v[64:67]
	v_mfma_f32_16x16x128_f8f6f4 v[68:71], v[136:143], v[160:167], v[68:71]
	v_mfma_f32_16x16x128_f8f6f4 v[48:51], v[144:151], v[176:183], v[48:51]
	v_mfma_f32_16x16x128_f8f6f4 v[52:55], v[136:143], v[176:183], v[52:55]
	v_mfma_f32_16x16x128_f8f6f4 v[32:35], v[144:151], v[196:203], v[32:35]
	v_mfma_f32_16x16x128_f8f6f4 v[36:39], v[136:143], v[196:203], v[36:39]
	v_mfma_f32_16x16x128_f8f6f4 v[20:23], v[144:151], v[204:211], v[20:23]
	v_mfma_f32_16x16x128_f8f6f4 v[16:19], v[136:143], v[204:211], v[16:19]
	s_barrier
	s_add_i32 s4, s5, s17
	s_mov_b32 m0, s4
	s_nop 0
	s_add_u32 vcc_lo, s14, s42
	s_addc_u32 vcc_hi, s15, s43
	global_load_lds_dwordx4 v0, vcc
	s_add_i32 m0, s4, 0x2000
	s_nop 0
	s_add_u32 vcc_lo, s14, s58
	s_addc_u32 vcc_hi, s15, s59
	global_load_lds_dwordx4 v0, vcc
	s_add_i32 s39, s39, 2
	s_add_u32 s2, s2, 0x100
	s_addc_u32 s3, s3, 0
	s_add_u32 s37, s37, 0x100
	s_addc_u32 s38, s38, 0
	s_cmp_gt_u32 s39, 5
	s_waitcnt vmcnt(6)
	s_barrier
	v_mfma_f32_16x16x128_f8f6f4 v[60:63], v[212:219], v[160:167], v[60:63]
	v_mfma_f32_16x16x128_f8f6f4 v[56:59], v[220:227], v[160:167], v[56:59]
	v_mfma_f32_16x16x128_f8f6f4 v[44:47], v[212:219], v[176:183], v[44:47]
	v_mfma_f32_16x16x128_f8f6f4 v[40:43], v[220:227], v[176:183], v[40:43]
	v_mfma_f32_16x16x128_f8f6f4 v[28:31], v[212:219], v[196:203], v[28:31]
	v_mfma_f32_16x16x128_f8f6f4 v[24:27], v[220:227], v[196:203], v[24:27]
	v_mfma_f32_16x16x128_f8f6f4 v[12:15], v[212:219], v[204:211], v[12:15]
	v_mfma_f32_16x16x128_f8f6f4 v[8:11], v[220:227], v[204:211], v[8:11]
	s_cbranch_scc0 .Ldb_MG0_cont
	s_branch .Ldb_MG0_xl
.LBB0_872:
	s_add_u32 s4, s2, 0xfff50080
	s_addc_u32 s5, s3, -1
	s_add_i32 s40, 0, 0x10000
	ds_read_b128 v[144:147], v239 offset:0
	ds_read_b128 v[148:151], v239 offset:1024
	ds_read_b128 v[136:139], v239 offset:2048
	ds_read_b128 v[140:143], v239 offset:3072
	s_cmp_eq_u32 s39, 4
	s_cselect_b32 s13, s9, s5
	s_cselect_b32 s12, s8, s4
	s_cselect_b32 s15, s11, s38
	s_cselect_b32 s14, s10, s37
	s_add_i32 m0, s22, 0xc000
	ds_read_b128 v[160:163], v236
	ds_read_b128 v[164:167], v236 offset:1024
	ds_read_b128 v[176:179], v236 offset:2048
	ds_read_b128 v[180:183], v236 offset:3072
	ds_read_b128 v[196:199], v236 offset:4096
	ds_read_b128 v[200:203], v236 offset:5120
	ds_read_b128 v[204:207], v236 offset:6144
	ds_read_b128 v[208:211], v236 offset:7168
	global_load_lds_dwordx4 v152, s[2:3]
	s_add_i32 m0, s22, 0xe000
	s_nop 0
	s_add_u32 vcc_lo, s2, s86
	s_addc_u32 vcc_hi, s3, s87
	global_load_lds_dwordx4 v152, vcc
	s_waitcnt lgkmcnt(8)
	s_barrier
	s_waitcnt lgkmcnt(0)
	v_mfma_f32_16x16x128_f8f6f4 v[128:131], v[144:151], v[160:167], v[128:131]
	v_mfma_f32_16x16x128_f8f6f4 v[132:135], v[136:143], v[160:167], v[132:135]
	v_mfma_f32_16x16x128_f8f6f4 v[112:115], v[144:151], v[176:183], v[112:115]
	v_mfma_f32_16x16x128_f8f6f4 v[116:119], v[136:143], v[176:183], v[116:119]
	v_mfma_f32_16x16x128_f8f6f4 v[96:99], v[144:151], v[196:203], v[96:99]
	v_mfma_f32_16x16x128_f8f6f4 v[100:103], v[136:143], v[196:203], v[100:103]
	v_mfma_f32_16x16x128_f8f6f4 v[80:83], v[144:151], v[204:211], v[80:83]
	v_mfma_f32_16x16x128_f8f6f4 v[84:87], v[136:143], v[204:211], v[84:87]
	s_barrier
; #define G_STAGE(bufoff, gbase, o0, h64) do { \
;         __builtin_amdgcn_global_load_lds((const unsigned*)((const char*)(gbase) + (o0)), (LAS unsigned*)(lds + (bufoff) + ldsw), 16, 0, 0); \
;         __builtin_amdgcn_global_load_lds((const unsigned*)((const char*)(gbase) + (h64) + (o0)), (LAS unsigned*)(lds + (bufoff) + ldsw + 8192), 16, 0, 0); } while (0)
; #define G_LDA(dst, b, h) do { _Pragma("unroll") for (int m = 0; m < 4; ++m) _Pragma("unroll") for (int k = 0; k < 2; ++k) dst[m][k] = *(const LAS bf16x8*)(lds + G_SA(b, h) + aoff + m * 2048 + k * 1024); } while (0)
; #define G_LDB(dst, b, h) do { _Pragma("unroll") for (int n = 0; n < 2; ++n) _Pragma("unroll") for (int k = 0; k < 2; ++k) dst[n][k] = *(const LAS bf16x8*)(lds + G_SB(b, h) + boff + n * 2048 + k * 1024); } while (0)
; #define G_WAIT_V(n) asm volatile("s_waitcnt vmcnt(" #n ")" ::: "memory")
; #define G_WAIT_L(n) asm volatile("s_waitcnt lgkmcnt(" #n ")" ::: "memory")
; #define G_BAR __builtin_amdgcn_s_barrier()
; #define G_SCHED __builtin_amdgcn_sched_barrier(0)
;     ...
;             G_LDB(B1, 0, 1); G_STAGE(G_SB(0, 0), b2, cB0, qB);
;             G_BAR; G_WAIT_L(0); G_MMA(0, 1, At, B1); G_BAR;
;             G_LDA(At, 0, 1); G_STAGE(G_SA(0, 0), a2, cA0, qA);
;             G_BAR; G_WAIT_L(0); G_MMA(1, 0, At, B0); G_BAR; G_SCHED;
;             G_STAGE(G_SB(0, 1), b2 + chB, cB0, qB);
;             G_WAIT_V(6); G_BAR; G_MMA(1, 1, At, B1); G_BAR;
;             G_LDB(B0, 1, 0); G_SCHED; G_LDA(At, 1, 0); G_STAGE(G_SA(0, 1), a2 + chA, cA0, qA);
;             G_WAIT_L(8); G_BAR; G_WAIT_L(0); G_MMA(0, 0, At, B0); G_BAR; G_SCHED;
	s_add_i32 s4, 0, 0x14000
	s_add_i32 s5, s40, s17
	ds_read_b128 v[212:215], v239 offset:16384
	ds_read_b128 v[216:219], v239 offset:17408
	ds_read_b128 v[220:223], v239 offset:18432
	ds_read_b128 v[224:227], v239 offset:19456
	s_mov_b32 m0, s5
	global_load_lds_dwordx4 v0, s[14:15]
	s_add_i32 m0, s5, 0x2000
	s_nop 0
	s_add_u32 vcc_lo, s14, s50
	s_addc_u32 vcc_hi, s15, s51
	global_load_lds_dwordx4 v0, vcc
	s_barrier
	s_waitcnt lgkmcnt(0)
	v_mfma_f32_16x16x128_f8f6f4 v[124:127], v[212:219], v[160:167], v[124:127]
	v_mfma_f32_16x16x128_f8f6f4 v[120:123], v[220:227], v[160:167], v[120:123]
	v_mfma_f32_16x16x128_f8f6f4 v[108:111], v[212:219], v[176:183], v[108:111]
	v_mfma_f32_16x16x128_f8f6f4 v[104:107], v[220:227], v[176:183], v[104:107]
	v_mfma_f32_16x16x128_f8f6f4 v[92:95], v[212:219], v[196:203], v[92:95]
	v_mfma_f32_16x16x128_f8f6f4 v[88:91], v[220:227], v[196:203], v[88:91]
	v_mfma_f32_16x16x128_f8f6f4 v[76:79], v[212:219], v[204:211], v[76:79]
	v_mfma_f32_16x16x128_f8f6f4 v[72:75], v[220:227], v[204:211], v[72:75]
	s_barrier
	s_mov_b32 m0, s22
	ds_read_b128 v[160:163], v236 offset:16384
	ds_read_b128 v[164:167], v236 offset:17408
	ds_read_b128 v[176:179], v236 offset:18432
	ds_read_b128 v[180:183], v236 offset:19456
	ds_read_b128 v[196:199], v236 offset:20480
	ds_read_b128 v[200:203], v236 offset:21504
	ds_read_b128 v[204:207], v236 offset:22528
	ds_read_b128 v[208:211], v236 offset:23552
	global_load_lds_dwordx4 v2, s[12:13]
	s_mov_b32 m0, s23
	s_nop 0
	s_add_u32 vcc_lo, s12, s86
	s_addc_u32 vcc_hi, s13, s87
	global_load_lds_dwordx4 v2, vcc
	s_barrier
	s_waitcnt lgkmcnt(0)
	v_mfma_f32_16x16x128_f8f6f4 v[64:67], v[144:151], v[160:167], v[64:67]
	v_mfma_f32_16x16x128_f8f6f4 v[68:71], v[136:143], v[160:167], v[68:71]
	v_mfma_f32_16x16x128_f8f6f4 v[48:51], v[144:151], v[176:183], v[48:51]
	v_mfma_f32_16x16x128_f8f6f4 v[52:55], v[136:143], v[176:183], v[52:55]
	v_mfma_f32_16x16x128_f8f6f4 v[32:35], v[144:151], v[196:203], v[32:35]
	v_mfma_f32_16x16x128_f8f6f4 v[36:39], v[136:143], v[196:203], v[36:39]
	v_mfma_f32_16x16x128_f8f6f4 v[20:23], v[144:151], v[204:211], v[20:23]
	v_mfma_f32_16x16x128_f8f6f4 v[16:19], v[136:143], v[204:211], v[16:19]
	s_barrier
	s_add_i32 s4, s4, s17
	s_mov_b32 m0, s4
	s_nop 0
	s_add_u32 vcc_lo, s14, s0
	s_addc_u32 vcc_hi, s15, s1
	global_load_lds_dwordx4 v0, vcc
	s_add_i32 m0, s4, 0x2000
	s_nop 0
	s_add_u32 vcc_lo, s14, s52
	s_addc_u32 vcc_hi, s15, s53
	global_load_lds_dwordx4 v0, vcc
	s_waitcnt vmcnt(6)
	s_barrier
	v_mfma_f32_16x16x128_f8f6f4 v[60:63], v[212:219], v[160:167], v[60:63]
	v_mfma_f32_16x16x128_f8f6f4 v[56:59], v[220:227], v[160:167], v[56:59]
	v_mfma_f32_16x16x128_f8f6f4 v[44:47], v[212:219], v[176:183], v[44:47]
	v_mfma_f32_16x16x128_f8f6f4 v[40:43], v[220:227], v[176:183], v[40:43]
	v_mfma_f32_16x16x128_f8f6f4 v[28:31], v[212:219], v[196:203], v[28:31]
	v_mfma_f32_16x16x128_f8f6f4 v[24:27], v[220:227], v[196:203], v[24:27]
	v_mfma_f32_16x16x128_f8f6f4 v[12:15], v[212:219], v[204:211], v[12:15]
	v_mfma_f32_16x16x128_f8f6f4 v[8:11], v[220:227], v[204:211], v[8:11]
	s_barrier
	s_add_i32 s4, 0, 0x18000
	ds_read_b128 v[144:147], v239 offset:32768
	ds_read_b128 v[148:151], v239 offset:33792
	ds_read_b128 v[136:139], v239 offset:34816
	ds_read_b128 v[140:143], v239 offset:35840
	s_mov_b32 m0, s24
	ds_read_b128 v[160:163], v236 offset:32768
	ds_read_b128 v[164:167], v236 offset:33792
	ds_read_b128 v[176:179], v236 offset:34816
	ds_read_b128 v[180:183], v236 offset:35840
	ds_read_b128 v[196:199], v236 offset:36864
	ds_read_b128 v[200:203], v236 offset:37888
	ds_read_b128 v[204:207], v236 offset:38912
	ds_read_b128 v[208:211], v236 offset:39936
	s_add_u32 vcc_lo, s12, s88
	s_addc_u32 vcc_hi, s13, s89
	global_load_lds_dwordx4 v2, vcc
	s_mov_b32 m0, s25
	s_nop 0
	s_add_u32 vcc_lo, s12, s64
	s_addc_u32 vcc_hi, s13, s65
	global_load_lds_dwordx4 v2, vcc
	s_waitcnt lgkmcnt(8)
	s_barrier
; #define G_STAGE(bufoff, gbase, o0, h64) do { \
;         __builtin_amdgcn_global_load_lds((const unsigned*)((const char*)(gbase) + (o0)), (LAS unsigned*)(lds + (bufoff) + ldsw), 16, 0, 0); \
;         __builtin_amdgcn_global_load_lds((const unsigned*)((const char*)(gbase) + (h64) + (o0)), (LAS unsigned*)(lds + (bufoff) + ldsw + 8192), 16, 0, 0); } while (0)
; #define G_LDA(dst, b, h) do { _Pragma("unroll") for (int m = 0; m < 4; ++m) _Pragma("unroll") for (int k = 0; k < 2; ++k) dst[m][k] = *(const LAS bf16x8*)(lds + G_SA(b, h) + aoff + m * 2048 + k * 1024); } while (0)
; #define G_LDB(dst, b, h) do { _Pragma("unroll") for (int n = 0; n < 2; ++n) _Pragma("unroll") for (int k = 0; k < 2; ++k) dst[n][k] = *(const LAS bf16x8*)(lds + G_SB(b, h) + boff + n * 2048 + k * 1024); } while (0)
; #define G_WAIT_V(n) asm volatile("s_waitcnt vmcnt(" #n ")" ::: "memory")
; #define G_WAIT_L(n) asm volatile("s_waitcnt lgkmcnt(" #n ")" ::: "memory")
; #define G_BAR __builtin_amdgcn_s_barrier()
; #define G_SCHED __builtin_amdgcn_sched_barrier(0)
;     ...
;             G_WAIT_L(8); G_BAR; G_WAIT_L(0); G_MMA(0, 0, At, B0); G_BAR; G_SCHED;
;             G_LDB(B1, 1, 1); G_STAGE(G_SB(1, 0), b3, cB0, qB);
;             G_BAR; G_WAIT_L(0); G_MMA(0, 1, At, B1); G_BAR;
;             G_LDA(At, 1, 1); G_STAGE(G_SA(1, 0), a3, cA0, qA);
;             G_BAR; G_WAIT_L(0); G_MMA(1, 0, At, B0); G_BAR; G_SCHED;
;             G_STAGE(G_SB(1, 1), b3 + chB, cB0, qB);
;             G_WAIT_V(6); G_BAR; G_MMA(1, 1, At, B1); G_BAR;
	s_waitcnt lgkmcnt(0)
	v_mfma_f32_16x16x128_f8f6f4 v[128:131], v[144:151], v[160:167], v[128:131]
	v_mfma_f32_16x16x128_f8f6f4 v[132:135], v[136:143], v[160:167], v[132:135]
	v_mfma_f32_16x16x128_f8f6f4 v[112:115], v[144:151], v[176:183], v[112:115]
	v_mfma_f32_16x16x128_f8f6f4 v[116:119], v[136:143], v[176:183], v[116:119]
	v_mfma_f32_16x16x128_f8f6f4 v[96:99], v[144:151], v[196:203], v[96:99]
	v_mfma_f32_16x16x128_f8f6f4 v[100:103], v[136:143], v[196:203], v[100:103]
	v_mfma_f32_16x16x128_f8f6f4 v[80:83], v[144:151], v[204:211], v[80:83]
	v_mfma_f32_16x16x128_f8f6f4 v[84:87], v[136:143], v[204:211], v[84:87]
	s_barrier
	s_add_i32 s5, 0, 0x1c000
	s_add_i32 s4, s4, s17
	s_mov_b32 m0, s4
	ds_read_b128 v[212:215], v239 offset:49152
	ds_read_b128 v[216:219], v239 offset:50176
	ds_read_b128 v[220:223], v239 offset:51200
	ds_read_b128 v[224:227], v239 offset:52224
	s_add_u32 vcc_lo, s14, s46
	s_addc_u32 vcc_hi, s15, s47
	global_load_lds_dwordx4 v0, vcc
	s_add_i32 m0, s4, 0x2000
	s_nop 0
	s_add_u32 vcc_lo, s14, s54
	s_addc_u32 vcc_hi, s15, s55
	global_load_lds_dwordx4 v0, vcc
	s_barrier
	s_waitcnt lgkmcnt(0)
	v_mfma_f32_16x16x128_f8f6f4 v[124:127], v[212:219], v[160:167], v[124:127]
	v_mfma_f32_16x16x128_f8f6f4 v[120:123], v[220:227], v[160:167], v[120:123]
	v_mfma_f32_16x16x128_f8f6f4 v[108:111], v[212:219], v[176:183], v[108:111]
	v_mfma_f32_16x16x128_f8f6f4 v[104:107], v[220:227], v[176:183], v[104:107]
	v_mfma_f32_16x16x128_f8f6f4 v[92:95], v[212:219], v[196:203], v[92:95]
	v_mfma_f32_16x16x128_f8f6f4 v[88:91], v[220:227], v[196:203], v[88:91]
	v_mfma_f32_16x16x128_f8f6f4 v[76:79], v[212:219], v[204:211], v[76:79]
	v_mfma_f32_16x16x128_f8f6f4 v[72:75], v[220:227], v[204:211], v[72:75]
	s_barrier
	s_mov_b32 m0, s26
	ds_read_b128 v[160:163], v236 offset:49152
	ds_read_b128 v[164:167], v236 offset:50176
	ds_read_b128 v[176:179], v236 offset:51200
	ds_read_b128 v[180:183], v236 offset:52224
	ds_read_b128 v[196:199], v236 offset:53248
	ds_read_b128 v[200:203], v236 offset:54272
	ds_read_b128 v[204:207], v236 offset:55296
	ds_read_b128 v[208:211], v236 offset:56320
	s_add_u32 vcc_lo, s12, s46
	s_addc_u32 vcc_hi, s13, s47
	global_load_lds_dwordx4 v2, vcc
	s_mov_b32 m0, s27
	s_nop 0
	s_add_u32 vcc_lo, s12, s66
	s_addc_u32 vcc_hi, s13, s67
	global_load_lds_dwordx4 v2, vcc
	s_barrier
	s_waitcnt lgkmcnt(0)
	v_mfma_f32_16x16x128_f8f6f4 v[64:67], v[144:151], v[160:167], v[64:67]
	v_mfma_f32_16x16x128_f8f6f4 v[68:71], v[136:143], v[160:167], v[68:71]
	v_mfma_f32_16x16x128_f8f6f4 v[48:51], v[144:151], v[176:183], v[48:51]
	v_mfma_f32_16x16x128_f8f6f4 v[52:55], v[136:143], v[176:183], v[52:55]
	v_mfma_f32_16x16x128_f8f6f4 v[32:35], v[144:151], v[196:203], v[32:35]
	v_mfma_f32_16x16x128_f8f6f4 v[36:39], v[136:143], v[196:203], v[36:39]
	v_mfma_f32_16x16x128_f8f6f4 v[20:23], v[144:151], v[204:211], v[20:23]
	v_mfma_f32_16x16x128_f8f6f4 v[16:19], v[136:143], v[204:211], v[16:19]
	s_barrier
	s_add_i32 s4, s5, s17
	s_mov_b32 m0, s4
	s_nop 0
	s_add_u32 vcc_lo, s14, s42
	s_addc_u32 vcc_hi, s15, s43
	global_load_lds_dwordx4 v0, vcc
	s_add_i32 m0, s4, 0x2000
	s_nop 0
	s_add_u32 vcc_lo, s14, s58
	s_addc_u32 vcc_hi, s15, s59
	global_load_lds_dwordx4 v0, vcc
	s_add_i32 s39, s39, 2
	s_add_u32 s2, s2, 0x100
	s_addc_u32 s3, s3, 0
	s_add_u32 s37, s37, 0x100
	s_addc_u32 s38, s38, 0
	s_cmp_gt_u32 s39, 5
	s_waitcnt vmcnt(6)
	s_barrier
	v_mfma_f32_16x16x128_f8f6f4 v[60:63], v[212:219], v[160:167], v[60:63]
	v_mfma_f32_16x16x128_f8f6f4 v[56:59], v[220:227], v[160:167], v[56:59]
	v_mfma_f32_16x16x128_f8f6f4 v[44:47], v[212:219], v[176:183], v[44:47]
	v_mfma_f32_16x16x128_f8f6f4 v[40:43], v[220:227], v[176:183], v[40:43]
	v_mfma_f32_16x16x128_f8f6f4 v[28:31], v[212:219], v[196:203], v[28:31]
	v_mfma_f32_16x16x128_f8f6f4 v[24:27], v[220:227], v[196:203], v[24:27]
	v_mfma_f32_16x16x128_f8f6f4 v[12:15], v[212:219], v[204:211], v[12:15]
	v_mfma_f32_16x16x128_f8f6f4 v[8:11], v[220:227], v[204:211], v[8:11]
	s_cbranch_scc0 .Ldb_MG0_cont

; #define G_STAGE(bufoff, gbase, o0, h64) do { \
;         __builtin_amdgcn_global_load_lds((const unsigned*)((const char*)(gbase) + (o0)), (LAS unsigned*)(lds + (bufoff) + ldsw), 16, 0, 0); \
;         __builtin_amdgcn_global_load_lds((const unsigned*)((const char*)(gbase) + (h64) + (o0)), (LAS unsigned*)(lds + (bufoff) + ldsw + 8192), 16, 0, 0); } while (0)
; #define G_LDA(dst, b, h) do { _Pragma("unroll") for (int m = 0; m < 4; ++m) _Pragma("unroll") for (int k = 0; k < 2; ++k) dst[m][k] = *(const LAS bf16x8*)(lds + G_SA(b, h) + aoff + m * 2048 + k * 1024); } while (0)
; #define G_LDB(dst, b, h) do { _Pragma("unroll") for (int n = 0; n < 2; ++n) _Pragma("unroll") for (int k = 0; k < 2; ++k) dst[n][k] = *(const LAS bf16x8*)(lds + G_SB(b, h) + boff + n * 2048 + k * 1024); } while (0)
; #define G_WAIT_V(n) asm volatile("s_waitcnt vmcnt(" #n ")" ::: "memory")
; #define G_WAIT_L(n) asm volatile("s_waitcnt lgkmcnt(" #n ")" ::: "memory")
;     ...
;         for (int t = 0; t < nt; t += 2) {
;             const bool last = (t == nt - 2);
;             const char* a1 = cA + (size_t)(t + 1) * ckA;
;             const char* a2 = last ? nA : cA + (size_t)(t + 2) * ckA; const char* b2 = last ? nB : cB + (size_t)(t + 2) * kB;
;             const char* a3 = a2 + ckA; const char* b3 = b2 + kB;
;             G_LDB(B0, 0, 0); G_SCHED; G_LDA(At, 0, 0); G_STAGE(G_SA(1, 1), a1 + chA, cA0, qA);
;             G_WAIT_L(8); G_BAR; G_WAIT_L(0); G_MMA(0, 0, At, B0); G_BAR; G_SCHED;
;             G_LDB(B1, 0, 1); G_STAGE(G_SB(0, 0), b2, cB0, qB);
;             G_BAR; G_WAIT_L(0); G_MMA(0, 1, At, B1); G_BAR;
;             G_LDA(At, 0, 1); G_STAGE(G_SA(0, 0), a2, cA0, qA);
;             G_BAR; G_WAIT_L(0); G_MMA(1, 0, At, B0); G_BAR; G_SCHED;
;             G_STAGE(G_SB(0, 1), b2 + chB, cB0, qB);
;             G_WAIT_V(6); G_BAR; G_MMA(1, 1, At, B1); G_BAR;
;             G_LDB(B0, 1, 0); G_SCHED; G_LDA(At, 1, 0); G_STAGE(G_SA(0, 1), a2 + chA, cA0, qA);
;             G_WAIT_L(8); G_BAR; G_WAIT_L(0); G_MMA(0, 0, At, B0); G_BAR; G_SCHED;
;     ...
;         if (!(cs.kind == K_MG_B && cur.aux < 2))
; #pragma unroll
;         for (int a = 0; a < 2; ++a)
; #pragma unroll
;             for (int b = 0; b < 2; ++b)
; #pragma unroll
;                 for (int m = 0; m < 4; ++m)
; #pragma unroll
;                     for (int n = 0; n < 2; ++n) acc[a][b][m][n] = (f32x4){0.f, 0.f, 0.f, 0.f};
.LBB0_1036:
	s_add_u32 s2, s2, 0x40080
	s_addc_u32 s3, s3, 0
	s_add_u32 s6, s6, 0x100
	s_waitcnt lgkmcnt(0)
	s_addc_u32 s7, s7, 0
	s_mov_b32 s15, -2
	s_mov_b64 s[42:43], 0x40000
	s_mov_b64 s[50:51], 0x60000
	s_mov_b64 s[52:53], 0x20080
	s_mov_b64 s[54:55], 0x40080
	s_mov_b64 s[58:59], 0x60080
	s_cmp_eq_u32 s101, 2
	s_cselect_b32 s101, 0, s101
	v_add_u32_e32 v255, 0x10000, v181
	s_add_u32 s4, s2, 0xfffc0080
	s_addc_u32 s5, s3, -1
	s_add_i32 s33, 0, 0x10000
	ds_read_b128 v[136:139], v255 offset:0
	ds_read_b128 v[140:143], v255 offset:1024
	ds_read_b128 v[144:147], v255 offset:2048
	ds_read_b128 v[148:151], v255 offset:3072
	s_cmp_eq_u32 s15, 12
	s_cselect_b32 s5, s17, s5
	s_cselect_b32 s4, s16, s4
	s_cselect_b32 s21, s19, s7
	s_cselect_b32 s20, s18, s6
	s_add_i32 m0, s24, 0xc000
	ds_read_b128 v[152:155], v182
	ds_read_b128 v[156:159], v182 offset:1024
	ds_read_b128 v[160:163], v182 offset:2048
	ds_read_b128 v[172:175], v182 offset:3072
	ds_read_b128 v[176:179], v182 offset:4096
	ds_read_b128 v[196:199], v182 offset:5120
	ds_read_b128 v[200:203], v182 offset:6144
	ds_read_b128 v[204:207], v182 offset:7168
	global_load_lds_dwordx4 v166, s[2:3]
	s_add_i32 m0, s24, 0xe000
	s_nop 0
	s_add_u32 vcc_lo, s2, s0
	s_addc_u32 vcc_hi, s3, s1
	global_load_lds_dwordx4 v166, vcc
	s_waitcnt lgkmcnt(8)
	s_cmp_eq_u32 s101, 1
	s_cbranch_scc1 .Ldb_WOUT_skp
	s_barrier
.Ldb_WOUT_skp:
	s_mov_b32 s101, 0
	s_waitcnt lgkmcnt(0)
	v_mfma_f32_16x16x32_bf16 v[132:135], v[136:139], v[152:155], 0
	v_mfma_f32_16x16x32_bf16 v[128:131], v[144:147], v[152:155], 0
	v_mfma_f32_16x16x32_bf16 v[116:119], v[136:139], v[160:163], 0
	v_mfma_f32_16x16x32_bf16 v[112:115], v[144:147], v[160:163], 0
	v_mfma_f32_16x16x32_bf16 v[100:103], v[136:139], v[176:179], 0
	v_mfma_f32_16x16x32_bf16 v[96:99], v[144:147], v[176:179], 0
	v_mfma_f32_16x16x32_bf16 v[84:87], v[136:139], v[200:203], 0
	v_mfma_f32_16x16x32_bf16 v[80:83], v[144:147], v[200:203], 0
	v_mfma_f32_16x16x32_bf16 v[132:135], v[140:143], v[156:159], v[132:135]
	v_mfma_f32_16x16x32_bf16 v[128:131], v[148:151], v[156:159], v[128:131]
	v_mfma_f32_16x16x32_bf16 v[116:119], v[140:143], v[172:175], v[116:119]
	v_mfma_f32_16x16x32_bf16 v[112:115], v[148:151], v[172:175], v[112:115]
	v_mfma_f32_16x16x32_bf16 v[100:103], v[140:143], v[196:199], v[100:103]
	v_mfma_f32_16x16x32_bf16 v[96:99], v[148:151], v[196:199], v[96:99]
	v_mfma_f32_16x16x32_bf16 v[84:87], v[140:143], v[204:207], v[84:87]
	v_mfma_f32_16x16x32_bf16 v[80:83], v[148:151], v[204:207], v[80:83]
	s_barrier
	s_add_i32 s41, 0, 0x14000
	s_add_i32 s100, s33, s23
	s_mov_b32 m0, s100
	ds_read_b128 v[208:211], v255 offset:16384
	ds_read_b128 v[212:215], v255 offset:17408
	ds_read_b128 v[216:219], v255 offset:18432
	ds_read_b128 v[220:223], v255 offset:19456
	global_load_lds_dwordx4 v164, s[20:21]
	s_add_i32 m0, s100, 0x2000
	s_nop 0
	s_add_u32 vcc_lo, s20, s0
	s_addc_u32 vcc_hi, s21, s1
	global_load_lds_dwordx4 v164, vcc
	s_barrier
	s_waitcnt lgkmcnt(0)
	v_mfma_f32_16x16x32_bf16 v[124:127], v[208:211], v[152:155], 0
	v_mfma_f32_16x16x32_bf16 v[120:123], v[216:219], v[152:155], 0
	v_mfma_f32_16x16x32_bf16 v[108:111], v[208:211], v[160:163], 0
	v_mfma_f32_16x16x32_bf16 v[104:107], v[216:219], v[160:163], 0
	v_mfma_f32_16x16x32_bf16 v[92:95], v[208:211], v[176:179], 0
	v_mfma_f32_16x16x32_bf16 v[88:91], v[216:219], v[176:179], 0
	v_mfma_f32_16x16x32_bf16 v[76:79], v[208:211], v[200:203], 0
	v_mfma_f32_16x16x32_bf16 v[72:75], v[216:219], v[200:203], 0
	v_mfma_f32_16x16x32_bf16 v[124:127], v[212:215], v[156:159], v[124:127]
	v_mfma_f32_16x16x32_bf16 v[120:123], v[220:223], v[156:159], v[120:123]
	v_mfma_f32_16x16x32_bf16 v[108:111], v[212:215], v[172:175], v[108:111]
	v_mfma_f32_16x16x32_bf16 v[104:107], v[220:223], v[172:175], v[104:107]
	v_mfma_f32_16x16x32_bf16 v[92:95], v[212:215], v[196:199], v[92:95]
	v_mfma_f32_16x16x32_bf16 v[88:91], v[220:223], v[196:199], v[88:91]
	v_mfma_f32_16x16x32_bf16 v[76:79], v[212:215], v[204:207], v[76:79]
	v_mfma_f32_16x16x32_bf16 v[72:75], v[220:223], v[204:207], v[72:75]
	s_barrier
	s_mov_b32 m0, s24
	v_lshl_add_u64 v[224:225], s[4:5], 0, v[2:3]
	ds_read_b128 v[152:155], v182 offset:16384
	ds_read_b128 v[156:159], v182 offset:17408
	ds_read_b128 v[160:163], v182 offset:18432
	ds_read_b128 v[172:175], v182 offset:19456
	ds_read_b128 v[176:179], v182 offset:20480
	ds_read_b128 v[196:199], v182 offset:21504
	ds_read_b128 v[200:203], v182 offset:22528
	ds_read_b128 v[204:207], v182 offset:23552
	global_load_lds_dwordx4 v2, s[4:5]
	s_mov_b32 m0, s25
	s_nop 0
	s_add_u32 vcc_lo, s4, s0
	s_addc_u32 vcc_hi, s5, s1
	global_load_lds_dwordx4 v2, vcc
	s_barrier
	s_waitcnt lgkmcnt(0)
	v_mfma_f32_16x16x32_bf16 v[68:71], v[136:139], v[152:155], 0
	v_mfma_f32_16x16x32_bf16 v[64:67], v[144:147], v[152:155], 0
	v_mfma_f32_16x16x32_bf16 v[52:55], v[136:139], v[160:163], 0
	v_mfma_f32_16x16x32_bf16 v[48:51], v[144:147], v[160:163], 0
	v_mfma_f32_16x16x32_bf16 v[36:39], v[136:139], v[176:179], 0
	v_mfma_f32_16x16x32_bf16 v[32:35], v[144:147], v[176:179], 0
	v_mfma_f32_16x16x32_bf16 v[20:23], v[136:139], v[200:203], 0
	v_mfma_f32_16x16x32_bf16 v[16:19], v[144:147], v[200:203], 0
	v_mfma_f32_16x16x32_bf16 v[68:71], v[140:143], v[156:159], v[68:71]
	v_mfma_f32_16x16x32_bf16 v[64:67], v[148:151], v[156:159], v[64:67]
	v_mfma_f32_16x16x32_bf16 v[52:55], v[140:143], v[172:175], v[52:55]
	v_mfma_f32_16x16x32_bf16 v[48:51], v[148:151], v[172:175], v[48:51]
	v_mfma_f32_16x16x32_bf16 v[36:39], v[140:143], v[196:199], v[36:39]
	v_mfma_f32_16x16x32_bf16 v[32:35], v[148:151], v[196:199], v[32:35]
	v_mfma_f32_16x16x32_bf16 v[20:23], v[140:143], v[204:207], v[20:23]
	v_mfma_f32_16x16x32_bf16 v[16:19], v[148:151], v[204:207], v[16:19]
	s_barrier
; #define G_STAGE(bufoff, gbase, o0, h64) do { \
;         __builtin_amdgcn_global_load_lds((const unsigned*)((const char*)(gbase) + (o0)), (LAS unsigned*)(lds + (bufoff) + ldsw), 16, 0, 0); \
;         __builtin_amdgcn_global_load_lds((const unsigned*)((const char*)(gbase) + (h64) + (o0)), (LAS unsigned*)(lds + (bufoff) + ldsw + 8192), 16, 0, 0); } while (0)
; #define G_LDA(dst, b, h) do { _Pragma("unroll") for (int m = 0; m < 4; ++m) _Pragma("unroll") for (int k = 0; k < 2; ++k) dst[m][k] = *(const LAS bf16x8*)(lds + G_SA(b, h) + aoff + m * 2048 + k * 1024); } while (0)
; #define G_LDB(dst, b, h) do { _Pragma("unroll") for (int n = 0; n < 2; ++n) _Pragma("unroll") for (int k = 0; k < 2; ++k) dst[n][k] = *(const LAS bf16x8*)(lds + G_SB(b, h) + boff + n * 2048 + k * 1024); } while (0)
; #define G_WAIT_V(n) asm volatile("s_waitcnt vmcnt(" #n ")" ::: "memory")
; #define G_WAIT_L(n) asm volatile("s_waitcnt lgkmcnt(" #n ")" ::: "memory")
; #define G_BAR __builtin_amdgcn_s_barrier()
; #define G_SCHED __builtin_amdgcn_sched_barrier(0)
;     ...
;             G_STAGE(G_SB(0, 1), b2 + chB, cB0, qB);
;             G_WAIT_V(6); G_BAR; G_MMA(1, 1, At, B1); G_BAR;
;             G_LDB(B0, 1, 0); G_SCHED; G_LDA(At, 1, 0); G_STAGE(G_SA(0, 1), a2 + chA, cA0, qA);
;             G_WAIT_L(8); G_BAR; G_WAIT_L(0); G_MMA(0, 0, At, B0); G_BAR; G_SCHED;
;             G_LDB(B1, 1, 1); G_STAGE(G_SB(1, 0), b3, cB0, qB);
;             G_BAR; G_WAIT_L(0); G_MMA(0, 1, At, B1); G_BAR;
;             G_LDA(At, 1, 1); G_STAGE(G_SA(1, 0), a3, cA0, qA);
;             G_BAR; G_WAIT_L(0); G_MMA(1, 0, At, B0); G_BAR; G_SCHED;
	s_add_i32 s100, s41, s23
	s_mov_b32 m0, s100
	s_nop 0
	s_add_u32 vcc_lo, s20, s42
	s_addc_u32 vcc_hi, s21, s43
	global_load_lds_dwordx4 v164, vcc
	s_add_i32 m0, s100, 0x2000
	s_nop 0
	s_add_u32 vcc_lo, s20, s50
	s_addc_u32 vcc_hi, s21, s51
	global_load_lds_dwordx4 v164, vcc
	s_waitcnt vmcnt(6)
	s_barrier
	v_mfma_f32_16x16x32_bf16 v[60:63], v[208:211], v[152:155], 0
	v_mfma_f32_16x16x32_bf16 v[56:59], v[216:219], v[152:155], 0
	v_mfma_f32_16x16x32_bf16 v[44:47], v[208:211], v[160:163], 0
	v_mfma_f32_16x16x32_bf16 v[40:43], v[216:219], v[160:163], 0
	v_mfma_f32_16x16x32_bf16 v[28:31], v[208:211], v[176:179], 0
	v_mfma_f32_16x16x32_bf16 v[24:27], v[216:219], v[176:179], 0
	v_mfma_f32_16x16x32_bf16 v[12:15], v[208:211], v[200:203], 0
	v_mfma_f32_16x16x32_bf16 v[8:11], v[216:219], v[200:203], 0
	v_mfma_f32_16x16x32_bf16 v[60:63], v[212:215], v[156:159], v[60:63]
	v_mfma_f32_16x16x32_bf16 v[56:59], v[220:223], v[156:159], v[56:59]
	v_mfma_f32_16x16x32_bf16 v[44:47], v[212:215], v[172:175], v[44:47]
	v_mfma_f32_16x16x32_bf16 v[40:43], v[220:223], v[172:175], v[40:43]
	v_mfma_f32_16x16x32_bf16 v[28:31], v[212:215], v[196:199], v[28:31]
	v_mfma_f32_16x16x32_bf16 v[24:27], v[220:223], v[196:199], v[24:27]
	v_mfma_f32_16x16x32_bf16 v[12:15], v[212:215], v[204:207], v[12:15]
	v_mfma_f32_16x16x32_bf16 v[8:11], v[220:223], v[204:207], v[8:11]
	s_barrier
	s_add_i32 s100, 0, 0x18000
	ds_read_b128 v[136:139], v255 offset:32768
	ds_read_b128 v[140:143], v255 offset:33792
	ds_read_b128 v[144:147], v255 offset:34816
	ds_read_b128 v[148:151], v255 offset:35840
	s_mov_b32 m0, s26
	ds_read_b128 v[152:155], v182 offset:32768
	ds_read_b128 v[156:159], v182 offset:33792
	ds_read_b128 v[160:163], v182 offset:34816
	ds_read_b128 v[172:175], v182 offset:35840
	ds_read_b128 v[176:179], v182 offset:36864
	ds_read_b128 v[196:199], v182 offset:37888
	ds_read_b128 v[200:203], v182 offset:38912
	ds_read_b128 v[204:207], v182 offset:39936
	s_add_u32 vcc_lo, s4, s42
	s_addc_u32 vcc_hi, s5, s43
	global_load_lds_dwordx4 v2, vcc
	s_mov_b32 m0, s27
	s_nop 0
	s_add_u32 vcc_lo, s4, s50
	s_addc_u32 vcc_hi, s5, s51
	global_load_lds_dwordx4 v2, vcc
	s_waitcnt lgkmcnt(8)
	s_barrier
	s_waitcnt lgkmcnt(0)
	v_mfma_f32_16x16x32_bf16 v[132:135], v[136:139], v[152:155], v[132:135]
	v_mfma_f32_16x16x32_bf16 v[128:131], v[144:147], v[152:155], v[128:131]
	v_mfma_f32_16x16x32_bf16 v[116:119], v[136:139], v[160:163], v[116:119]
	v_mfma_f32_16x16x32_bf16 v[112:115], v[144:147], v[160:163], v[112:115]
	v_mfma_f32_16x16x32_bf16 v[100:103], v[136:139], v[176:179], v[100:103]
	v_mfma_f32_16x16x32_bf16 v[96:99], v[144:147], v[176:179], v[96:99]
	v_mfma_f32_16x16x32_bf16 v[84:87], v[136:139], v[200:203], v[84:87]
	v_mfma_f32_16x16x32_bf16 v[80:83], v[144:147], v[200:203], v[80:83]
	v_mfma_f32_16x16x32_bf16 v[132:135], v[140:143], v[156:159], v[132:135]
	v_mfma_f32_16x16x32_bf16 v[128:131], v[148:151], v[156:159], v[128:131]
	v_mfma_f32_16x16x32_bf16 v[116:119], v[140:143], v[172:175], v[116:119]
	v_mfma_f32_16x16x32_bf16 v[112:115], v[148:151], v[172:175], v[112:115]
	v_mfma_f32_16x16x32_bf16 v[100:103], v[140:143], v[196:199], v[100:103]
	v_mfma_f32_16x16x32_bf16 v[96:99], v[148:151], v[196:199], v[96:99]
	v_mfma_f32_16x16x32_bf16 v[84:87], v[140:143], v[204:207], v[84:87]
	v_mfma_f32_16x16x32_bf16 v[80:83], v[148:151], v[204:207], v[80:83]
	s_barrier
	s_add_i32 s5, 0, 0x1c000
	s_add_i32 s4, s100, s23
	s_mov_b32 m0, s4
	ds_read_b128 v[208:211], v255 offset:49152
	ds_read_b128 v[212:215], v255 offset:50176
	ds_read_b128 v[216:219], v255 offset:51200
	ds_read_b128 v[220:223], v255 offset:52224
	s_add_u32 vcc_lo, s20, s46
	s_addc_u32 vcc_hi, s21, s47
	global_load_lds_dwordx4 v164, vcc
	s_add_i32 m0, s4, 0x2000
	s_nop 0
	s_add_u32 vcc_lo, s20, s52
	s_addc_u32 vcc_hi, s21, s53
	global_load_lds_dwordx4 v164, vcc
	s_barrier
	s_waitcnt lgkmcnt(0)
	v_mfma_f32_16x16x32_bf16 v[124:127], v[208:211], v[152:155], v[124:127]
	v_mfma_f32_16x16x32_bf16 v[120:123], v[216:219], v[152:155], v[120:123]
	v_mfma_f32_16x16x32_bf16 v[108:111], v[208:211], v[160:163], v[108:111]
	v_mfma_f32_16x16x32_bf16 v[104:107], v[216:219], v[160:163], v[104:107]
	v_mfma_f32_16x16x32_bf16 v[92:95], v[208:211], v[176:179], v[92:95]
	v_mfma_f32_16x16x32_bf16 v[88:91], v[216:219], v[176:179], v[88:91]
	v_mfma_f32_16x16x32_bf16 v[76:79], v[208:211], v[200:203], v[76:79]
	v_mfma_f32_16x16x32_bf16 v[72:75], v[216:219], v[200:203], v[72:75]
	v_mfma_f32_16x16x32_bf16 v[124:127], v[212:215], v[156:159], v[124:127]
	v_mfma_f32_16x16x32_bf16 v[120:123], v[220:223], v[156:159], v[120:123]
	v_mfma_f32_16x16x32_bf16 v[108:111], v[212:215], v[172:175], v[108:111]
	v_mfma_f32_16x16x32_bf16 v[104:107], v[220:223], v[172:175], v[104:107]
	v_mfma_f32_16x16x32_bf16 v[92:95], v[212:215], v[196:199], v[92:95]
	v_mfma_f32_16x16x32_bf16 v[88:91], v[220:223], v[196:199], v[88:91]
	v_mfma_f32_16x16x32_bf16 v[76:79], v[212:215], v[204:207], v[76:79]
	v_mfma_f32_16x16x32_bf16 v[72:75], v[220:223], v[204:207], v[72:75]
	s_barrier
	s_mov_b32 m0, s29
	v_lshl_add_u64 v[226:227], v[224:225], 0, s[46:47]
	ds_read_b128 v[152:155], v182 offset:49152
	ds_read_b128 v[156:159], v182 offset:50176
	ds_read_b128 v[160:163], v182 offset:51200
	ds_read_b128 v[172:175], v182 offset:52224
	ds_read_b128 v[176:179], v182 offset:53248
	ds_read_b128 v[196:199], v182 offset:54272
	ds_read_b128 v[200:203], v182 offset:55296
	ds_read_b128 v[204:207], v182 offset:56320
	global_load_lds_dwordx4 v[226:227], off
	v_lshl_add_u64 v[224:225], v[224:225], 0, s[52:53]
	s_mov_b32 m0, s30
	s_nop 0
	global_load_lds_dwordx4 v[224:225], off
	s_barrier
; #define G_STAGE(bufoff, gbase, o0, h64) do { \
;         __builtin_amdgcn_global_load_lds((const unsigned*)((const char*)(gbase) + (o0)), (LAS unsigned*)(lds + (bufoff) + ldsw), 16, 0, 0); \
;         __builtin_amdgcn_global_load_lds((const unsigned*)((const char*)(gbase) + (h64) + (o0)), (LAS unsigned*)(lds + (bufoff) + ldsw + 8192), 16, 0, 0); } while (0)
; #define G_LDA(dst, b, h) do { _Pragma("unroll") for (int m = 0; m < 4; ++m) _Pragma("unroll") for (int k = 0; k < 2; ++k) dst[m][k] = *(const LAS bf16x8*)(lds + G_SA(b, h) + aoff + m * 2048 + k * 1024); } while (0)
; #define G_LDB(dst, b, h) do { _Pragma("unroll") for (int n = 0; n < 2; ++n) _Pragma("unroll") for (int k = 0; k < 2; ++k) dst[n][k] = *(const LAS bf16x8*)(lds + G_SB(b, h) + boff + n * 2048 + k * 1024); } while (0)
; #define G_WAIT_V(n) asm volatile("s_waitcnt vmcnt(" #n ")" ::: "memory")
; #define G_BAR __builtin_amdgcn_s_barrier()
;     ...
;         for (int t = 0; t < nt; t += 2) {
;             const bool last = (t == nt - 2);
;             const char* a1 = cA + (size_t)(t + 1) * ckA;
;             const char* a2 = last ? nA : cA + (size_t)(t + 2) * ckA; const char* b2 = last ? nB : cB + (size_t)(t + 2) * kB;
;             const char* a3 = a2 + ckA; const char* b3 = b2 + kB;
;             G_LDB(B0, 0, 0); G_SCHED; G_LDA(At, 0, 0); G_STAGE(G_SA(1, 1), a1 + chA, cA0, qA);
;             G_WAIT_L(8); G_BAR; G_WAIT_L(0); G_MMA(0, 0, At, B0); G_BAR; G_SCHED;
;             G_LDB(B1, 0, 1); G_STAGE(G_SB(0, 0), b2, cB0, qB);
;             G_BAR; G_WAIT_L(0); G_MMA(0, 1, At, B1); G_BAR;
;             G_LDA(At, 0, 1); G_STAGE(G_SA(0, 0), a2, cA0, qA);
;             G_BAR; G_WAIT_L(0); G_MMA(1, 0, At, B0); G_BAR; G_SCHED;
;             G_STAGE(G_SB(0, 1), b2 + chB, cB0, qB);
;             G_WAIT_V(6); G_BAR; G_MMA(1, 1, At, B1); G_BAR;
;             G_LDB(B0, 1, 0); G_SCHED; G_LDA(At, 1, 0); G_STAGE(G_SA(0, 1), a2 + chA, cA0, qA);
;             G_WAIT_L(8); G_BAR; G_WAIT_L(0); G_MMA(0, 0, At, B0); G_BAR; G_SCHED;
;             G_LDB(B1, 1, 1); G_STAGE(G_SB(1, 0), b3, cB0, qB);
;             G_BAR; G_WAIT_L(0); G_MMA(0, 1, At, B1); G_BAR;
;             G_LDA(At, 1, 1); G_STAGE(G_SA(1, 0), a3, cA0, qA);
;             G_BAR; G_WAIT_L(0); G_MMA(1, 0, At, B0); G_BAR; G_SCHED;
;             G_STAGE(G_SB(1, 1), b3 + chB, cB0, qB);
;             G_WAIT_V(6); G_BAR; G_MMA(1, 1, At, B1); G_BAR;
	s_waitcnt lgkmcnt(0)
	v_mfma_f32_16x16x32_bf16 v[68:71], v[136:139], v[152:155], v[68:71]
	v_mfma_f32_16x16x32_bf16 v[64:67], v[144:147], v[152:155], v[64:67]
	v_mfma_f32_16x16x32_bf16 v[52:55], v[136:139], v[160:163], v[52:55]
	v_mfma_f32_16x16x32_bf16 v[48:51], v[144:147], v[160:163], v[48:51]
	v_mfma_f32_16x16x32_bf16 v[36:39], v[136:139], v[176:179], v[36:39]
	v_mfma_f32_16x16x32_bf16 v[32:35], v[144:147], v[176:179], v[32:35]
	v_mfma_f32_16x16x32_bf16 v[20:23], v[136:139], v[200:203], v[20:23]
	v_mfma_f32_16x16x32_bf16 v[16:19], v[144:147], v[200:203], v[16:19]
	v_mfma_f32_16x16x32_bf16 v[68:71], v[140:143], v[156:159], v[68:71]
	v_mfma_f32_16x16x32_bf16 v[64:67], v[148:151], v[156:159], v[64:67]
	v_mfma_f32_16x16x32_bf16 v[52:55], v[140:143], v[172:175], v[52:55]
	v_mfma_f32_16x16x32_bf16 v[48:51], v[148:151], v[172:175], v[48:51]
	v_mfma_f32_16x16x32_bf16 v[36:39], v[140:143], v[196:199], v[36:39]
	v_mfma_f32_16x16x32_bf16 v[32:35], v[148:151], v[196:199], v[32:35]
	v_mfma_f32_16x16x32_bf16 v[20:23], v[140:143], v[204:207], v[20:23]
	v_mfma_f32_16x16x32_bf16 v[16:19], v[148:151], v[204:207], v[16:19]
	s_barrier
	s_add_i32 s4, s5, s23
	s_mov_b32 m0, s4
	s_nop 0
	s_add_u32 vcc_lo, s20, s54
	s_addc_u32 vcc_hi, s21, s55
	global_load_lds_dwordx4 v164, vcc
	s_add_i32 m0, s4, 0x2000
	s_nop 0
	s_add_u32 vcc_lo, s20, s58
	s_addc_u32 vcc_hi, s21, s59
	global_load_lds_dwordx4 v164, vcc
	s_add_i32 s15, s15, 2
	s_add_u32 s2, s2, 0x100
	s_addc_u32 s3, s3, 0
	s_add_u32 s6, s6, 0x100
	s_addc_u32 s7, s7, 0
	s_cmp_gt_u32 s15, 13
	s_waitcnt vmcnt(6)
	s_barrier
	v_mfma_f32_16x16x32_bf16 v[60:63], v[208:211], v[152:155], v[60:63]
	v_mfma_f32_16x16x32_bf16 v[56:59], v[216:219], v[152:155], v[56:59]
	v_mfma_f32_16x16x32_bf16 v[44:47], v[208:211], v[160:163], v[44:47]
	v_mfma_f32_16x16x32_bf16 v[40:43], v[216:219], v[160:163], v[40:43]
	v_mfma_f32_16x16x32_bf16 v[28:31], v[208:211], v[176:179], v[28:31]
	v_mfma_f32_16x16x32_bf16 v[24:27], v[216:219], v[176:179], v[24:27]
	v_mfma_f32_16x16x32_bf16 v[12:15], v[208:211], v[200:203], v[12:15]
	v_mfma_f32_16x16x32_bf16 v[8:11], v[216:219], v[200:203], v[8:11]
	v_mfma_f32_16x16x32_bf16 v[60:63], v[212:215], v[156:159], v[60:63]
	v_mfma_f32_16x16x32_bf16 v[56:59], v[220:223], v[156:159], v[56:59]
	v_mfma_f32_16x16x32_bf16 v[44:47], v[212:215], v[172:175], v[44:47]
	v_mfma_f32_16x16x32_bf16 v[40:43], v[220:223], v[172:175], v[40:43]
	v_mfma_f32_16x16x32_bf16 v[28:31], v[212:215], v[196:199], v[28:31]
	v_mfma_f32_16x16x32_bf16 v[24:27], v[220:223], v[196:199], v[24:27]
	v_mfma_f32_16x16x32_bf16 v[12:15], v[212:215], v[204:207], v[12:15]
	v_mfma_f32_16x16x32_bf16 v[8:11], v[220:223], v[204:207], v[8:11]
	s_cbranch_scc0 .Ldb_WOUT_cont
	s_branch .Ldb_WOUT_xl
.LBB0_1037:
	s_add_u32 s4, s2, 0xfffc0080
	s_addc_u32 s5, s3, -1
	s_add_i32 s33, 0, 0x10000
	ds_read_b128 v[136:139], v255 offset:0
	ds_read_b128 v[140:143], v255 offset:1024
	ds_read_b128 v[144:147], v255 offset:2048
	ds_read_b128 v[148:151], v255 offset:3072
	s_cmp_eq_u32 s15, 12
	s_cselect_b32 s5, s17, s5
	s_cselect_b32 s4, s16, s4
	s_cselect_b32 s21, s19, s7
	s_cselect_b32 s20, s18, s6
	s_add_i32 m0, s24, 0xc000
	ds_read_b128 v[152:155], v182
	ds_read_b128 v[156:159], v182 offset:1024
	ds_read_b128 v[160:163], v182 offset:2048
	ds_read_b128 v[172:175], v182 offset:3072
	ds_read_b128 v[176:179], v182 offset:4096
	ds_read_b128 v[196:199], v182 offset:5120
	ds_read_b128 v[200:203], v182 offset:6144
	ds_read_b128 v[204:207], v182 offset:7168
	global_load_lds_dwordx4 v166, s[2:3]
	s_add_i32 m0, s24, 0xe000
	s_nop 0
	s_add_u32 vcc_lo, s2, s0
	s_addc_u32 vcc_hi, s3, s1
	global_load_lds_dwordx4 v166, vcc
	s_waitcnt lgkmcnt(8)
	s_barrier
	s_waitcnt lgkmcnt(0)
	v_mfma_f32_16x16x32_bf16 v[132:135], v[136:139], v[152:155], v[132:135]
	v_mfma_f32_16x16x32_bf16 v[128:131], v[144:147], v[152:155], v[128:131]
	v_mfma_f32_16x16x32_bf16 v[116:119], v[136:139], v[160:163], v[116:119]
	v_mfma_f32_16x16x32_bf16 v[112:115], v[144:147], v[160:163], v[112:115]
	v_mfma_f32_16x16x32_bf16 v[100:103], v[136:139], v[176:179], v[100:103]
	v_mfma_f32_16x16x32_bf16 v[96:99], v[144:147], v[176:179], v[96:99]
	v_mfma_f32_16x16x32_bf16 v[84:87], v[136:139], v[200:203], v[84:87]
	v_mfma_f32_16x16x32_bf16 v[80:83], v[144:147], v[200:203], v[80:83]
	v_mfma_f32_16x16x32_bf16 v[132:135], v[140:143], v[156:159], v[132:135]
	v_mfma_f32_16x16x32_bf16 v[128:131], v[148:151], v[156:159], v[128:131]
	v_mfma_f32_16x16x32_bf16 v[116:119], v[140:143], v[172:175], v[116:119]
	v_mfma_f32_16x16x32_bf16 v[112:115], v[148:151], v[172:175], v[112:115]
	v_mfma_f32_16x16x32_bf16 v[100:103], v[140:143], v[196:199], v[100:103]
	v_mfma_f32_16x16x32_bf16 v[96:99], v[148:151], v[196:199], v[96:99]
	v_mfma_f32_16x16x32_bf16 v[84:87], v[140:143], v[204:207], v[84:87]
	v_mfma_f32_16x16x32_bf16 v[80:83], v[148:151], v[204:207], v[80:83]
	s_barrier
	s_add_i32 s41, 0, 0x14000
	s_add_i32 s100, s33, s23
	s_mov_b32 m0, s100
	ds_read_b128 v[208:211], v255 offset:16384
	ds_read_b128 v[212:215], v255 offset:17408
	ds_read_b128 v[216:219], v255 offset:18432
	ds_read_b128 v[220:223], v255 offset:19456
	global_load_lds_dwordx4 v164, s[20:21]
	s_add_i32 m0, s100, 0x2000
	s_nop 0
	s_add_u32 vcc_lo, s20, s0
	s_addc_u32 vcc_hi, s21, s1
	global_load_lds_dwordx4 v164, vcc
	s_barrier
; #define G_STAGE(bufoff, gbase, o0, h64) do { \
;         __builtin_amdgcn_global_load_lds((const unsigned*)((const char*)(gbase) + (o0)), (LAS unsigned*)(lds + (bufoff) + ldsw), 16, 0, 0); \
;         __builtin_amdgcn_global_load_lds((const unsigned*)((const char*)(gbase) + (h64) + (o0)), (LAS unsigned*)(lds + (bufoff) + ldsw + 8192), 16, 0, 0); } while (0)
; #define G_LDA(dst, b, h) do { _Pragma("unroll") for (int m = 0; m < 4; ++m) _Pragma("unroll") for (int k = 0; k < 2; ++k) dst[m][k] = *(const LAS bf16x8*)(lds + G_SA(b, h) + aoff + m * 2048 + k * 1024); } while (0)
; #define G_LDB(dst, b, h) do { _Pragma("unroll") for (int n = 0; n < 2; ++n) _Pragma("unroll") for (int k = 0; k < 2; ++k) dst[n][k] = *(const LAS bf16x8*)(lds + G_SB(b, h) + boff + n * 2048 + k * 1024); } while (0)
; #define G_WAIT_V(n) asm volatile("s_waitcnt vmcnt(" #n ")" ::: "memory")
; #define G_WAIT_L(n) asm volatile("s_waitcnt lgkmcnt(" #n ")" ::: "memory")
; #define G_BAR __builtin_amdgcn_s_barrier()
; #define G_SCHED __builtin_amdgcn_sched_barrier(0)
;     ...
;             G_BAR; G_WAIT_L(0); G_MMA(0, 1, At, B1); G_BAR;
;             G_LDA(At, 0, 1); G_STAGE(G_SA(0, 0), a2, cA0, qA);
;             G_BAR; G_WAIT_L(0); G_MMA(1, 0, At, B0); G_BAR; G_SCHED;
;             G_STAGE(G_SB(0, 1), b2 + chB, cB0, qB);
;             G_WAIT_V(6); G_BAR; G_MMA(1, 1, At, B1); G_BAR;
;             G_LDB(B0, 1, 0); G_SCHED; G_LDA(At, 1, 0); G_STAGE(G_SA(0, 1), a2 + chA, cA0, qA);
;             G_WAIT_L(8); G_BAR; G_WAIT_L(0); G_MMA(0, 0, At, B0); G_BAR; G_SCHED;
;             G_LDB(B1, 1, 1); G_STAGE(G_SB(1, 0), b3, cB0, qB);
;             G_BAR; G_WAIT_L(0); G_MMA(0, 1, At, B1); G_BAR;
;             G_LDA(At, 1, 1); G_STAGE(G_SA(1, 0), a3, cA0, qA);
;             G_BAR; G_WAIT_L(0); G_MMA(1, 0, At, B0); G_BAR; G_SCHED;
	s_waitcnt lgkmcnt(0)
	v_mfma_f32_16x16x32_bf16 v[124:127], v[208:211], v[152:155], v[124:127]
	v_mfma_f32_16x16x32_bf16 v[120:123], v[216:219], v[152:155], v[120:123]
	v_mfma_f32_16x16x32_bf16 v[108:111], v[208:211], v[160:163], v[108:111]
	v_mfma_f32_16x16x32_bf16 v[104:107], v[216:219], v[160:163], v[104:107]
	v_mfma_f32_16x16x32_bf16 v[92:95], v[208:211], v[176:179], v[92:95]
	v_mfma_f32_16x16x32_bf16 v[88:91], v[216:219], v[176:179], v[88:91]
	v_mfma_f32_16x16x32_bf16 v[76:79], v[208:211], v[200:203], v[76:79]
	v_mfma_f32_16x16x32_bf16 v[72:75], v[216:219], v[200:203], v[72:75]
	v_mfma_f32_16x16x32_bf16 v[124:127], v[212:215], v[156:159], v[124:127]
	v_mfma_f32_16x16x32_bf16 v[120:123], v[220:223], v[156:159], v[120:123]
	v_mfma_f32_16x16x32_bf16 v[108:111], v[212:215], v[172:175], v[108:111]
	v_mfma_f32_16x16x32_bf16 v[104:107], v[220:223], v[172:175], v[104:107]
	v_mfma_f32_16x16x32_bf16 v[92:95], v[212:215], v[196:199], v[92:95]
	v_mfma_f32_16x16x32_bf16 v[88:91], v[220:223], v[196:199], v[88:91]
	v_mfma_f32_16x16x32_bf16 v[76:79], v[212:215], v[204:207], v[76:79]
	v_mfma_f32_16x16x32_bf16 v[72:75], v[220:223], v[204:207], v[72:75]
	s_barrier
	s_mov_b32 m0, s24
	v_lshl_add_u64 v[224:225], s[4:5], 0, v[2:3]
	ds_read_b128 v[152:155], v182 offset:16384
	ds_read_b128 v[156:159], v182 offset:17408
	ds_read_b128 v[160:163], v182 offset:18432
	ds_read_b128 v[172:175], v182 offset:19456
	ds_read_b128 v[176:179], v182 offset:20480
	ds_read_b128 v[196:199], v182 offset:21504
	ds_read_b128 v[200:203], v182 offset:22528
	ds_read_b128 v[204:207], v182 offset:23552
	global_load_lds_dwordx4 v2, s[4:5]
	s_mov_b32 m0, s25
	s_nop 0
	s_add_u32 vcc_lo, s4, s0
	s_addc_u32 vcc_hi, s5, s1
	global_load_lds_dwordx4 v2, vcc
	s_barrier
	s_waitcnt lgkmcnt(0)
	v_mfma_f32_16x16x32_bf16 v[68:71], v[136:139], v[152:155], v[68:71]
	v_mfma_f32_16x16x32_bf16 v[64:67], v[144:147], v[152:155], v[64:67]
	v_mfma_f32_16x16x32_bf16 v[52:55], v[136:139], v[160:163], v[52:55]
	v_mfma_f32_16x16x32_bf16 v[48:51], v[144:147], v[160:163], v[48:51]
	v_mfma_f32_16x16x32_bf16 v[36:39], v[136:139], v[176:179], v[36:39]
	v_mfma_f32_16x16x32_bf16 v[32:35], v[144:147], v[176:179], v[32:35]
	v_mfma_f32_16x16x32_bf16 v[20:23], v[136:139], v[200:203], v[20:23]
	v_mfma_f32_16x16x32_bf16 v[16:19], v[144:147], v[200:203], v[16:19]
	v_mfma_f32_16x16x32_bf16 v[68:71], v[140:143], v[156:159], v[68:71]
	v_mfma_f32_16x16x32_bf16 v[64:67], v[148:151], v[156:159], v[64:67]
	v_mfma_f32_16x16x32_bf16 v[52:55], v[140:143], v[172:175], v[52:55]
	v_mfma_f32_16x16x32_bf16 v[48:51], v[148:151], v[172:175], v[48:51]
	v_mfma_f32_16x16x32_bf16 v[36:39], v[140:143], v[196:199], v[36:39]
	v_mfma_f32_16x16x32_bf16 v[32:35], v[148:151], v[196:199], v[32:35]
	v_mfma_f32_16x16x32_bf16 v[20:23], v[140:143], v[204:207], v[20:23]
	v_mfma_f32_16x16x32_bf16 v[16:19], v[148:151], v[204:207], v[16:19]
	s_barrier
	s_add_i32 s100, s41, s23
	s_mov_b32 m0, s100
	s_nop 0
	s_add_u32 vcc_lo, s20, s42
	s_addc_u32 vcc_hi, s21, s43
	global_load_lds_dwordx4 v164, vcc
	s_add_i32 m0, s100, 0x2000
	s_nop 0
	s_add_u32 vcc_lo, s20, s50
	s_addc_u32 vcc_hi, s21, s51
	global_load_lds_dwordx4 v164, vcc
	s_waitcnt vmcnt(6)
	s_barrier
	v_mfma_f32_16x16x32_bf16 v[60:63], v[208:211], v[152:155], v[60:63]
	v_mfma_f32_16x16x32_bf16 v[56:59], v[216:219], v[152:155], v[56:59]
	v_mfma_f32_16x16x32_bf16 v[44:47], v[208:211], v[160:163], v[44:47]
	v_mfma_f32_16x16x32_bf16 v[40:43], v[216:219], v[160:163], v[40:43]
	v_mfma_f32_16x16x32_bf16 v[28:31], v[208:211], v[176:179], v[28:31]
	v_mfma_f32_16x16x32_bf16 v[24:27], v[216:219], v[176:179], v[24:27]
	v_mfma_f32_16x16x32_bf16 v[12:15], v[208:211], v[200:203], v[12:15]
	v_mfma_f32_16x16x32_bf16 v[8:11], v[216:219], v[200:203], v[8:11]
	v_mfma_f32_16x16x32_bf16 v[60:63], v[212:215], v[156:159], v[60:63]
	v_mfma_f32_16x16x32_bf16 v[56:59], v[220:223], v[156:159], v[56:59]
	v_mfma_f32_16x16x32_bf16 v[44:47], v[212:215], v[172:175], v[44:47]
	v_mfma_f32_16x16x32_bf16 v[40:43], v[220:223], v[172:175], v[40:43]
	v_mfma_f32_16x16x32_bf16 v[28:31], v[212:215], v[196:199], v[28:31]
	v_mfma_f32_16x16x32_bf16 v[24:27], v[220:223], v[196:199], v[24:27]
	v_mfma_f32_16x16x32_bf16 v[12:15], v[212:215], v[204:207], v[12:15]
	v_mfma_f32_16x16x32_bf16 v[8:11], v[220:223], v[204:207], v[8:11]
	s_barrier
	s_add_i32 s100, 0, 0x18000
	ds_read_b128 v[136:139], v255 offset:32768
	ds_read_b128 v[140:143], v255 offset:33792
	ds_read_b128 v[144:147], v255 offset:34816
	ds_read_b128 v[148:151], v255 offset:35840
	s_mov_b32 m0, s26
	ds_read_b128 v[152:155], v182 offset:32768
	ds_read_b128 v[156:159], v182 offset:33792
	ds_read_b128 v[160:163], v182 offset:34816
	ds_read_b128 v[172:175], v182 offset:35840
	ds_read_b128 v[176:179], v182 offset:36864
	ds_read_b128 v[196:199], v182 offset:37888
	ds_read_b128 v[200:203], v182 offset:38912
	ds_read_b128 v[204:207], v182 offset:39936
	s_add_u32 vcc_lo, s4, s42
	s_addc_u32 vcc_hi, s5, s43
	global_load_lds_dwordx4 v2, vcc
	s_mov_b32 m0, s27
	s_nop 0
	s_add_u32 vcc_lo, s4, s50
	s_addc_u32 vcc_hi, s5, s51
	global_load_lds_dwordx4 v2, vcc
	s_waitcnt lgkmcnt(8)
	s_barrier
; #define G_STAGE(bufoff, gbase, o0, h64) do { \
;         __builtin_amdgcn_global_load_lds((const unsigned*)((const char*)(gbase) + (o0)), (LAS unsigned*)(lds + (bufoff) + ldsw), 16, 0, 0); \
;         __builtin_amdgcn_global_load_lds((const unsigned*)((const char*)(gbase) + (h64) + (o0)), (LAS unsigned*)(lds + (bufoff) + ldsw + 8192), 16, 0, 0); } while (0)
; #define G_LDA(dst, b, h) do { _Pragma("unroll") for (int m = 0; m < 4; ++m) _Pragma("unroll") for (int k = 0; k < 2; ++k) dst[m][k] = *(const LAS bf16x8*)(lds + G_SA(b, h) + aoff + m * 2048 + k * 1024); } while (0)
; #define G_LDB(dst, b, h) do { _Pragma("unroll") for (int n = 0; n < 2; ++n) _Pragma("unroll") for (int k = 0; k < 2; ++k) dst[n][k] = *(const LAS bf16x8*)(lds + G_SB(b, h) + boff + n * 2048 + k * 1024); } while (0)
; #define G_WAIT_V(n) asm volatile("s_waitcnt vmcnt(" #n ")" ::: "memory")
; #define G_WAIT_L(n) asm volatile("s_waitcnt lgkmcnt(" #n ")" ::: "memory")
; #define G_BAR __builtin_amdgcn_s_barrier()
; #define G_SCHED __builtin_amdgcn_sched_barrier(0)
;     ...
;             G_WAIT_L(8); G_BAR; G_WAIT_L(0); G_MMA(0, 0, At, B0); G_BAR; G_SCHED;
;             G_LDB(B1, 1, 1); G_STAGE(G_SB(1, 0), b3, cB0, qB);
;             G_BAR; G_WAIT_L(0); G_MMA(0, 1, At, B1); G_BAR;
;             G_LDA(At, 1, 1); G_STAGE(G_SA(1, 0), a3, cA0, qA);
;             G_BAR; G_WAIT_L(0); G_MMA(1, 0, At, B0); G_BAR; G_SCHED;
;             G_STAGE(G_SB(1, 1), b3 + chB, cB0, qB);
;             G_WAIT_V(6); G_BAR; G_MMA(1, 1, At, B1); G_BAR;
	s_waitcnt lgkmcnt(0)
	v_mfma_f32_16x16x32_bf16 v[132:135], v[136:139], v[152:155], v[132:135]
	v_mfma_f32_16x16x32_bf16 v[128:131], v[144:147], v[152:155], v[128:131]
	v_mfma_f32_16x16x32_bf16 v[116:119], v[136:139], v[160:163], v[116:119]
	v_mfma_f32_16x16x32_bf16 v[112:115], v[144:147], v[160:163], v[112:115]
	v_mfma_f32_16x16x32_bf16 v[100:103], v[136:139], v[176:179], v[100:103]
	v_mfma_f32_16x16x32_bf16 v[96:99], v[144:147], v[176:179], v[96:99]
	v_mfma_f32_16x16x32_bf16 v[84:87], v[136:139], v[200:203], v[84:87]
	v_mfma_f32_16x16x32_bf16 v[80:83], v[144:147], v[200:203], v[80:83]
	v_mfma_f32_16x16x32_bf16 v[132:135], v[140:143], v[156:159], v[132:135]
	v_mfma_f32_16x16x32_bf16 v[128:131], v[148:151], v[156:159], v[128:131]
	v_mfma_f32_16x16x32_bf16 v[116:119], v[140:143], v[172:175], v[116:119]
	v_mfma_f32_16x16x32_bf16 v[112:115], v[148:151], v[172:175], v[112:115]
	v_mfma_f32_16x16x32_bf16 v[100:103], v[140:143], v[196:199], v[100:103]
	v_mfma_f32_16x16x32_bf16 v[96:99], v[148:151], v[196:199], v[96:99]
	v_mfma_f32_16x16x32_bf16 v[84:87], v[140:143], v[204:207], v[84:87]
	v_mfma_f32_16x16x32_bf16 v[80:83], v[148:151], v[204:207], v[80:83]
	s_barrier
	s_add_i32 s5, 0, 0x1c000
	s_add_i32 s4, s100, s23
	s_mov_b32 m0, s4
	ds_read_b128 v[208:211], v255 offset:49152
	ds_read_b128 v[212:215], v255 offset:50176
	ds_read_b128 v[216:219], v255 offset:51200
	ds_read_b128 v[220:223], v255 offset:52224
	s_add_u32 vcc_lo, s20, s46
	s_addc_u32 vcc_hi, s21, s47
	global_load_lds_dwordx4 v164, vcc
	s_add_i32 m0, s4, 0x2000
	s_nop 0
	s_add_u32 vcc_lo, s20, s52
	s_addc_u32 vcc_hi, s21, s53
	global_load_lds_dwordx4 v164, vcc
	s_barrier
	s_waitcnt lgkmcnt(0)
	v_mfma_f32_16x16x32_bf16 v[124:127], v[208:211], v[152:155], v[124:127]
	v_mfma_f32_16x16x32_bf16 v[120:123], v[216:219], v[152:155], v[120:123]
	v_mfma_f32_16x16x32_bf16 v[108:111], v[208:211], v[160:163], v[108:111]
	v_mfma_f32_16x16x32_bf16 v[104:107], v[216:219], v[160:163], v[104:107]
	v_mfma_f32_16x16x32_bf16 v[92:95], v[208:211], v[176:179], v[92:95]
	v_mfma_f32_16x16x32_bf16 v[88:91], v[216:219], v[176:179], v[88:91]
	v_mfma_f32_16x16x32_bf16 v[76:79], v[208:211], v[200:203], v[76:79]
	v_mfma_f32_16x16x32_bf16 v[72:75], v[216:219], v[200:203], v[72:75]
	v_mfma_f32_16x16x32_bf16 v[124:127], v[212:215], v[156:159], v[124:127]
	v_mfma_f32_16x16x32_bf16 v[120:123], v[220:223], v[156:159], v[120:123]
	v_mfma_f32_16x16x32_bf16 v[108:111], v[212:215], v[172:175], v[108:111]
	v_mfma_f32_16x16x32_bf16 v[104:107], v[220:223], v[172:175], v[104:107]
	v_mfma_f32_16x16x32_bf16 v[92:95], v[212:215], v[196:199], v[92:95]
	v_mfma_f32_16x16x32_bf16 v[88:91], v[220:223], v[196:199], v[88:91]
	v_mfma_f32_16x16x32_bf16 v[76:79], v[212:215], v[204:207], v[76:79]
	v_mfma_f32_16x16x32_bf16 v[72:75], v[220:223], v[204:207], v[72:75]
	s_barrier
	s_mov_b32 m0, s29
	v_lshl_add_u64 v[226:227], v[224:225], 0, s[46:47]
	ds_read_b128 v[152:155], v182 offset:49152
	ds_read_b128 v[156:159], v182 offset:50176
	ds_read_b128 v[160:163], v182 offset:51200
	ds_read_b128 v[172:175], v182 offset:52224
	ds_read_b128 v[176:179], v182 offset:53248
	ds_read_b128 v[196:199], v182 offset:54272
	ds_read_b128 v[200:203], v182 offset:55296
	ds_read_b128 v[204:207], v182 offset:56320
	global_load_lds_dwordx4 v[226:227], off
	v_lshl_add_u64 v[224:225], v[224:225], 0, s[52:53]
	s_mov_b32 m0, s30
	s_nop 0
	global_load_lds_dwordx4 v[224:225], off
	s_barrier
	s_waitcnt lgkmcnt(0)
	v_mfma_f32_16x16x32_bf16 v[68:71], v[136:139], v[152:155], v[68:71]
	v_mfma_f32_16x16x32_bf16 v[64:67], v[144:147], v[152:155], v[64:67]
	v_mfma_f32_16x16x32_bf16 v[52:55], v[136:139], v[160:163], v[52:55]
	v_mfma_f32_16x16x32_bf16 v[48:51], v[144:147], v[160:163], v[48:51]
	v_mfma_f32_16x16x32_bf16 v[36:39], v[136:139], v[176:179], v[36:39]
	v_mfma_f32_16x16x32_bf16 v[32:35], v[144:147], v[176:179], v[32:35]
	v_mfma_f32_16x16x32_bf16 v[20:23], v[136:139], v[200:203], v[20:23]
	v_mfma_f32_16x16x32_bf16 v[16:19], v[144:147], v[200:203], v[16:19]
	v_mfma_f32_16x16x32_bf16 v[68:71], v[140:143], v[156:159], v[68:71]
	v_mfma_f32_16x16x32_bf16 v[64:67], v[148:151], v[156:159], v[64:67]
	v_mfma_f32_16x16x32_bf16 v[52:55], v[140:143], v[172:175], v[52:55]
	v_mfma_f32_16x16x32_bf16 v[48:51], v[148:151], v[172:175], v[48:51]
	v_mfma_f32_16x16x32_bf16 v[36:39], v[140:143], v[196:199], v[36:39]
	v_mfma_f32_16x16x32_bf16 v[32:35], v[148:151], v[196:199], v[32:35]
	v_mfma_f32_16x16x32_bf16 v[20:23], v[140:143], v[204:207], v[20:23]
	v_mfma_f32_16x16x32_bf16 v[16:19], v[148:151], v[204:207], v[16:19]
	s_barrier
	s_add_i32 s4, s5, s23
	s_mov_b32 m0, s4
	s_nop 0
	s_add_u32 vcc_lo, s20, s54
	s_addc_u32 vcc_hi, s21, s55
	global_load_lds_dwordx4 v164, vcc
	s_add_i32 m0, s4, 0x2000
	s_nop 0
	s_add_u32 vcc_lo, s20, s58
	s_addc_u32 vcc_hi, s21, s59
	global_load_lds_dwordx4 v164, vcc
	s_add_i32 s15, s15, 2
	s_add_u32 s2, s2, 0x100
	s_addc_u32 s3, s3, 0
	s_add_u32 s6, s6, 0x100
	s_addc_u32 s7, s7, 0
	s_cmp_gt_u32 s15, 13
	s_waitcnt vmcnt(6)
	s_barrier
	v_mfma_f32_16x16x32_bf16 v[60:63], v[208:211], v[152:155], v[60:63]
	v_mfma_f32_16x16x32_bf16 v[56:59], v[216:219], v[152:155], v[56:59]
	v_mfma_f32_16x16x32_bf16 v[44:47], v[208:211], v[160:163], v[44:47]
	v_mfma_f32_16x16x32_bf16 v[40:43], v[216:219], v[160:163], v[40:43]
	v_mfma_f32_16x16x32_bf16 v[28:31], v[208:211], v[176:179], v[28:31]
	v_mfma_f32_16x16x32_bf16 v[24:27], v[216:219], v[176:179], v[24:27]
	v_mfma_f32_16x16x32_bf16 v[12:15], v[208:211], v[200:203], v[12:15]
	v_mfma_f32_16x16x32_bf16 v[8:11], v[216:219], v[200:203], v[8:11]
	v_mfma_f32_16x16x32_bf16 v[60:63], v[212:215], v[156:159], v[60:63]
	v_mfma_f32_16x16x32_bf16 v[56:59], v[220:223], v[156:159], v[56:59]
	v_mfma_f32_16x16x32_bf16 v[44:47], v[212:215], v[172:175], v[44:47]
	v_mfma_f32_16x16x32_bf16 v[40:43], v[220:223], v[172:175], v[40:43]
	v_mfma_f32_16x16x32_bf16 v[28:31], v[212:215], v[196:199], v[28:31]
	v_mfma_f32_16x16x32_bf16 v[24:27], v[220:223], v[196:199], v[24:27]
	v_mfma_f32_16x16x32_bf16 v[12:15], v[212:215], v[204:207], v[12:15]
	v_mfma_f32_16x16x32_bf16 v[8:11], v[220:223], v[204:207], v[8:11]
	s_cbranch_scc0 .Ldb_WOUT_cont

; #define G_STAGE(bufoff, gbase, o0, h64) do { \
;         __builtin_amdgcn_global_load_lds((const unsigned*)((const char*)(gbase) + (o0)), (LAS unsigned*)(lds + (bufoff) + ldsw), 16, 0, 0); \
;         __builtin_amdgcn_global_load_lds((const unsigned*)((const char*)(gbase) + (h64) + (o0)), (LAS unsigned*)(lds + (bufoff) + ldsw + 8192), 16, 0, 0); } while (0)
; #define G_LDA(dst, b, h) do { _Pragma("unroll") for (int m = 0; m < 4; ++m) _Pragma("unroll") for (int k = 0; k < 2; ++k) dst[m][k] = *(const LAS bf16x8*)(lds + G_SA(b, h) + aoff + m * 2048 + k * 1024); } while (0)
; #define G_LDB(dst, b, h) do { _Pragma("unroll") for (int n = 0; n < 2; ++n) _Pragma("unroll") for (int k = 0; k < 2; ++k) dst[n][k] = *(const LAS bf16x8*)(lds + G_SB(b, h) + boff + n * 2048 + k * 1024); } while (0)
; #define G_WAIT_V(n) asm volatile("s_waitcnt vmcnt(" #n ")" ::: "memory")
; #define G_WAIT_L(n) asm volatile("s_waitcnt lgkmcnt(" #n ")" ::: "memory")
;     ...
;         for (int t = 0; t < nt; t += 2) {
;             const bool last = (t == nt - 2);
;             const char* a1 = cA + (size_t)(t + 1) * ckA;
;             const char* a2 = last ? nA : cA + (size_t)(t + 2) * ckA; const char* b2 = last ? nB : cB + (size_t)(t + 2) * kB;
;             const char* a3 = a2 + ckA; const char* b3 = b2 + kB;
;             G_LDB(B0, 0, 0); G_SCHED; G_LDA(At, 0, 0); G_STAGE(G_SA(1, 1), a1 + chA, cA0, qA);
;             G_WAIT_L(8); G_BAR; G_WAIT_L(0); G_MMA(0, 0, At, B0); G_BAR; G_SCHED;
;             G_LDB(B1, 0, 1); G_STAGE(G_SB(0, 0), b2, cB0, qB);
;             G_BAR; G_WAIT_L(0); G_MMA(0, 1, At, B1); G_BAR;
;             G_LDA(At, 0, 1); G_STAGE(G_SA(0, 0), a2, cA0, qA);
;             G_BAR; G_WAIT_L(0); G_MMA(1, 0, At, B0); G_BAR; G_SCHED;
;             G_STAGE(G_SB(0, 1), b2 + chB, cB0, qB);
;             G_WAIT_V(6); G_BAR; G_MMA(1, 1, At, B1); G_BAR;
;             G_LDB(B0, 1, 0); G_SCHED; G_LDA(At, 1, 0); G_STAGE(G_SA(0, 1), a2 + chA, cA0, qA);
;             G_WAIT_L(8); G_BAR; G_WAIT_L(0); G_MMA(0, 0, At, B0); G_BAR; G_SCHED;
;     ...
;         if (!(cs.kind == K_MG_B && cur.aux < 2))
; #pragma unroll
;         for (int a = 0; a < 2; ++a)
; #pragma unroll
;             for (int b = 0; b < 2; ++b)
; #pragma unroll
;                 for (int m = 0; m < 4; ++m)
; #pragma unroll
;                     for (int n = 0; n < 2; ++n) acc[a][b][m][n] = (f32x4){0.f, 0.f, 0.f, 0.f};
.LBB0_1119:
	s_add_u32 s2, s16, 0x40080
	s_addc_u32 s3, s17, 0
	s_add_u32 s16, s18, 0x100
	s_addc_u32 s17, s19, 0
	s_mov_b32 s18, -2
	s_mov_b64 s[42:43], 0x40000
	s_mov_b64 s[50:51], 0x60000
	s_mov_b64 s[52:53], 0x20080
	s_mov_b64 s[54:55], 0x40080
	s_mov_b64 s[58:59], 0x60080
	s_cmp_eq_u32 s101, 2
	s_cselect_b32 s101, 0, s101
	v_add_u32_e32 v235, 0x10000, v149
	s_add_u32 s4, s2, 0xfffc0080
	s_addc_u32 s5, s3, -1
	s_add_i32 s19, 0, 0x10000
	ds_read_b128 v[140:143], v235 offset:0
	ds_read_b128 v[144:147], v235 offset:1024
	ds_read_b128 v[152:155], v235 offset:2048
	ds_read_b128 v[156:159], v235 offset:3072
	s_cmp_eq_u32 s18, 12
	s_cselect_b32 s5, s13, s5
	s_cselect_b32 s4, s12, s4
	s_cselect_b32 s41, s15, s17
	s_cselect_b32 s40, s14, s16
	s_add_i32 m0, s26, 0xc000
	ds_read_b128 v[160:163], v150
	ds_read_b128 v[164:167], v150 offset:1024
	ds_read_b128 v[172:175], v150 offset:2048
	ds_read_b128 v[176:179], v150 offset:3072
	ds_read_b128 v[180:183], v150 offset:4096
	ds_read_b128 v[196:199], v150 offset:5120
	ds_read_b128 v[200:203], v150 offset:6144
	ds_read_b128 v[204:207], v150 offset:7168
	global_load_lds_dwordx4 v138, s[2:3]
	s_add_i32 m0, s26, 0xe000
	s_nop 0
	s_add_u32 vcc_lo, s2, s0
	s_addc_u32 vcc_hi, s3, s1
	global_load_lds_dwordx4 v138, vcc
	s_waitcnt lgkmcnt(8)
	s_cmp_eq_u32 s101, 1
	s_cbranch_scc1 .Ldb_FFI_skp
	s_barrier
.Ldb_FFI_skp:
	s_mov_b32 s101, 0
	s_waitcnt lgkmcnt(0)
	v_mfma_f32_16x16x32_bf16 v[132:135], v[140:143], v[160:163], 0
	v_mfma_f32_16x16x32_bf16 v[124:127], v[152:155], v[160:163], 0
	v_mfma_f32_16x16x32_bf16 v[116:119], v[140:143], v[172:175], 0
	v_mfma_f32_16x16x32_bf16 v[108:111], v[152:155], v[172:175], 0
	v_mfma_f32_16x16x32_bf16 v[100:103], v[140:143], v[180:183], 0
	v_mfma_f32_16x16x32_bf16 v[92:95], v[152:155], v[180:183], 0
	v_mfma_f32_16x16x32_bf16 v[84:87], v[140:143], v[200:203], 0
	v_mfma_f32_16x16x32_bf16 v[76:79], v[152:155], v[200:203], 0
	v_mfma_f32_16x16x32_bf16 v[132:135], v[144:147], v[164:167], v[132:135]
	v_mfma_f32_16x16x32_bf16 v[124:127], v[156:159], v[164:167], v[124:127]
	v_mfma_f32_16x16x32_bf16 v[116:119], v[144:147], v[176:179], v[116:119]
	v_mfma_f32_16x16x32_bf16 v[108:111], v[156:159], v[176:179], v[108:111]
	v_mfma_f32_16x16x32_bf16 v[100:103], v[144:147], v[196:199], v[100:103]
	v_mfma_f32_16x16x32_bf16 v[92:95], v[156:159], v[196:199], v[92:95]
	v_mfma_f32_16x16x32_bf16 v[84:87], v[144:147], v[204:207], v[84:87]
	v_mfma_f32_16x16x32_bf16 v[76:79], v[156:159], v[204:207], v[76:79]
	s_barrier
	s_add_i32 s39, 0, 0x14000
	s_add_i32 s19, s19, s21
	s_mov_b32 m0, s19
	ds_read_b128 v[208:211], v235 offset:16384
	ds_read_b128 v[212:215], v235 offset:17408
	ds_read_b128 v[216:219], v235 offset:18432
	ds_read_b128 v[220:223], v235 offset:19456
	global_load_lds_dwordx4 v2, s[40:41]
	s_add_i32 m0, s19, 0x2000
	s_nop 0
	s_add_u32 vcc_lo, s40, s0
	s_addc_u32 vcc_hi, s41, s1
	global_load_lds_dwordx4 v2, vcc
	s_barrier
	s_waitcnt lgkmcnt(0)
	v_mfma_f32_16x16x32_bf16 v[128:131], v[208:211], v[160:163], 0
	v_mfma_f32_16x16x32_bf16 v[120:123], v[216:219], v[160:163], 0
	v_mfma_f32_16x16x32_bf16 v[112:115], v[208:211], v[172:175], 0
	v_mfma_f32_16x16x32_bf16 v[104:107], v[216:219], v[172:175], 0
	v_mfma_f32_16x16x32_bf16 v[96:99], v[208:211], v[180:183], 0
	v_mfma_f32_16x16x32_bf16 v[88:91], v[216:219], v[180:183], 0
	v_mfma_f32_16x16x32_bf16 v[80:83], v[208:211], v[200:203], 0
	v_mfma_f32_16x16x32_bf16 v[72:75], v[216:219], v[200:203], 0
	v_mfma_f32_16x16x32_bf16 v[128:131], v[212:215], v[164:167], v[128:131]
	v_mfma_f32_16x16x32_bf16 v[120:123], v[220:223], v[164:167], v[120:123]
	v_mfma_f32_16x16x32_bf16 v[112:115], v[212:215], v[176:179], v[112:115]
	v_mfma_f32_16x16x32_bf16 v[104:107], v[220:223], v[176:179], v[104:107]
	v_mfma_f32_16x16x32_bf16 v[96:99], v[212:215], v[196:199], v[96:99]
	v_mfma_f32_16x16x32_bf16 v[88:91], v[220:223], v[196:199], v[88:91]
	v_mfma_f32_16x16x32_bf16 v[80:83], v[212:215], v[204:207], v[80:83]
	v_mfma_f32_16x16x32_bf16 v[72:75], v[220:223], v[204:207], v[72:75]
	s_barrier
	s_mov_b32 m0, s26
	v_lshl_add_u64 v[224:225], s[4:5], 0, v[136:137]
	ds_read_b128 v[160:163], v150 offset:16384
	ds_read_b128 v[164:167], v150 offset:17408
	ds_read_b128 v[172:175], v150 offset:18432
	ds_read_b128 v[176:179], v150 offset:19456
	ds_read_b128 v[180:183], v150 offset:20480
	ds_read_b128 v[196:199], v150 offset:21504
	ds_read_b128 v[200:203], v150 offset:22528
	ds_read_b128 v[204:207], v150 offset:23552
	global_load_lds_dwordx4 v136, s[4:5]
	s_mov_b32 m0, s27
	s_nop 0
	s_add_u32 vcc_lo, s4, s0
	s_addc_u32 vcc_hi, s5, s1
	global_load_lds_dwordx4 v136, vcc
	s_barrier
	s_waitcnt lgkmcnt(0)
	v_mfma_f32_16x16x32_bf16 v[68:71], v[140:143], v[160:163], 0
	v_mfma_f32_16x16x32_bf16 v[60:63], v[152:155], v[160:163], 0
	v_mfma_f32_16x16x32_bf16 v[52:55], v[140:143], v[172:175], 0
	v_mfma_f32_16x16x32_bf16 v[44:47], v[152:155], v[172:175], 0
	v_mfma_f32_16x16x32_bf16 v[36:39], v[140:143], v[180:183], 0
	v_mfma_f32_16x16x32_bf16 v[28:31], v[152:155], v[180:183], 0
	v_mfma_f32_16x16x32_bf16 v[20:23], v[140:143], v[200:203], 0
	v_mfma_f32_16x16x32_bf16 v[12:15], v[152:155], v[200:203], 0
	v_mfma_f32_16x16x32_bf16 v[68:71], v[144:147], v[164:167], v[68:71]
	v_mfma_f32_16x16x32_bf16 v[60:63], v[156:159], v[164:167], v[60:63]
	v_mfma_f32_16x16x32_bf16 v[52:55], v[144:147], v[176:179], v[52:55]
	v_mfma_f32_16x16x32_bf16 v[44:47], v[156:159], v[176:179], v[44:47]
	v_mfma_f32_16x16x32_bf16 v[36:39], v[144:147], v[196:199], v[36:39]
	v_mfma_f32_16x16x32_bf16 v[28:31], v[156:159], v[196:199], v[28:31]
	v_mfma_f32_16x16x32_bf16 v[20:23], v[144:147], v[204:207], v[20:23]
	v_mfma_f32_16x16x32_bf16 v[12:15], v[156:159], v[204:207], v[12:15]
	s_barrier
; #define G_STAGE(bufoff, gbase, o0, h64) do { \
;         __builtin_amdgcn_global_load_lds((const unsigned*)((const char*)(gbase) + (o0)), (LAS unsigned*)(lds + (bufoff) + ldsw), 16, 0, 0); \
;         __builtin_amdgcn_global_load_lds((const unsigned*)((const char*)(gbase) + (h64) + (o0)), (LAS unsigned*)(lds + (bufoff) + ldsw + 8192), 16, 0, 0); } while (0)
; #define G_LDA(dst, b, h) do { _Pragma("unroll") for (int m = 0; m < 4; ++m) _Pragma("unroll") for (int k = 0; k < 2; ++k) dst[m][k] = *(const LAS bf16x8*)(lds + G_SA(b, h) + aoff + m * 2048 + k * 1024); } while (0)
; #define G_LDB(dst, b, h) do { _Pragma("unroll") for (int n = 0; n < 2; ++n) _Pragma("unroll") for (int k = 0; k < 2; ++k) dst[n][k] = *(const LAS bf16x8*)(lds + G_SB(b, h) + boff + n * 2048 + k * 1024); } while (0)
; #define G_WAIT_V(n) asm volatile("s_waitcnt vmcnt(" #n ")" ::: "memory")
; #define G_WAIT_L(n) asm volatile("s_waitcnt lgkmcnt(" #n ")" ::: "memory")
; #define G_BAR __builtin_amdgcn_s_barrier()
; #define G_SCHED __builtin_amdgcn_sched_barrier(0)
;     ...
;             G_STAGE(G_SB(0, 1), b2 + chB, cB0, qB);
;             G_WAIT_V(6); G_BAR; G_MMA(1, 1, At, B1); G_BAR;
;             G_LDB(B0, 1, 0); G_SCHED; G_LDA(At, 1, 0); G_STAGE(G_SA(0, 1), a2 + chA, cA0, qA);
;             G_WAIT_L(8); G_BAR; G_WAIT_L(0); G_MMA(0, 0, At, B0); G_BAR; G_SCHED;
;             G_LDB(B1, 1, 1); G_STAGE(G_SB(1, 0), b3, cB0, qB);
;             G_BAR; G_WAIT_L(0); G_MMA(0, 1, At, B1); G_BAR;
;             G_LDA(At, 1, 1); G_STAGE(G_SA(1, 0), a3, cA0, qA);
;             G_BAR; G_WAIT_L(0); G_MMA(1, 0, At, B0); G_BAR; G_SCHED;
	s_add_i32 s100, s39, s21
	s_mov_b32 m0, s100
	s_nop 0
	s_add_u32 vcc_lo, s40, s42
	s_addc_u32 vcc_hi, s41, s43
	global_load_lds_dwordx4 v2, vcc
	s_add_i32 m0, s100, 0x2000
	s_nop 0
	s_add_u32 vcc_lo, s40, s50
	s_addc_u32 vcc_hi, s41, s51
	global_load_lds_dwordx4 v2, vcc
	s_waitcnt vmcnt(6)
	s_barrier
	v_mfma_f32_16x16x32_bf16 v[64:67], v[208:211], v[160:163], 0
	v_mfma_f32_16x16x32_bf16 v[56:59], v[216:219], v[160:163], 0
	v_mfma_f32_16x16x32_bf16 v[48:51], v[208:211], v[172:175], 0
	v_mfma_f32_16x16x32_bf16 v[40:43], v[216:219], v[172:175], 0
	v_mfma_f32_16x16x32_bf16 v[32:35], v[208:211], v[180:183], 0
	v_mfma_f32_16x16x32_bf16 v[24:27], v[216:219], v[180:183], 0
	v_mfma_f32_16x16x32_bf16 v[16:19], v[208:211], v[200:203], 0
	v_mfma_f32_16x16x32_bf16 v[8:11], v[216:219], v[200:203], 0
	v_mfma_f32_16x16x32_bf16 v[64:67], v[212:215], v[164:167], v[64:67]
	v_mfma_f32_16x16x32_bf16 v[56:59], v[220:223], v[164:167], v[56:59]
	v_mfma_f32_16x16x32_bf16 v[48:51], v[212:215], v[176:179], v[48:51]
	v_mfma_f32_16x16x32_bf16 v[40:43], v[220:223], v[176:179], v[40:43]
	v_mfma_f32_16x16x32_bf16 v[32:35], v[212:215], v[196:199], v[32:35]
	v_mfma_f32_16x16x32_bf16 v[24:27], v[220:223], v[196:199], v[24:27]
	v_mfma_f32_16x16x32_bf16 v[16:19], v[212:215], v[204:207], v[16:19]
	v_mfma_f32_16x16x32_bf16 v[8:11], v[220:223], v[204:207], v[8:11]
	s_barrier
	s_add_i32 s100, 0, 0x18000
	ds_read_b128 v[140:143], v235 offset:32768
	ds_read_b128 v[144:147], v235 offset:33792
	ds_read_b128 v[152:155], v235 offset:34816
	ds_read_b128 v[156:159], v235 offset:35840
	s_mov_b32 m0, s29
	ds_read_b128 v[160:163], v150 offset:32768
	ds_read_b128 v[164:167], v150 offset:33792
	ds_read_b128 v[172:175], v150 offset:34816
	ds_read_b128 v[176:179], v150 offset:35840
	ds_read_b128 v[180:183], v150 offset:36864
	ds_read_b128 v[196:199], v150 offset:37888
	ds_read_b128 v[200:203], v150 offset:38912
	ds_read_b128 v[204:207], v150 offset:39936
	s_add_u32 vcc_lo, s4, s42
	s_addc_u32 vcc_hi, s5, s43
	global_load_lds_dwordx4 v136, vcc
	s_mov_b32 m0, s30
	s_nop 0
	s_add_u32 vcc_lo, s4, s50
	s_addc_u32 vcc_hi, s5, s51
	global_load_lds_dwordx4 v136, vcc
	s_waitcnt lgkmcnt(8)
	s_barrier
	s_waitcnt lgkmcnt(0)
	v_mfma_f32_16x16x32_bf16 v[132:135], v[140:143], v[160:163], v[132:135]
	v_mfma_f32_16x16x32_bf16 v[124:127], v[152:155], v[160:163], v[124:127]
	v_mfma_f32_16x16x32_bf16 v[116:119], v[140:143], v[172:175], v[116:119]
	v_mfma_f32_16x16x32_bf16 v[108:111], v[152:155], v[172:175], v[108:111]
	v_mfma_f32_16x16x32_bf16 v[100:103], v[140:143], v[180:183], v[100:103]
	v_mfma_f32_16x16x32_bf16 v[92:95], v[152:155], v[180:183], v[92:95]
	v_mfma_f32_16x16x32_bf16 v[84:87], v[140:143], v[200:203], v[84:87]
	v_mfma_f32_16x16x32_bf16 v[76:79], v[152:155], v[200:203], v[76:79]
	v_mfma_f32_16x16x32_bf16 v[132:135], v[144:147], v[164:167], v[132:135]
	v_mfma_f32_16x16x32_bf16 v[124:127], v[156:159], v[164:167], v[124:127]
	v_mfma_f32_16x16x32_bf16 v[116:119], v[144:147], v[176:179], v[116:119]
	v_mfma_f32_16x16x32_bf16 v[108:111], v[156:159], v[176:179], v[108:111]
	v_mfma_f32_16x16x32_bf16 v[100:103], v[144:147], v[196:199], v[100:103]
	v_mfma_f32_16x16x32_bf16 v[92:95], v[156:159], v[196:199], v[92:95]
	v_mfma_f32_16x16x32_bf16 v[84:87], v[144:147], v[204:207], v[84:87]
	v_mfma_f32_16x16x32_bf16 v[76:79], v[156:159], v[204:207], v[76:79]
	s_barrier
	s_add_i32 s5, 0, 0x1c000
	s_add_i32 s4, s100, s21
	s_mov_b32 m0, s4
	ds_read_b128 v[208:211], v235 offset:49152
	ds_read_b128 v[212:215], v235 offset:50176
	ds_read_b128 v[216:219], v235 offset:51200
	ds_read_b128 v[220:223], v235 offset:52224
	s_add_u32 vcc_lo, s40, s46
	s_addc_u32 vcc_hi, s41, s47
	global_load_lds_dwordx4 v2, vcc
	s_add_i32 m0, s4, 0x2000
	s_nop 0
	s_add_u32 vcc_lo, s40, s52
	s_addc_u32 vcc_hi, s41, s53
	global_load_lds_dwordx4 v2, vcc
	s_barrier
	s_waitcnt lgkmcnt(0)
	v_mfma_f32_16x16x32_bf16 v[128:131], v[208:211], v[160:163], v[128:131]
	v_mfma_f32_16x16x32_bf16 v[120:123], v[216:219], v[160:163], v[120:123]
	v_mfma_f32_16x16x32_bf16 v[112:115], v[208:211], v[172:175], v[112:115]
	v_mfma_f32_16x16x32_bf16 v[104:107], v[216:219], v[172:175], v[104:107]
	v_mfma_f32_16x16x32_bf16 v[96:99], v[208:211], v[180:183], v[96:99]
	v_mfma_f32_16x16x32_bf16 v[88:91], v[216:219], v[180:183], v[88:91]
	v_mfma_f32_16x16x32_bf16 v[80:83], v[208:211], v[200:203], v[80:83]
	v_mfma_f32_16x16x32_bf16 v[72:75], v[216:219], v[200:203], v[72:75]
	v_mfma_f32_16x16x32_bf16 v[128:131], v[212:215], v[164:167], v[128:131]
	v_mfma_f32_16x16x32_bf16 v[120:123], v[220:223], v[164:167], v[120:123]
	v_mfma_f32_16x16x32_bf16 v[112:115], v[212:215], v[176:179], v[112:115]
	v_mfma_f32_16x16x32_bf16 v[104:107], v[220:223], v[176:179], v[104:107]
	v_mfma_f32_16x16x32_bf16 v[96:99], v[212:215], v[196:199], v[96:99]
	v_mfma_f32_16x16x32_bf16 v[88:91], v[220:223], v[196:199], v[88:91]
	v_mfma_f32_16x16x32_bf16 v[80:83], v[212:215], v[204:207], v[80:83]
	v_mfma_f32_16x16x32_bf16 v[72:75], v[220:223], v[204:207], v[72:75]
	s_barrier
	s_mov_b32 m0, s31
	v_lshl_add_u64 v[226:227], v[224:225], 0, s[46:47]
	ds_read_b128 v[160:163], v150 offset:49152
	ds_read_b128 v[164:167], v150 offset:50176
	ds_read_b128 v[172:175], v150 offset:51200
	ds_read_b128 v[176:179], v150 offset:52224
	ds_read_b128 v[180:183], v150 offset:53248
	ds_read_b128 v[196:199], v150 offset:54272
	ds_read_b128 v[200:203], v150 offset:55296
	ds_read_b128 v[204:207], v150 offset:56320
	global_load_lds_dwordx4 v[226:227], off
	v_lshl_add_u64 v[224:225], v[224:225], 0, s[52:53]
	s_mov_b32 m0, s34
	s_nop 0
	global_load_lds_dwordx4 v[224:225], off
	s_barrier
; #define G_STAGE(bufoff, gbase, o0, h64) do { \
;         __builtin_amdgcn_global_load_lds((const unsigned*)((const char*)(gbase) + (o0)), (LAS unsigned*)(lds + (bufoff) + ldsw), 16, 0, 0); \
;         __builtin_amdgcn_global_load_lds((const unsigned*)((const char*)(gbase) + (h64) + (o0)), (LAS unsigned*)(lds + (bufoff) + ldsw + 8192), 16, 0, 0); } while (0)
; #define G_LDA(dst, b, h) do { _Pragma("unroll") for (int m = 0; m < 4; ++m) _Pragma("unroll") for (int k = 0; k < 2; ++k) dst[m][k] = *(const LAS bf16x8*)(lds + G_SA(b, h) + aoff + m * 2048 + k * 1024); } while (0)
; #define G_LDB(dst, b, h) do { _Pragma("unroll") for (int n = 0; n < 2; ++n) _Pragma("unroll") for (int k = 0; k < 2; ++k) dst[n][k] = *(const LAS bf16x8*)(lds + G_SB(b, h) + boff + n * 2048 + k * 1024); } while (0)
; #define G_WAIT_V(n) asm volatile("s_waitcnt vmcnt(" #n ")" ::: "memory")
; #define G_BAR __builtin_amdgcn_s_barrier()
;     ...
;         for (int t = 0; t < nt; t += 2) {
;             const bool last = (t == nt - 2);
;             const char* a1 = cA + (size_t)(t + 1) * ckA;
;             const char* a2 = last ? nA : cA + (size_t)(t + 2) * ckA; const char* b2 = last ? nB : cB + (size_t)(t + 2) * kB;
;             const char* a3 = a2 + ckA; const char* b3 = b2 + kB;
;             G_LDB(B0, 0, 0); G_SCHED; G_LDA(At, 0, 0); G_STAGE(G_SA(1, 1), a1 + chA, cA0, qA);
;             G_WAIT_L(8); G_BAR; G_WAIT_L(0); G_MMA(0, 0, At, B0); G_BAR; G_SCHED;
;             G_LDB(B1, 0, 1); G_STAGE(G_SB(0, 0), b2, cB0, qB);
;             G_BAR; G_WAIT_L(0); G_MMA(0, 1, At, B1); G_BAR;
;             G_LDA(At, 0, 1); G_STAGE(G_SA(0, 0), a2, cA0, qA);
;             G_BAR; G_WAIT_L(0); G_MMA(1, 0, At, B0); G_BAR; G_SCHED;
;             G_STAGE(G_SB(0, 1), b2 + chB, cB0, qB);
;             G_WAIT_V(6); G_BAR; G_MMA(1, 1, At, B1); G_BAR;
;             G_LDB(B0, 1, 0); G_SCHED; G_LDA(At, 1, 0); G_STAGE(G_SA(0, 1), a2 + chA, cA0, qA);
;             G_WAIT_L(8); G_BAR; G_WAIT_L(0); G_MMA(0, 0, At, B0); G_BAR; G_SCHED;
;             G_LDB(B1, 1, 1); G_STAGE(G_SB(1, 0), b3, cB0, qB);
;             G_BAR; G_WAIT_L(0); G_MMA(0, 1, At, B1); G_BAR;
;             G_LDA(At, 1, 1); G_STAGE(G_SA(1, 0), a3, cA0, qA);
;             G_BAR; G_WAIT_L(0); G_MMA(1, 0, At, B0); G_BAR; G_SCHED;
;             G_STAGE(G_SB(1, 1), b3 + chB, cB0, qB);
;             G_WAIT_V(6); G_BAR; G_MMA(1, 1, At, B1); G_BAR;
	s_waitcnt lgkmcnt(0)
	v_mfma_f32_16x16x32_bf16 v[68:71], v[140:143], v[160:163], v[68:71]
	v_mfma_f32_16x16x32_bf16 v[60:63], v[152:155], v[160:163], v[60:63]
	v_mfma_f32_16x16x32_bf16 v[52:55], v[140:143], v[172:175], v[52:55]
	v_mfma_f32_16x16x32_bf16 v[44:47], v[152:155], v[172:175], v[44:47]
	v_mfma_f32_16x16x32_bf16 v[36:39], v[140:143], v[180:183], v[36:39]
	v_mfma_f32_16x16x32_bf16 v[28:31], v[152:155], v[180:183], v[28:31]
	v_mfma_f32_16x16x32_bf16 v[20:23], v[140:143], v[200:203], v[20:23]
	v_mfma_f32_16x16x32_bf16 v[12:15], v[152:155], v[200:203], v[12:15]
	v_mfma_f32_16x16x32_bf16 v[68:71], v[144:147], v[164:167], v[68:71]
	v_mfma_f32_16x16x32_bf16 v[60:63], v[156:159], v[164:167], v[60:63]
	v_mfma_f32_16x16x32_bf16 v[52:55], v[144:147], v[176:179], v[52:55]
	v_mfma_f32_16x16x32_bf16 v[44:47], v[156:159], v[176:179], v[44:47]
	v_mfma_f32_16x16x32_bf16 v[36:39], v[144:147], v[196:199], v[36:39]
	v_mfma_f32_16x16x32_bf16 v[28:31], v[156:159], v[196:199], v[28:31]
	v_mfma_f32_16x16x32_bf16 v[20:23], v[144:147], v[204:207], v[20:23]
	v_mfma_f32_16x16x32_bf16 v[12:15], v[156:159], v[204:207], v[12:15]
	s_barrier
	s_add_i32 s4, s5, s21
	s_mov_b32 m0, s4
	s_nop 0
	s_add_u32 vcc_lo, s40, s54
	s_addc_u32 vcc_hi, s41, s55
	global_load_lds_dwordx4 v2, vcc
	s_add_i32 m0, s4, 0x2000
	s_nop 0
	s_add_u32 vcc_lo, s40, s58
	s_addc_u32 vcc_hi, s41, s59
	global_load_lds_dwordx4 v2, vcc
	s_add_i32 s18, s18, 2
	s_add_u32 s2, s2, 0x100
	s_addc_u32 s3, s3, 0
	s_add_u32 s16, s16, 0x100
	s_addc_u32 s17, s17, 0
	s_cmp_gt_u32 s18, 13
	s_waitcnt vmcnt(6)
	s_barrier
	v_mfma_f32_16x16x32_bf16 v[64:67], v[208:211], v[160:163], v[64:67]
	v_mfma_f32_16x16x32_bf16 v[56:59], v[216:219], v[160:163], v[56:59]
	v_mfma_f32_16x16x32_bf16 v[48:51], v[208:211], v[172:175], v[48:51]
	v_mfma_f32_16x16x32_bf16 v[40:43], v[216:219], v[172:175], v[40:43]
	v_mfma_f32_16x16x32_bf16 v[32:35], v[208:211], v[180:183], v[32:35]
	v_mfma_f32_16x16x32_bf16 v[24:27], v[216:219], v[180:183], v[24:27]
	v_mfma_f32_16x16x32_bf16 v[16:19], v[208:211], v[200:203], v[16:19]
	v_mfma_f32_16x16x32_bf16 v[8:11], v[216:219], v[200:203], v[8:11]
	v_mfma_f32_16x16x32_bf16 v[64:67], v[212:215], v[164:167], v[64:67]
	v_mfma_f32_16x16x32_bf16 v[56:59], v[220:223], v[164:167], v[56:59]
	v_mfma_f32_16x16x32_bf16 v[48:51], v[212:215], v[176:179], v[48:51]
	v_mfma_f32_16x16x32_bf16 v[40:43], v[220:223], v[176:179], v[40:43]
	v_mfma_f32_16x16x32_bf16 v[32:35], v[212:215], v[196:199], v[32:35]
	v_mfma_f32_16x16x32_bf16 v[24:27], v[220:223], v[196:199], v[24:27]
	v_mfma_f32_16x16x32_bf16 v[16:19], v[212:215], v[204:207], v[16:19]
	v_mfma_f32_16x16x32_bf16 v[8:11], v[220:223], v[204:207], v[8:11]
	s_cbranch_scc0 .Ldb_FFI_cont
	s_branch .Ldb_FFI_xl
.LBB0_1120:
	s_add_u32 s4, s2, 0xfffc0080
	s_addc_u32 s5, s3, -1
	s_add_i32 s19, 0, 0x10000
	ds_read_b128 v[140:143], v235 offset:0
	ds_read_b128 v[144:147], v235 offset:1024
	ds_read_b128 v[152:155], v235 offset:2048
	ds_read_b128 v[156:159], v235 offset:3072
	s_cmp_eq_u32 s18, 12
	s_cselect_b32 s5, s13, s5
	s_cselect_b32 s4, s12, s4
	s_cselect_b32 s41, s15, s17
	s_cselect_b32 s40, s14, s16
	s_add_i32 m0, s26, 0xc000
	ds_read_b128 v[160:163], v150
	ds_read_b128 v[164:167], v150 offset:1024
	ds_read_b128 v[172:175], v150 offset:2048
	ds_read_b128 v[176:179], v150 offset:3072
	ds_read_b128 v[180:183], v150 offset:4096
	ds_read_b128 v[196:199], v150 offset:5120
	ds_read_b128 v[200:203], v150 offset:6144
	ds_read_b128 v[204:207], v150 offset:7168
	global_load_lds_dwordx4 v138, s[2:3]
	s_add_i32 m0, s26, 0xe000
	s_nop 0
	s_add_u32 vcc_lo, s2, s0
	s_addc_u32 vcc_hi, s3, s1
	global_load_lds_dwordx4 v138, vcc
	s_waitcnt lgkmcnt(8)
	s_barrier
	s_waitcnt lgkmcnt(0)
	v_mfma_f32_16x16x32_bf16 v[132:135], v[140:143], v[160:163], v[132:135]
	v_mfma_f32_16x16x32_bf16 v[124:127], v[152:155], v[160:163], v[124:127]
	v_mfma_f32_16x16x32_bf16 v[116:119], v[140:143], v[172:175], v[116:119]
	v_mfma_f32_16x16x32_bf16 v[108:111], v[152:155], v[172:175], v[108:111]
	v_mfma_f32_16x16x32_bf16 v[100:103], v[140:143], v[180:183], v[100:103]
	v_mfma_f32_16x16x32_bf16 v[92:95], v[152:155], v[180:183], v[92:95]
	v_mfma_f32_16x16x32_bf16 v[84:87], v[140:143], v[200:203], v[84:87]
	v_mfma_f32_16x16x32_bf16 v[76:79], v[152:155], v[200:203], v[76:79]
	v_mfma_f32_16x16x32_bf16 v[132:135], v[144:147], v[164:167], v[132:135]
	v_mfma_f32_16x16x32_bf16 v[124:127], v[156:159], v[164:167], v[124:127]
	v_mfma_f32_16x16x32_bf16 v[116:119], v[144:147], v[176:179], v[116:119]
	v_mfma_f32_16x16x32_bf16 v[108:111], v[156:159], v[176:179], v[108:111]
	v_mfma_f32_16x16x32_bf16 v[100:103], v[144:147], v[196:199], v[100:103]
	v_mfma_f32_16x16x32_bf16 v[92:95], v[156:159], v[196:199], v[92:95]
	v_mfma_f32_16x16x32_bf16 v[84:87], v[144:147], v[204:207], v[84:87]
	v_mfma_f32_16x16x32_bf16 v[76:79], v[156:159], v[204:207], v[76:79]
	s_barrier
	s_add_i32 s39, 0, 0x14000
	s_add_i32 s19, s19, s21
	s_mov_b32 m0, s19
	ds_read_b128 v[208:211], v235 offset:16384
	ds_read_b128 v[212:215], v235 offset:17408
	ds_read_b128 v[216:219], v235 offset:18432
	ds_read_b128 v[220:223], v235 offset:19456
	global_load_lds_dwordx4 v2, s[40:41]
	s_add_i32 m0, s19, 0x2000
	s_nop 0
	s_add_u32 vcc_lo, s40, s0
	s_addc_u32 vcc_hi, s41, s1
	global_load_lds_dwordx4 v2, vcc
	s_barrier
; #define G_STAGE(bufoff, gbase, o0, h64) do { \
;         __builtin_amdgcn_global_load_lds((const unsigned*)((const char*)(gbase) + (o0)), (LAS unsigned*)(lds + (bufoff) + ldsw), 16, 0, 0); \
;         __builtin_amdgcn_global_load_lds((const unsigned*)((const char*)(gbase) + (h64) + (o0)), (LAS unsigned*)(lds + (bufoff) + ldsw + 8192), 16, 0, 0); } while (0)
; #define G_LDA(dst, b, h) do { _Pragma("unroll") for (int m = 0; m < 4; ++m) _Pragma("unroll") for (int k = 0; k < 2; ++k) dst[m][k] = *(const LAS bf16x8*)(lds + G_SA(b, h) + aoff + m * 2048 + k * 1024); } while (0)
; #define G_LDB(dst, b, h) do { _Pragma("unroll") for (int n = 0; n < 2; ++n) _Pragma("unroll") for (int k = 0; k < 2; ++k) dst[n][k] = *(const LAS bf16x8*)(lds + G_SB(b, h) + boff + n * 2048 + k * 1024); } while (0)
; #define G_WAIT_V(n) asm volatile("s_waitcnt vmcnt(" #n ")" ::: "memory")
; #define G_WAIT_L(n) asm volatile("s_waitcnt lgkmcnt(" #n ")" ::: "memory")
; #define G_BAR __builtin_amdgcn_s_barrier()
; #define G_SCHED __builtin_amdgcn_sched_barrier(0)
;     ...
;             G_BAR; G_WAIT_L(0); G_MMA(0, 1, At, B1); G_BAR;
;             G_LDA(At, 0, 1); G_STAGE(G_SA(0, 0), a2, cA0, qA);
;             G_BAR; G_WAIT_L(0); G_MMA(1, 0, At, B0); G_BAR; G_SCHED;
;             G_STAGE(G_SB(0, 1), b2 + chB, cB0, qB);
;             G_WAIT_V(6); G_BAR; G_MMA(1, 1, At, B1); G_BAR;
;             G_LDB(B0, 1, 0); G_SCHED; G_LDA(At, 1, 0); G_STAGE(G_SA(0, 1), a2 + chA, cA0, qA);
;             G_WAIT_L(8); G_BAR; G_WAIT_L(0); G_MMA(0, 0, At, B0); G_BAR; G_SCHED;
;             G_LDB(B1, 1, 1); G_STAGE(G_SB(1, 0), b3, cB0, qB);
;             G_BAR; G_WAIT_L(0); G_MMA(0, 1, At, B1); G_BAR;
;             G_LDA(At, 1, 1); G_STAGE(G_SA(1, 0), a3, cA0, qA);
;             G_BAR; G_WAIT_L(0); G_MMA(1, 0, At, B0); G_BAR; G_SCHED;
	s_waitcnt lgkmcnt(0)
	v_mfma_f32_16x16x32_bf16 v[128:131], v[208:211], v[160:163], v[128:131]
	v_mfma_f32_16x16x32_bf16 v[120:123], v[216:219], v[160:163], v[120:123]
	v_mfma_f32_16x16x32_bf16 v[112:115], v[208:211], v[172:175], v[112:115]
	v_mfma_f32_16x16x32_bf16 v[104:107], v[216:219], v[172:175], v[104:107]
	v_mfma_f32_16x16x32_bf16 v[96:99], v[208:211], v[180:183], v[96:99]
	v_mfma_f32_16x16x32_bf16 v[88:91], v[216:219], v[180:183], v[88:91]
	v_mfma_f32_16x16x32_bf16 v[80:83], v[208:211], v[200:203], v[80:83]
	v_mfma_f32_16x16x32_bf16 v[72:75], v[216:219], v[200:203], v[72:75]
	v_mfma_f32_16x16x32_bf16 v[128:131], v[212:215], v[164:167], v[128:131]
	v_mfma_f32_16x16x32_bf16 v[120:123], v[220:223], v[164:167], v[120:123]
	v_mfma_f32_16x16x32_bf16 v[112:115], v[212:215], v[176:179], v[112:115]
	v_mfma_f32_16x16x32_bf16 v[104:107], v[220:223], v[176:179], v[104:107]
	v_mfma_f32_16x16x32_bf16 v[96:99], v[212:215], v[196:199], v[96:99]
	v_mfma_f32_16x16x32_bf16 v[88:91], v[220:223], v[196:199], v[88:91]
	v_mfma_f32_16x16x32_bf16 v[80:83], v[212:215], v[204:207], v[80:83]
	v_mfma_f32_16x16x32_bf16 v[72:75], v[220:223], v[204:207], v[72:75]
	s_barrier
	s_mov_b32 m0, s26
	v_lshl_add_u64 v[224:225], s[4:5], 0, v[136:137]
	ds_read_b128 v[160:163], v150 offset:16384
	ds_read_b128 v[164:167], v150 offset:17408
	ds_read_b128 v[172:175], v150 offset:18432
	ds_read_b128 v[176:179], v150 offset:19456
	ds_read_b128 v[180:183], v150 offset:20480
	ds_read_b128 v[196:199], v150 offset:21504
	ds_read_b128 v[200:203], v150 offset:22528
	ds_read_b128 v[204:207], v150 offset:23552
	global_load_lds_dwordx4 v136, s[4:5]
	s_mov_b32 m0, s27
	s_nop 0
	s_add_u32 vcc_lo, s4, s0
	s_addc_u32 vcc_hi, s5, s1
	global_load_lds_dwordx4 v136, vcc
	s_barrier
	s_waitcnt lgkmcnt(0)
	v_mfma_f32_16x16x32_bf16 v[68:71], v[140:143], v[160:163], v[68:71]
	v_mfma_f32_16x16x32_bf16 v[60:63], v[152:155], v[160:163], v[60:63]
	v_mfma_f32_16x16x32_bf16 v[52:55], v[140:143], v[172:175], v[52:55]
	v_mfma_f32_16x16x32_bf16 v[44:47], v[152:155], v[172:175], v[44:47]
	v_mfma_f32_16x16x32_bf16 v[36:39], v[140:143], v[180:183], v[36:39]
	v_mfma_f32_16x16x32_bf16 v[28:31], v[152:155], v[180:183], v[28:31]
	v_mfma_f32_16x16x32_bf16 v[20:23], v[140:143], v[200:203], v[20:23]
	v_mfma_f32_16x16x32_bf16 v[12:15], v[152:155], v[200:203], v[12:15]
	v_mfma_f32_16x16x32_bf16 v[68:71], v[144:147], v[164:167], v[68:71]
	v_mfma_f32_16x16x32_bf16 v[60:63], v[156:159], v[164:167], v[60:63]
	v_mfma_f32_16x16x32_bf16 v[52:55], v[144:147], v[176:179], v[52:55]
	v_mfma_f32_16x16x32_bf16 v[44:47], v[156:159], v[176:179], v[44:47]
	v_mfma_f32_16x16x32_bf16 v[36:39], v[144:147], v[196:199], v[36:39]
	v_mfma_f32_16x16x32_bf16 v[28:31], v[156:159], v[196:199], v[28:31]
	v_mfma_f32_16x16x32_bf16 v[20:23], v[144:147], v[204:207], v[20:23]
	v_mfma_f32_16x16x32_bf16 v[12:15], v[156:159], v[204:207], v[12:15]
	s_barrier
	s_add_i32 s100, s39, s21
	s_mov_b32 m0, s100
	s_nop 0
	s_add_u32 vcc_lo, s40, s42
	s_addc_u32 vcc_hi, s41, s43
	global_load_lds_dwordx4 v2, vcc
	s_add_i32 m0, s100, 0x2000
	s_nop 0
	s_add_u32 vcc_lo, s40, s50
	s_addc_u32 vcc_hi, s41, s51
	global_load_lds_dwordx4 v2, vcc
	s_waitcnt vmcnt(6)
	s_barrier
	v_mfma_f32_16x16x32_bf16 v[64:67], v[208:211], v[160:163], v[64:67]
	v_mfma_f32_16x16x32_bf16 v[56:59], v[216:219], v[160:163], v[56:59]
	v_mfma_f32_16x16x32_bf16 v[48:51], v[208:211], v[172:175], v[48:51]
	v_mfma_f32_16x16x32_bf16 v[40:43], v[216:219], v[172:175], v[40:43]
	v_mfma_f32_16x16x32_bf16 v[32:35], v[208:211], v[180:183], v[32:35]
	v_mfma_f32_16x16x32_bf16 v[24:27], v[216:219], v[180:183], v[24:27]
	v_mfma_f32_16x16x32_bf16 v[16:19], v[208:211], v[200:203], v[16:19]
	v_mfma_f32_16x16x32_bf16 v[8:11], v[216:219], v[200:203], v[8:11]
	v_mfma_f32_16x16x32_bf16 v[64:67], v[212:215], v[164:167], v[64:67]
	v_mfma_f32_16x16x32_bf16 v[56:59], v[220:223], v[164:167], v[56:59]
	v_mfma_f32_16x16x32_bf16 v[48:51], v[212:215], v[176:179], v[48:51]
	v_mfma_f32_16x16x32_bf16 v[40:43], v[220:223], v[176:179], v[40:43]
	v_mfma_f32_16x16x32_bf16 v[32:35], v[212:215], v[196:199], v[32:35]
	v_mfma_f32_16x16x32_bf16 v[24:27], v[220:223], v[196:199], v[24:27]
	v_mfma_f32_16x16x32_bf16 v[16:19], v[212:215], v[204:207], v[16:19]
	v_mfma_f32_16x16x32_bf16 v[8:11], v[220:223], v[204:207], v[8:11]
	s_barrier
	s_add_i32 s100, 0, 0x18000
	ds_read_b128 v[140:143], v235 offset:32768
	ds_read_b128 v[144:147], v235 offset:33792
	ds_read_b128 v[152:155], v235 offset:34816
	ds_read_b128 v[156:159], v235 offset:35840
	s_mov_b32 m0, s29
	ds_read_b128 v[160:163], v150 offset:32768
	ds_read_b128 v[164:167], v150 offset:33792
	ds_read_b128 v[172:175], v150 offset:34816
	ds_read_b128 v[176:179], v150 offset:35840
	ds_read_b128 v[180:183], v150 offset:36864
	ds_read_b128 v[196:199], v150 offset:37888
	ds_read_b128 v[200:203], v150 offset:38912
	ds_read_b128 v[204:207], v150 offset:39936
	s_add_u32 vcc_lo, s4, s42
	s_addc_u32 vcc_hi, s5, s43
	global_load_lds_dwordx4 v136, vcc
	s_mov_b32 m0, s30
	s_nop 0
	s_add_u32 vcc_lo, s4, s50
	s_addc_u32 vcc_hi, s5, s51
	global_load_lds_dwordx4 v136, vcc
	s_waitcnt lgkmcnt(8)
	s_barrier
; #define G_STAGE(bufoff, gbase, o0, h64) do { \
;         __builtin_amdgcn_global_load_lds((const unsigned*)((const char*)(gbase) + (o0)), (LAS unsigned*)(lds + (bufoff) + ldsw), 16, 0, 0); \
;         __builtin_amdgcn_global_load_lds((const unsigned*)((const char*)(gbase) + (h64) + (o0)), (LAS unsigned*)(lds + (bufoff) + ldsw + 8192), 16, 0, 0); } while (0)
; #define G_LDA(dst, b, h) do { _Pragma("unroll") for (int m = 0; m < 4; ++m) _Pragma("unroll") for (int k = 0; k < 2; ++k) dst[m][k] = *(const LAS bf16x8*)(lds + G_SA(b, h) + aoff + m * 2048 + k * 1024); } while (0)
; #define G_LDB(dst, b, h) do { _Pragma("unroll") for (int n = 0; n < 2; ++n) _Pragma("unroll") for (int k = 0; k < 2; ++k) dst[n][k] = *(const LAS bf16x8*)(lds + G_SB(b, h) + boff + n * 2048 + k * 1024); } while (0)
; #define G_WAIT_V(n) asm volatile("s_waitcnt vmcnt(" #n ")" ::: "memory")
; #define G_WAIT_L(n) asm volatile("s_waitcnt lgkmcnt(" #n ")" ::: "memory")
; #define G_BAR __builtin_amdgcn_s_barrier()
; #define G_SCHED __builtin_amdgcn_sched_barrier(0)
;     ...
;             G_WAIT_L(8); G_BAR; G_WAIT_L(0); G_MMA(0, 0, At, B0); G_BAR; G_SCHED;
;             G_LDB(B1, 1, 1); G_STAGE(G_SB(1, 0), b3, cB0, qB);
;             G_BAR; G_WAIT_L(0); G_MMA(0, 1, At, B1); G_BAR;
;             G_LDA(At, 1, 1); G_STAGE(G_SA(1, 0), a3, cA0, qA);
;             G_BAR; G_WAIT_L(0); G_MMA(1, 0, At, B0); G_BAR; G_SCHED;
;             G_STAGE(G_SB(1, 1), b3 + chB, cB0, qB);
;             G_WAIT_V(6); G_BAR; G_MMA(1, 1, At, B1); G_BAR;
	s_waitcnt lgkmcnt(0)
	v_mfma_f32_16x16x32_bf16 v[132:135], v[140:143], v[160:163], v[132:135]
	v_mfma_f32_16x16x32_bf16 v[124:127], v[152:155], v[160:163], v[124:127]
	v_mfma_f32_16x16x32_bf16 v[116:119], v[140:143], v[172:175], v[116:119]
	v_mfma_f32_16x16x32_bf16 v[108:111], v[152:155], v[172:175], v[108:111]
	v_mfma_f32_16x16x32_bf16 v[100:103], v[140:143], v[180:183], v[100:103]
	v_mfma_f32_16x16x32_bf16 v[92:95], v[152:155], v[180:183], v[92:95]
	v_mfma_f32_16x16x32_bf16 v[84:87], v[140:143], v[200:203], v[84:87]
	v_mfma_f32_16x16x32_bf16 v[76:79], v[152:155], v[200:203], v[76:79]
	v_mfma_f32_16x16x32_bf16 v[132:135], v[144:147], v[164:167], v[132:135]
	v_mfma_f32_16x16x32_bf16 v[124:127], v[156:159], v[164:167], v[124:127]
	v_mfma_f32_16x16x32_bf16 v[116:119], v[144:147], v[176:179], v[116:119]
	v_mfma_f32_16x16x32_bf16 v[108:111], v[156:159], v[176:179], v[108:111]
	v_mfma_f32_16x16x32_bf16 v[100:103], v[144:147], v[196:199], v[100:103]
	v_mfma_f32_16x16x32_bf16 v[92:95], v[156:159], v[196:199], v[92:95]
	v_mfma_f32_16x16x32_bf16 v[84:87], v[144:147], v[204:207], v[84:87]
	v_mfma_f32_16x16x32_bf16 v[76:79], v[156:159], v[204:207], v[76:79]
	s_barrier
	s_add_i32 s5, 0, 0x1c000
	s_add_i32 s4, s100, s21
	s_mov_b32 m0, s4
	ds_read_b128 v[208:211], v235 offset:49152
	ds_read_b128 v[212:215], v235 offset:50176
	ds_read_b128 v[216:219], v235 offset:51200
	ds_read_b128 v[220:223], v235 offset:52224
	s_add_u32 vcc_lo, s40, s46
	s_addc_u32 vcc_hi, s41, s47
	global_load_lds_dwordx4 v2, vcc
	s_add_i32 m0, s4, 0x2000
	s_nop 0
	s_add_u32 vcc_lo, s40, s52
	s_addc_u32 vcc_hi, s41, s53
	global_load_lds_dwordx4 v2, vcc
	s_barrier
	s_waitcnt lgkmcnt(0)
	v_mfma_f32_16x16x32_bf16 v[128:131], v[208:211], v[160:163], v[128:131]
	v_mfma_f32_16x16x32_bf16 v[120:123], v[216:219], v[160:163], v[120:123]
	v_mfma_f32_16x16x32_bf16 v[112:115], v[208:211], v[172:175], v[112:115]
	v_mfma_f32_16x16x32_bf16 v[104:107], v[216:219], v[172:175], v[104:107]
	v_mfma_f32_16x16x32_bf16 v[96:99], v[208:211], v[180:183], v[96:99]
	v_mfma_f32_16x16x32_bf16 v[88:91], v[216:219], v[180:183], v[88:91]
	v_mfma_f32_16x16x32_bf16 v[80:83], v[208:211], v[200:203], v[80:83]
	v_mfma_f32_16x16x32_bf16 v[72:75], v[216:219], v[200:203], v[72:75]
	v_mfma_f32_16x16x32_bf16 v[128:131], v[212:215], v[164:167], v[128:131]
	v_mfma_f32_16x16x32_bf16 v[120:123], v[220:223], v[164:167], v[120:123]
	v_mfma_f32_16x16x32_bf16 v[112:115], v[212:215], v[176:179], v[112:115]
	v_mfma_f32_16x16x32_bf16 v[104:107], v[220:223], v[176:179], v[104:107]
	v_mfma_f32_16x16x32_bf16 v[96:99], v[212:215], v[196:199], v[96:99]
	v_mfma_f32_16x16x32_bf16 v[88:91], v[220:223], v[196:199], v[88:91]
	v_mfma_f32_16x16x32_bf16 v[80:83], v[212:215], v[204:207], v[80:83]
	v_mfma_f32_16x16x32_bf16 v[72:75], v[220:223], v[204:207], v[72:75]
	s_barrier
	s_mov_b32 m0, s31
	v_lshl_add_u64 v[226:227], v[224:225], 0, s[46:47]
	ds_read_b128 v[160:163], v150 offset:49152
	ds_read_b128 v[164:167], v150 offset:50176
	ds_read_b128 v[172:175], v150 offset:51200
	ds_read_b128 v[176:179], v150 offset:52224
	ds_read_b128 v[180:183], v150 offset:53248
	ds_read_b128 v[196:199], v150 offset:54272
	ds_read_b128 v[200:203], v150 offset:55296
	ds_read_b128 v[204:207], v150 offset:56320
	global_load_lds_dwordx4 v[226:227], off
	v_lshl_add_u64 v[224:225], v[224:225], 0, s[52:53]
	s_mov_b32 m0, s34
	s_nop 0
	global_load_lds_dwordx4 v[224:225], off
	s_barrier
	s_waitcnt lgkmcnt(0)
	v_mfma_f32_16x16x32_bf16 v[68:71], v[140:143], v[160:163], v[68:71]
	v_mfma_f32_16x16x32_bf16 v[60:63], v[152:155], v[160:163], v[60:63]
	v_mfma_f32_16x16x32_bf16 v[52:55], v[140:143], v[172:175], v[52:55]
	v_mfma_f32_16x16x32_bf16 v[44:47], v[152:155], v[172:175], v[44:47]
	v_mfma_f32_16x16x32_bf16 v[36:39], v[140:143], v[180:183], v[36:39]
	v_mfma_f32_16x16x32_bf16 v[28:31], v[152:155], v[180:183], v[28:31]
	v_mfma_f32_16x16x32_bf16 v[20:23], v[140:143], v[200:203], v[20:23]
	v_mfma_f32_16x16x32_bf16 v[12:15], v[152:155], v[200:203], v[12:15]
	v_mfma_f32_16x16x32_bf16 v[68:71], v[144:147], v[164:167], v[68:71]
	v_mfma_f32_16x16x32_bf16 v[60:63], v[156:159], v[164:167], v[60:63]
	v_mfma_f32_16x16x32_bf16 v[52:55], v[144:147], v[176:179], v[52:55]
	v_mfma_f32_16x16x32_bf16 v[44:47], v[156:159], v[176:179], v[44:47]
	v_mfma_f32_16x16x32_bf16 v[36:39], v[144:147], v[196:199], v[36:39]
	v_mfma_f32_16x16x32_bf16 v[28:31], v[156:159], v[196:199], v[28:31]
	v_mfma_f32_16x16x32_bf16 v[20:23], v[144:147], v[204:207], v[20:23]
	v_mfma_f32_16x16x32_bf16 v[12:15], v[156:159], v[204:207], v[12:15]
	s_barrier
	s_add_i32 s4, s5, s21
	s_mov_b32 m0, s4
	s_nop 0
	s_add_u32 vcc_lo, s40, s54
	s_addc_u32 vcc_hi, s41, s55
	global_load_lds_dwordx4 v2, vcc
	s_add_i32 m0, s4, 0x2000
	s_nop 0
	s_add_u32 vcc_lo, s40, s58
	s_addc_u32 vcc_hi, s41, s59
	global_load_lds_dwordx4 v2, vcc
	s_add_i32 s18, s18, 2
	s_add_u32 s2, s2, 0x100
	s_addc_u32 s3, s3, 0
	s_add_u32 s16, s16, 0x100
	s_addc_u32 s17, s17, 0
	s_cmp_gt_u32 s18, 13
	s_waitcnt vmcnt(6)
	s_barrier
	v_mfma_f32_16x16x32_bf16 v[64:67], v[208:211], v[160:163], v[64:67]
	v_mfma_f32_16x16x32_bf16 v[56:59], v[216:219], v[160:163], v[56:59]
	v_mfma_f32_16x16x32_bf16 v[48:51], v[208:211], v[172:175], v[48:51]
	v_mfma_f32_16x16x32_bf16 v[40:43], v[216:219], v[172:175], v[40:43]
	v_mfma_f32_16x16x32_bf16 v[32:35], v[208:211], v[180:183], v[32:35]
	v_mfma_f32_16x16x32_bf16 v[24:27], v[216:219], v[180:183], v[24:27]
	v_mfma_f32_16x16x32_bf16 v[16:19], v[208:211], v[200:203], v[16:19]
	v_mfma_f32_16x16x32_bf16 v[8:11], v[216:219], v[200:203], v[8:11]
	v_mfma_f32_16x16x32_bf16 v[64:67], v[212:215], v[164:167], v[64:67]
	v_mfma_f32_16x16x32_bf16 v[56:59], v[220:223], v[164:167], v[56:59]
	v_mfma_f32_16x16x32_bf16 v[48:51], v[212:215], v[176:179], v[48:51]
	v_mfma_f32_16x16x32_bf16 v[40:43], v[220:223], v[176:179], v[40:43]
	v_mfma_f32_16x16x32_bf16 v[32:35], v[212:215], v[196:199], v[32:35]
	v_mfma_f32_16x16x32_bf16 v[24:27], v[220:223], v[196:199], v[24:27]
	v_mfma_f32_16x16x32_bf16 v[16:19], v[212:215], v[204:207], v[16:19]
	v_mfma_f32_16x16x32_bf16 v[8:11], v[220:223], v[204:207], v[8:11]
	s_cbranch_scc0 .Ldb_FFI_cont

; #define G_STAGE(bufoff, gbase, o0, h64) do { \
;         __builtin_amdgcn_global_load_lds((const unsigned*)((const char*)(gbase) + (o0)), (LAS unsigned*)(lds + (bufoff) + ldsw), 16, 0, 0); \
;         __builtin_amdgcn_global_load_lds((const unsigned*)((const char*)(gbase) + (h64) + (o0)), (LAS unsigned*)(lds + (bufoff) + ldsw + 8192), 16, 0, 0); } while (0)
; #define G_LDA(dst, b, h) do { _Pragma("unroll") for (int m = 0; m < 4; ++m) _Pragma("unroll") for (int k = 0; k < 2; ++k) dst[m][k] = *(const LAS bf16x8*)(lds + G_SA(b, h) + aoff + m * 2048 + k * 1024); } while (0)
; #define G_LDB(dst, b, h) do { _Pragma("unroll") for (int n = 0; n < 2; ++n) _Pragma("unroll") for (int k = 0; k < 2; ++k) dst[n][k] = *(const LAS bf16x8*)(lds + G_SB(b, h) + boff + n * 2048 + k * 1024); } while (0)
; #define G_WAIT_V(n) asm volatile("s_waitcnt vmcnt(" #n ")" ::: "memory")
; #define G_WAIT_L(n) asm volatile("s_waitcnt lgkmcnt(" #n ")" ::: "memory")
;     ...
;         for (int t = 0; t < nt; t += 2) {
;             const bool last = (t == nt - 2);
;             const char* a1 = cA + (size_t)(t + 1) * ckA;
;             const char* a2 = last ? nA : cA + (size_t)(t + 2) * ckA; const char* b2 = last ? nB : cB + (size_t)(t + 2) * kB;
;             const char* a3 = a2 + ckA; const char* b3 = b2 + kB;
;             G_LDB(B0, 0, 0); G_SCHED; G_LDA(At, 0, 0); G_STAGE(G_SA(1, 1), a1 + chA, cA0, qA);
;             G_WAIT_L(8); G_BAR; G_WAIT_L(0); G_MMA(0, 0, At, B0); G_BAR; G_SCHED;
;             G_LDB(B1, 0, 1); G_STAGE(G_SB(0, 0), b2, cB0, qB);
;             G_BAR; G_WAIT_L(0); G_MMA(0, 1, At, B1); G_BAR;
;             G_LDA(At, 0, 1); G_STAGE(G_SA(0, 0), a2, cA0, qA);
;             G_BAR; G_WAIT_L(0); G_MMA(1, 0, At, B0); G_BAR; G_SCHED;
;             G_STAGE(G_SB(0, 1), b2 + chB, cB0, qB);
;             G_WAIT_V(6); G_BAR; G_MMA(1, 1, At, B1); G_BAR;
;             G_LDB(B0, 1, 0); G_SCHED; G_LDA(At, 1, 0); G_STAGE(G_SA(0, 1), a2 + chA, cA0, qA);
;             G_WAIT_L(8); G_BAR; G_WAIT_L(0); G_MMA(0, 0, At, B0); G_BAR; G_SCHED;
;     ...
;         if (!(cs.kind == K_MG_B && cur.aux < 2))
; #pragma unroll
;         for (int a = 0; a < 2; ++a)
; #pragma unroll
;             for (int b = 0; b < 2; ++b)
; #pragma unroll
;                 for (int m = 0; m < 4; ++m)
; #pragma unroll
;                     for (int n = 0; n < 2; ++n) acc[a][b][m][n] = (f32x4){0.f, 0.f, 0.f, 0.f};
.LBB0_1184:
	s_add_u32 s2, s2, 0xb0080
	s_addc_u32 s3, s3, 0
	s_add_u32 s6, s6, 0x100
	s_waitcnt lgkmcnt(0)
	s_addc_u32 s7, s7, 0
	s_mov_b32 s21, -2
	s_mov_b64 s[52:53], 0xb0080
	s_mov_b64 s[54:55], 0x108080
	s_cmp_eq_u32 s101, 2
	s_cselect_b32 s101, 0, s101
	v_add_u32_e32 v255, 0x10000, v185
	s_add_u32 s4, s2, 0xfff50080
	s_addc_u32 s5, s3, -1
	s_add_i32 s33, 0, 0x10000
	ds_read_b128 v[136:139], v255 offset:0
	ds_read_b128 v[140:143], v255 offset:1024
	ds_read_b128 v[144:147], v255 offset:2048
	ds_read_b128 v[148:151], v255 offset:3072
	s_cmp_eq_u32 s21, 40
	s_cselect_b32 s5, s17, s5
	s_cselect_b32 s4, s16, s4
	s_cselect_b32 s23, s19, s7
	s_cselect_b32 s22, s18, s6
	s_add_i32 m0, s26, 0xc000
	ds_read_b128 v[152:155], v195
	ds_read_b128 v[156:159], v195 offset:1024
	ds_read_b128 v[160:163], v195 offset:2048
	ds_read_b128 v[164:167], v195 offset:3072
	ds_read_b128 v[176:179], v195 offset:4096
	ds_read_b128 v[180:183], v195 offset:5120
	ds_read_b128 v[196:199], v195 offset:6144
	ds_read_b128 v[200:203], v195 offset:7168
	global_load_lds_dwordx4 v174, s[2:3]
	s_add_i32 m0, s26, 0xe000
	s_nop 0
	s_add_u32 vcc_lo, s2, s86
	s_addc_u32 vcc_hi, s3, s87
	global_load_lds_dwordx4 v174, vcc
	s_waitcnt lgkmcnt(8)
	s_cmp_eq_u32 s101, 1
	s_cbranch_scc1 .Ldb_FFO_skp
	s_barrier
.Ldb_FFO_skp:
	s_mov_b32 s101, 0
	s_waitcnt lgkmcnt(0)
	v_mfma_f32_16x16x32_bf16 v[132:135], v[136:139], v[152:155], 0
	v_mfma_f32_16x16x32_bf16 v[128:131], v[144:147], v[152:155], 0
	v_mfma_f32_16x16x32_bf16 v[116:119], v[136:139], v[160:163], 0
	v_mfma_f32_16x16x32_bf16 v[112:115], v[144:147], v[160:163], 0
	v_mfma_f32_16x16x32_bf16 v[100:103], v[136:139], v[176:179], 0
	v_mfma_f32_16x16x32_bf16 v[96:99], v[144:147], v[176:179], 0
	v_mfma_f32_16x16x32_bf16 v[84:87], v[136:139], v[196:199], 0
	v_mfma_f32_16x16x32_bf16 v[80:83], v[144:147], v[196:199], 0
	v_mfma_f32_16x16x32_bf16 v[132:135], v[140:143], v[156:159], v[132:135]
	v_mfma_f32_16x16x32_bf16 v[128:131], v[148:151], v[156:159], v[128:131]
	v_mfma_f32_16x16x32_bf16 v[116:119], v[140:143], v[164:167], v[116:119]
	v_mfma_f32_16x16x32_bf16 v[112:115], v[148:151], v[164:167], v[112:115]
	v_mfma_f32_16x16x32_bf16 v[100:103], v[140:143], v[180:183], v[100:103]
	v_mfma_f32_16x16x32_bf16 v[96:99], v[148:151], v[180:183], v[96:99]
	v_mfma_f32_16x16x32_bf16 v[84:87], v[140:143], v[200:203], v[84:87]
	v_mfma_f32_16x16x32_bf16 v[80:83], v[148:151], v[200:203], v[80:83]
	s_barrier
	s_add_i32 s44, 0, 0x14000
	s_add_i32 s100, s33, s25
	s_mov_b32 m0, s100
	ds_read_b128 v[204:207], v255 offset:16384
	ds_read_b128 v[208:211], v255 offset:17408
	ds_read_b128 v[212:215], v255 offset:18432
	ds_read_b128 v[216:219], v255 offset:19456
	global_load_lds_dwordx4 v172, s[22:23]
	s_add_i32 m0, s100, 0x2000
	s_nop 0
	s_add_u32 vcc_lo, s22, s86
	s_addc_u32 vcc_hi, s23, s87
	global_load_lds_dwordx4 v172, vcc
	s_barrier
	s_waitcnt lgkmcnt(0)
	v_mfma_f32_16x16x32_bf16 v[124:127], v[204:207], v[152:155], 0
	v_mfma_f32_16x16x32_bf16 v[120:123], v[212:215], v[152:155], 0
	v_mfma_f32_16x16x32_bf16 v[108:111], v[204:207], v[160:163], 0
	v_mfma_f32_16x16x32_bf16 v[104:107], v[212:215], v[160:163], 0
	v_mfma_f32_16x16x32_bf16 v[92:95], v[204:207], v[176:179], 0
	v_mfma_f32_16x16x32_bf16 v[88:91], v[212:215], v[176:179], 0
	v_mfma_f32_16x16x32_bf16 v[76:79], v[204:207], v[196:199], 0
	v_mfma_f32_16x16x32_bf16 v[72:75], v[212:215], v[196:199], 0
	v_mfma_f32_16x16x32_bf16 v[124:127], v[208:211], v[156:159], v[124:127]
	v_mfma_f32_16x16x32_bf16 v[120:123], v[216:219], v[156:159], v[120:123]
	v_mfma_f32_16x16x32_bf16 v[108:111], v[208:211], v[164:167], v[108:111]
	v_mfma_f32_16x16x32_bf16 v[104:107], v[216:219], v[164:167], v[104:107]
	v_mfma_f32_16x16x32_bf16 v[92:95], v[208:211], v[180:183], v[92:95]
	v_mfma_f32_16x16x32_bf16 v[88:91], v[216:219], v[180:183], v[88:91]
	v_mfma_f32_16x16x32_bf16 v[76:79], v[208:211], v[200:203], v[76:79]
	v_mfma_f32_16x16x32_bf16 v[72:75], v[216:219], v[200:203], v[72:75]
	s_barrier
	s_mov_b32 m0, s26
	v_lshl_add_u64 v[222:223], s[4:5], 0, v[2:3]
	ds_read_b128 v[152:155], v195 offset:16384
	ds_read_b128 v[156:159], v195 offset:17408
	ds_read_b128 v[160:163], v195 offset:18432
	ds_read_b128 v[164:167], v195 offset:19456
	ds_read_b128 v[176:179], v195 offset:20480
	ds_read_b128 v[180:183], v195 offset:21504
	ds_read_b128 v[196:199], v195 offset:22528
	ds_read_b128 v[200:203], v195 offset:23552
	global_load_lds_dwordx4 v2, s[4:5]
	s_mov_b32 m0, s27
	s_nop 0
	s_add_u32 vcc_lo, s4, s86
	s_addc_u32 vcc_hi, s5, s87
	global_load_lds_dwordx4 v2, vcc
	s_barrier
	s_waitcnt lgkmcnt(0)
	v_mfma_f32_16x16x32_bf16 v[68:71], v[136:139], v[152:155], 0
	v_mfma_f32_16x16x32_bf16 v[64:67], v[144:147], v[152:155], 0
	v_mfma_f32_16x16x32_bf16 v[52:55], v[136:139], v[160:163], 0
	v_mfma_f32_16x16x32_bf16 v[48:51], v[144:147], v[160:163], 0
	v_mfma_f32_16x16x32_bf16 v[36:39], v[136:139], v[176:179], 0
	v_mfma_f32_16x16x32_bf16 v[32:35], v[144:147], v[176:179], 0
	v_mfma_f32_16x16x32_bf16 v[20:23], v[136:139], v[196:199], 0
	v_mfma_f32_16x16x32_bf16 v[16:19], v[144:147], v[196:199], 0
	v_mfma_f32_16x16x32_bf16 v[68:71], v[140:143], v[156:159], v[68:71]
	v_mfma_f32_16x16x32_bf16 v[64:67], v[148:151], v[156:159], v[64:67]
	v_mfma_f32_16x16x32_bf16 v[52:55], v[140:143], v[164:167], v[52:55]
	v_mfma_f32_16x16x32_bf16 v[48:51], v[148:151], v[164:167], v[48:51]
	v_mfma_f32_16x16x32_bf16 v[36:39], v[140:143], v[180:183], v[36:39]
	v_mfma_f32_16x16x32_bf16 v[32:35], v[148:151], v[180:183], v[32:35]
	v_mfma_f32_16x16x32_bf16 v[20:23], v[140:143], v[200:203], v[20:23]
	v_mfma_f32_16x16x32_bf16 v[16:19], v[148:151], v[200:203], v[16:19]
	s_barrier
; #define G_STAGE(bufoff, gbase, o0, h64) do { \
;         __builtin_amdgcn_global_load_lds((const unsigned*)((const char*)(gbase) + (o0)), (LAS unsigned*)(lds + (bufoff) + ldsw), 16, 0, 0); \
;         __builtin_amdgcn_global_load_lds((const unsigned*)((const char*)(gbase) + (h64) + (o0)), (LAS unsigned*)(lds + (bufoff) + ldsw + 8192), 16, 0, 0); } while (0)
; #define G_LDA(dst, b, h) do { _Pragma("unroll") for (int m = 0; m < 4; ++m) _Pragma("unroll") for (int k = 0; k < 2; ++k) dst[m][k] = *(const LAS bf16x8*)(lds + G_SA(b, h) + aoff + m * 2048 + k * 1024); } while (0)
; #define G_LDB(dst, b, h) do { _Pragma("unroll") for (int n = 0; n < 2; ++n) _Pragma("unroll") for (int k = 0; k < 2; ++k) dst[n][k] = *(const LAS bf16x8*)(lds + G_SB(b, h) + boff + n * 2048 + k * 1024); } while (0)
; #define G_WAIT_V(n) asm volatile("s_waitcnt vmcnt(" #n ")" ::: "memory")
; #define G_WAIT_L(n) asm volatile("s_waitcnt lgkmcnt(" #n ")" ::: "memory")
; #define G_BAR __builtin_amdgcn_s_barrier()
; #define G_SCHED __builtin_amdgcn_sched_barrier(0)
;     ...
;             G_STAGE(G_SB(0, 1), b2 + chB, cB0, qB);
;             G_WAIT_V(6); G_BAR; G_MMA(1, 1, At, B1); G_BAR;
;             G_LDB(B0, 1, 0); G_SCHED; G_LDA(At, 1, 0); G_STAGE(G_SA(0, 1), a2 + chA, cA0, qA);
;             G_WAIT_L(8); G_BAR; G_WAIT_L(0); G_MMA(0, 0, At, B0); G_BAR; G_SCHED;
;             G_LDB(B1, 1, 1); G_STAGE(G_SB(1, 0), b3, cB0, qB);
;             G_BAR; G_WAIT_L(0); G_MMA(0, 1, At, B1); G_BAR;
;             G_LDA(At, 1, 1); G_STAGE(G_SA(1, 0), a3, cA0, qA);
;             G_BAR; G_WAIT_L(0); G_MMA(1, 0, At, B0); G_BAR; G_SCHED;
	s_add_i32 s100, s44, s25
	s_mov_b32 m0, s100
	s_nop 0
	s_add_u32 vcc_lo, s22, s88
	s_addc_u32 vcc_hi, s23, s89
	global_load_lds_dwordx4 v172, vcc
	s_add_i32 m0, s100, 0x2000
	s_nop 0
	s_add_u32 vcc_lo, s22, s64
	s_addc_u32 vcc_hi, s23, s65
	global_load_lds_dwordx4 v172, vcc
	s_waitcnt vmcnt(6)
	s_barrier
	v_mfma_f32_16x16x32_bf16 v[60:63], v[204:207], v[152:155], 0
	v_mfma_f32_16x16x32_bf16 v[56:59], v[212:215], v[152:155], 0
	v_mfma_f32_16x16x32_bf16 v[44:47], v[204:207], v[160:163], 0
	v_mfma_f32_16x16x32_bf16 v[40:43], v[212:215], v[160:163], 0
	v_mfma_f32_16x16x32_bf16 v[28:31], v[204:207], v[176:179], 0
	v_mfma_f32_16x16x32_bf16 v[24:27], v[212:215], v[176:179], 0
	v_mfma_f32_16x16x32_bf16 v[12:15], v[204:207], v[196:199], 0
	v_mfma_f32_16x16x32_bf16 v[8:11], v[212:215], v[196:199], 0
	v_mfma_f32_16x16x32_bf16 v[60:63], v[208:211], v[156:159], v[60:63]
	v_mfma_f32_16x16x32_bf16 v[56:59], v[216:219], v[156:159], v[56:59]
	v_mfma_f32_16x16x32_bf16 v[44:47], v[208:211], v[164:167], v[44:47]
	v_mfma_f32_16x16x32_bf16 v[40:43], v[216:219], v[164:167], v[40:43]
	v_mfma_f32_16x16x32_bf16 v[28:31], v[208:211], v[180:183], v[28:31]
	v_mfma_f32_16x16x32_bf16 v[24:27], v[216:219], v[180:183], v[24:27]
	v_mfma_f32_16x16x32_bf16 v[12:15], v[208:211], v[200:203], v[12:15]
	v_mfma_f32_16x16x32_bf16 v[8:11], v[216:219], v[200:203], v[8:11]
	s_barrier
	s_add_i32 s100, 0, 0x18000
	ds_read_b128 v[136:139], v255 offset:32768
	ds_read_b128 v[140:143], v255 offset:33792
	ds_read_b128 v[144:147], v255 offset:34816
	ds_read_b128 v[148:151], v255 offset:35840
	s_mov_b32 m0, s29
	ds_read_b128 v[152:155], v195 offset:32768
	ds_read_b128 v[156:159], v195 offset:33792
	ds_read_b128 v[160:163], v195 offset:34816
	ds_read_b128 v[164:167], v195 offset:35840
	ds_read_b128 v[176:179], v195 offset:36864
	ds_read_b128 v[180:183], v195 offset:37888
	ds_read_b128 v[196:199], v195 offset:38912
	ds_read_b128 v[200:203], v195 offset:39936
	s_add_u32 vcc_lo, s4, s88
	s_addc_u32 vcc_hi, s5, s89
	global_load_lds_dwordx4 v2, vcc
	s_mov_b32 m0, s30
	s_nop 0
	s_add_u32 vcc_lo, s4, s64
	s_addc_u32 vcc_hi, s5, s65
	global_load_lds_dwordx4 v2, vcc
	s_waitcnt lgkmcnt(8)
	s_barrier
	s_waitcnt lgkmcnt(0)
	v_mfma_f32_16x16x32_bf16 v[132:135], v[136:139], v[152:155], v[132:135]
	v_mfma_f32_16x16x32_bf16 v[128:131], v[144:147], v[152:155], v[128:131]
	v_mfma_f32_16x16x32_bf16 v[116:119], v[136:139], v[160:163], v[116:119]
	v_mfma_f32_16x16x32_bf16 v[112:115], v[144:147], v[160:163], v[112:115]
	v_mfma_f32_16x16x32_bf16 v[100:103], v[136:139], v[176:179], v[100:103]
	v_mfma_f32_16x16x32_bf16 v[96:99], v[144:147], v[176:179], v[96:99]
	v_mfma_f32_16x16x32_bf16 v[84:87], v[136:139], v[196:199], v[84:87]
	v_mfma_f32_16x16x32_bf16 v[80:83], v[144:147], v[196:199], v[80:83]
	v_mfma_f32_16x16x32_bf16 v[132:135], v[140:143], v[156:159], v[132:135]
	v_mfma_f32_16x16x32_bf16 v[128:131], v[148:151], v[156:159], v[128:131]
	v_mfma_f32_16x16x32_bf16 v[116:119], v[140:143], v[164:167], v[116:119]
	v_mfma_f32_16x16x32_bf16 v[112:115], v[148:151], v[164:167], v[112:115]
	v_mfma_f32_16x16x32_bf16 v[100:103], v[140:143], v[180:183], v[100:103]
	v_mfma_f32_16x16x32_bf16 v[96:99], v[148:151], v[180:183], v[96:99]
	v_mfma_f32_16x16x32_bf16 v[84:87], v[140:143], v[200:203], v[84:87]
	v_mfma_f32_16x16x32_bf16 v[80:83], v[148:151], v[200:203], v[80:83]
	s_barrier
	s_add_i32 s5, 0, 0x1c000
	s_add_i32 s4, s100, s25
	s_mov_b32 m0, s4
	ds_read_b128 v[204:207], v255 offset:49152
	ds_read_b128 v[208:211], v255 offset:50176
	ds_read_b128 v[212:215], v255 offset:51200
	ds_read_b128 v[216:219], v255 offset:52224
	s_add_u32 vcc_lo, s22, s46
	s_addc_u32 vcc_hi, s23, s47
	global_load_lds_dwordx4 v172, vcc
	s_add_i32 m0, s4, 0x2000
	s_nop 0
	s_add_u32 vcc_lo, s22, s66
	s_addc_u32 vcc_hi, s23, s67
	global_load_lds_dwordx4 v172, vcc
	s_barrier
	s_waitcnt lgkmcnt(0)
	v_mfma_f32_16x16x32_bf16 v[124:127], v[204:207], v[152:155], v[124:127]
	v_mfma_f32_16x16x32_bf16 v[120:123], v[212:215], v[152:155], v[120:123]
	v_mfma_f32_16x16x32_bf16 v[108:111], v[204:207], v[160:163], v[108:111]
	v_mfma_f32_16x16x32_bf16 v[104:107], v[212:215], v[160:163], v[104:107]
	v_mfma_f32_16x16x32_bf16 v[92:95], v[204:207], v[176:179], v[92:95]
	v_mfma_f32_16x16x32_bf16 v[88:91], v[212:215], v[176:179], v[88:91]
	v_mfma_f32_16x16x32_bf16 v[76:79], v[204:207], v[196:199], v[76:79]
	v_mfma_f32_16x16x32_bf16 v[72:75], v[212:215], v[196:199], v[72:75]
	v_mfma_f32_16x16x32_bf16 v[124:127], v[208:211], v[156:159], v[124:127]
	v_mfma_f32_16x16x32_bf16 v[120:123], v[216:219], v[156:159], v[120:123]
	v_mfma_f32_16x16x32_bf16 v[108:111], v[208:211], v[164:167], v[108:111]
	v_mfma_f32_16x16x32_bf16 v[104:107], v[216:219], v[164:167], v[104:107]
	v_mfma_f32_16x16x32_bf16 v[92:95], v[208:211], v[180:183], v[92:95]
	v_mfma_f32_16x16x32_bf16 v[88:91], v[216:219], v[180:183], v[88:91]
	v_mfma_f32_16x16x32_bf16 v[76:79], v[208:211], v[200:203], v[76:79]
	v_mfma_f32_16x16x32_bf16 v[72:75], v[216:219], v[200:203], v[72:75]
	s_barrier
	s_mov_b32 m0, s31
	v_lshl_add_u64 v[224:225], v[222:223], 0, s[46:47]
	ds_read_b128 v[152:155], v195 offset:49152
	ds_read_b128 v[156:159], v195 offset:50176
	ds_read_b128 v[160:163], v195 offset:51200
	ds_read_b128 v[164:167], v195 offset:52224
	ds_read_b128 v[176:179], v195 offset:53248
	ds_read_b128 v[180:183], v195 offset:54272
	ds_read_b128 v[196:199], v195 offset:55296
	ds_read_b128 v[200:203], v195 offset:56320
	global_load_lds_dwordx4 v[224:225], off
	v_lshl_add_u64 v[222:223], v[222:223], 0, s[66:67]
	s_mov_b32 m0, s34
	s_nop 0
	global_load_lds_dwordx4 v[222:223], off
	s_barrier
; #define G_STAGE(bufoff, gbase, o0, h64) do { \
;         __builtin_amdgcn_global_load_lds((const unsigned*)((const char*)(gbase) + (o0)), (LAS unsigned*)(lds + (bufoff) + ldsw), 16, 0, 0); \
;         __builtin_amdgcn_global_load_lds((const unsigned*)((const char*)(gbase) + (h64) + (o0)), (LAS unsigned*)(lds + (bufoff) + ldsw + 8192), 16, 0, 0); } while (0)
; #define G_LDA(dst, b, h) do { _Pragma("unroll") for (int m = 0; m < 4; ++m) _Pragma("unroll") for (int k = 0; k < 2; ++k) dst[m][k] = *(const LAS bf16x8*)(lds + G_SA(b, h) + aoff + m * 2048 + k * 1024); } while (0)
; #define G_LDB(dst, b, h) do { _Pragma("unroll") for (int n = 0; n < 2; ++n) _Pragma("unroll") for (int k = 0; k < 2; ++k) dst[n][k] = *(const LAS bf16x8*)(lds + G_SB(b, h) + boff + n * 2048 + k * 1024); } while (0)
; #define G_WAIT_V(n) asm volatile("s_waitcnt vmcnt(" #n ")" ::: "memory")
; #define G_BAR __builtin_amdgcn_s_barrier()
;     ...
;         for (int t = 0; t < nt; t += 2) {
;             const bool last = (t == nt - 2);
;             const char* a1 = cA + (size_t)(t + 1) * ckA;
;             const char* a2 = last ? nA : cA + (size_t)(t + 2) * ckA; const char* b2 = last ? nB : cB + (size_t)(t + 2) * kB;
;             const char* a3 = a2 + ckA; const char* b3 = b2 + kB;
;             G_LDB(B0, 0, 0); G_SCHED; G_LDA(At, 0, 0); G_STAGE(G_SA(1, 1), a1 + chA, cA0, qA);
;             G_WAIT_L(8); G_BAR; G_WAIT_L(0); G_MMA(0, 0, At, B0); G_BAR; G_SCHED;
;             G_LDB(B1, 0, 1); G_STAGE(G_SB(0, 0), b2, cB0, qB);
;             G_BAR; G_WAIT_L(0); G_MMA(0, 1, At, B1); G_BAR;
;             G_LDA(At, 0, 1); G_STAGE(G_SA(0, 0), a2, cA0, qA);
;             G_BAR; G_WAIT_L(0); G_MMA(1, 0, At, B0); G_BAR; G_SCHED;
;             G_STAGE(G_SB(0, 1), b2 + chB, cB0, qB);
;             G_WAIT_V(6); G_BAR; G_MMA(1, 1, At, B1); G_BAR;
;             G_LDB(B0, 1, 0); G_SCHED; G_LDA(At, 1, 0); G_STAGE(G_SA(0, 1), a2 + chA, cA0, qA);
;             G_WAIT_L(8); G_BAR; G_WAIT_L(0); G_MMA(0, 0, At, B0); G_BAR; G_SCHED;
;             G_LDB(B1, 1, 1); G_STAGE(G_SB(1, 0), b3, cB0, qB);
;             G_BAR; G_WAIT_L(0); G_MMA(0, 1, At, B1); G_BAR;
;             G_LDA(At, 1, 1); G_STAGE(G_SA(1, 0), a3, cA0, qA);
;             G_BAR; G_WAIT_L(0); G_MMA(1, 0, At, B0); G_BAR; G_SCHED;
;             G_STAGE(G_SB(1, 1), b3 + chB, cB0, qB);
;             G_WAIT_V(6); G_BAR; G_MMA(1, 1, At, B1); G_BAR;
	s_waitcnt lgkmcnt(0)
	v_mfma_f32_16x16x32_bf16 v[68:71], v[136:139], v[152:155], v[68:71]
	v_mfma_f32_16x16x32_bf16 v[64:67], v[144:147], v[152:155], v[64:67]
	v_mfma_f32_16x16x32_bf16 v[52:55], v[136:139], v[160:163], v[52:55]
	v_mfma_f32_16x16x32_bf16 v[48:51], v[144:147], v[160:163], v[48:51]
	v_mfma_f32_16x16x32_bf16 v[36:39], v[136:139], v[176:179], v[36:39]
	v_mfma_f32_16x16x32_bf16 v[32:35], v[144:147], v[176:179], v[32:35]
	v_mfma_f32_16x16x32_bf16 v[20:23], v[136:139], v[196:199], v[20:23]
	v_mfma_f32_16x16x32_bf16 v[16:19], v[144:147], v[196:199], v[16:19]
	v_mfma_f32_16x16x32_bf16 v[68:71], v[140:143], v[156:159], v[68:71]
	v_mfma_f32_16x16x32_bf16 v[64:67], v[148:151], v[156:159], v[64:67]
	v_mfma_f32_16x16x32_bf16 v[52:55], v[140:143], v[164:167], v[52:55]
	v_mfma_f32_16x16x32_bf16 v[48:51], v[148:151], v[164:167], v[48:51]
	v_mfma_f32_16x16x32_bf16 v[36:39], v[140:143], v[180:183], v[36:39]
	v_mfma_f32_16x16x32_bf16 v[32:35], v[148:151], v[180:183], v[32:35]
	v_mfma_f32_16x16x32_bf16 v[20:23], v[140:143], v[200:203], v[20:23]
	v_mfma_f32_16x16x32_bf16 v[16:19], v[148:151], v[200:203], v[16:19]
	s_barrier
	s_add_i32 s4, s5, s25
	s_mov_b32 m0, s4
	s_nop 0
	s_add_u32 vcc_lo, s22, s52
	s_addc_u32 vcc_hi, s23, s53
	global_load_lds_dwordx4 v172, vcc
	s_add_i32 m0, s4, 0x2000
	s_nop 0
	s_add_u32 vcc_lo, s22, s54
	s_addc_u32 vcc_hi, s23, s55
	global_load_lds_dwordx4 v172, vcc
	s_add_i32 s21, s21, 2
	s_add_u32 s2, s2, 0x100
	s_addc_u32 s3, s3, 0
	s_add_u32 s6, s6, 0x100
	s_addc_u32 s7, s7, 0
	s_cmp_gt_u32 s21, 41
	s_waitcnt vmcnt(6)
	s_barrier
	v_mfma_f32_16x16x32_bf16 v[60:63], v[204:207], v[152:155], v[60:63]
	v_mfma_f32_16x16x32_bf16 v[56:59], v[212:215], v[152:155], v[56:59]
	v_mfma_f32_16x16x32_bf16 v[44:47], v[204:207], v[160:163], v[44:47]
	v_mfma_f32_16x16x32_bf16 v[40:43], v[212:215], v[160:163], v[40:43]
	v_mfma_f32_16x16x32_bf16 v[28:31], v[204:207], v[176:179], v[28:31]
	v_mfma_f32_16x16x32_bf16 v[24:27], v[212:215], v[176:179], v[24:27]
	v_mfma_f32_16x16x32_bf16 v[12:15], v[204:207], v[196:199], v[12:15]
	v_mfma_f32_16x16x32_bf16 v[8:11], v[212:215], v[196:199], v[8:11]
	v_mfma_f32_16x16x32_bf16 v[60:63], v[208:211], v[156:159], v[60:63]
	v_mfma_f32_16x16x32_bf16 v[56:59], v[216:219], v[156:159], v[56:59]
	v_mfma_f32_16x16x32_bf16 v[44:47], v[208:211], v[164:167], v[44:47]
	v_mfma_f32_16x16x32_bf16 v[40:43], v[216:219], v[164:167], v[40:43]
	v_mfma_f32_16x16x32_bf16 v[28:31], v[208:211], v[180:183], v[28:31]
	v_mfma_f32_16x16x32_bf16 v[24:27], v[216:219], v[180:183], v[24:27]
	v_mfma_f32_16x16x32_bf16 v[12:15], v[208:211], v[200:203], v[12:15]
	v_mfma_f32_16x16x32_bf16 v[8:11], v[216:219], v[200:203], v[8:11]
	s_cbranch_scc0 .Ldb_FFO_cont
	s_branch .Ldb_FFO_xl
.LBB0_1185:
	s_add_u32 s4, s2, 0xfff50080
	s_addc_u32 s5, s3, -1
	s_add_i32 s33, 0, 0x10000
	ds_read_b128 v[136:139], v255 offset:0
	ds_read_b128 v[140:143], v255 offset:1024
	ds_read_b128 v[144:147], v255 offset:2048
	ds_read_b128 v[148:151], v255 offset:3072
	s_cmp_eq_u32 s21, 40
	s_cselect_b32 s5, s17, s5
	s_cselect_b32 s4, s16, s4
	s_cselect_b32 s23, s19, s7
	s_cselect_b32 s22, s18, s6
	s_add_i32 m0, s26, 0xc000
	ds_read_b128 v[152:155], v195
	ds_read_b128 v[156:159], v195 offset:1024
	ds_read_b128 v[160:163], v195 offset:2048
	ds_read_b128 v[164:167], v195 offset:3072
	ds_read_b128 v[176:179], v195 offset:4096
	ds_read_b128 v[180:183], v195 offset:5120
	ds_read_b128 v[196:199], v195 offset:6144
	ds_read_b128 v[200:203], v195 offset:7168
	global_load_lds_dwordx4 v174, s[2:3]
	s_add_i32 m0, s26, 0xe000
	s_nop 0
	s_add_u32 vcc_lo, s2, s86
	s_addc_u32 vcc_hi, s3, s87
	global_load_lds_dwordx4 v174, vcc
	s_waitcnt lgkmcnt(8)
	s_barrier
	s_waitcnt lgkmcnt(0)
	v_mfma_f32_16x16x32_bf16 v[132:135], v[136:139], v[152:155], v[132:135]
	v_mfma_f32_16x16x32_bf16 v[128:131], v[144:147], v[152:155], v[128:131]
	v_mfma_f32_16x16x32_bf16 v[116:119], v[136:139], v[160:163], v[116:119]
	v_mfma_f32_16x16x32_bf16 v[112:115], v[144:147], v[160:163], v[112:115]
	v_mfma_f32_16x16x32_bf16 v[100:103], v[136:139], v[176:179], v[100:103]
	v_mfma_f32_16x16x32_bf16 v[96:99], v[144:147], v[176:179], v[96:99]
	v_mfma_f32_16x16x32_bf16 v[84:87], v[136:139], v[196:199], v[84:87]
	v_mfma_f32_16x16x32_bf16 v[80:83], v[144:147], v[196:199], v[80:83]
	v_mfma_f32_16x16x32_bf16 v[132:135], v[140:143], v[156:159], v[132:135]
	v_mfma_f32_16x16x32_bf16 v[128:131], v[148:151], v[156:159], v[128:131]
	v_mfma_f32_16x16x32_bf16 v[116:119], v[140:143], v[164:167], v[116:119]
	v_mfma_f32_16x16x32_bf16 v[112:115], v[148:151], v[164:167], v[112:115]
	v_mfma_f32_16x16x32_bf16 v[100:103], v[140:143], v[180:183], v[100:103]
	v_mfma_f32_16x16x32_bf16 v[96:99], v[148:151], v[180:183], v[96:99]
	v_mfma_f32_16x16x32_bf16 v[84:87], v[140:143], v[200:203], v[84:87]
	v_mfma_f32_16x16x32_bf16 v[80:83], v[148:151], v[200:203], v[80:83]
	s_barrier
	s_add_i32 s44, 0, 0x14000
	s_add_i32 s100, s33, s25
	s_mov_b32 m0, s100
	ds_read_b128 v[204:207], v255 offset:16384
	ds_read_b128 v[208:211], v255 offset:17408
	ds_read_b128 v[212:215], v255 offset:18432
	ds_read_b128 v[216:219], v255 offset:19456
	global_load_lds_dwordx4 v172, s[22:23]
	s_add_i32 m0, s100, 0x2000
	s_nop 0
	s_add_u32 vcc_lo, s22, s86
	s_addc_u32 vcc_hi, s23, s87
	global_load_lds_dwordx4 v172, vcc
	s_barrier
; #define G_STAGE(bufoff, gbase, o0, h64) do { \
;         __builtin_amdgcn_global_load_lds((const unsigned*)((const char*)(gbase) + (o0)), (LAS unsigned*)(lds + (bufoff) + ldsw), 16, 0, 0); \
;         __builtin_amdgcn_global_load_lds((const unsigned*)((const char*)(gbase) + (h64) + (o0)), (LAS unsigned*)(lds + (bufoff) + ldsw + 8192), 16, 0, 0); } while (0)
; #define G_LDA(dst, b, h) do { _Pragma("unroll") for (int m = 0; m < 4; ++m) _Pragma("unroll") for (int k = 0; k < 2; ++k) dst[m][k] = *(const LAS bf16x8*)(lds + G_SA(b, h) + aoff + m * 2048 + k * 1024); } while (0)
; #define G_LDB(dst, b, h) do { _Pragma("unroll") for (int n = 0; n < 2; ++n) _Pragma("unroll") for (int k = 0; k < 2; ++k) dst[n][k] = *(const LAS bf16x8*)(lds + G_SB(b, h) + boff + n * 2048 + k * 1024); } while (0)
; #define G_WAIT_V(n) asm volatile("s_waitcnt vmcnt(" #n ")" ::: "memory")
; #define G_WAIT_L(n) asm volatile("s_waitcnt lgkmcnt(" #n ")" ::: "memory")
; #define G_BAR __builtin_amdgcn_s_barrier()
; #define G_SCHED __builtin_amdgcn_sched_barrier(0)
;     ...
;             G_WAIT_L(8); G_BAR; G_WAIT_L(0); G_MMA(0, 0, At, B0); G_BAR; G_SCHED;
;             G_LDB(B1, 0, 1); G_STAGE(G_SB(0, 0), b2, cB0, qB);
;             G_BAR; G_WAIT_L(0); G_MMA(0, 1, At, B1); G_BAR;
;             G_LDA(At, 0, 1); G_STAGE(G_SA(0, 0), a2, cA0, qA);
;             G_BAR; G_WAIT_L(0); G_MMA(1, 0, At, B0); G_BAR; G_SCHED;
;             G_STAGE(G_SB(0, 1), b2 + chB, cB0, qB);
;             G_WAIT_V(6); G_BAR; G_MMA(1, 1, At, B1); G_BAR;
;             G_LDB(B0, 1, 0); G_SCHED; G_LDA(At, 1, 0); G_STAGE(G_SA(0, 1), a2 + chA, cA0, qA);
;             G_WAIT_L(8); G_BAR; G_WAIT_L(0); G_MMA(0, 0, At, B0); G_BAR; G_SCHED;
	s_waitcnt lgkmcnt(0)
	v_mfma_f32_16x16x32_bf16 v[124:127], v[204:207], v[152:155], v[124:127]
	v_mfma_f32_16x16x32_bf16 v[120:123], v[212:215], v[152:155], v[120:123]
	v_mfma_f32_16x16x32_bf16 v[108:111], v[204:207], v[160:163], v[108:111]
	v_mfma_f32_16x16x32_bf16 v[104:107], v[212:215], v[160:163], v[104:107]
	v_mfma_f32_16x16x32_bf16 v[92:95], v[204:207], v[176:179], v[92:95]
	v_mfma_f32_16x16x32_bf16 v[88:91], v[212:215], v[176:179], v[88:91]
	v_mfma_f32_16x16x32_bf16 v[76:79], v[204:207], v[196:199], v[76:79]
	v_mfma_f32_16x16x32_bf16 v[72:75], v[212:215], v[196:199], v[72:75]
	v_mfma_f32_16x16x32_bf16 v[124:127], v[208:211], v[156:159], v[124:127]
	v_mfma_f32_16x16x32_bf16 v[120:123], v[216:219], v[156:159], v[120:123]
	v_mfma_f32_16x16x32_bf16 v[108:111], v[208:211], v[164:167], v[108:111]
	v_mfma_f32_16x16x32_bf16 v[104:107], v[216:219], v[164:167], v[104:107]
	v_mfma_f32_16x16x32_bf16 v[92:95], v[208:211], v[180:183], v[92:95]
	v_mfma_f32_16x16x32_bf16 v[88:91], v[216:219], v[180:183], v[88:91]
	v_mfma_f32_16x16x32_bf16 v[76:79], v[208:211], v[200:203], v[76:79]
	v_mfma_f32_16x16x32_bf16 v[72:75], v[216:219], v[200:203], v[72:75]
	s_barrier
	s_mov_b32 m0, s26
	v_lshl_add_u64 v[222:223], s[4:5], 0, v[2:3]
	ds_read_b128 v[152:155], v195 offset:16384
	ds_read_b128 v[156:159], v195 offset:17408
	ds_read_b128 v[160:163], v195 offset:18432
	ds_read_b128 v[164:167], v195 offset:19456
	ds_read_b128 v[176:179], v195 offset:20480
	ds_read_b128 v[180:183], v195 offset:21504
	ds_read_b128 v[196:199], v195 offset:22528
	ds_read_b128 v[200:203], v195 offset:23552
	global_load_lds_dwordx4 v2, s[4:5]
	s_mov_b32 m0, s27
	s_nop 0
	s_add_u32 vcc_lo, s4, s86
	s_addc_u32 vcc_hi, s5, s87
	global_load_lds_dwordx4 v2, vcc
	s_barrier
	s_waitcnt lgkmcnt(0)
	v_mfma_f32_16x16x32_bf16 v[68:71], v[136:139], v[152:155], v[68:71]
	v_mfma_f32_16x16x32_bf16 v[64:67], v[144:147], v[152:155], v[64:67]
	v_mfma_f32_16x16x32_bf16 v[52:55], v[136:139], v[160:163], v[52:55]
	v_mfma_f32_16x16x32_bf16 v[48:51], v[144:147], v[160:163], v[48:51]
	v_mfma_f32_16x16x32_bf16 v[36:39], v[136:139], v[176:179], v[36:39]
	v_mfma_f32_16x16x32_bf16 v[32:35], v[144:147], v[176:179], v[32:35]
	v_mfma_f32_16x16x32_bf16 v[20:23], v[136:139], v[196:199], v[20:23]
	v_mfma_f32_16x16x32_bf16 v[16:19], v[144:147], v[196:199], v[16:19]
	v_mfma_f32_16x16x32_bf16 v[68:71], v[140:143], v[156:159], v[68:71]
	v_mfma_f32_16x16x32_bf16 v[64:67], v[148:151], v[156:159], v[64:67]
	v_mfma_f32_16x16x32_bf16 v[52:55], v[140:143], v[164:167], v[52:55]
	v_mfma_f32_16x16x32_bf16 v[48:51], v[148:151], v[164:167], v[48:51]
	v_mfma_f32_16x16x32_bf16 v[36:39], v[140:143], v[180:183], v[36:39]
	v_mfma_f32_16x16x32_bf16 v[32:35], v[148:151], v[180:183], v[32:35]
	v_mfma_f32_16x16x32_bf16 v[20:23], v[140:143], v[200:203], v[20:23]
	v_mfma_f32_16x16x32_bf16 v[16:19], v[148:151], v[200:203], v[16:19]
	s_barrier
	s_add_i32 s100, s44, s25
	s_mov_b32 m0, s100
	s_nop 0
	s_add_u32 vcc_lo, s22, s88
	s_addc_u32 vcc_hi, s23, s89
	global_load_lds_dwordx4 v172, vcc
	s_add_i32 m0, s100, 0x2000
	s_nop 0
	s_add_u32 vcc_lo, s22, s64
	s_addc_u32 vcc_hi, s23, s65
	global_load_lds_dwordx4 v172, vcc
	s_waitcnt vmcnt(6)
	s_barrier
	v_mfma_f32_16x16x32_bf16 v[60:63], v[204:207], v[152:155], v[60:63]
	v_mfma_f32_16x16x32_bf16 v[56:59], v[212:215], v[152:155], v[56:59]
	v_mfma_f32_16x16x32_bf16 v[44:47], v[204:207], v[160:163], v[44:47]
	v_mfma_f32_16x16x32_bf16 v[40:43], v[212:215], v[160:163], v[40:43]
	v_mfma_f32_16x16x32_bf16 v[28:31], v[204:207], v[176:179], v[28:31]
	v_mfma_f32_16x16x32_bf16 v[24:27], v[212:215], v[176:179], v[24:27]
	v_mfma_f32_16x16x32_bf16 v[12:15], v[204:207], v[196:199], v[12:15]
	v_mfma_f32_16x16x32_bf16 v[8:11], v[212:215], v[196:199], v[8:11]
	v_mfma_f32_16x16x32_bf16 v[60:63], v[208:211], v[156:159], v[60:63]
	v_mfma_f32_16x16x32_bf16 v[56:59], v[216:219], v[156:159], v[56:59]
	v_mfma_f32_16x16x32_bf16 v[44:47], v[208:211], v[164:167], v[44:47]
	v_mfma_f32_16x16x32_bf16 v[40:43], v[216:219], v[164:167], v[40:43]
	v_mfma_f32_16x16x32_bf16 v[28:31], v[208:211], v[180:183], v[28:31]
	v_mfma_f32_16x16x32_bf16 v[24:27], v[216:219], v[180:183], v[24:27]
	v_mfma_f32_16x16x32_bf16 v[12:15], v[208:211], v[200:203], v[12:15]
	v_mfma_f32_16x16x32_bf16 v[8:11], v[216:219], v[200:203], v[8:11]
	s_barrier
	s_add_i32 s100, 0, 0x18000
	ds_read_b128 v[136:139], v255 offset:32768
	ds_read_b128 v[140:143], v255 offset:33792
	ds_read_b128 v[144:147], v255 offset:34816
	ds_read_b128 v[148:151], v255 offset:35840
	s_mov_b32 m0, s29
	ds_read_b128 v[152:155], v195 offset:32768
	ds_read_b128 v[156:159], v195 offset:33792
	ds_read_b128 v[160:163], v195 offset:34816
	ds_read_b128 v[164:167], v195 offset:35840
	ds_read_b128 v[176:179], v195 offset:36864
	ds_read_b128 v[180:183], v195 offset:37888
	ds_read_b128 v[196:199], v195 offset:38912
	ds_read_b128 v[200:203], v195 offset:39936
	s_add_u32 vcc_lo, s4, s88
	s_addc_u32 vcc_hi, s5, s89
	global_load_lds_dwordx4 v2, vcc
	s_mov_b32 m0, s30
	s_nop 0
	s_add_u32 vcc_lo, s4, s64
	s_addc_u32 vcc_hi, s5, s65
	global_load_lds_dwordx4 v2, vcc
	s_waitcnt lgkmcnt(8)
	s_barrier
; #define G_STAGE(bufoff, gbase, o0, h64) do { \
;         __builtin_amdgcn_global_load_lds((const unsigned*)((const char*)(gbase) + (o0)), (LAS unsigned*)(lds + (bufoff) + ldsw), 16, 0, 0); \
;         __builtin_amdgcn_global_load_lds((const unsigned*)((const char*)(gbase) + (h64) + (o0)), (LAS unsigned*)(lds + (bufoff) + ldsw + 8192), 16, 0, 0); } while (0)
; #define G_LDA(dst, b, h) do { _Pragma("unroll") for (int m = 0; m < 4; ++m) _Pragma("unroll") for (int k = 0; k < 2; ++k) dst[m][k] = *(const LAS bf16x8*)(lds + G_SA(b, h) + aoff + m * 2048 + k * 1024); } while (0)
; #define G_LDB(dst, b, h) do { _Pragma("unroll") for (int n = 0; n < 2; ++n) _Pragma("unroll") for (int k = 0; k < 2; ++k) dst[n][k] = *(const LAS bf16x8*)(lds + G_SB(b, h) + boff + n * 2048 + k * 1024); } while (0)
; #define G_WAIT_V(n) asm volatile("s_waitcnt vmcnt(" #n ")" ::: "memory")
; #define G_WAIT_L(n) asm volatile("s_waitcnt lgkmcnt(" #n ")" ::: "memory")
; #define G_BAR __builtin_amdgcn_s_barrier()
; #define G_SCHED __builtin_amdgcn_sched_barrier(0)
;     ...
;             G_WAIT_L(8); G_BAR; G_WAIT_L(0); G_MMA(0, 0, At, B0); G_BAR; G_SCHED;
;             G_LDB(B1, 1, 1); G_STAGE(G_SB(1, 0), b3, cB0, qB);
;             G_BAR; G_WAIT_L(0); G_MMA(0, 1, At, B1); G_BAR;
;             G_LDA(At, 1, 1); G_STAGE(G_SA(1, 0), a3, cA0, qA);
;             G_BAR; G_WAIT_L(0); G_MMA(1, 0, At, B0); G_BAR; G_SCHED;
;             G_STAGE(G_SB(1, 1), b3 + chB, cB0, qB);
;             G_WAIT_V(6); G_BAR; G_MMA(1, 1, At, B1); G_BAR;
;         }
	s_waitcnt lgkmcnt(0)
	v_mfma_f32_16x16x32_bf16 v[132:135], v[136:139], v[152:155], v[132:135]
	v_mfma_f32_16x16x32_bf16 v[128:131], v[144:147], v[152:155], v[128:131]
	v_mfma_f32_16x16x32_bf16 v[116:119], v[136:139], v[160:163], v[116:119]
	v_mfma_f32_16x16x32_bf16 v[112:115], v[144:147], v[160:163], v[112:115]
	v_mfma_f32_16x16x32_bf16 v[100:103], v[136:139], v[176:179], v[100:103]
	v_mfma_f32_16x16x32_bf16 v[96:99], v[144:147], v[176:179], v[96:99]
	v_mfma_f32_16x16x32_bf16 v[84:87], v[136:139], v[196:199], v[84:87]
	v_mfma_f32_16x16x32_bf16 v[80:83], v[144:147], v[196:199], v[80:83]
	v_mfma_f32_16x16x32_bf16 v[132:135], v[140:143], v[156:159], v[132:135]
	v_mfma_f32_16x16x32_bf16 v[128:131], v[148:151], v[156:159], v[128:131]
	v_mfma_f32_16x16x32_bf16 v[116:119], v[140:143], v[164:167], v[116:119]
	v_mfma_f32_16x16x32_bf16 v[112:115], v[148:151], v[164:167], v[112:115]
	v_mfma_f32_16x16x32_bf16 v[100:103], v[140:143], v[180:183], v[100:103]
	v_mfma_f32_16x16x32_bf16 v[96:99], v[148:151], v[180:183], v[96:99]
	v_mfma_f32_16x16x32_bf16 v[84:87], v[140:143], v[200:203], v[84:87]
	v_mfma_f32_16x16x32_bf16 v[80:83], v[148:151], v[200:203], v[80:83]
	s_barrier
	s_add_i32 s5, 0, 0x1c000
	s_add_i32 s4, s100, s25
	s_mov_b32 m0, s4
	ds_read_b128 v[204:207], v255 offset:49152
	ds_read_b128 v[208:211], v255 offset:50176
	ds_read_b128 v[212:215], v255 offset:51200
	ds_read_b128 v[216:219], v255 offset:52224
	s_add_u32 vcc_lo, s22, s46
	s_addc_u32 vcc_hi, s23, s47
	global_load_lds_dwordx4 v172, vcc
	s_add_i32 m0, s4, 0x2000
	s_nop 0
	s_add_u32 vcc_lo, s22, s66
	s_addc_u32 vcc_hi, s23, s67
	global_load_lds_dwordx4 v172, vcc
	s_barrier
	s_waitcnt lgkmcnt(0)
	v_mfma_f32_16x16x32_bf16 v[124:127], v[204:207], v[152:155], v[124:127]
	v_mfma_f32_16x16x32_bf16 v[120:123], v[212:215], v[152:155], v[120:123]
	v_mfma_f32_16x16x32_bf16 v[108:111], v[204:207], v[160:163], v[108:111]
	v_mfma_f32_16x16x32_bf16 v[104:107], v[212:215], v[160:163], v[104:107]
	v_mfma_f32_16x16x32_bf16 v[92:95], v[204:207], v[176:179], v[92:95]
	v_mfma_f32_16x16x32_bf16 v[88:91], v[212:215], v[176:179], v[88:91]
	v_mfma_f32_16x16x32_bf16 v[76:79], v[204:207], v[196:199], v[76:79]
	v_mfma_f32_16x16x32_bf16 v[72:75], v[212:215], v[196:199], v[72:75]
	v_mfma_f32_16x16x32_bf16 v[124:127], v[208:211], v[156:159], v[124:127]
	v_mfma_f32_16x16x32_bf16 v[120:123], v[216:219], v[156:159], v[120:123]
	v_mfma_f32_16x16x32_bf16 v[108:111], v[208:211], v[164:167], v[108:111]
	v_mfma_f32_16x16x32_bf16 v[104:107], v[216:219], v[164:167], v[104:107]
	v_mfma_f32_16x16x32_bf16 v[92:95], v[208:211], v[180:183], v[92:95]
	v_mfma_f32_16x16x32_bf16 v[88:91], v[216:219], v[180:183], v[88:91]
	v_mfma_f32_16x16x32_bf16 v[76:79], v[208:211], v[200:203], v[76:79]
	v_mfma_f32_16x16x32_bf16 v[72:75], v[216:219], v[200:203], v[72:75]
	s_barrier
	s_mov_b32 m0, s31
	v_lshl_add_u64 v[224:225], v[222:223], 0, s[46:47]
	ds_read_b128 v[152:155], v195 offset:49152
	ds_read_b128 v[156:159], v195 offset:50176
	ds_read_b128 v[160:163], v195 offset:51200
	ds_read_b128 v[164:167], v195 offset:52224
	ds_read_b128 v[176:179], v195 offset:53248
	ds_read_b128 v[180:183], v195 offset:54272
	ds_read_b128 v[196:199], v195 offset:55296
	ds_read_b128 v[200:203], v195 offset:56320
	global_load_lds_dwordx4 v[224:225], off
	v_lshl_add_u64 v[222:223], v[222:223], 0, s[66:67]
	s_mov_b32 m0, s34
	s_nop 0
	global_load_lds_dwordx4 v[222:223], off
	s_barrier
	s_waitcnt lgkmcnt(0)
	v_mfma_f32_16x16x32_bf16 v[68:71], v[136:139], v[152:155], v[68:71]
	v_mfma_f32_16x16x32_bf16 v[64:67], v[144:147], v[152:155], v[64:67]
	v_mfma_f32_16x16x32_bf16 v[52:55], v[136:139], v[160:163], v[52:55]
	v_mfma_f32_16x16x32_bf16 v[48:51], v[144:147], v[160:163], v[48:51]
	v_mfma_f32_16x16x32_bf16 v[36:39], v[136:139], v[176:179], v[36:39]
	v_mfma_f32_16x16x32_bf16 v[32:35], v[144:147], v[176:179], v[32:35]
	v_mfma_f32_16x16x32_bf16 v[20:23], v[136:139], v[196:199], v[20:23]
	v_mfma_f32_16x16x32_bf16 v[16:19], v[144:147], v[196:199], v[16:19]
	v_mfma_f32_16x16x32_bf16 v[68:71], v[140:143], v[156:159], v[68:71]
	v_mfma_f32_16x16x32_bf16 v[64:67], v[148:151], v[156:159], v[64:67]
	v_mfma_f32_16x16x32_bf16 v[52:55], v[140:143], v[164:167], v[52:55]
	v_mfma_f32_16x16x32_bf16 v[48:51], v[148:151], v[164:167], v[48:51]
	v_mfma_f32_16x16x32_bf16 v[36:39], v[140:143], v[180:183], v[36:39]
	v_mfma_f32_16x16x32_bf16 v[32:35], v[148:151], v[180:183], v[32:35]
	v_mfma_f32_16x16x32_bf16 v[20:23], v[140:143], v[200:203], v[20:23]
	v_mfma_f32_16x16x32_bf16 v[16:19], v[148:151], v[200:203], v[16:19]
	s_barrier
	s_add_i32 s4, s5, s25
	s_mov_b32 m0, s4
	s_nop 0
	s_add_u32 vcc_lo, s22, s52
	s_addc_u32 vcc_hi, s23, s53
	global_load_lds_dwordx4 v172, vcc
	s_add_i32 m0, s4, 0x2000
	s_nop 0
	s_add_u32 vcc_lo, s22, s54
	s_addc_u32 vcc_hi, s23, s55
	global_load_lds_dwordx4 v172, vcc
	s_add_i32 s21, s21, 2
	s_add_u32 s2, s2, 0x100
	s_addc_u32 s3, s3, 0
	s_add_u32 s6, s6, 0x100
	s_addc_u32 s7, s7, 0
	s_cmp_gt_u32 s21, 41
	s_waitcnt vmcnt(6)
	s_barrier
	v_mfma_f32_16x16x32_bf16 v[60:63], v[204:207], v[152:155], v[60:63]
	v_mfma_f32_16x16x32_bf16 v[56:59], v[212:215], v[152:155], v[56:59]
	v_mfma_f32_16x16x32_bf16 v[44:47], v[204:207], v[160:163], v[44:47]
	v_mfma_f32_16x16x32_bf16 v[40:43], v[212:215], v[160:163], v[40:43]
	v_mfma_f32_16x16x32_bf16 v[28:31], v[204:207], v[176:179], v[28:31]
	v_mfma_f32_16x16x32_bf16 v[24:27], v[212:215], v[176:179], v[24:27]
	v_mfma_f32_16x16x32_bf16 v[12:15], v[204:207], v[196:199], v[12:15]
	v_mfma_f32_16x16x32_bf16 v[8:11], v[212:215], v[196:199], v[8:11]
	v_mfma_f32_16x16x32_bf16 v[60:63], v[208:211], v[156:159], v[60:63]
	v_mfma_f32_16x16x32_bf16 v[56:59], v[216:219], v[156:159], v[56:59]
	v_mfma_f32_16x16x32_bf16 v[44:47], v[208:211], v[164:167], v[44:47]
	v_mfma_f32_16x16x32_bf16 v[40:43], v[216:219], v[164:167], v[40:43]
	v_mfma_f32_16x16x32_bf16 v[28:31], v[208:211], v[180:183], v[28:31]
	v_mfma_f32_16x16x32_bf16 v[24:27], v[216:219], v[180:183], v[24:27]
	v_mfma_f32_16x16x32_bf16 v[12:15], v[208:211], v[200:203], v[12:15]
	v_mfma_f32_16x16x32_bf16 v[8:11], v[216:219], v[200:203], v[8:11]
	s_cbranch_scc0 .Ldb_FFO_cont

; #define G_STAGE(bufoff, gbase, o0, h64) do { \
;         __builtin_amdgcn_global_load_lds((const unsigned*)((const char*)(gbase) + (o0)), (LAS unsigned*)(lds + (bufoff) + ldsw), 16, 0, 0); \
;         __builtin_amdgcn_global_load_lds((const unsigned*)((const char*)(gbase) + (h64) + (o0)), (LAS unsigned*)(lds + (bufoff) + ldsw + 8192), 16, 0, 0); } while (0)
; #define G_LDA(dst, b, h) do { _Pragma("unroll") for (int m = 0; m < 4; ++m) _Pragma("unroll") for (int k = 0; k < 2; ++k) dst[m][k] = *(const LAS bf16x8*)(lds + G_SA(b, h) + aoff + m * 2048 + k * 1024); } while (0)
; #define G_LDB(dst, b, h) do { _Pragma("unroll") for (int n = 0; n < 2; ++n) _Pragma("unroll") for (int k = 0; k < 2; ++k) dst[n][k] = *(const LAS bf16x8*)(lds + G_SB(b, h) + boff + n * 2048 + k * 1024); } while (0)
; #define G_WAIT_L(n) asm volatile("s_waitcnt lgkmcnt(" #n ")" ::: "memory")
; #define G_BAR __builtin_amdgcn_s_barrier()
; #define G_SCHED __builtin_amdgcn_sched_barrier(0)
;     ...
;         const bool has_next = sched_next<PH, SUB>(E.ws, E.layer, ui + 1, nxt, E.x);
;         if (!has_next) nxt = cur;
;         const char* nA = nxt.A; const char* nB = nxt.B;
; #pragma unroll 1
;         for (int t = 0; t < nt; t += 2) {
;             const bool last = (t == nt - 2);
;             const char* a1 = cA + (size_t)(t + 1) * ckA;
;             const char* a2 = last ? nA : cA + (size_t)(t + 2) * ckA; const char* b2 = last ? nB : cB + (size_t)(t + 2) * kB;
;             const char* a3 = a2 + ckA; const char* b3 = b2 + kB;
;             G_LDB(B0, 0, 0); G_SCHED; G_LDA(At, 0, 0); G_STAGE(G_SA(1, 1), a1 + chA, cA0, qA);
;             G_WAIT_L(8); G_BAR; G_WAIT_L(0); G_MMA(0, 0, At, B0); G_BAR; G_SCHED;
;             G_LDB(B1, 0, 1); G_STAGE(G_SB(0, 0), b2, cB0, qB);
;             G_BAR; G_WAIT_L(0); G_MMA(0, 1, At, B1); G_BAR;
;             G_LDA(At, 0, 1); G_STAGE(G_SA(0, 0), a2, cA0, qA);
;     ...
;         if (!(cs.kind == K_MG_B && cur.aux < 2))
; #pragma unroll
;         for (int a = 0; a < 2; ++a)
; #pragma unroll
;             for (int b = 0; b < 2; ++b)
; #pragma unroll
;                 for (int m = 0; m < 4; ++m)
; #pragma unroll
;                     for (int n = 0; n < 2; ++n) acc[a][b][m][n] = (f32x4){0.f, 0.f, 0.f, 0.f};
.LBB0_1259:
	s_mov_b64 s[18:19], 0
	s_mov_b64 s[14:15], -1
	s_mov_b64 s[16:17], 0
	s_mov_b64 s[58:59], 0x10000
	s_cmp_eq_u32 s101, 2
	s_cselect_b32 s101, 0, s101
	v_add_u32_e32 v255, 0x10000, v137
	s_add_u32 s22, s10, s18
	s_addc_u32 s23, s11, s19
	s_add_u32 s20, s22, 0x100
	s_addc_u32 s21, s23, 0
	s_and_b64 s[4:5], s[16:17], exec
	s_cselect_b32 s20, s6, s20
	s_cselect_b32 s21, s7, s21
	s_add_u32 s4, s12, s18
	s_addc_u32 s5, s13, s19
	s_add_u32 s18, s4, 0x100
	s_addc_u32 s19, s5, 0
	s_add_i32 s44, 0, 0x10000
	ds_read_b128 v[140:143], v255 offset:0
	ds_read_b128 v[144:147], v255 offset:1024
	ds_read_b128 v[148:151], v255 offset:2048
	ds_read_b128 v[152:155], v255 offset:3072
	s_and_b64 s[4:5], s[16:17], exec
	s_cselect_b32 s16, s8, s18
	s_cselect_b32 s17, s9, s19
	s_add_i32 s5, 0, 0x14000
	s_add_i32 s43, 0, 0x18000
	s_add_i32 s18, 0, 0x1c000
	s_add_i32 s45, s44, s25
	s_add_i32 s51, s5, s25
	s_add_i32 s19, s43, s25
	s_add_i32 s53, s18, s25
	s_mov_b64 s[64:65], 0x8000
	s_mov_b64 s[62:63], 0x10080
	s_add_i32 m0, s31, 0xc000
	s_add_i32 s4, s31, 0xe000
	s_add_i32 s54, s45, 0x2000
	s_add_i32 s50, s51, 0x2000
	s_add_i32 s44, s19, 0x2000
	s_add_i32 s52, s53, 0x2000
	ds_read_b128 v[156:159], v138
	ds_read_b128 v[160:163], v138 offset:1024
	ds_read_b128 v[164:167], v138 offset:2048
	ds_read_b128 v[172:175], v138 offset:3072
	ds_read_b128 v[176:179], v138 offset:4096
	ds_read_b128 v[180:183], v138 offset:5120
	ds_read_b128 v[196:199], v138 offset:6144
	ds_read_b128 v[200:203], v138 offset:7168
	s_add_u32 vcc_lo, s22, s62
	s_addc_u32 vcc_hi, s23, s63
	global_load_lds_dwordx4 v2, vcc
	s_mov_b32 m0, s4
	s_nop 0
	s_add_u32 vcc_lo, s22, s68
	s_addc_u32 vcc_hi, s23, s69
	global_load_lds_dwordx4 v2, vcc
	s_waitcnt lgkmcnt(8)
	s_cmp_eq_u32 s101, 1
	s_cbranch_scc1 .Ldb_PLE0_skp
	s_barrier
.Ldb_PLE0_skp:
	s_mov_b32 s101, 0
	s_waitcnt lgkmcnt(0)
	v_mfma_f32_16x16x32_bf16 v[132:135], v[140:143], v[156:159], 0
	v_mfma_f32_16x16x32_bf16 v[128:131], v[148:151], v[156:159], 0
	v_mfma_f32_16x16x32_bf16 v[124:127], v[140:143], v[164:167], 0
	v_mfma_f32_16x16x32_bf16 v[116:119], v[148:151], v[164:167], 0
	v_mfma_f32_16x16x32_bf16 v[108:111], v[140:143], v[176:179], 0
	v_mfma_f32_16x16x32_bf16 v[100:103], v[148:151], v[176:179], 0
	v_mfma_f32_16x16x32_bf16 v[92:95], v[140:143], v[196:199], 0
	v_mfma_f32_16x16x32_bf16 v[84:87], v[148:151], v[196:199], 0
	v_mfma_f32_16x16x32_bf16 v[132:135], v[144:147], v[160:163], v[132:135]
	v_mfma_f32_16x16x32_bf16 v[128:131], v[152:155], v[160:163], v[128:131]
	v_mfma_f32_16x16x32_bf16 v[124:127], v[144:147], v[172:175], v[124:127]
	v_mfma_f32_16x16x32_bf16 v[116:119], v[152:155], v[172:175], v[116:119]
	v_mfma_f32_16x16x32_bf16 v[108:111], v[144:147], v[180:183], v[108:111]
	v_mfma_f32_16x16x32_bf16 v[100:103], v[152:155], v[180:183], v[100:103]
	v_mfma_f32_16x16x32_bf16 v[92:95], v[144:147], v[200:203], v[92:95]
	v_mfma_f32_16x16x32_bf16 v[84:87], v[152:155], v[200:203], v[84:87]
	s_barrier
	s_mov_b32 m0, s45
	v_lshl_add_u64 v[184:185], s[16:17], 0, v[0:1]
	ds_read_b128 v[204:207], v255 offset:16384
	ds_read_b128 v[208:211], v255 offset:17408
	ds_read_b128 v[212:215], v255 offset:18432
	ds_read_b128 v[216:219], v255 offset:19456
	global_load_lds_dwordx4 v0, s[16:17]
	s_mov_b32 m0, s54
	s_nop 0
	s_add_u32 vcc_lo, s16, s64
	s_addc_u32 vcc_hi, s17, s65
	global_load_lds_dwordx4 v0, vcc
	s_barrier
	s_waitcnt lgkmcnt(0)
	v_mfma_f32_16x16x32_bf16 v[120:123], v[204:207], v[156:159], 0
	v_mfma_f32_16x16x32_bf16 v[112:115], v[212:215], v[156:159], 0
	v_mfma_f32_16x16x32_bf16 v[104:107], v[204:207], v[164:167], 0
	v_mfma_f32_16x16x32_bf16 v[96:99], v[212:215], v[164:167], 0
	v_mfma_f32_16x16x32_bf16 v[88:91], v[204:207], v[176:179], 0
	v_mfma_f32_16x16x32_bf16 v[80:83], v[212:215], v[176:179], 0
	v_mfma_f32_16x16x32_bf16 v[76:79], v[204:207], v[196:199], 0
	v_mfma_f32_16x16x32_bf16 v[72:75], v[212:215], v[196:199], 0
	v_mfma_f32_16x16x32_bf16 v[120:123], v[208:211], v[160:163], v[120:123]
	v_mfma_f32_16x16x32_bf16 v[112:115], v[216:219], v[160:163], v[112:115]
	v_mfma_f32_16x16x32_bf16 v[104:107], v[208:211], v[172:175], v[104:107]
	v_mfma_f32_16x16x32_bf16 v[96:99], v[216:219], v[172:175], v[96:99]
	v_mfma_f32_16x16x32_bf16 v[88:91], v[208:211], v[180:183], v[88:91]
	v_mfma_f32_16x16x32_bf16 v[80:83], v[216:219], v[180:183], v[80:83]
	v_mfma_f32_16x16x32_bf16 v[76:79], v[208:211], v[200:203], v[76:79]
	v_mfma_f32_16x16x32_bf16 v[72:75], v[216:219], v[200:203], v[72:75]
	s_barrier
	s_mov_b32 m0, s31
	v_lshl_add_u64 v[220:221], s[20:21], 0, v[2:3]
	s_mov_b64 s[4:5], 0x8000
	ds_read_b128 v[156:159], v138 offset:16384
	ds_read_b128 v[160:163], v138 offset:17408
	ds_read_b128 v[164:167], v138 offset:18432
	ds_read_b128 v[172:175], v138 offset:19456
	ds_read_b128 v[176:179], v138 offset:20480
	ds_read_b128 v[180:183], v138 offset:21504
	ds_read_b128 v[196:199], v138 offset:22528
	ds_read_b128 v[200:203], v138 offset:23552
	global_load_lds_dwordx4 v2, s[20:21]
	s_mov_b32 m0, s33
	s_mov_b64 s[16:17], 0x18000
	s_add_u32 vcc_lo, s20, s4
	s_addc_u32 vcc_hi, s21, s5
	global_load_lds_dwordx4 v2, vcc
	s_barrier
; #define G_STAGE(bufoff, gbase, o0, h64) do { \
;         __builtin_amdgcn_global_load_lds((const unsigned*)((const char*)(gbase) + (o0)), (LAS unsigned*)(lds + (bufoff) + ldsw), 16, 0, 0); \
;         __builtin_amdgcn_global_load_lds((const unsigned*)((const char*)(gbase) + (h64) + (o0)), (LAS unsigned*)(lds + (bufoff) + ldsw + 8192), 16, 0, 0); } while (0)
; #define G_LDA(dst, b, h) do { _Pragma("unroll") for (int m = 0; m < 4; ++m) _Pragma("unroll") for (int k = 0; k < 2; ++k) dst[m][k] = *(const LAS bf16x8*)(lds + G_SA(b, h) + aoff + m * 2048 + k * 1024); } while (0)
; #define G_LDB(dst, b, h) do { _Pragma("unroll") for (int n = 0; n < 2; ++n) _Pragma("unroll") for (int k = 0; k < 2; ++k) dst[n][k] = *(const LAS bf16x8*)(lds + G_SB(b, h) + boff + n * 2048 + k * 1024); } while (0)
; #define G_WAIT_V(n) asm volatile("s_waitcnt vmcnt(" #n ")" ::: "memory")
; #define G_WAIT_L(n) asm volatile("s_waitcnt lgkmcnt(" #n ")" ::: "memory")
; #define G_BAR __builtin_amdgcn_s_barrier()
; #define G_SCHED __builtin_amdgcn_sched_barrier(0)
;     ...
;             G_LDA(At, 0, 1); G_STAGE(G_SA(0, 0), a2, cA0, qA);
;             G_BAR; G_WAIT_L(0); G_MMA(1, 0, At, B0); G_BAR; G_SCHED;
;             G_STAGE(G_SB(0, 1), b2 + chB, cB0, qB);
;             G_WAIT_V(6); G_BAR; G_MMA(1, 1, At, B1); G_BAR;
;             G_LDB(B0, 1, 0); G_SCHED; G_LDA(At, 1, 0); G_STAGE(G_SA(0, 1), a2 + chA, cA0, qA);
;             G_WAIT_L(8); G_BAR; G_WAIT_L(0); G_MMA(0, 0, At, B0); G_BAR; G_SCHED;
;             G_LDB(B1, 1, 1); G_STAGE(G_SB(1, 0), b3, cB0, qB);
	s_waitcnt lgkmcnt(0)
	s_mov_b64 s[20:21], 0x8080
	s_waitcnt lgkmcnt(0)
	v_mfma_f32_16x16x32_bf16 v[68:71], v[140:143], v[156:159], 0
	v_mfma_f32_16x16x32_bf16 v[64:67], v[148:151], v[156:159], 0
	v_mfma_f32_16x16x32_bf16 v[60:63], v[140:143], v[164:167], 0
	v_mfma_f32_16x16x32_bf16 v[52:55], v[148:151], v[164:167], 0
	v_mfma_f32_16x16x32_bf16 v[44:47], v[140:143], v[176:179], 0
	v_mfma_f32_16x16x32_bf16 v[36:39], v[148:151], v[176:179], 0
	v_mfma_f32_16x16x32_bf16 v[28:31], v[140:143], v[196:199], 0
	v_mfma_f32_16x16x32_bf16 v[20:23], v[148:151], v[196:199], 0
	v_mfma_f32_16x16x32_bf16 v[68:71], v[144:147], v[160:163], v[68:71]
	v_mfma_f32_16x16x32_bf16 v[64:67], v[152:155], v[160:163], v[64:67]
	v_mfma_f32_16x16x32_bf16 v[60:63], v[144:147], v[172:175], v[60:63]
	v_mfma_f32_16x16x32_bf16 v[52:55], v[152:155], v[172:175], v[52:55]
	v_mfma_f32_16x16x32_bf16 v[44:47], v[144:147], v[180:183], v[44:47]
	v_mfma_f32_16x16x32_bf16 v[36:39], v[152:155], v[180:183], v[36:39]
	v_mfma_f32_16x16x32_bf16 v[28:31], v[144:147], v[200:203], v[28:31]
	v_mfma_f32_16x16x32_bf16 v[20:23], v[152:155], v[200:203], v[20:23]
	s_barrier
	s_mov_b32 m0, s51
	v_lshl_add_u64 v[140:141], v[184:185], 0, s[58:59]
	global_load_lds_dwordx4 v[140:141], off
	v_lshl_add_u64 v[140:141], v[184:185], 0, s[16:17]
	s_mov_b32 m0, s50
	s_nop 0
	global_load_lds_dwordx4 v[140:141], off
	s_waitcnt vmcnt(6)
	s_barrier
	v_mfma_f32_16x16x32_bf16 v[56:59], v[204:207], v[156:159], 0
	v_mfma_f32_16x16x32_bf16 v[48:51], v[212:215], v[156:159], 0
	v_mfma_f32_16x16x32_bf16 v[40:43], v[204:207], v[164:167], 0
	v_mfma_f32_16x16x32_bf16 v[32:35], v[212:215], v[164:167], 0
	v_mfma_f32_16x16x32_bf16 v[24:27], v[204:207], v[176:179], 0
	v_mfma_f32_16x16x32_bf16 v[16:19], v[212:215], v[176:179], 0
	v_mfma_f32_16x16x32_bf16 v[12:15], v[204:207], v[196:199], 0
	v_mfma_f32_16x16x32_bf16 v[8:11], v[212:215], v[196:199], 0
	v_mfma_f32_16x16x32_bf16 v[56:59], v[208:211], v[160:163], v[56:59]
	v_mfma_f32_16x16x32_bf16 v[48:51], v[216:219], v[160:163], v[48:51]
	v_mfma_f32_16x16x32_bf16 v[40:43], v[208:211], v[172:175], v[40:43]
	v_mfma_f32_16x16x32_bf16 v[32:35], v[216:219], v[172:175], v[32:35]
	v_mfma_f32_16x16x32_bf16 v[24:27], v[208:211], v[180:183], v[24:27]
	v_mfma_f32_16x16x32_bf16 v[16:19], v[216:219], v[180:183], v[16:19]
	v_mfma_f32_16x16x32_bf16 v[12:15], v[208:211], v[200:203], v[12:15]
	v_mfma_f32_16x16x32_bf16 v[8:11], v[216:219], v[200:203], v[8:11]
	s_barrier
	ds_read_b128 v[140:143], v255 offset:32768
	ds_read_b128 v[144:147], v255 offset:33792
	ds_read_b128 v[148:151], v255 offset:34816
	ds_read_b128 v[152:155], v255 offset:35840
	s_mov_b32 m0, s34
	v_lshl_add_u64 v[204:205], v[220:221], 0, s[58:59]
	ds_read_b128 v[156:159], v138 offset:32768
	ds_read_b128 v[160:163], v138 offset:33792
	ds_read_b128 v[164:167], v138 offset:34816
	ds_read_b128 v[172:175], v138 offset:35840
	ds_read_b128 v[176:179], v138 offset:36864
	ds_read_b128 v[180:183], v138 offset:37888
	ds_read_b128 v[196:199], v138 offset:38912
	ds_read_b128 v[200:203], v138 offset:39936
	global_load_lds_dwordx4 v[204:205], off
	v_lshl_add_u64 v[204:205], v[220:221], 0, s[16:17]
	s_mov_b32 m0, s35
	s_nop 0
	global_load_lds_dwordx4 v[204:205], off
	s_waitcnt lgkmcnt(8)
	s_barrier
	s_waitcnt lgkmcnt(0)
	v_mfma_f32_16x16x32_bf16 v[132:135], v[140:143], v[156:159], v[132:135]
	v_mfma_f32_16x16x32_bf16 v[128:131], v[148:151], v[156:159], v[128:131]
	v_mfma_f32_16x16x32_bf16 v[124:127], v[140:143], v[164:167], v[124:127]
	v_mfma_f32_16x16x32_bf16 v[116:119], v[148:151], v[164:167], v[116:119]
	v_mfma_f32_16x16x32_bf16 v[108:111], v[140:143], v[176:179], v[108:111]
	v_mfma_f32_16x16x32_bf16 v[100:103], v[148:151], v[176:179], v[100:103]
	v_mfma_f32_16x16x32_bf16 v[92:95], v[140:143], v[196:199], v[92:95]
	v_mfma_f32_16x16x32_bf16 v[84:87], v[148:151], v[196:199], v[84:87]
	v_mfma_f32_16x16x32_bf16 v[132:135], v[144:147], v[160:163], v[132:135]
	v_mfma_f32_16x16x32_bf16 v[128:131], v[152:155], v[160:163], v[128:131]
	v_mfma_f32_16x16x32_bf16 v[124:127], v[144:147], v[172:175], v[124:127]
	v_mfma_f32_16x16x32_bf16 v[116:119], v[152:155], v[172:175], v[116:119]
	v_mfma_f32_16x16x32_bf16 v[108:111], v[144:147], v[180:183], v[108:111]
	v_mfma_f32_16x16x32_bf16 v[100:103], v[152:155], v[180:183], v[100:103]
	v_mfma_f32_16x16x32_bf16 v[92:95], v[144:147], v[200:203], v[92:95]
	v_mfma_f32_16x16x32_bf16 v[84:87], v[152:155], v[200:203], v[84:87]
	s_barrier
	s_mov_b32 m0, s19
	v_lshl_add_u64 v[222:223], v[184:185], 0, s[46:47]
	ds_read_b128 v[204:207], v255 offset:49152
	ds_read_b128 v[208:211], v255 offset:50176
	ds_read_b128 v[212:215], v255 offset:51200
	ds_read_b128 v[216:219], v255 offset:52224
	global_load_lds_dwordx4 v[222:223], off
	v_lshl_add_u64 v[222:223], v[184:185], 0, s[20:21]
	s_mov_b32 m0, s44
	s_mov_b64 s[4:5], 0x10080
	global_load_lds_dwordx4 v[222:223], off
	s_barrier
	s_waitcnt lgkmcnt(0)
	v_mfma_f32_16x16x32_bf16 v[120:123], v[204:207], v[156:159], v[120:123]
	v_mfma_f32_16x16x32_bf16 v[112:115], v[212:215], v[156:159], v[112:115]
	v_mfma_f32_16x16x32_bf16 v[104:107], v[204:207], v[164:167], v[104:107]
	v_mfma_f32_16x16x32_bf16 v[96:99], v[212:215], v[164:167], v[96:99]
	v_mfma_f32_16x16x32_bf16 v[88:91], v[204:207], v[176:179], v[88:91]
	v_mfma_f32_16x16x32_bf16 v[80:83], v[212:215], v[176:179], v[80:83]
	v_mfma_f32_16x16x32_bf16 v[76:79], v[204:207], v[196:199], v[76:79]
	v_mfma_f32_16x16x32_bf16 v[72:75], v[212:215], v[196:199], v[72:75]
	v_mfma_f32_16x16x32_bf16 v[120:123], v[208:211], v[160:163], v[120:123]
	v_mfma_f32_16x16x32_bf16 v[112:115], v[216:219], v[160:163], v[112:115]
	v_mfma_f32_16x16x32_bf16 v[104:107], v[208:211], v[172:175], v[104:107]
	v_mfma_f32_16x16x32_bf16 v[96:99], v[216:219], v[172:175], v[96:99]
	v_mfma_f32_16x16x32_bf16 v[88:91], v[208:211], v[180:183], v[88:91]
	v_mfma_f32_16x16x32_bf16 v[80:83], v[216:219], v[180:183], v[80:83]
	v_mfma_f32_16x16x32_bf16 v[76:79], v[208:211], v[200:203], v[76:79]
	v_mfma_f32_16x16x32_bf16 v[72:75], v[216:219], v[200:203], v[72:75]
	s_barrier
; #define G_STAGE(bufoff, gbase, o0, h64) do { \
;         __builtin_amdgcn_global_load_lds((const unsigned*)((const char*)(gbase) + (o0)), (LAS unsigned*)(lds + (bufoff) + ldsw), 16, 0, 0); \
;         __builtin_amdgcn_global_load_lds((const unsigned*)((const char*)(gbase) + (h64) + (o0)), (LAS unsigned*)(lds + (bufoff) + ldsw + 8192), 16, 0, 0); } while (0)
; #define G_LDA(dst, b, h) do { _Pragma("unroll") for (int m = 0; m < 4; ++m) _Pragma("unroll") for (int k = 0; k < 2; ++k) dst[m][k] = *(const LAS bf16x8*)(lds + G_SA(b, h) + aoff + m * 2048 + k * 1024); } while (0)
; #define G_LDB(dst, b, h) do { _Pragma("unroll") for (int n = 0; n < 2; ++n) _Pragma("unroll") for (int k = 0; k < 2; ++k) dst[n][k] = *(const LAS bf16x8*)(lds + G_SB(b, h) + boff + n * 2048 + k * 1024); } while (0)
; #define G_WAIT_V(n) asm volatile("s_waitcnt vmcnt(" #n ")" ::: "memory")
; #define G_WAIT_L(n) asm volatile("s_waitcnt lgkmcnt(" #n ")" ::: "memory")
; #define G_BAR __builtin_amdgcn_s_barrier()
; #define G_SCHED __builtin_amdgcn_sched_barrier(0)
;     ...
;         for (int t = 0; t < nt; t += 2) {
;             const bool last = (t == nt - 2);
;             const char* a1 = cA + (size_t)(t + 1) * ckA;
;             const char* a2 = last ? nA : cA + (size_t)(t + 2) * ckA; const char* b2 = last ? nB : cB + (size_t)(t + 2) * kB;
;             const char* a3 = a2 + ckA; const char* b3 = b2 + kB;
;             G_LDB(B0, 0, 0); G_SCHED; G_LDA(At, 0, 0); G_STAGE(G_SA(1, 1), a1 + chA, cA0, qA);
;             G_WAIT_L(8); G_BAR; G_WAIT_L(0); G_MMA(0, 0, At, B0); G_BAR; G_SCHED;
;     ...
;             G_LDB(B1, 1, 1); G_STAGE(G_SB(1, 0), b3, cB0, qB);
;             G_BAR; G_WAIT_L(0); G_MMA(0, 1, At, B1); G_BAR;
;             G_LDA(At, 1, 1); G_STAGE(G_SA(1, 0), a3, cA0, qA);
;             G_BAR; G_WAIT_L(0); G_MMA(1, 0, At, B0); G_BAR; G_SCHED;
;             G_STAGE(G_SB(1, 1), b3 + chB, cB0, qB);
;             G_WAIT_V(6); G_BAR; G_MMA(1, 1, At, B1); G_BAR;
;         }
	s_mov_b32 m0, s36
	v_lshl_add_u64 v[222:223], v[220:221], 0, s[46:47]
	ds_read_b128 v[156:159], v138 offset:49152
	ds_read_b128 v[160:163], v138 offset:50176
	ds_read_b128 v[164:167], v138 offset:51200
	ds_read_b128 v[172:175], v138 offset:52224
	ds_read_b128 v[176:179], v138 offset:53248
	ds_read_b128 v[180:183], v138 offset:54272
	ds_read_b128 v[196:199], v138 offset:55296
	ds_read_b128 v[200:203], v138 offset:56320
	global_load_lds_dwordx4 v[222:223], off
	v_lshl_add_u64 v[220:221], v[220:221], 0, s[20:21]
	s_mov_b32 m0, s37
	s_nop 0
	global_load_lds_dwordx4 v[220:221], off
	s_barrier
	s_waitcnt lgkmcnt(0)
	v_mfma_f32_16x16x32_bf16 v[68:71], v[140:143], v[156:159], v[68:71]
	v_mfma_f32_16x16x32_bf16 v[64:67], v[148:151], v[156:159], v[64:67]
	v_mfma_f32_16x16x32_bf16 v[60:63], v[140:143], v[164:167], v[60:63]
	v_mfma_f32_16x16x32_bf16 v[52:55], v[148:151], v[164:167], v[52:55]
	v_mfma_f32_16x16x32_bf16 v[44:47], v[140:143], v[176:179], v[44:47]
	v_mfma_f32_16x16x32_bf16 v[36:39], v[148:151], v[176:179], v[36:39]
	v_mfma_f32_16x16x32_bf16 v[28:31], v[140:143], v[196:199], v[28:31]
	v_mfma_f32_16x16x32_bf16 v[20:23], v[148:151], v[196:199], v[20:23]
	v_mfma_f32_16x16x32_bf16 v[68:71], v[144:147], v[160:163], v[68:71]
	v_mfma_f32_16x16x32_bf16 v[64:67], v[152:155], v[160:163], v[64:67]
	v_mfma_f32_16x16x32_bf16 v[60:63], v[144:147], v[172:175], v[60:63]
	v_mfma_f32_16x16x32_bf16 v[52:55], v[152:155], v[172:175], v[52:55]
	v_mfma_f32_16x16x32_bf16 v[44:47], v[144:147], v[180:183], v[44:47]
	v_mfma_f32_16x16x32_bf16 v[36:39], v[152:155], v[180:183], v[36:39]
	v_mfma_f32_16x16x32_bf16 v[28:31], v[144:147], v[200:203], v[28:31]
	v_mfma_f32_16x16x32_bf16 v[20:23], v[152:155], v[200:203], v[20:23]
	s_barrier
	s_mov_b32 m0, s53
	v_lshl_add_u64 v[140:141], v[184:185], 0, s[4:5]
	global_load_lds_dwordx4 v[140:141], off
	v_lshl_add_u64 v[140:141], v[184:185], 0, s[68:69]
	s_mov_b32 m0, s52
	s_nop 0
	global_load_lds_dwordx4 v[140:141], off
	s_waitcnt vmcnt(6)
	s_barrier
	v_mfma_f32_16x16x32_bf16 v[56:59], v[204:207], v[156:159], v[56:59]
	v_mfma_f32_16x16x32_bf16 v[48:51], v[212:215], v[156:159], v[48:51]
	v_mfma_f32_16x16x32_bf16 v[40:43], v[204:207], v[164:167], v[40:43]
	v_mfma_f32_16x16x32_bf16 v[32:35], v[212:215], v[164:167], v[32:35]
	v_mfma_f32_16x16x32_bf16 v[24:27], v[204:207], v[176:179], v[24:27]
	v_mfma_f32_16x16x32_bf16 v[16:19], v[212:215], v[176:179], v[16:19]
	v_mfma_f32_16x16x32_bf16 v[12:15], v[204:207], v[196:199], v[12:15]
	v_mfma_f32_16x16x32_bf16 v[8:11], v[212:215], v[196:199], v[8:11]
	v_mfma_f32_16x16x32_bf16 v[56:59], v[208:211], v[160:163], v[56:59]
	v_mfma_f32_16x16x32_bf16 v[48:51], v[216:219], v[160:163], v[48:51]
	v_mfma_f32_16x16x32_bf16 v[40:43], v[208:211], v[172:175], v[40:43]
	v_mfma_f32_16x16x32_bf16 v[32:35], v[216:219], v[172:175], v[32:35]
	v_mfma_f32_16x16x32_bf16 v[24:27], v[208:211], v[180:183], v[24:27]
	v_mfma_f32_16x16x32_bf16 v[16:19], v[216:219], v[180:183], v[16:19]
	v_mfma_f32_16x16x32_bf16 v[12:15], v[208:211], v[200:203], v[12:15]
	v_mfma_f32_16x16x32_bf16 v[8:11], v[216:219], v[200:203], v[8:11]
	s_andn2_b64 vcc, exec, s[14:15]
	s_mov_b64 s[16:17], -1
	s_mov_b64 s[14:15], 0
	s_mov_b64 s[18:19], 0x100
	s_cbranch_vccz .Ldb_PLE0_cont
	s_branch .Ldb_PLE0_xl
.LBB0_1260:
	s_add_u32 s22, s10, s18
	s_addc_u32 s23, s11, s19
	s_add_u32 s20, s22, 0x100
	s_addc_u32 s21, s23, 0
	s_and_b64 s[4:5], s[16:17], exec
	s_cselect_b32 s20, s6, s20
	s_cselect_b32 s21, s7, s21
	s_add_u32 s4, s12, s18
	s_addc_u32 s5, s13, s19
	s_add_u32 s18, s4, 0x100
	s_addc_u32 s19, s5, 0
	s_add_i32 s44, 0, 0x10000
	ds_read_b128 v[140:143], v255 offset:0
	ds_read_b128 v[144:147], v255 offset:1024
	ds_read_b128 v[148:151], v255 offset:2048
	ds_read_b128 v[152:155], v255 offset:3072
	s_and_b64 s[4:5], s[16:17], exec
	s_cselect_b32 s16, s8, s18
	s_cselect_b32 s17, s9, s19
	s_add_i32 s5, 0, 0x14000
	s_add_i32 s43, 0, 0x18000
	s_add_i32 s18, 0, 0x1c000
	s_add_i32 s45, s44, s25
	s_add_i32 s51, s5, s25
	s_add_i32 s19, s43, s25
	s_add_i32 s53, s18, s25
	s_mov_b64 s[64:65], 0x8000
	s_mov_b64 s[62:63], 0x10080
	s_add_i32 m0, s31, 0xc000
	s_add_i32 s4, s31, 0xe000
	s_add_i32 s54, s45, 0x2000
	s_add_i32 s50, s51, 0x2000
	s_add_i32 s44, s19, 0x2000
	s_add_i32 s52, s53, 0x2000
	ds_read_b128 v[156:159], v138
	ds_read_b128 v[160:163], v138 offset:1024
	ds_read_b128 v[164:167], v138 offset:2048
	ds_read_b128 v[172:175], v138 offset:3072
	ds_read_b128 v[176:179], v138 offset:4096
	ds_read_b128 v[180:183], v138 offset:5120
	ds_read_b128 v[196:199], v138 offset:6144
	ds_read_b128 v[200:203], v138 offset:7168
	s_add_u32 vcc_lo, s22, s62
	s_addc_u32 vcc_hi, s23, s63
	global_load_lds_dwordx4 v2, vcc
	s_mov_b32 m0, s4
	s_nop 0
	s_add_u32 vcc_lo, s22, s68
	s_addc_u32 vcc_hi, s23, s69
	global_load_lds_dwordx4 v2, vcc
	s_waitcnt lgkmcnt(8)
	s_barrier
	s_waitcnt lgkmcnt(0)
	v_mfma_f32_16x16x32_bf16 v[132:135], v[140:143], v[156:159], v[132:135]
	v_mfma_f32_16x16x32_bf16 v[128:131], v[148:151], v[156:159], v[128:131]
	v_mfma_f32_16x16x32_bf16 v[124:127], v[140:143], v[164:167], v[124:127]
	v_mfma_f32_16x16x32_bf16 v[116:119], v[148:151], v[164:167], v[116:119]
	v_mfma_f32_16x16x32_bf16 v[108:111], v[140:143], v[176:179], v[108:111]
	v_mfma_f32_16x16x32_bf16 v[100:103], v[148:151], v[176:179], v[100:103]
	v_mfma_f32_16x16x32_bf16 v[92:95], v[140:143], v[196:199], v[92:95]
	v_mfma_f32_16x16x32_bf16 v[84:87], v[148:151], v[196:199], v[84:87]
	v_mfma_f32_16x16x32_bf16 v[132:135], v[144:147], v[160:163], v[132:135]
	v_mfma_f32_16x16x32_bf16 v[128:131], v[152:155], v[160:163], v[128:131]
	v_mfma_f32_16x16x32_bf16 v[124:127], v[144:147], v[172:175], v[124:127]
	v_mfma_f32_16x16x32_bf16 v[116:119], v[152:155], v[172:175], v[116:119]
	v_mfma_f32_16x16x32_bf16 v[108:111], v[144:147], v[180:183], v[108:111]
	v_mfma_f32_16x16x32_bf16 v[100:103], v[152:155], v[180:183], v[100:103]
	v_mfma_f32_16x16x32_bf16 v[92:95], v[144:147], v[200:203], v[92:95]
	v_mfma_f32_16x16x32_bf16 v[84:87], v[152:155], v[200:203], v[84:87]
	s_barrier
; #define G_STAGE(bufoff, gbase, o0, h64) do { \
;         __builtin_amdgcn_global_load_lds((const unsigned*)((const char*)(gbase) + (o0)), (LAS unsigned*)(lds + (bufoff) + ldsw), 16, 0, 0); \
;         __builtin_amdgcn_global_load_lds((const unsigned*)((const char*)(gbase) + (h64) + (o0)), (LAS unsigned*)(lds + (bufoff) + ldsw + 8192), 16, 0, 0); } while (0)
; #define G_LDA(dst, b, h) do { _Pragma("unroll") for (int m = 0; m < 4; ++m) _Pragma("unroll") for (int k = 0; k < 2; ++k) dst[m][k] = *(const LAS bf16x8*)(lds + G_SA(b, h) + aoff + m * 2048 + k * 1024); } while (0)
; #define G_LDB(dst, b, h) do { _Pragma("unroll") for (int n = 0; n < 2; ++n) _Pragma("unroll") for (int k = 0; k < 2; ++k) dst[n][k] = *(const LAS bf16x8*)(lds + G_SB(b, h) + boff + n * 2048 + k * 1024); } while (0)
; #define G_WAIT_V(n) asm volatile("s_waitcnt vmcnt(" #n ")" ::: "memory")
; #define G_WAIT_L(n) asm volatile("s_waitcnt lgkmcnt(" #n ")" ::: "memory")
; #define G_BAR __builtin_amdgcn_s_barrier()
; #define G_SCHED __builtin_amdgcn_sched_barrier(0)
;     ...
;             G_LDB(B1, 0, 1); G_STAGE(G_SB(0, 0), b2, cB0, qB);
;             G_BAR; G_WAIT_L(0); G_MMA(0, 1, At, B1); G_BAR;
;             G_LDA(At, 0, 1); G_STAGE(G_SA(0, 0), a2, cA0, qA);
;             G_BAR; G_WAIT_L(0); G_MMA(1, 0, At, B0); G_BAR; G_SCHED;
;             G_STAGE(G_SB(0, 1), b2 + chB, cB0, qB);
;             G_WAIT_V(6); G_BAR; G_MMA(1, 1, At, B1); G_BAR;
;             G_LDB(B0, 1, 0); G_SCHED; G_LDA(At, 1, 0); G_STAGE(G_SA(0, 1), a2 + chA, cA0, qA);
;             G_WAIT_L(8); G_BAR; G_WAIT_L(0); G_MMA(0, 0, At, B0); G_BAR; G_SCHED;
	s_mov_b32 m0, s45
	v_lshl_add_u64 v[184:185], s[16:17], 0, v[0:1]
	ds_read_b128 v[204:207], v255 offset:16384
	ds_read_b128 v[208:211], v255 offset:17408
	ds_read_b128 v[212:215], v255 offset:18432
	ds_read_b128 v[216:219], v255 offset:19456
	global_load_lds_dwordx4 v0, s[16:17]
	s_mov_b32 m0, s54
	s_nop 0
	s_add_u32 vcc_lo, s16, s64
	s_addc_u32 vcc_hi, s17, s65
	global_load_lds_dwordx4 v0, vcc
	s_barrier
	s_waitcnt lgkmcnt(0)
	v_mfma_f32_16x16x32_bf16 v[120:123], v[204:207], v[156:159], v[120:123]
	v_mfma_f32_16x16x32_bf16 v[112:115], v[212:215], v[156:159], v[112:115]
	v_mfma_f32_16x16x32_bf16 v[104:107], v[204:207], v[164:167], v[104:107]
	v_mfma_f32_16x16x32_bf16 v[96:99], v[212:215], v[164:167], v[96:99]
	v_mfma_f32_16x16x32_bf16 v[88:91], v[204:207], v[176:179], v[88:91]
	v_mfma_f32_16x16x32_bf16 v[80:83], v[212:215], v[176:179], v[80:83]
	v_mfma_f32_16x16x32_bf16 v[76:79], v[204:207], v[196:199], v[76:79]
	v_mfma_f32_16x16x32_bf16 v[72:75], v[212:215], v[196:199], v[72:75]
	v_mfma_f32_16x16x32_bf16 v[120:123], v[208:211], v[160:163], v[120:123]
	v_mfma_f32_16x16x32_bf16 v[112:115], v[216:219], v[160:163], v[112:115]
	v_mfma_f32_16x16x32_bf16 v[104:107], v[208:211], v[172:175], v[104:107]
	v_mfma_f32_16x16x32_bf16 v[96:99], v[216:219], v[172:175], v[96:99]
	v_mfma_f32_16x16x32_bf16 v[88:91], v[208:211], v[180:183], v[88:91]
	v_mfma_f32_16x16x32_bf16 v[80:83], v[216:219], v[180:183], v[80:83]
	v_mfma_f32_16x16x32_bf16 v[76:79], v[208:211], v[200:203], v[76:79]
	v_mfma_f32_16x16x32_bf16 v[72:75], v[216:219], v[200:203], v[72:75]
	s_barrier
	s_mov_b32 m0, s31
	v_lshl_add_u64 v[220:221], s[20:21], 0, v[2:3]
	s_mov_b64 s[4:5], 0x8000
	ds_read_b128 v[156:159], v138 offset:16384
	ds_read_b128 v[160:163], v138 offset:17408
	ds_read_b128 v[164:167], v138 offset:18432
	ds_read_b128 v[172:175], v138 offset:19456
	ds_read_b128 v[176:179], v138 offset:20480
	ds_read_b128 v[180:183], v138 offset:21504
	ds_read_b128 v[196:199], v138 offset:22528
	ds_read_b128 v[200:203], v138 offset:23552
	global_load_lds_dwordx4 v2, s[20:21]
	s_mov_b32 m0, s33
	s_mov_b64 s[16:17], 0x18000
	s_add_u32 vcc_lo, s20, s4
	s_addc_u32 vcc_hi, s21, s5
	global_load_lds_dwordx4 v2, vcc
	s_barrier
	s_waitcnt lgkmcnt(0)
	s_mov_b64 s[20:21], 0x8080
	s_waitcnt lgkmcnt(0)
	v_mfma_f32_16x16x32_bf16 v[68:71], v[140:143], v[156:159], v[68:71]
	v_mfma_f32_16x16x32_bf16 v[64:67], v[148:151], v[156:159], v[64:67]
	v_mfma_f32_16x16x32_bf16 v[60:63], v[140:143], v[164:167], v[60:63]
	v_mfma_f32_16x16x32_bf16 v[52:55], v[148:151], v[164:167], v[52:55]
	v_mfma_f32_16x16x32_bf16 v[44:47], v[140:143], v[176:179], v[44:47]
	v_mfma_f32_16x16x32_bf16 v[36:39], v[148:151], v[176:179], v[36:39]
	v_mfma_f32_16x16x32_bf16 v[28:31], v[140:143], v[196:199], v[28:31]
	v_mfma_f32_16x16x32_bf16 v[20:23], v[148:151], v[196:199], v[20:23]
	v_mfma_f32_16x16x32_bf16 v[68:71], v[144:147], v[160:163], v[68:71]
	v_mfma_f32_16x16x32_bf16 v[64:67], v[152:155], v[160:163], v[64:67]
	v_mfma_f32_16x16x32_bf16 v[60:63], v[144:147], v[172:175], v[60:63]
	v_mfma_f32_16x16x32_bf16 v[52:55], v[152:155], v[172:175], v[52:55]
	v_mfma_f32_16x16x32_bf16 v[44:47], v[144:147], v[180:183], v[44:47]
	v_mfma_f32_16x16x32_bf16 v[36:39], v[152:155], v[180:183], v[36:39]
	v_mfma_f32_16x16x32_bf16 v[28:31], v[144:147], v[200:203], v[28:31]
	v_mfma_f32_16x16x32_bf16 v[20:23], v[152:155], v[200:203], v[20:23]
	s_barrier
	s_mov_b32 m0, s51
	v_lshl_add_u64 v[140:141], v[184:185], 0, s[58:59]
	global_load_lds_dwordx4 v[140:141], off
	v_lshl_add_u64 v[140:141], v[184:185], 0, s[16:17]
	s_mov_b32 m0, s50
	s_nop 0
	global_load_lds_dwordx4 v[140:141], off
	s_waitcnt vmcnt(6)
	s_barrier
	v_mfma_f32_16x16x32_bf16 v[56:59], v[204:207], v[156:159], v[56:59]
	v_mfma_f32_16x16x32_bf16 v[48:51], v[212:215], v[156:159], v[48:51]
	v_mfma_f32_16x16x32_bf16 v[40:43], v[204:207], v[164:167], v[40:43]
	v_mfma_f32_16x16x32_bf16 v[32:35], v[212:215], v[164:167], v[32:35]
	v_mfma_f32_16x16x32_bf16 v[24:27], v[204:207], v[176:179], v[24:27]
	v_mfma_f32_16x16x32_bf16 v[16:19], v[212:215], v[176:179], v[16:19]
	v_mfma_f32_16x16x32_bf16 v[12:15], v[204:207], v[196:199], v[12:15]
	v_mfma_f32_16x16x32_bf16 v[8:11], v[212:215], v[196:199], v[8:11]
	v_mfma_f32_16x16x32_bf16 v[56:59], v[208:211], v[160:163], v[56:59]
	v_mfma_f32_16x16x32_bf16 v[48:51], v[216:219], v[160:163], v[48:51]
	v_mfma_f32_16x16x32_bf16 v[40:43], v[208:211], v[172:175], v[40:43]
	v_mfma_f32_16x16x32_bf16 v[32:35], v[216:219], v[172:175], v[32:35]
	v_mfma_f32_16x16x32_bf16 v[24:27], v[208:211], v[180:183], v[24:27]
	v_mfma_f32_16x16x32_bf16 v[16:19], v[216:219], v[180:183], v[16:19]
	v_mfma_f32_16x16x32_bf16 v[12:15], v[208:211], v[200:203], v[12:15]
	v_mfma_f32_16x16x32_bf16 v[8:11], v[216:219], v[200:203], v[8:11]
	s_barrier
	ds_read_b128 v[140:143], v255 offset:32768
	ds_read_b128 v[144:147], v255 offset:33792
	ds_read_b128 v[148:151], v255 offset:34816
	ds_read_b128 v[152:155], v255 offset:35840
	s_mov_b32 m0, s34
	v_lshl_add_u64 v[204:205], v[220:221], 0, s[58:59]
	ds_read_b128 v[156:159], v138 offset:32768
	ds_read_b128 v[160:163], v138 offset:33792
	ds_read_b128 v[164:167], v138 offset:34816
	ds_read_b128 v[172:175], v138 offset:35840
	ds_read_b128 v[176:179], v138 offset:36864
	ds_read_b128 v[180:183], v138 offset:37888
	ds_read_b128 v[196:199], v138 offset:38912
	ds_read_b128 v[200:203], v138 offset:39936
	global_load_lds_dwordx4 v[204:205], off
	v_lshl_add_u64 v[204:205], v[220:221], 0, s[16:17]
	s_mov_b32 m0, s35
	s_nop 0
	global_load_lds_dwordx4 v[204:205], off
	s_waitcnt lgkmcnt(8)
	s_barrier
; #define G_STAGE(bufoff, gbase, o0, h64) do { \
;         __builtin_amdgcn_global_load_lds((const unsigned*)((const char*)(gbase) + (o0)), (LAS unsigned*)(lds + (bufoff) + ldsw), 16, 0, 0); \
;         __builtin_amdgcn_global_load_lds((const unsigned*)((const char*)(gbase) + (h64) + (o0)), (LAS unsigned*)(lds + (bufoff) + ldsw + 8192), 16, 0, 0); } while (0)
; #define G_LDA(dst, b, h) do { _Pragma("unroll") for (int m = 0; m < 4; ++m) _Pragma("unroll") for (int k = 0; k < 2; ++k) dst[m][k] = *(const LAS bf16x8*)(lds + G_SA(b, h) + aoff + m * 2048 + k * 1024); } while (0)
; #define G_LDB(dst, b, h) do { _Pragma("unroll") for (int n = 0; n < 2; ++n) _Pragma("unroll") for (int k = 0; k < 2; ++k) dst[n][k] = *(const LAS bf16x8*)(lds + G_SB(b, h) + boff + n * 2048 + k * 1024); } while (0)
; #define G_WAIT_V(n) asm volatile("s_waitcnt vmcnt(" #n ")" ::: "memory")
; #define G_WAIT_L(n) asm volatile("s_waitcnt lgkmcnt(" #n ")" ::: "memory")
; #define G_BAR __builtin_amdgcn_s_barrier()
; #define G_SCHED __builtin_amdgcn_sched_barrier(0)
;     ...
;             G_WAIT_L(8); G_BAR; G_WAIT_L(0); G_MMA(0, 0, At, B0); G_BAR; G_SCHED;
;             G_LDB(B1, 1, 1); G_STAGE(G_SB(1, 0), b3, cB0, qB);
;             G_BAR; G_WAIT_L(0); G_MMA(0, 1, At, B1); G_BAR;
;             G_LDA(At, 1, 1); G_STAGE(G_SA(1, 0), a3, cA0, qA);
;             G_BAR; G_WAIT_L(0); G_MMA(1, 0, At, B0); G_BAR; G_SCHED;
;             G_STAGE(G_SB(1, 1), b3 + chB, cB0, qB);
;             G_WAIT_V(6); G_BAR; G_MMA(1, 1, At, B1); G_BAR;
;         }
	s_waitcnt lgkmcnt(0)
	v_mfma_f32_16x16x32_bf16 v[132:135], v[140:143], v[156:159], v[132:135]
	v_mfma_f32_16x16x32_bf16 v[128:131], v[148:151], v[156:159], v[128:131]
	v_mfma_f32_16x16x32_bf16 v[124:127], v[140:143], v[164:167], v[124:127]
	v_mfma_f32_16x16x32_bf16 v[116:119], v[148:151], v[164:167], v[116:119]
	v_mfma_f32_16x16x32_bf16 v[108:111], v[140:143], v[176:179], v[108:111]
	v_mfma_f32_16x16x32_bf16 v[100:103], v[148:151], v[176:179], v[100:103]
	v_mfma_f32_16x16x32_bf16 v[92:95], v[140:143], v[196:199], v[92:95]
	v_mfma_f32_16x16x32_bf16 v[84:87], v[148:151], v[196:199], v[84:87]
	v_mfma_f32_16x16x32_bf16 v[132:135], v[144:147], v[160:163], v[132:135]
	v_mfma_f32_16x16x32_bf16 v[128:131], v[152:155], v[160:163], v[128:131]
	v_mfma_f32_16x16x32_bf16 v[124:127], v[144:147], v[172:175], v[124:127]
	v_mfma_f32_16x16x32_bf16 v[116:119], v[152:155], v[172:175], v[116:119]
	v_mfma_f32_16x16x32_bf16 v[108:111], v[144:147], v[180:183], v[108:111]
	v_mfma_f32_16x16x32_bf16 v[100:103], v[152:155], v[180:183], v[100:103]
	v_mfma_f32_16x16x32_bf16 v[92:95], v[144:147], v[200:203], v[92:95]
	v_mfma_f32_16x16x32_bf16 v[84:87], v[152:155], v[200:203], v[84:87]
	s_barrier
	s_mov_b32 m0, s19
	v_lshl_add_u64 v[222:223], v[184:185], 0, s[46:47]
	ds_read_b128 v[204:207], v255 offset:49152
	ds_read_b128 v[208:211], v255 offset:50176
	ds_read_b128 v[212:215], v255 offset:51200
	ds_read_b128 v[216:219], v255 offset:52224
	global_load_lds_dwordx4 v[222:223], off
	v_lshl_add_u64 v[222:223], v[184:185], 0, s[20:21]
	s_mov_b32 m0, s44
	s_mov_b64 s[4:5], 0x10080
	global_load_lds_dwordx4 v[222:223], off
	s_barrier
	s_waitcnt lgkmcnt(0)
	v_mfma_f32_16x16x32_bf16 v[120:123], v[204:207], v[156:159], v[120:123]
	v_mfma_f32_16x16x32_bf16 v[112:115], v[212:215], v[156:159], v[112:115]
	v_mfma_f32_16x16x32_bf16 v[104:107], v[204:207], v[164:167], v[104:107]
	v_mfma_f32_16x16x32_bf16 v[96:99], v[212:215], v[164:167], v[96:99]
	v_mfma_f32_16x16x32_bf16 v[88:91], v[204:207], v[176:179], v[88:91]
	v_mfma_f32_16x16x32_bf16 v[80:83], v[212:215], v[176:179], v[80:83]
	v_mfma_f32_16x16x32_bf16 v[76:79], v[204:207], v[196:199], v[76:79]
	v_mfma_f32_16x16x32_bf16 v[72:75], v[212:215], v[196:199], v[72:75]
	v_mfma_f32_16x16x32_bf16 v[120:123], v[208:211], v[160:163], v[120:123]
	v_mfma_f32_16x16x32_bf16 v[112:115], v[216:219], v[160:163], v[112:115]
	v_mfma_f32_16x16x32_bf16 v[104:107], v[208:211], v[172:175], v[104:107]
	v_mfma_f32_16x16x32_bf16 v[96:99], v[216:219], v[172:175], v[96:99]
	v_mfma_f32_16x16x32_bf16 v[88:91], v[208:211], v[180:183], v[88:91]
	v_mfma_f32_16x16x32_bf16 v[80:83], v[216:219], v[180:183], v[80:83]
	v_mfma_f32_16x16x32_bf16 v[76:79], v[208:211], v[200:203], v[76:79]
	v_mfma_f32_16x16x32_bf16 v[72:75], v[216:219], v[200:203], v[72:75]
	s_barrier
	s_mov_b32 m0, s36
	v_lshl_add_u64 v[222:223], v[220:221], 0, s[46:47]
	ds_read_b128 v[156:159], v138 offset:49152
	ds_read_b128 v[160:163], v138 offset:50176
	ds_read_b128 v[164:167], v138 offset:51200
	ds_read_b128 v[172:175], v138 offset:52224
	ds_read_b128 v[176:179], v138 offset:53248
	ds_read_b128 v[180:183], v138 offset:54272
	ds_read_b128 v[196:199], v138 offset:55296
	ds_read_b128 v[200:203], v138 offset:56320
	global_load_lds_dwordx4 v[222:223], off
	v_lshl_add_u64 v[220:221], v[220:221], 0, s[20:21]
	s_mov_b32 m0, s37
	s_nop 0
	global_load_lds_dwordx4 v[220:221], off
	s_barrier
	s_waitcnt lgkmcnt(0)
	v_mfma_f32_16x16x32_bf16 v[68:71], v[140:143], v[156:159], v[68:71]
	v_mfma_f32_16x16x32_bf16 v[64:67], v[148:151], v[156:159], v[64:67]
	v_mfma_f32_16x16x32_bf16 v[60:63], v[140:143], v[164:167], v[60:63]
	v_mfma_f32_16x16x32_bf16 v[52:55], v[148:151], v[164:167], v[52:55]
	v_mfma_f32_16x16x32_bf16 v[44:47], v[140:143], v[176:179], v[44:47]
	v_mfma_f32_16x16x32_bf16 v[36:39], v[148:151], v[176:179], v[36:39]
	v_mfma_f32_16x16x32_bf16 v[28:31], v[140:143], v[196:199], v[28:31]
	v_mfma_f32_16x16x32_bf16 v[20:23], v[148:151], v[196:199], v[20:23]
	v_mfma_f32_16x16x32_bf16 v[68:71], v[144:147], v[160:163], v[68:71]
	v_mfma_f32_16x16x32_bf16 v[64:67], v[152:155], v[160:163], v[64:67]
	v_mfma_f32_16x16x32_bf16 v[60:63], v[144:147], v[172:175], v[60:63]
	v_mfma_f32_16x16x32_bf16 v[52:55], v[152:155], v[172:175], v[52:55]
	v_mfma_f32_16x16x32_bf16 v[44:47], v[144:147], v[180:183], v[44:47]
	v_mfma_f32_16x16x32_bf16 v[36:39], v[152:155], v[180:183], v[36:39]
	v_mfma_f32_16x16x32_bf16 v[28:31], v[144:147], v[200:203], v[28:31]
	v_mfma_f32_16x16x32_bf16 v[20:23], v[152:155], v[200:203], v[20:23]
	s_barrier
	s_mov_b32 m0, s53
	v_lshl_add_u64 v[140:141], v[184:185], 0, s[4:5]
	global_load_lds_dwordx4 v[140:141], off
	v_lshl_add_u64 v[140:141], v[184:185], 0, s[68:69]
	s_mov_b32 m0, s52
	s_nop 0
	global_load_lds_dwordx4 v[140:141], off
	s_waitcnt vmcnt(6)
	s_barrier
	v_mfma_f32_16x16x32_bf16 v[56:59], v[204:207], v[156:159], v[56:59]
	v_mfma_f32_16x16x32_bf16 v[48:51], v[212:215], v[156:159], v[48:51]
	v_mfma_f32_16x16x32_bf16 v[40:43], v[204:207], v[164:167], v[40:43]
	v_mfma_f32_16x16x32_bf16 v[32:35], v[212:215], v[164:167], v[32:35]
	v_mfma_f32_16x16x32_bf16 v[24:27], v[204:207], v[176:179], v[24:27]
	v_mfma_f32_16x16x32_bf16 v[16:19], v[212:215], v[176:179], v[16:19]
	v_mfma_f32_16x16x32_bf16 v[12:15], v[204:207], v[196:199], v[12:15]
	v_mfma_f32_16x16x32_bf16 v[8:11], v[212:215], v[196:199], v[8:11]
	v_mfma_f32_16x16x32_bf16 v[56:59], v[208:211], v[160:163], v[56:59]
	v_mfma_f32_16x16x32_bf16 v[48:51], v[216:219], v[160:163], v[48:51]
	v_mfma_f32_16x16x32_bf16 v[40:43], v[208:211], v[172:175], v[40:43]
	v_mfma_f32_16x16x32_bf16 v[32:35], v[216:219], v[172:175], v[32:35]
	v_mfma_f32_16x16x32_bf16 v[24:27], v[208:211], v[180:183], v[24:27]
	v_mfma_f32_16x16x32_bf16 v[16:19], v[216:219], v[180:183], v[16:19]
	v_mfma_f32_16x16x32_bf16 v[12:15], v[208:211], v[200:203], v[12:15]
	v_mfma_f32_16x16x32_bf16 v[8:11], v[216:219], v[200:203], v[8:11]
	s_andn2_b64 vcc, exec, s[14:15]
	s_mov_b64 s[16:17], -1
	s_mov_b64 s[14:15], 0
	s_mov_b64 s[18:19], 0x100
	s_cbranch_vccz .Ldb_PLE0_cont

; #define G_STAGE(bufoff, gbase, o0, h64) do { \
;         __builtin_amdgcn_global_load_lds((const unsigned*)((const char*)(gbase) + (o0)), (LAS unsigned*)(lds + (bufoff) + ldsw), 16, 0, 0); \
;         __builtin_amdgcn_global_load_lds((const unsigned*)((const char*)(gbase) + (h64) + (o0)), (LAS unsigned*)(lds + (bufoff) + ldsw + 8192), 16, 0, 0); } while (0)
; #define G_LDA(dst, b, h) do { _Pragma("unroll") for (int m = 0; m < 4; ++m) _Pragma("unroll") for (int k = 0; k < 2; ++k) dst[m][k] = *(const LAS bf16x8*)(lds + G_SA(b, h) + aoff + m * 2048 + k * 1024); } while (0)
; #define G_LDB(dst, b, h) do { _Pragma("unroll") for (int n = 0; n < 2; ++n) _Pragma("unroll") for (int k = 0; k < 2; ++k) dst[n][k] = *(const LAS bf16x8*)(lds + G_SB(b, h) + boff + n * 2048 + k * 1024); } while (0)
; #define G_WAIT_L(n) asm volatile("s_waitcnt lgkmcnt(" #n ")" ::: "memory")
; #define G_BAR __builtin_amdgcn_s_barrier()
; #define G_SCHED __builtin_amdgcn_sched_barrier(0)
;     ...
;         const bool has_next = sched_next<PH, SUB>(E.ws, E.layer, ui + 1, nxt, E.x);
;         if (!has_next) nxt = cur;
;         const char* nA = nxt.A; const char* nB = nxt.B;
; #pragma unroll 1
;         for (int t = 0; t < nt; t += 2) {
;             const bool last = (t == nt - 2);
;             const char* a1 = cA + (size_t)(t + 1) * ckA;
;             const char* a2 = last ? nA : cA + (size_t)(t + 2) * ckA; const char* b2 = last ? nB : cB + (size_t)(t + 2) * kB;
;             const char* a3 = a2 + ckA; const char* b3 = b2 + kB;
;             G_LDB(B0, 0, 0); G_SCHED; G_LDA(At, 0, 0); G_STAGE(G_SA(1, 1), a1 + chA, cA0, qA);
;             G_WAIT_L(8); G_BAR; G_WAIT_L(0); G_MMA(0, 0, At, B0); G_BAR; G_SCHED;
;             G_LDB(B1, 0, 1); G_STAGE(G_SB(0, 0), b2, cB0, qB);
;             G_BAR; G_WAIT_L(0); G_MMA(0, 1, At, B1); G_BAR;
;             G_LDA(At, 0, 1); G_STAGE(G_SA(0, 0), a2, cA0, qA);
;     ...
;         if (!(cs.kind == K_MG_B && cur.aux < 2))
; #pragma unroll
;         for (int a = 0; a < 2; ++a)
; #pragma unroll
;             for (int b = 0; b < 2; ++b)
; #pragma unroll
;                 for (int m = 0; m < 4; ++m)
; #pragma unroll
;                     for (int n = 0; n < 2; ++n) acc[a][b][m][n] = (f32x4){0.f, 0.f, 0.f, 0.f};
.LBB0_1282:
	s_add_u32 s2, s24, 0x40080
	s_addc_u32 s3, s25, 0
	s_add_u32 s22, s22, 0x100
	s_waitcnt lgkmcnt(0)
	s_addc_u32 s23, s23, 0
	s_mov_b32 s24, -2
	s_mov_b64 s[54:55], 0x40000
	s_mov_b64 s[58:59], 0x60000
	s_mov_b64 s[62:63], 0x20080
	s_mov_b64 s[64:65], 0x40080
	s_mov_b64 s[66:67], 0x60080
	s_cmp_eq_u32 s101, 2
	s_cselect_b32 s101, 0, s101
	v_add_u32_e32 v255, 0x10000, v181
	s_add_u32 s4, s2, 0xfffc0080
	s_addc_u32 s5, s3, -1
	s_add_i32 s25, 0, 0x10000
	ds_read_b128 v[136:139], v255 offset:0
	ds_read_b128 v[140:143], v255 offset:1024
	ds_read_b128 v[144:147], v255 offset:2048
	ds_read_b128 v[148:151], v255 offset:3072
	s_cmp_eq_u32 s24, 12
	s_cselect_b32 s5, s19, s5
	s_cselect_b32 s4, s18, s4
	s_cselect_b32 s41, s21, s23
	s_cselect_b32 s40, s20, s22
	s_add_i32 m0, s29, 0xc000
	ds_read_b128 v[152:155], v182
	ds_read_b128 v[160:163], v182 offset:1024
	ds_read_b128 v[164:167], v182 offset:2048
	ds_read_b128 v[172:175], v182 offset:3072
	ds_read_b128 v[176:179], v182 offset:4096
	ds_read_b128 v[196:199], v182 offset:5120
	ds_read_b128 v[200:203], v182 offset:6144
	ds_read_b128 v[204:207], v182 offset:7168
	global_load_lds_dwordx4 v158, s[2:3]
	s_add_i32 m0, s29, 0xe000
	s_nop 0
	s_add_u32 vcc_lo, s2, s0
	s_addc_u32 vcc_hi, s3, s1
	global_load_lds_dwordx4 v158, vcc
	s_waitcnt lgkmcnt(8)
	s_cmp_eq_u32 s101, 1
	s_cbranch_scc1 .Ldb_PLE1_skp
	s_barrier
.Ldb_PLE1_skp:
	s_mov_b32 s101, 0
	s_waitcnt lgkmcnt(0)
	v_mfma_f32_16x16x32_bf16 v[132:135], v[136:139], v[152:155], 0
	v_mfma_f32_16x16x32_bf16 v[128:131], v[144:147], v[152:155], 0
	v_mfma_f32_16x16x32_bf16 v[116:119], v[136:139], v[164:167], 0
	v_mfma_f32_16x16x32_bf16 v[112:115], v[144:147], v[164:167], 0
	v_mfma_f32_16x16x32_bf16 v[100:103], v[136:139], v[176:179], 0
	v_mfma_f32_16x16x32_bf16 v[96:99], v[144:147], v[176:179], 0
	v_mfma_f32_16x16x32_bf16 v[84:87], v[136:139], v[200:203], 0
	v_mfma_f32_16x16x32_bf16 v[80:83], v[144:147], v[200:203], 0
	v_mfma_f32_16x16x32_bf16 v[132:135], v[140:143], v[160:163], v[132:135]
	v_mfma_f32_16x16x32_bf16 v[128:131], v[148:151], v[160:163], v[128:131]
	v_mfma_f32_16x16x32_bf16 v[116:119], v[140:143], v[172:175], v[116:119]
	v_mfma_f32_16x16x32_bf16 v[112:115], v[148:151], v[172:175], v[112:115]
	v_mfma_f32_16x16x32_bf16 v[100:103], v[140:143], v[196:199], v[100:103]
	v_mfma_f32_16x16x32_bf16 v[96:99], v[148:151], v[196:199], v[96:99]
	v_mfma_f32_16x16x32_bf16 v[84:87], v[140:143], v[204:207], v[84:87]
	v_mfma_f32_16x16x32_bf16 v[80:83], v[148:151], v[204:207], v[80:83]
	s_barrier
	s_add_i32 s44, 0, 0x14000
	s_add_i32 s25, s25, s27
	s_mov_b32 m0, s25
	ds_read_b128 v[208:211], v255 offset:16384
	ds_read_b128 v[212:215], v255 offset:17408
	ds_read_b128 v[216:219], v255 offset:18432
	ds_read_b128 v[220:223], v255 offset:19456
	global_load_lds_dwordx4 v156, s[40:41]
	s_add_i32 m0, s25, 0x2000
	s_nop 0
	s_add_u32 vcc_lo, s40, s0
	s_addc_u32 vcc_hi, s41, s1
	global_load_lds_dwordx4 v156, vcc
	s_barrier
	s_waitcnt lgkmcnt(0)
	v_mfma_f32_16x16x32_bf16 v[124:127], v[208:211], v[152:155], 0
	v_mfma_f32_16x16x32_bf16 v[120:123], v[216:219], v[152:155], 0
	v_mfma_f32_16x16x32_bf16 v[108:111], v[208:211], v[164:167], 0
	v_mfma_f32_16x16x32_bf16 v[104:107], v[216:219], v[164:167], 0
	v_mfma_f32_16x16x32_bf16 v[92:95], v[208:211], v[176:179], 0
	v_mfma_f32_16x16x32_bf16 v[88:91], v[216:219], v[176:179], 0
	v_mfma_f32_16x16x32_bf16 v[76:79], v[208:211], v[200:203], 0
	v_mfma_f32_16x16x32_bf16 v[72:75], v[216:219], v[200:203], 0
	v_mfma_f32_16x16x32_bf16 v[124:127], v[212:215], v[160:163], v[124:127]
	v_mfma_f32_16x16x32_bf16 v[120:123], v[220:223], v[160:163], v[120:123]
	v_mfma_f32_16x16x32_bf16 v[108:111], v[212:215], v[172:175], v[108:111]
	v_mfma_f32_16x16x32_bf16 v[104:107], v[220:223], v[172:175], v[104:107]
	v_mfma_f32_16x16x32_bf16 v[92:95], v[212:215], v[196:199], v[92:95]
	v_mfma_f32_16x16x32_bf16 v[88:91], v[220:223], v[196:199], v[88:91]
	v_mfma_f32_16x16x32_bf16 v[76:79], v[212:215], v[204:207], v[76:79]
	v_mfma_f32_16x16x32_bf16 v[72:75], v[220:223], v[204:207], v[72:75]
	s_barrier
	s_mov_b32 m0, s29
	v_lshl_add_u64 v[224:225], s[4:5], 0, v[2:3]
	ds_read_b128 v[152:155], v182 offset:16384
	ds_read_b128 v[160:163], v182 offset:17408
	ds_read_b128 v[164:167], v182 offset:18432
	ds_read_b128 v[172:175], v182 offset:19456
	ds_read_b128 v[176:179], v182 offset:20480
	ds_read_b128 v[196:199], v182 offset:21504
	ds_read_b128 v[200:203], v182 offset:22528
	ds_read_b128 v[204:207], v182 offset:23552
	global_load_lds_dwordx4 v2, s[4:5]
	s_mov_b32 m0, s30
	s_nop 0
	s_add_u32 vcc_lo, s4, s0
	s_addc_u32 vcc_hi, s5, s1
	global_load_lds_dwordx4 v2, vcc
	s_barrier
	s_waitcnt lgkmcnt(0)
	v_mfma_f32_16x16x32_bf16 v[68:71], v[136:139], v[152:155], 0
	v_mfma_f32_16x16x32_bf16 v[64:67], v[144:147], v[152:155], 0
	v_mfma_f32_16x16x32_bf16 v[52:55], v[136:139], v[164:167], 0
	v_mfma_f32_16x16x32_bf16 v[48:51], v[144:147], v[164:167], 0
	v_mfma_f32_16x16x32_bf16 v[36:39], v[136:139], v[176:179], 0
	v_mfma_f32_16x16x32_bf16 v[32:35], v[144:147], v[176:179], 0
	v_mfma_f32_16x16x32_bf16 v[20:23], v[136:139], v[200:203], 0
	v_mfma_f32_16x16x32_bf16 v[16:19], v[144:147], v[200:203], 0
	v_mfma_f32_16x16x32_bf16 v[68:71], v[140:143], v[160:163], v[68:71]
	v_mfma_f32_16x16x32_bf16 v[64:67], v[148:151], v[160:163], v[64:67]
	v_mfma_f32_16x16x32_bf16 v[52:55], v[140:143], v[172:175], v[52:55]
	v_mfma_f32_16x16x32_bf16 v[48:51], v[148:151], v[172:175], v[48:51]
	v_mfma_f32_16x16x32_bf16 v[36:39], v[140:143], v[196:199], v[36:39]
	v_mfma_f32_16x16x32_bf16 v[32:35], v[148:151], v[196:199], v[32:35]
	v_mfma_f32_16x16x32_bf16 v[20:23], v[140:143], v[204:207], v[20:23]
	v_mfma_f32_16x16x32_bf16 v[16:19], v[148:151], v[204:207], v[16:19]
	s_barrier
; #define G_STAGE(bufoff, gbase, o0, h64) do { \
;         __builtin_amdgcn_global_load_lds((const unsigned*)((const char*)(gbase) + (o0)), (LAS unsigned*)(lds + (bufoff) + ldsw), 16, 0, 0); \
;         __builtin_amdgcn_global_load_lds((const unsigned*)((const char*)(gbase) + (h64) + (o0)), (LAS unsigned*)(lds + (bufoff) + ldsw + 8192), 16, 0, 0); } while (0)
; #define G_LDA(dst, b, h) do { _Pragma("unroll") for (int m = 0; m < 4; ++m) _Pragma("unroll") for (int k = 0; k < 2; ++k) dst[m][k] = *(const LAS bf16x8*)(lds + G_SA(b, h) + aoff + m * 2048 + k * 1024); } while (0)
; #define G_LDB(dst, b, h) do { _Pragma("unroll") for (int n = 0; n < 2; ++n) _Pragma("unroll") for (int k = 0; k < 2; ++k) dst[n][k] = *(const LAS bf16x8*)(lds + G_SB(b, h) + boff + n * 2048 + k * 1024); } while (0)
; #define G_WAIT_V(n) asm volatile("s_waitcnt vmcnt(" #n ")" ::: "memory")
; #define G_WAIT_L(n) asm volatile("s_waitcnt lgkmcnt(" #n ")" ::: "memory")
; #define G_BAR __builtin_amdgcn_s_barrier()
; #define G_SCHED __builtin_amdgcn_sched_barrier(0)
;     ...
;             G_BAR; G_WAIT_L(0); G_MMA(1, 0, At, B0); G_BAR; G_SCHED;
;             G_STAGE(G_SB(0, 1), b2 + chB, cB0, qB);
;             G_WAIT_V(6); G_BAR; G_MMA(1, 1, At, B1); G_BAR;
;             G_LDB(B0, 1, 0); G_SCHED; G_LDA(At, 1, 0); G_STAGE(G_SA(0, 1), a2 + chA, cA0, qA);
;             G_WAIT_L(8); G_BAR; G_WAIT_L(0); G_MMA(0, 0, At, B0); G_BAR; G_SCHED;
;             G_LDB(B1, 1, 1); G_STAGE(G_SB(1, 0), b3, cB0, qB);
;             G_BAR; G_WAIT_L(0); G_MMA(0, 1, At, B1); G_BAR;
	s_add_i32 s100, s44, s27
	s_mov_b32 m0, s100
	s_nop 0
	s_add_u32 vcc_lo, s40, s54
	s_addc_u32 vcc_hi, s41, s55
	global_load_lds_dwordx4 v156, vcc
	s_add_i32 m0, s100, 0x2000
	s_nop 0
	s_add_u32 vcc_lo, s40, s58
	s_addc_u32 vcc_hi, s41, s59
	global_load_lds_dwordx4 v156, vcc
	s_waitcnt vmcnt(6)
	s_barrier
	v_mfma_f32_16x16x32_bf16 v[60:63], v[208:211], v[152:155], 0
	v_mfma_f32_16x16x32_bf16 v[56:59], v[216:219], v[152:155], 0
	v_mfma_f32_16x16x32_bf16 v[44:47], v[208:211], v[164:167], 0
	v_mfma_f32_16x16x32_bf16 v[40:43], v[216:219], v[164:167], 0
	v_mfma_f32_16x16x32_bf16 v[28:31], v[208:211], v[176:179], 0
	v_mfma_f32_16x16x32_bf16 v[24:27], v[216:219], v[176:179], 0
	v_mfma_f32_16x16x32_bf16 v[12:15], v[208:211], v[200:203], 0
	v_mfma_f32_16x16x32_bf16 v[8:11], v[216:219], v[200:203], 0
	v_mfma_f32_16x16x32_bf16 v[60:63], v[212:215], v[160:163], v[60:63]
	v_mfma_f32_16x16x32_bf16 v[56:59], v[220:223], v[160:163], v[56:59]
	v_mfma_f32_16x16x32_bf16 v[44:47], v[212:215], v[172:175], v[44:47]
	v_mfma_f32_16x16x32_bf16 v[40:43], v[220:223], v[172:175], v[40:43]
	v_mfma_f32_16x16x32_bf16 v[28:31], v[212:215], v[196:199], v[28:31]
	v_mfma_f32_16x16x32_bf16 v[24:27], v[220:223], v[196:199], v[24:27]
	v_mfma_f32_16x16x32_bf16 v[12:15], v[212:215], v[204:207], v[12:15]
	v_mfma_f32_16x16x32_bf16 v[8:11], v[220:223], v[204:207], v[8:11]
	s_barrier
	s_add_i32 s100, 0, 0x18000
	ds_read_b128 v[136:139], v255 offset:32768
	ds_read_b128 v[140:143], v255 offset:33792
	ds_read_b128 v[144:147], v255 offset:34816
	ds_read_b128 v[148:151], v255 offset:35840
	s_mov_b32 m0, s31
	ds_read_b128 v[152:155], v182 offset:32768
	ds_read_b128 v[160:163], v182 offset:33792
	ds_read_b128 v[164:167], v182 offset:34816
	ds_read_b128 v[172:175], v182 offset:35840
	ds_read_b128 v[176:179], v182 offset:36864
	ds_read_b128 v[196:199], v182 offset:37888
	ds_read_b128 v[200:203], v182 offset:38912
	ds_read_b128 v[204:207], v182 offset:39936
	s_add_u32 vcc_lo, s4, s54
	s_addc_u32 vcc_hi, s5, s55
	global_load_lds_dwordx4 v2, vcc
	s_mov_b32 m0, s34
	s_nop 0
	s_add_u32 vcc_lo, s4, s58
	s_addc_u32 vcc_hi, s5, s59
	global_load_lds_dwordx4 v2, vcc
	s_waitcnt lgkmcnt(8)
	s_barrier
	s_waitcnt lgkmcnt(0)
	v_mfma_f32_16x16x32_bf16 v[132:135], v[136:139], v[152:155], v[132:135]
	v_mfma_f32_16x16x32_bf16 v[128:131], v[144:147], v[152:155], v[128:131]
	v_mfma_f32_16x16x32_bf16 v[116:119], v[136:139], v[164:167], v[116:119]
	v_mfma_f32_16x16x32_bf16 v[112:115], v[144:147], v[164:167], v[112:115]
	v_mfma_f32_16x16x32_bf16 v[100:103], v[136:139], v[176:179], v[100:103]
	v_mfma_f32_16x16x32_bf16 v[96:99], v[144:147], v[176:179], v[96:99]
	v_mfma_f32_16x16x32_bf16 v[84:87], v[136:139], v[200:203], v[84:87]
	v_mfma_f32_16x16x32_bf16 v[80:83], v[144:147], v[200:203], v[80:83]
	v_mfma_f32_16x16x32_bf16 v[132:135], v[140:143], v[160:163], v[132:135]
	v_mfma_f32_16x16x32_bf16 v[128:131], v[148:151], v[160:163], v[128:131]
	v_mfma_f32_16x16x32_bf16 v[116:119], v[140:143], v[172:175], v[116:119]
	v_mfma_f32_16x16x32_bf16 v[112:115], v[148:151], v[172:175], v[112:115]
	v_mfma_f32_16x16x32_bf16 v[100:103], v[140:143], v[196:199], v[100:103]
	v_mfma_f32_16x16x32_bf16 v[96:99], v[148:151], v[196:199], v[96:99]
	v_mfma_f32_16x16x32_bf16 v[84:87], v[140:143], v[204:207], v[84:87]
	v_mfma_f32_16x16x32_bf16 v[80:83], v[148:151], v[204:207], v[80:83]
	s_barrier
	s_add_i32 s5, 0, 0x1c000
	s_add_i32 s4, s100, s27
	s_mov_b32 m0, s4
	ds_read_b128 v[208:211], v255 offset:49152
	ds_read_b128 v[212:215], v255 offset:50176
	ds_read_b128 v[216:219], v255 offset:51200
	ds_read_b128 v[220:223], v255 offset:52224
	s_add_u32 vcc_lo, s40, s46
	s_addc_u32 vcc_hi, s41, s47
	global_load_lds_dwordx4 v156, vcc
	s_add_i32 m0, s4, 0x2000
	s_nop 0
	s_add_u32 vcc_lo, s40, s62
	s_addc_u32 vcc_hi, s41, s63
	global_load_lds_dwordx4 v156, vcc
	s_barrier
	s_waitcnt lgkmcnt(0)
	v_mfma_f32_16x16x32_bf16 v[124:127], v[208:211], v[152:155], v[124:127]
	v_mfma_f32_16x16x32_bf16 v[120:123], v[216:219], v[152:155], v[120:123]
	v_mfma_f32_16x16x32_bf16 v[108:111], v[208:211], v[164:167], v[108:111]
	v_mfma_f32_16x16x32_bf16 v[104:107], v[216:219], v[164:167], v[104:107]
	v_mfma_f32_16x16x32_bf16 v[92:95], v[208:211], v[176:179], v[92:95]
	v_mfma_f32_16x16x32_bf16 v[88:91], v[216:219], v[176:179], v[88:91]
	v_mfma_f32_16x16x32_bf16 v[76:79], v[208:211], v[200:203], v[76:79]
	v_mfma_f32_16x16x32_bf16 v[72:75], v[216:219], v[200:203], v[72:75]
	v_mfma_f32_16x16x32_bf16 v[124:127], v[212:215], v[160:163], v[124:127]
	v_mfma_f32_16x16x32_bf16 v[120:123], v[220:223], v[160:163], v[120:123]
	v_mfma_f32_16x16x32_bf16 v[108:111], v[212:215], v[172:175], v[108:111]
	v_mfma_f32_16x16x32_bf16 v[104:107], v[220:223], v[172:175], v[104:107]
	v_mfma_f32_16x16x32_bf16 v[92:95], v[212:215], v[196:199], v[92:95]
	v_mfma_f32_16x16x32_bf16 v[88:91], v[220:223], v[196:199], v[88:91]
	v_mfma_f32_16x16x32_bf16 v[76:79], v[212:215], v[204:207], v[76:79]
	v_mfma_f32_16x16x32_bf16 v[72:75], v[220:223], v[204:207], v[72:75]
	s_barrier
	s_mov_b32 m0, s35
	v_lshl_add_u64 v[226:227], v[224:225], 0, s[46:47]
	ds_read_b128 v[152:155], v182 offset:49152
	ds_read_b128 v[160:163], v182 offset:50176
	ds_read_b128 v[164:167], v182 offset:51200
	ds_read_b128 v[172:175], v182 offset:52224
	ds_read_b128 v[176:179], v182 offset:53248
	ds_read_b128 v[196:199], v182 offset:54272
	ds_read_b128 v[200:203], v182 offset:55296
	ds_read_b128 v[204:207], v182 offset:56320
	global_load_lds_dwordx4 v[226:227], off
	v_lshl_add_u64 v[224:225], v[224:225], 0, s[62:63]
	s_mov_b32 m0, s36
	s_nop 0
	global_load_lds_dwordx4 v[224:225], off
	s_barrier
; #define G_STAGE(bufoff, gbase, o0, h64) do { \
;         __builtin_amdgcn_global_load_lds((const unsigned*)((const char*)(gbase) + (o0)), (LAS unsigned*)(lds + (bufoff) + ldsw), 16, 0, 0); \
;         __builtin_amdgcn_global_load_lds((const unsigned*)((const char*)(gbase) + (h64) + (o0)), (LAS unsigned*)(lds + (bufoff) + ldsw + 8192), 16, 0, 0); } while (0)
; #define G_LDA(dst, b, h) do { _Pragma("unroll") for (int m = 0; m < 4; ++m) _Pragma("unroll") for (int k = 0; k < 2; ++k) dst[m][k] = *(const LAS bf16x8*)(lds + G_SA(b, h) + aoff + m * 2048 + k * 1024); } while (0)
; #define G_LDB(dst, b, h) do { _Pragma("unroll") for (int n = 0; n < 2; ++n) _Pragma("unroll") for (int k = 0; k < 2; ++k) dst[n][k] = *(const LAS bf16x8*)(lds + G_SB(b, h) + boff + n * 2048 + k * 1024); } while (0)
; #define G_WAIT_V(n) asm volatile("s_waitcnt vmcnt(" #n ")" ::: "memory")
; #define G_WAIT_L(n) asm volatile("s_waitcnt lgkmcnt(" #n ")" ::: "memory")
; #define G_BAR __builtin_amdgcn_s_barrier()
; #define G_SCHED __builtin_amdgcn_sched_barrier(0)
;     ...
;         for (int t = 0; t < nt; t += 2) {
;             const bool last = (t == nt - 2);
;             const char* a1 = cA + (size_t)(t + 1) * ckA;
;             const char* a2 = last ? nA : cA + (size_t)(t + 2) * ckA; const char* b2 = last ? nB : cB + (size_t)(t + 2) * kB;
;             const char* a3 = a2 + ckA; const char* b3 = b2 + kB;
;             G_LDB(B0, 0, 0); G_SCHED; G_LDA(At, 0, 0); G_STAGE(G_SA(1, 1), a1 + chA, cA0, qA);
;             G_WAIT_L(8); G_BAR; G_WAIT_L(0); G_MMA(0, 0, At, B0); G_BAR; G_SCHED;
;             G_LDB(B1, 0, 1); G_STAGE(G_SB(0, 0), b2, cB0, qB);
;     ...
;             G_BAR; G_WAIT_L(0); G_MMA(0, 1, At, B1); G_BAR;
;             G_LDA(At, 1, 1); G_STAGE(G_SA(1, 0), a3, cA0, qA);
;             G_BAR; G_WAIT_L(0); G_MMA(1, 0, At, B0); G_BAR; G_SCHED;
;             G_STAGE(G_SB(1, 1), b3 + chB, cB0, qB);
;             G_WAIT_V(6); G_BAR; G_MMA(1, 1, At, B1); G_BAR;
;         }
	s_waitcnt lgkmcnt(0)
	v_mfma_f32_16x16x32_bf16 v[68:71], v[136:139], v[152:155], v[68:71]
	v_mfma_f32_16x16x32_bf16 v[64:67], v[144:147], v[152:155], v[64:67]
	v_mfma_f32_16x16x32_bf16 v[52:55], v[136:139], v[164:167], v[52:55]
	v_mfma_f32_16x16x32_bf16 v[48:51], v[144:147], v[164:167], v[48:51]
	v_mfma_f32_16x16x32_bf16 v[36:39], v[136:139], v[176:179], v[36:39]
	v_mfma_f32_16x16x32_bf16 v[32:35], v[144:147], v[176:179], v[32:35]
	v_mfma_f32_16x16x32_bf16 v[20:23], v[136:139], v[200:203], v[20:23]
	v_mfma_f32_16x16x32_bf16 v[16:19], v[144:147], v[200:203], v[16:19]
	v_mfma_f32_16x16x32_bf16 v[68:71], v[140:143], v[160:163], v[68:71]
	v_mfma_f32_16x16x32_bf16 v[64:67], v[148:151], v[160:163], v[64:67]
	v_mfma_f32_16x16x32_bf16 v[52:55], v[140:143], v[172:175], v[52:55]
	v_mfma_f32_16x16x32_bf16 v[48:51], v[148:151], v[172:175], v[48:51]
	v_mfma_f32_16x16x32_bf16 v[36:39], v[140:143], v[196:199], v[36:39]
	v_mfma_f32_16x16x32_bf16 v[32:35], v[148:151], v[196:199], v[32:35]
	v_mfma_f32_16x16x32_bf16 v[20:23], v[140:143], v[204:207], v[20:23]
	v_mfma_f32_16x16x32_bf16 v[16:19], v[148:151], v[204:207], v[16:19]
	s_barrier
	s_add_i32 s4, s5, s27
	s_mov_b32 m0, s4
	s_nop 0
	s_add_u32 vcc_lo, s40, s64
	s_addc_u32 vcc_hi, s41, s65
	global_load_lds_dwordx4 v156, vcc
	s_add_i32 m0, s4, 0x2000
	s_nop 0
	s_add_u32 vcc_lo, s40, s66
	s_addc_u32 vcc_hi, s41, s67
	global_load_lds_dwordx4 v156, vcc
	s_add_i32 s24, s24, 2
	s_add_u32 s2, s2, 0x100
	s_addc_u32 s3, s3, 0
	s_add_u32 s22, s22, 0x100
	s_addc_u32 s23, s23, 0
	s_cmp_gt_u32 s24, 13
	s_waitcnt vmcnt(6)
	s_barrier
	v_mfma_f32_16x16x32_bf16 v[60:63], v[208:211], v[152:155], v[60:63]
	v_mfma_f32_16x16x32_bf16 v[56:59], v[216:219], v[152:155], v[56:59]
	v_mfma_f32_16x16x32_bf16 v[44:47], v[208:211], v[164:167], v[44:47]
	v_mfma_f32_16x16x32_bf16 v[40:43], v[216:219], v[164:167], v[40:43]
	v_mfma_f32_16x16x32_bf16 v[28:31], v[208:211], v[176:179], v[28:31]
	v_mfma_f32_16x16x32_bf16 v[24:27], v[216:219], v[176:179], v[24:27]
	v_mfma_f32_16x16x32_bf16 v[12:15], v[208:211], v[200:203], v[12:15]
	v_mfma_f32_16x16x32_bf16 v[8:11], v[216:219], v[200:203], v[8:11]
	v_mfma_f32_16x16x32_bf16 v[60:63], v[212:215], v[160:163], v[60:63]
	v_mfma_f32_16x16x32_bf16 v[56:59], v[220:223], v[160:163], v[56:59]
	v_mfma_f32_16x16x32_bf16 v[44:47], v[212:215], v[172:175], v[44:47]
	v_mfma_f32_16x16x32_bf16 v[40:43], v[220:223], v[172:175], v[40:43]
	v_mfma_f32_16x16x32_bf16 v[28:31], v[212:215], v[196:199], v[28:31]
	v_mfma_f32_16x16x32_bf16 v[24:27], v[220:223], v[196:199], v[24:27]
	v_mfma_f32_16x16x32_bf16 v[12:15], v[212:215], v[204:207], v[12:15]
	v_mfma_f32_16x16x32_bf16 v[8:11], v[220:223], v[204:207], v[8:11]
	s_cbranch_scc0 .Ldb_PLE1_cont
	s_branch .Ldb_PLE1_xl
.LBB0_1283:
	s_add_u32 s4, s2, 0xfffc0080
	s_addc_u32 s5, s3, -1
	s_add_i32 s25, 0, 0x10000
	ds_read_b128 v[136:139], v255 offset:0
	ds_read_b128 v[140:143], v255 offset:1024
	ds_read_b128 v[144:147], v255 offset:2048
	ds_read_b128 v[148:151], v255 offset:3072
	s_cmp_eq_u32 s24, 12
	s_cselect_b32 s5, s19, s5
	s_cselect_b32 s4, s18, s4
	s_cselect_b32 s41, s21, s23
	s_cselect_b32 s40, s20, s22
	s_add_i32 m0, s29, 0xc000
	ds_read_b128 v[152:155], v182
	ds_read_b128 v[160:163], v182 offset:1024
	ds_read_b128 v[164:167], v182 offset:2048
	ds_read_b128 v[172:175], v182 offset:3072
	ds_read_b128 v[176:179], v182 offset:4096
	ds_read_b128 v[196:199], v182 offset:5120
	ds_read_b128 v[200:203], v182 offset:6144
	ds_read_b128 v[204:207], v182 offset:7168
	global_load_lds_dwordx4 v158, s[2:3]
	s_add_i32 m0, s29, 0xe000
	s_nop 0
	s_add_u32 vcc_lo, s2, s0
	s_addc_u32 vcc_hi, s3, s1
	global_load_lds_dwordx4 v158, vcc
	s_waitcnt lgkmcnt(8)
	s_barrier
	s_waitcnt lgkmcnt(0)
	v_mfma_f32_16x16x32_bf16 v[132:135], v[136:139], v[152:155], v[132:135]
	v_mfma_f32_16x16x32_bf16 v[128:131], v[144:147], v[152:155], v[128:131]
	v_mfma_f32_16x16x32_bf16 v[116:119], v[136:139], v[164:167], v[116:119]
	v_mfma_f32_16x16x32_bf16 v[112:115], v[144:147], v[164:167], v[112:115]
	v_mfma_f32_16x16x32_bf16 v[100:103], v[136:139], v[176:179], v[100:103]
	v_mfma_f32_16x16x32_bf16 v[96:99], v[144:147], v[176:179], v[96:99]
	v_mfma_f32_16x16x32_bf16 v[84:87], v[136:139], v[200:203], v[84:87]
	v_mfma_f32_16x16x32_bf16 v[80:83], v[144:147], v[200:203], v[80:83]
	v_mfma_f32_16x16x32_bf16 v[132:135], v[140:143], v[160:163], v[132:135]
	v_mfma_f32_16x16x32_bf16 v[128:131], v[148:151], v[160:163], v[128:131]
	v_mfma_f32_16x16x32_bf16 v[116:119], v[140:143], v[172:175], v[116:119]
	v_mfma_f32_16x16x32_bf16 v[112:115], v[148:151], v[172:175], v[112:115]
	v_mfma_f32_16x16x32_bf16 v[100:103], v[140:143], v[196:199], v[100:103]
	v_mfma_f32_16x16x32_bf16 v[96:99], v[148:151], v[196:199], v[96:99]
	v_mfma_f32_16x16x32_bf16 v[84:87], v[140:143], v[204:207], v[84:87]
	v_mfma_f32_16x16x32_bf16 v[80:83], v[148:151], v[204:207], v[80:83]
	s_barrier
	s_add_i32 s44, 0, 0x14000
	s_add_i32 s25, s25, s27
	s_mov_b32 m0, s25
	ds_read_b128 v[208:211], v255 offset:16384
	ds_read_b128 v[212:215], v255 offset:17408
	ds_read_b128 v[216:219], v255 offset:18432
	ds_read_b128 v[220:223], v255 offset:19456
	global_load_lds_dwordx4 v156, s[40:41]
	s_add_i32 m0, s25, 0x2000
	s_nop 0
	s_add_u32 vcc_lo, s40, s0
	s_addc_u32 vcc_hi, s41, s1
	global_load_lds_dwordx4 v156, vcc
	s_barrier
; #define G_STAGE(bufoff, gbase, o0, h64) do { \
;         __builtin_amdgcn_global_load_lds((const unsigned*)((const char*)(gbase) + (o0)), (LAS unsigned*)(lds + (bufoff) + ldsw), 16, 0, 0); \
;         __builtin_amdgcn_global_load_lds((const unsigned*)((const char*)(gbase) + (h64) + (o0)), (LAS unsigned*)(lds + (bufoff) + ldsw + 8192), 16, 0, 0); } while (0)
; #define G_LDA(dst, b, h) do { _Pragma("unroll") for (int m = 0; m < 4; ++m) _Pragma("unroll") for (int k = 0; k < 2; ++k) dst[m][k] = *(const LAS bf16x8*)(lds + G_SA(b, h) + aoff + m * 2048 + k * 1024); } while (0)
; #define G_LDB(dst, b, h) do { _Pragma("unroll") for (int n = 0; n < 2; ++n) _Pragma("unroll") for (int k = 0; k < 2; ++k) dst[n][k] = *(const LAS bf16x8*)(lds + G_SB(b, h) + boff + n * 2048 + k * 1024); } while (0)
; #define G_WAIT_V(n) asm volatile("s_waitcnt vmcnt(" #n ")" ::: "memory")
; #define G_WAIT_L(n) asm volatile("s_waitcnt lgkmcnt(" #n ")" ::: "memory")
; #define G_BAR __builtin_amdgcn_s_barrier()
; #define G_SCHED __builtin_amdgcn_sched_barrier(0)
;     ...
;             G_LDB(B1, 0, 1); G_STAGE(G_SB(0, 0), b2, cB0, qB);
;             G_BAR; G_WAIT_L(0); G_MMA(0, 1, At, B1); G_BAR;
;             G_LDA(At, 0, 1); G_STAGE(G_SA(0, 0), a2, cA0, qA);
;             G_BAR; G_WAIT_L(0); G_MMA(1, 0, At, B0); G_BAR; G_SCHED;
;             G_STAGE(G_SB(0, 1), b2 + chB, cB0, qB);
;             G_WAIT_V(6); G_BAR; G_MMA(1, 1, At, B1); G_BAR;
;             G_LDB(B0, 1, 0); G_SCHED; G_LDA(At, 1, 0); G_STAGE(G_SA(0, 1), a2 + chA, cA0, qA);
;             G_WAIT_L(8); G_BAR; G_WAIT_L(0); G_MMA(0, 0, At, B0); G_BAR; G_SCHED;
	s_waitcnt lgkmcnt(0)
	v_mfma_f32_16x16x32_bf16 v[124:127], v[208:211], v[152:155], v[124:127]
	v_mfma_f32_16x16x32_bf16 v[120:123], v[216:219], v[152:155], v[120:123]
	v_mfma_f32_16x16x32_bf16 v[108:111], v[208:211], v[164:167], v[108:111]
	v_mfma_f32_16x16x32_bf16 v[104:107], v[216:219], v[164:167], v[104:107]
	v_mfma_f32_16x16x32_bf16 v[92:95], v[208:211], v[176:179], v[92:95]
	v_mfma_f32_16x16x32_bf16 v[88:91], v[216:219], v[176:179], v[88:91]
	v_mfma_f32_16x16x32_bf16 v[76:79], v[208:211], v[200:203], v[76:79]
	v_mfma_f32_16x16x32_bf16 v[72:75], v[216:219], v[200:203], v[72:75]
	v_mfma_f32_16x16x32_bf16 v[124:127], v[212:215], v[160:163], v[124:127]
	v_mfma_f32_16x16x32_bf16 v[120:123], v[220:223], v[160:163], v[120:123]
	v_mfma_f32_16x16x32_bf16 v[108:111], v[212:215], v[172:175], v[108:111]
	v_mfma_f32_16x16x32_bf16 v[104:107], v[220:223], v[172:175], v[104:107]
	v_mfma_f32_16x16x32_bf16 v[92:95], v[212:215], v[196:199], v[92:95]
	v_mfma_f32_16x16x32_bf16 v[88:91], v[220:223], v[196:199], v[88:91]
	v_mfma_f32_16x16x32_bf16 v[76:79], v[212:215], v[204:207], v[76:79]
	v_mfma_f32_16x16x32_bf16 v[72:75], v[220:223], v[204:207], v[72:75]
	s_barrier
	s_mov_b32 m0, s29
	v_lshl_add_u64 v[224:225], s[4:5], 0, v[2:3]
	ds_read_b128 v[152:155], v182 offset:16384
	ds_read_b128 v[160:163], v182 offset:17408
	ds_read_b128 v[164:167], v182 offset:18432
	ds_read_b128 v[172:175], v182 offset:19456
	ds_read_b128 v[176:179], v182 offset:20480
	ds_read_b128 v[196:199], v182 offset:21504
	ds_read_b128 v[200:203], v182 offset:22528
	ds_read_b128 v[204:207], v182 offset:23552
	global_load_lds_dwordx4 v2, s[4:5]
	s_mov_b32 m0, s30
	s_nop 0
	s_add_u32 vcc_lo, s4, s0
	s_addc_u32 vcc_hi, s5, s1
	global_load_lds_dwordx4 v2, vcc
	s_barrier
	s_waitcnt lgkmcnt(0)
	v_mfma_f32_16x16x32_bf16 v[68:71], v[136:139], v[152:155], v[68:71]
	v_mfma_f32_16x16x32_bf16 v[64:67], v[144:147], v[152:155], v[64:67]
	v_mfma_f32_16x16x32_bf16 v[52:55], v[136:139], v[164:167], v[52:55]
	v_mfma_f32_16x16x32_bf16 v[48:51], v[144:147], v[164:167], v[48:51]
	v_mfma_f32_16x16x32_bf16 v[36:39], v[136:139], v[176:179], v[36:39]
	v_mfma_f32_16x16x32_bf16 v[32:35], v[144:147], v[176:179], v[32:35]
	v_mfma_f32_16x16x32_bf16 v[20:23], v[136:139], v[200:203], v[20:23]
	v_mfma_f32_16x16x32_bf16 v[16:19], v[144:147], v[200:203], v[16:19]
	v_mfma_f32_16x16x32_bf16 v[68:71], v[140:143], v[160:163], v[68:71]
	v_mfma_f32_16x16x32_bf16 v[64:67], v[148:151], v[160:163], v[64:67]
	v_mfma_f32_16x16x32_bf16 v[52:55], v[140:143], v[172:175], v[52:55]
	v_mfma_f32_16x16x32_bf16 v[48:51], v[148:151], v[172:175], v[48:51]
	v_mfma_f32_16x16x32_bf16 v[36:39], v[140:143], v[196:199], v[36:39]
	v_mfma_f32_16x16x32_bf16 v[32:35], v[148:151], v[196:199], v[32:35]
	v_mfma_f32_16x16x32_bf16 v[20:23], v[140:143], v[204:207], v[20:23]
	v_mfma_f32_16x16x32_bf16 v[16:19], v[148:151], v[204:207], v[16:19]
	s_barrier
	s_add_i32 s100, s44, s27
	s_mov_b32 m0, s100
	s_nop 0
	s_add_u32 vcc_lo, s40, s54
	s_addc_u32 vcc_hi, s41, s55
	global_load_lds_dwordx4 v156, vcc
	s_add_i32 m0, s100, 0x2000
	s_nop 0
	s_add_u32 vcc_lo, s40, s58
	s_addc_u32 vcc_hi, s41, s59
	global_load_lds_dwordx4 v156, vcc
	s_waitcnt vmcnt(6)
	s_barrier
	v_mfma_f32_16x16x32_bf16 v[60:63], v[208:211], v[152:155], v[60:63]
	v_mfma_f32_16x16x32_bf16 v[56:59], v[216:219], v[152:155], v[56:59]
	v_mfma_f32_16x16x32_bf16 v[44:47], v[208:211], v[164:167], v[44:47]
	v_mfma_f32_16x16x32_bf16 v[40:43], v[216:219], v[164:167], v[40:43]
	v_mfma_f32_16x16x32_bf16 v[28:31], v[208:211], v[176:179], v[28:31]
	v_mfma_f32_16x16x32_bf16 v[24:27], v[216:219], v[176:179], v[24:27]
	v_mfma_f32_16x16x32_bf16 v[12:15], v[208:211], v[200:203], v[12:15]
	v_mfma_f32_16x16x32_bf16 v[8:11], v[216:219], v[200:203], v[8:11]
	v_mfma_f32_16x16x32_bf16 v[60:63], v[212:215], v[160:163], v[60:63]
	v_mfma_f32_16x16x32_bf16 v[56:59], v[220:223], v[160:163], v[56:59]
	v_mfma_f32_16x16x32_bf16 v[44:47], v[212:215], v[172:175], v[44:47]
	v_mfma_f32_16x16x32_bf16 v[40:43], v[220:223], v[172:175], v[40:43]
	v_mfma_f32_16x16x32_bf16 v[28:31], v[212:215], v[196:199], v[28:31]
	v_mfma_f32_16x16x32_bf16 v[24:27], v[220:223], v[196:199], v[24:27]
	v_mfma_f32_16x16x32_bf16 v[12:15], v[212:215], v[204:207], v[12:15]
	v_mfma_f32_16x16x32_bf16 v[8:11], v[220:223], v[204:207], v[8:11]
	s_barrier
	s_add_i32 s100, 0, 0x18000
	ds_read_b128 v[136:139], v255 offset:32768
	ds_read_b128 v[140:143], v255 offset:33792
	ds_read_b128 v[144:147], v255 offset:34816
	ds_read_b128 v[148:151], v255 offset:35840
	s_mov_b32 m0, s31
	ds_read_b128 v[152:155], v182 offset:32768
	ds_read_b128 v[160:163], v182 offset:33792
	ds_read_b128 v[164:167], v182 offset:34816
	ds_read_b128 v[172:175], v182 offset:35840
	ds_read_b128 v[176:179], v182 offset:36864
	ds_read_b128 v[196:199], v182 offset:37888
	ds_read_b128 v[200:203], v182 offset:38912
	ds_read_b128 v[204:207], v182 offset:39936
	s_add_u32 vcc_lo, s4, s54
	s_addc_u32 vcc_hi, s5, s55
	global_load_lds_dwordx4 v2, vcc
	s_mov_b32 m0, s34
	s_nop 0
	s_add_u32 vcc_lo, s4, s58
	s_addc_u32 vcc_hi, s5, s59
	global_load_lds_dwordx4 v2, vcc
	s_waitcnt lgkmcnt(8)
	s_barrier
; #define G_STAGE(bufoff, gbase, o0, h64) do { \
;         __builtin_amdgcn_global_load_lds((const unsigned*)((const char*)(gbase) + (o0)), (LAS unsigned*)(lds + (bufoff) + ldsw), 16, 0, 0); \
;         __builtin_amdgcn_global_load_lds((const unsigned*)((const char*)(gbase) + (h64) + (o0)), (LAS unsigned*)(lds + (bufoff) + ldsw + 8192), 16, 0, 0); } while (0)
; #define G_LDA(dst, b, h) do { _Pragma("unroll") for (int m = 0; m < 4; ++m) _Pragma("unroll") for (int k = 0; k < 2; ++k) dst[m][k] = *(const LAS bf16x8*)(lds + G_SA(b, h) + aoff + m * 2048 + k * 1024); } while (0)
; #define G_LDB(dst, b, h) do { _Pragma("unroll") for (int n = 0; n < 2; ++n) _Pragma("unroll") for (int k = 0; k < 2; ++k) dst[n][k] = *(const LAS bf16x8*)(lds + G_SB(b, h) + boff + n * 2048 + k * 1024); } while (0)
; #define G_WAIT_V(n) asm volatile("s_waitcnt vmcnt(" #n ")" ::: "memory")
; #define G_WAIT_L(n) asm volatile("s_waitcnt lgkmcnt(" #n ")" ::: "memory")
; #define G_BAR __builtin_amdgcn_s_barrier()
; #define G_SCHED __builtin_amdgcn_sched_barrier(0)
;     ...
;             G_WAIT_L(8); G_BAR; G_WAIT_L(0); G_MMA(0, 0, At, B0); G_BAR; G_SCHED;
;             G_LDB(B1, 1, 1); G_STAGE(G_SB(1, 0), b3, cB0, qB);
;             G_BAR; G_WAIT_L(0); G_MMA(0, 1, At, B1); G_BAR;
;             G_LDA(At, 1, 1); G_STAGE(G_SA(1, 0), a3, cA0, qA);
;             G_BAR; G_WAIT_L(0); G_MMA(1, 0, At, B0); G_BAR; G_SCHED;
;             G_STAGE(G_SB(1, 1), b3 + chB, cB0, qB);
;             G_WAIT_V(6); G_BAR; G_MMA(1, 1, At, B1); G_BAR;
;         }
	s_waitcnt lgkmcnt(0)
	v_mfma_f32_16x16x32_bf16 v[132:135], v[136:139], v[152:155], v[132:135]
	v_mfma_f32_16x16x32_bf16 v[128:131], v[144:147], v[152:155], v[128:131]
	v_mfma_f32_16x16x32_bf16 v[116:119], v[136:139], v[164:167], v[116:119]
	v_mfma_f32_16x16x32_bf16 v[112:115], v[144:147], v[164:167], v[112:115]
	v_mfma_f32_16x16x32_bf16 v[100:103], v[136:139], v[176:179], v[100:103]
	v_mfma_f32_16x16x32_bf16 v[96:99], v[144:147], v[176:179], v[96:99]
	v_mfma_f32_16x16x32_bf16 v[84:87], v[136:139], v[200:203], v[84:87]
	v_mfma_f32_16x16x32_bf16 v[80:83], v[144:147], v[200:203], v[80:83]
	v_mfma_f32_16x16x32_bf16 v[132:135], v[140:143], v[160:163], v[132:135]
	v_mfma_f32_16x16x32_bf16 v[128:131], v[148:151], v[160:163], v[128:131]
	v_mfma_f32_16x16x32_bf16 v[116:119], v[140:143], v[172:175], v[116:119]
	v_mfma_f32_16x16x32_bf16 v[112:115], v[148:151], v[172:175], v[112:115]
	v_mfma_f32_16x16x32_bf16 v[100:103], v[140:143], v[196:199], v[100:103]
	v_mfma_f32_16x16x32_bf16 v[96:99], v[148:151], v[196:199], v[96:99]
	v_mfma_f32_16x16x32_bf16 v[84:87], v[140:143], v[204:207], v[84:87]
	v_mfma_f32_16x16x32_bf16 v[80:83], v[148:151], v[204:207], v[80:83]
	s_barrier
	s_add_i32 s5, 0, 0x1c000
	s_add_i32 s4, s100, s27
	s_mov_b32 m0, s4
	ds_read_b128 v[208:211], v255 offset:49152
	ds_read_b128 v[212:215], v255 offset:50176
	ds_read_b128 v[216:219], v255 offset:51200
	ds_read_b128 v[220:223], v255 offset:52224
	s_add_u32 vcc_lo, s40, s46
	s_addc_u32 vcc_hi, s41, s47
	global_load_lds_dwordx4 v156, vcc
	s_add_i32 m0, s4, 0x2000
	s_nop 0
	s_add_u32 vcc_lo, s40, s62
	s_addc_u32 vcc_hi, s41, s63
	global_load_lds_dwordx4 v156, vcc
	s_barrier
	s_waitcnt lgkmcnt(0)
	v_mfma_f32_16x16x32_bf16 v[124:127], v[208:211], v[152:155], v[124:127]
	v_mfma_f32_16x16x32_bf16 v[120:123], v[216:219], v[152:155], v[120:123]
	v_mfma_f32_16x16x32_bf16 v[108:111], v[208:211], v[164:167], v[108:111]
	v_mfma_f32_16x16x32_bf16 v[104:107], v[216:219], v[164:167], v[104:107]
	v_mfma_f32_16x16x32_bf16 v[92:95], v[208:211], v[176:179], v[92:95]
	v_mfma_f32_16x16x32_bf16 v[88:91], v[216:219], v[176:179], v[88:91]
	v_mfma_f32_16x16x32_bf16 v[76:79], v[208:211], v[200:203], v[76:79]
	v_mfma_f32_16x16x32_bf16 v[72:75], v[216:219], v[200:203], v[72:75]
	v_mfma_f32_16x16x32_bf16 v[124:127], v[212:215], v[160:163], v[124:127]
	v_mfma_f32_16x16x32_bf16 v[120:123], v[220:223], v[160:163], v[120:123]
	v_mfma_f32_16x16x32_bf16 v[108:111], v[212:215], v[172:175], v[108:111]
	v_mfma_f32_16x16x32_bf16 v[104:107], v[220:223], v[172:175], v[104:107]
	v_mfma_f32_16x16x32_bf16 v[92:95], v[212:215], v[196:199], v[92:95]
	v_mfma_f32_16x16x32_bf16 v[88:91], v[220:223], v[196:199], v[88:91]
	v_mfma_f32_16x16x32_bf16 v[76:79], v[212:215], v[204:207], v[76:79]
	v_mfma_f32_16x16x32_bf16 v[72:75], v[220:223], v[204:207], v[72:75]
	s_barrier
	s_mov_b32 m0, s35
	v_lshl_add_u64 v[226:227], v[224:225], 0, s[46:47]
	ds_read_b128 v[152:155], v182 offset:49152
	ds_read_b128 v[160:163], v182 offset:50176
	ds_read_b128 v[164:167], v182 offset:51200
	ds_read_b128 v[172:175], v182 offset:52224
	ds_read_b128 v[176:179], v182 offset:53248
	ds_read_b128 v[196:199], v182 offset:54272
	ds_read_b128 v[200:203], v182 offset:55296
	ds_read_b128 v[204:207], v182 offset:56320
	global_load_lds_dwordx4 v[226:227], off
	v_lshl_add_u64 v[224:225], v[224:225], 0, s[62:63]
	s_mov_b32 m0, s36
	s_nop 0
	global_load_lds_dwordx4 v[224:225], off
	s_barrier
	s_waitcnt lgkmcnt(0)
	v_mfma_f32_16x16x32_bf16 v[68:71], v[136:139], v[152:155], v[68:71]
	v_mfma_f32_16x16x32_bf16 v[64:67], v[144:147], v[152:155], v[64:67]
	v_mfma_f32_16x16x32_bf16 v[52:55], v[136:139], v[164:167], v[52:55]
	v_mfma_f32_16x16x32_bf16 v[48:51], v[144:147], v[164:167], v[48:51]
	v_mfma_f32_16x16x32_bf16 v[36:39], v[136:139], v[176:179], v[36:39]
	v_mfma_f32_16x16x32_bf16 v[32:35], v[144:147], v[176:179], v[32:35]
	v_mfma_f32_16x16x32_bf16 v[20:23], v[136:139], v[200:203], v[20:23]
	v_mfma_f32_16x16x32_bf16 v[16:19], v[144:147], v[200:203], v[16:19]
	v_mfma_f32_16x16x32_bf16 v[68:71], v[140:143], v[160:163], v[68:71]
	v_mfma_f32_16x16x32_bf16 v[64:67], v[148:151], v[160:163], v[64:67]
	v_mfma_f32_16x16x32_bf16 v[52:55], v[140:143], v[172:175], v[52:55]
	v_mfma_f32_16x16x32_bf16 v[48:51], v[148:151], v[172:175], v[48:51]
	v_mfma_f32_16x16x32_bf16 v[36:39], v[140:143], v[196:199], v[36:39]
	v_mfma_f32_16x16x32_bf16 v[32:35], v[148:151], v[196:199], v[32:35]
	v_mfma_f32_16x16x32_bf16 v[20:23], v[140:143], v[204:207], v[20:23]
	v_mfma_f32_16x16x32_bf16 v[16:19], v[148:151], v[204:207], v[16:19]
	s_barrier
	s_add_i32 s4, s5, s27
	s_mov_b32 m0, s4
	s_nop 0
	s_add_u32 vcc_lo, s40, s64
	s_addc_u32 vcc_hi, s41, s65
	global_load_lds_dwordx4 v156, vcc
	s_add_i32 m0, s4, 0x2000
	s_nop 0
	s_add_u32 vcc_lo, s40, s66
	s_addc_u32 vcc_hi, s41, s67
	global_load_lds_dwordx4 v156, vcc
	s_add_i32 s24, s24, 2
	s_add_u32 s2, s2, 0x100
	s_addc_u32 s3, s3, 0
	s_add_u32 s22, s22, 0x100
	s_addc_u32 s23, s23, 0
	s_cmp_gt_u32 s24, 13
	s_waitcnt vmcnt(6)
	s_barrier
	v_mfma_f32_16x16x32_bf16 v[60:63], v[208:211], v[152:155], v[60:63]
	v_mfma_f32_16x16x32_bf16 v[56:59], v[216:219], v[152:155], v[56:59]
	v_mfma_f32_16x16x32_bf16 v[44:47], v[208:211], v[164:167], v[44:47]
	v_mfma_f32_16x16x32_bf16 v[40:43], v[216:219], v[164:167], v[40:43]
	v_mfma_f32_16x16x32_bf16 v[28:31], v[208:211], v[176:179], v[28:31]
	v_mfma_f32_16x16x32_bf16 v[24:27], v[216:219], v[176:179], v[24:27]
	v_mfma_f32_16x16x32_bf16 v[12:15], v[208:211], v[200:203], v[12:15]
	v_mfma_f32_16x16x32_bf16 v[8:11], v[216:219], v[200:203], v[8:11]
	v_mfma_f32_16x16x32_bf16 v[60:63], v[212:215], v[160:163], v[60:63]
	v_mfma_f32_16x16x32_bf16 v[56:59], v[220:223], v[160:163], v[56:59]
	v_mfma_f32_16x16x32_bf16 v[44:47], v[212:215], v[172:175], v[44:47]
	v_mfma_f32_16x16x32_bf16 v[40:43], v[220:223], v[172:175], v[40:43]
	v_mfma_f32_16x16x32_bf16 v[28:31], v[212:215], v[196:199], v[28:31]
	v_mfma_f32_16x16x32_bf16 v[24:27], v[220:223], v[196:199], v[24:27]
	v_mfma_f32_16x16x32_bf16 v[12:15], v[212:215], v[204:207], v[12:15]
	v_mfma_f32_16x16x32_bf16 v[8:11], v[220:223], v[204:207], v[8:11]
	s_cbranch_scc0 .Ldb_PLE1_cont
